# in-proj c_fl (panel 15) epilogue: per-head biases loaded once and taken by readlane instead of 64 reloads each behind vmcnt(0)
# speedup vs baseline: 1.0081x; 1.0081x over previous
.LBB0_477:
	s_and_saveexec_b64 s[42:43], s[38:39]
	s_cbranch_execz .LBB0_479
	v_lshlrev_b32_e32 v255, 2, v227
	global_load_dword v254, v255, s[56:57]
	s_waitcnt vmcnt(0)
	v_and_b32_e32 v64, 0xfcf, v174
	v_lshlrev_b32_e32 v190, 2, v64
	v_readlane_b32 s100, v254, 0
	s_nop 1
	v_mov_b32_e32 v64, s100
	s_ashr_i32 s23, s23, 9
	s_and_b32 s30, s23, -8
	s_ashr_i32 s31, s30, 31
	v_lshl_add_u64 v[72:73], s[52:53], 0, v[190:191]
	s_lshl_b64 s[34:35], s[30:31], 14
	v_fmac_f32_e32 v64, v60, v172
	v_mul_f32_e64 v65, |v64|, s94
	v_fma_f32 v66, |v64|, s94, -v65
	v_rndne_f32_e32 v67, v65
	v_fma_f32 v66, |v64|, s64, v66
	v_sub_f32_e32 v65, v65, v67
	v_add_f32_e32 v65, v65, v66
	v_exp_f32_e32 v65, v65
	v_cvt_i32_f32_e32 v66, v67
	v_cmp_ngt_f32_e64 vcc, |v64|, s58
	v_min_f32_e32 v60, 0, v64
	v_ldexp_f32 v65, v65, v66
	v_cndmask_b32_e32 v65, 0, v65, vcc
	v_cmp_nlt_f32_e64 vcc, |v64|, s59
	s_nop 1
	v_cndmask_b32_e32 v66, v226, v65, vcc
	v_add_f32_e32 v67, 1.0, v66
	v_add_f32_e32 v64, -1.0, v67
	v_sub_f32_e32 v65, v64, v67
	v_add_f32_e32 v65, 1.0, v65
	v_sub_f32_e32 v64, v66, v64
	v_add_f32_e32 v68, v64, v65
	v_frexp_mant_f32_e32 v64, v67
	v_cmp_gt_f32_e32 vcc, s77, v64
	v_cvt_f64_f32_e32 v[64:65], v67
	v_frexp_exp_i32_f64_e32 v64, v[64:65]
	v_subbrev_co_u32_e32 v64, vcc, 0, v64, vcc
	v_sub_u32_e32 v65, 0, v64
	v_ldexp_f32 v67, v67, v65
	v_ldexp_f32 v65, v68, v65
	v_add_f32_e32 v68, -1.0, v67
	v_add_f32_e32 v69, 1.0, v68
	v_sub_f32_e32 v69, v67, v69
	v_add_f32_e32 v69, v65, v69
	v_add_f32_e32 v70, v68, v69
	v_sub_f32_e32 v68, v68, v70
	v_add_f32_e32 v68, v69, v68
	v_add_f32_e32 v69, 1.0, v67
	v_add_f32_e32 v71, -1.0, v69
	v_sub_f32_e32 v67, v67, v71
	v_add_f32_e32 v65, v65, v67
	v_add_f32_e32 v67, v69, v65
	v_sub_f32_e32 v69, v69, v67
	v_add_f32_e32 v65, v65, v69
	v_rcp_f32_e32 v69, v67
	v_cvt_f32_i32_e32 v64, v64
	v_cmp_neq_f32_e32 vcc, s62, v66
	v_mul_f32_e32 v71, v70, v69
	v_mul_f32_e32 v74, v67, v71
	v_fma_f32 v75, v71, v67, -v74
	v_fmac_f32_e32 v75, v71, v65
	v_add_f32_e32 v76, v74, v75
	v_sub_f32_e32 v77, v70, v76
	v_sub_f32_e32 v70, v70, v77
	v_sub_f32_e32 v74, v76, v74
	v_sub_f32_e32 v70, v70, v76
	v_add_f32_e32 v68, v68, v70
	v_sub_f32_e32 v70, v74, v75
	v_add_f32_e32 v68, v70, v68
	v_add_f32_e32 v70, v77, v68
	v_mul_f32_e32 v74, v69, v70
	v_mul_f32_e32 v75, v67, v74
	v_fma_f32 v67, v74, v67, -v75
	v_fmac_f32_e32 v67, v74, v65
	v_sub_f32_e32 v65, v77, v70
	v_add_f32_e32 v65, v68, v65
	v_add_f32_e32 v68, v75, v67
	v_sub_f32_e32 v76, v70, v68
	v_sub_f32_e32 v70, v70, v76
	v_sub_f32_e32 v75, v68, v75
	v_sub_f32_e32 v68, v70, v68
	v_add_f32_e32 v65, v65, v68
	v_sub_f32_e32 v67, v75, v67
	v_add_f32_e32 v65, v67, v65
	v_add_f32_e32 v67, v71, v74
	v_add_f32_e32 v65, v76, v65
	v_sub_f32_e32 v68, v67, v71
	v_mul_f32_e32 v65, v69, v65
	v_sub_f32_e32 v68, v74, v68
	v_add_f32_e32 v65, v68, v65
	v_mul_f32_e32 v71, 0x3f317218, v64
	v_add_f32_e32 v68, v67, v65
	v_fma_f32 v74, v64, s78, -v71
	v_mul_f32_e32 v69, v68, v68
	v_fmac_f32_e32 v74, 0xb102e308, v64
	v_sub_f32_e32 v64, v68, v67
	v_fmamk_f32 v70, v69, 0x3e9b6dac, v185
	v_sub_f32_e32 v64, v65, v64
	v_add_f32_e32 v65, v71, v74
	v_fmaak_f32 v70, v69, v70, 0x3f2aaada
	v_sub_f32_e32 v67, v65, v71
	v_ldexp_f32 v71, v68, 1
	v_mul_f32_e32 v68, v68, v69
	v_mul_f32_e32 v68, v68, v70
	v_add_f32_e32 v69, v71, v68
	v_sub_f32_e32 v70, v69, v71
	v_ldexp_f32 v64, v64, 1
	v_sub_f32_e32 v68, v68, v70
	v_add_f32_e32 v64, v64, v68
	v_add_f32_e32 v68, v69, v64
	v_sub_f32_e32 v69, v68, v69
	v_sub_f32_e32 v64, v64, v69
	v_add_f32_e32 v69, v65, v68
	v_sub_f32_e32 v70, v69, v65
	v_sub_f32_e32 v71, v69, v70
	v_sub_f32_e32 v67, v74, v67
	v_sub_f32_e32 v65, v65, v71
	v_sub_f32_e32 v68, v68, v70
	v_add_f32_e32 v65, v68, v65
	v_add_f32_e32 v68, v67, v64
	v_sub_f32_e32 v70, v68, v67
	v_sub_f32_e32 v71, v68, v70
	v_sub_f32_e32 v67, v67, v71
	v_sub_f32_e32 v64, v64, v70
	v_add_f32_e32 v65, v68, v65
	v_add_f32_e32 v64, v64, v67
	v_add_f32_e32 v67, v69, v65
	v_sub_f32_e32 v68, v67, v69
	v_sub_f32_e32 v65, v65, v68
	v_add_f32_e32 v64, v64, v65
	v_add_f32_e32 v64, v67, v64
	v_cndmask_b32_e32 v64, v226, v64, vcc
	v_cmp_lt_f32_e64 vcc, |v66|, s63
	s_nop 1
	v_cndmask_b32_e32 v64, v64, v66, vcc
	v_sub_f32_e32 v60, v60, v64
	v_mul_f32_e32 v60, 0x3fb8aa3b, v60
	v_lshl_add_u64 v[64:65], v[72:73], 0, s[34:35]
	global_store_dword v[64:65], v60, off
	v_readlane_b32 s100, v254, 1
	s_nop 1
	v_mov_b32_e32 v60, s100
	s_or_b32 s34, s30, 1
	s_ashr_i32 s35, s34, 31
	s_lshl_b64 s[34:35], s[34:35], 14
	v_fmac_f32_e32 v60, v61, v172
	v_mul_f32_e64 v61, |v60|, s94
	v_fma_f32 v67, |v60|, s94, -v61
	v_rndne_f32_e32 v68, v61
	v_fma_f32 v67, |v60|, s64, v67
	v_sub_f32_e32 v61, v61, v68
	v_add_f32_e32 v61, v61, v67
	v_exp_f32_e32 v61, v61
	v_cvt_i32_f32_e32 v67, v68
	v_cmp_ngt_f32_e64 vcc, |v60|, s58
	v_min_f32_e32 v66, 0, v60
	v_ldexp_f32 v61, v61, v67
	v_cndmask_b32_e32 v61, 0, v61, vcc
	v_cmp_nlt_f32_e64 vcc, |v60|, s59
	s_nop 1
	v_cndmask_b32_e32 v67, v226, v61, vcc
	v_add_f32_e32 v68, 1.0, v67
	v_add_f32_e32 v60, -1.0, v68
	v_sub_f32_e32 v61, v60, v68
	v_add_f32_e32 v61, 1.0, v61
	v_sub_f32_e32 v60, v67, v60
	v_add_f32_e32 v69, v60, v61
	v_frexp_mant_f32_e32 v60, v68
	v_cmp_gt_f32_e32 vcc, s77, v60
	v_cvt_f64_f32_e32 v[60:61], v68
	v_frexp_exp_i32_f64_e32 v60, v[60:61]
	v_subbrev_co_u32_e32 v60, vcc, 0, v60, vcc
	v_sub_u32_e32 v61, 0, v60
	v_ldexp_f32 v68, v68, v61
	v_ldexp_f32 v61, v69, v61
	v_add_f32_e32 v69, -1.0, v68
	v_add_f32_e32 v70, 1.0, v69
	v_sub_f32_e32 v70, v68, v70
	v_add_f32_e32 v70, v61, v70
	v_add_f32_e32 v71, v69, v70
	v_sub_f32_e32 v69, v69, v71
	v_add_f32_e32 v69, v70, v69
	v_add_f32_e32 v70, 1.0, v68
	v_add_f32_e32 v74, -1.0, v70
	v_sub_f32_e32 v68, v68, v74
	v_add_f32_e32 v61, v61, v68
	v_add_f32_e32 v68, v70, v61
	v_sub_f32_e32 v70, v70, v68
	v_add_f32_e32 v61, v61, v70
	v_rcp_f32_e32 v70, v68
	v_cvt_f32_i32_e32 v60, v60
	v_cmp_neq_f32_e32 vcc, s62, v67
	v_mul_f32_e32 v74, v71, v70
	v_mul_f32_e32 v75, v68, v74
	v_fma_f32 v76, v74, v68, -v75
	v_fmac_f32_e32 v76, v74, v61
	v_add_f32_e32 v77, v75, v76
	v_sub_f32_e32 v78, v71, v77
	v_sub_f32_e32 v71, v71, v78
	v_sub_f32_e32 v75, v77, v75
	v_sub_f32_e32 v71, v71, v77
	v_add_f32_e32 v69, v69, v71
	v_sub_f32_e32 v71, v75, v76
	v_add_f32_e32 v69, v71, v69
	v_add_f32_e32 v71, v78, v69
	v_mul_f32_e32 v75, v70, v71
	v_mul_f32_e32 v76, v68, v75
	v_fma_f32 v68, v75, v68, -v76
	v_fmac_f32_e32 v68, v75, v61
	v_sub_f32_e32 v61, v78, v71
	v_add_f32_e32 v61, v69, v61
	v_add_f32_e32 v69, v76, v68
	v_sub_f32_e32 v77, v71, v69
	v_sub_f32_e32 v71, v71, v77
	v_sub_f32_e32 v76, v69, v76
	v_sub_f32_e32 v69, v71, v69
	v_add_f32_e32 v61, v61, v69
	v_sub_f32_e32 v68, v76, v68
	v_add_f32_e32 v61, v68, v61
	v_add_f32_e32 v68, v74, v75
	v_add_f32_e32 v61, v77, v61
	v_sub_f32_e32 v69, v68, v74
	v_mul_f32_e32 v61, v70, v61
	v_sub_f32_e32 v69, v75, v69
	v_add_f32_e32 v61, v69, v61
	v_mul_f32_e32 v74, 0x3f317218, v60
	v_add_f32_e32 v69, v68, v61
	v_fma_f32 v75, v60, s78, -v74
	v_mul_f32_e32 v70, v69, v69
	v_fmac_f32_e32 v75, 0xb102e308, v60
	v_sub_f32_e32 v60, v69, v68
	v_fmamk_f32 v71, v70, 0x3e9b6dac, v185
	v_sub_f32_e32 v60, v61, v60
	v_add_f32_e32 v61, v74, v75
	v_fmaak_f32 v71, v70, v71, 0x3f2aaada
	v_sub_f32_e32 v68, v61, v74
	v_ldexp_f32 v74, v69, 1
	v_mul_f32_e32 v69, v69, v70
	v_mul_f32_e32 v69, v69, v71
	v_add_f32_e32 v70, v74, v69
	v_sub_f32_e32 v71, v70, v74
	v_ldexp_f32 v60, v60, 1
	v_sub_f32_e32 v69, v69, v71
	v_add_f32_e32 v60, v60, v69
	v_add_f32_e32 v69, v70, v60
	v_sub_f32_e32 v70, v69, v70
	v_sub_f32_e32 v60, v60, v70
	v_add_f32_e32 v70, v61, v69
	v_sub_f32_e32 v71, v70, v61
	v_sub_f32_e32 v74, v70, v71
	v_sub_f32_e32 v68, v75, v68
	v_sub_f32_e32 v61, v61, v74
	v_sub_f32_e32 v69, v69, v71
	v_add_f32_e32 v61, v69, v61
	v_add_f32_e32 v69, v68, v60
	v_sub_f32_e32 v71, v69, v68
	v_sub_f32_e32 v74, v69, v71
	v_sub_f32_e32 v68, v68, v74
	v_sub_f32_e32 v60, v60, v71
	v_add_f32_e32 v61, v69, v61
	v_add_f32_e32 v60, v60, v68
	v_add_f32_e32 v68, v70, v61
	v_sub_f32_e32 v69, v68, v70
	v_sub_f32_e32 v61, v61, v69
	v_add_f32_e32 v60, v60, v61
	v_add_f32_e32 v60, v68, v60
	v_cndmask_b32_e32 v60, v226, v60, vcc
	v_cmp_lt_f32_e64 vcc, |v67|, s63
	s_nop 1
	v_cndmask_b32_e32 v60, v60, v67, vcc
	v_sub_f32_e32 v60, v66, v60
	v_mul_f32_e32 v66, 0x3fb8aa3b, v60
	v_lshl_add_u64 v[60:61], v[72:73], 0, s[34:35]
	global_store_dword v[60:61], v66, off
	v_readlane_b32 s100, v254, 2
	s_nop 1
	v_mov_b32_e32 v66, s100
	s_or_b32 s34, s30, 2
	s_ashr_i32 s35, s34, 31
	s_lshl_b64 s[34:35], s[34:35], 14
	v_fmac_f32_e32 v66, v62, v172
	v_mul_f32_e64 v67, |v66|, s94
	v_fma_f32 v68, |v66|, s94, -v67
	v_rndne_f32_e32 v69, v67
	v_fma_f32 v68, |v66|, s64, v68
	v_sub_f32_e32 v67, v67, v69
	v_add_f32_e32 v67, v67, v68
	v_exp_f32_e32 v67, v67
	v_cvt_i32_f32_e32 v68, v69
	v_cmp_ngt_f32_e64 vcc, |v66|, s58
	v_min_f32_e32 v62, 0, v66
	v_ldexp_f32 v67, v67, v68
	v_cndmask_b32_e32 v67, 0, v67, vcc
	v_cmp_nlt_f32_e64 vcc, |v66|, s59
	s_nop 1
	v_cndmask_b32_e32 v68, v226, v67, vcc
	v_add_f32_e32 v69, 1.0, v68
	v_add_f32_e32 v66, -1.0, v69
	v_sub_f32_e32 v67, v66, v69
	v_add_f32_e32 v67, 1.0, v67
	v_sub_f32_e32 v66, v68, v66
	v_add_f32_e32 v70, v66, v67
	v_frexp_mant_f32_e32 v66, v69
	v_cmp_gt_f32_e32 vcc, s77, v66
	v_cvt_f64_f32_e32 v[66:67], v69
	v_frexp_exp_i32_f64_e32 v66, v[66:67]
	v_subbrev_co_u32_e32 v66, vcc, 0, v66, vcc
	v_sub_u32_e32 v67, 0, v66
	v_ldexp_f32 v69, v69, v67
	v_ldexp_f32 v67, v70, v67
	v_add_f32_e32 v70, -1.0, v69
	v_add_f32_e32 v71, 1.0, v70
	v_sub_f32_e32 v71, v69, v71
	v_add_f32_e32 v71, v67, v71
	v_add_f32_e32 v74, v70, v71
	v_sub_f32_e32 v70, v70, v74
	v_add_f32_e32 v70, v71, v70
	v_add_f32_e32 v71, 1.0, v69
	v_add_f32_e32 v75, -1.0, v71
	v_sub_f32_e32 v69, v69, v75
	v_add_f32_e32 v67, v67, v69
	v_add_f32_e32 v69, v71, v67
	v_sub_f32_e32 v71, v71, v69
	v_add_f32_e32 v67, v67, v71
	v_rcp_f32_e32 v71, v69
	v_cvt_f32_i32_e32 v66, v66
	v_cmp_neq_f32_e32 vcc, s62, v68
	v_mul_f32_e32 v75, v74, v71
	v_mul_f32_e32 v76, v69, v75
	v_fma_f32 v77, v75, v69, -v76
	v_fmac_f32_e32 v77, v75, v67
	v_add_f32_e32 v78, v76, v77
	v_sub_f32_e32 v79, v74, v78
	v_sub_f32_e32 v74, v74, v79
	v_sub_f32_e32 v76, v78, v76
	v_sub_f32_e32 v74, v74, v78
	v_add_f32_e32 v70, v70, v74
	v_sub_f32_e32 v74, v76, v77
	v_add_f32_e32 v70, v74, v70
	v_add_f32_e32 v74, v79, v70
	v_mul_f32_e32 v76, v71, v74
	v_mul_f32_e32 v77, v69, v76
	v_fma_f32 v69, v76, v69, -v77
	v_fmac_f32_e32 v69, v76, v67
	v_sub_f32_e32 v67, v79, v74
	v_add_f32_e32 v67, v70, v67
	v_add_f32_e32 v70, v77, v69
	v_sub_f32_e32 v78, v74, v70
	v_sub_f32_e32 v74, v74, v78
	v_sub_f32_e32 v77, v70, v77
	v_sub_f32_e32 v70, v74, v70
	v_add_f32_e32 v67, v67, v70
	v_sub_f32_e32 v69, v77, v69
	v_add_f32_e32 v67, v69, v67
	v_add_f32_e32 v69, v75, v76
	v_add_f32_e32 v67, v78, v67
	v_sub_f32_e32 v70, v69, v75
	v_mul_f32_e32 v67, v71, v67
	v_sub_f32_e32 v70, v76, v70
	v_add_f32_e32 v67, v70, v67
	v_mul_f32_e32 v75, 0x3f317218, v66
	v_add_f32_e32 v70, v69, v67
	v_fma_f32 v76, v66, s78, -v75
	v_mul_f32_e32 v71, v70, v70
	v_fmac_f32_e32 v76, 0xb102e308, v66
	v_sub_f32_e32 v66, v70, v69
	v_fmamk_f32 v74, v71, 0x3e9b6dac, v185
	v_sub_f32_e32 v66, v67, v66
	v_add_f32_e32 v67, v75, v76
	v_fmaak_f32 v74, v71, v74, 0x3f2aaada
	v_sub_f32_e32 v69, v67, v75
	v_ldexp_f32 v75, v70, 1
	v_mul_f32_e32 v70, v70, v71
	v_mul_f32_e32 v70, v70, v74
	v_add_f32_e32 v71, v75, v70
	v_sub_f32_e32 v74, v71, v75
	v_ldexp_f32 v66, v66, 1
	v_sub_f32_e32 v70, v70, v74
	v_add_f32_e32 v66, v66, v70
	v_add_f32_e32 v70, v71, v66
	v_sub_f32_e32 v71, v70, v71
	v_sub_f32_e32 v66, v66, v71
	v_add_f32_e32 v71, v67, v70
	v_sub_f32_e32 v74, v71, v67
	v_sub_f32_e32 v75, v71, v74
	v_sub_f32_e32 v69, v76, v69
	v_sub_f32_e32 v67, v67, v75
	v_sub_f32_e32 v70, v70, v74
	v_add_f32_e32 v67, v70, v67
	v_add_f32_e32 v70, v69, v66
	v_sub_f32_e32 v74, v70, v69
	v_sub_f32_e32 v75, v70, v74
	v_sub_f32_e32 v69, v69, v75
	v_sub_f32_e32 v66, v66, v74
	v_add_f32_e32 v67, v70, v67
	v_add_f32_e32 v66, v66, v69
	v_add_f32_e32 v69, v71, v67
	v_sub_f32_e32 v70, v69, v71
	v_sub_f32_e32 v67, v67, v70
	v_add_f32_e32 v66, v66, v67
	v_add_f32_e32 v66, v69, v66
	v_cndmask_b32_e32 v66, v226, v66, vcc
	v_cmp_lt_f32_e64 vcc, |v68|, s63
	s_nop 1
	v_cndmask_b32_e32 v66, v66, v68, vcc
	v_sub_f32_e32 v62, v62, v66
	v_mul_f32_e32 v62, 0x3fb8aa3b, v62
	v_lshl_add_u64 v[66:67], v[72:73], 0, s[34:35]
	global_store_dword v[66:67], v62, off
	v_readlane_b32 s100, v254, 3
	s_nop 1
	v_mov_b32_e32 v62, s100
	s_or_b32 s34, s30, 3
	s_ashr_i32 s35, s34, 31
	s_lshl_b64 s[34:35], s[34:35], 14
	v_fmac_f32_e32 v62, v63, v172
	v_mul_f32_e64 v63, |v62|, s94
	v_fma_f32 v69, |v62|, s94, -v63
	v_rndne_f32_e32 v70, v63
	v_fma_f32 v69, |v62|, s64, v69
	v_sub_f32_e32 v63, v63, v70
	v_add_f32_e32 v63, v63, v69
	v_exp_f32_e32 v63, v63
	v_cvt_i32_f32_e32 v69, v70
	v_cmp_ngt_f32_e64 vcc, |v62|, s58
	v_min_f32_e32 v68, 0, v62
	v_ldexp_f32 v63, v63, v69
	v_cndmask_b32_e32 v63, 0, v63, vcc
	v_cmp_nlt_f32_e64 vcc, |v62|, s59
	s_nop 1
	v_cndmask_b32_e32 v69, v226, v63, vcc
	v_add_f32_e32 v70, 1.0, v69
	v_add_f32_e32 v62, -1.0, v70
	v_sub_f32_e32 v63, v62, v70
	v_add_f32_e32 v63, 1.0, v63
	v_sub_f32_e32 v62, v69, v62
	v_add_f32_e32 v71, v62, v63
	v_frexp_mant_f32_e32 v62, v70
	v_cmp_gt_f32_e32 vcc, s77, v62
	v_cvt_f64_f32_e32 v[62:63], v70
	v_frexp_exp_i32_f64_e32 v62, v[62:63]
	v_subbrev_co_u32_e32 v62, vcc, 0, v62, vcc
	v_sub_u32_e32 v63, 0, v62
	v_ldexp_f32 v70, v70, v63
	v_ldexp_f32 v63, v71, v63
	v_add_f32_e32 v71, -1.0, v70
	v_add_f32_e32 v74, 1.0, v71
	v_sub_f32_e32 v74, v70, v74
	v_add_f32_e32 v74, v63, v74
	v_add_f32_e32 v75, v71, v74
	v_sub_f32_e32 v71, v71, v75
	v_add_f32_e32 v71, v74, v71
	v_add_f32_e32 v74, 1.0, v70
	v_add_f32_e32 v76, -1.0, v74
	v_sub_f32_e32 v70, v70, v76
	v_add_f32_e32 v63, v63, v70
	v_add_f32_e32 v70, v74, v63
	v_sub_f32_e32 v74, v74, v70
	v_add_f32_e32 v63, v63, v74
	v_rcp_f32_e32 v74, v70
	v_cvt_f32_i32_e32 v62, v62
	v_cmp_neq_f32_e32 vcc, s62, v69
	v_mul_f32_e32 v76, v75, v74
	v_mul_f32_e32 v77, v70, v76
	v_fma_f32 v78, v76, v70, -v77
	v_fmac_f32_e32 v78, v76, v63
	v_add_f32_e32 v79, v77, v78
	v_sub_f32_e32 v80, v75, v79
	v_sub_f32_e32 v75, v75, v80
	v_sub_f32_e32 v77, v79, v77
	v_sub_f32_e32 v75, v75, v79
	v_add_f32_e32 v71, v71, v75
	v_sub_f32_e32 v75, v77, v78
	v_add_f32_e32 v71, v75, v71
	v_add_f32_e32 v75, v80, v71
	v_mul_f32_e32 v77, v74, v75
	v_mul_f32_e32 v78, v70, v77
	v_fma_f32 v70, v77, v70, -v78
	v_fmac_f32_e32 v70, v77, v63
	v_sub_f32_e32 v63, v80, v75
	v_add_f32_e32 v63, v71, v63
	v_add_f32_e32 v71, v78, v70
	v_sub_f32_e32 v79, v75, v71
	v_sub_f32_e32 v75, v75, v79
	v_sub_f32_e32 v78, v71, v78
	v_sub_f32_e32 v71, v75, v71
	v_add_f32_e32 v63, v63, v71
	v_sub_f32_e32 v70, v78, v70
	v_add_f32_e32 v63, v70, v63
	v_add_f32_e32 v70, v76, v77
	v_add_f32_e32 v63, v79, v63
	v_sub_f32_e32 v71, v70, v76
	v_mul_f32_e32 v63, v74, v63
	v_sub_f32_e32 v71, v77, v71
	v_add_f32_e32 v63, v71, v63
	v_mul_f32_e32 v76, 0x3f317218, v62
	v_add_f32_e32 v71, v70, v63
	v_fma_f32 v77, v62, s78, -v76
	v_mul_f32_e32 v74, v71, v71
	v_fmac_f32_e32 v77, 0xb102e308, v62
	v_sub_f32_e32 v62, v71, v70
	v_fmamk_f32 v75, v74, 0x3e9b6dac, v185
	v_sub_f32_e32 v62, v63, v62
	v_add_f32_e32 v63, v76, v77
	v_fmaak_f32 v75, v74, v75, 0x3f2aaada
	v_sub_f32_e32 v70, v63, v76
	v_ldexp_f32 v76, v71, 1
	v_mul_f32_e32 v71, v71, v74
	v_mul_f32_e32 v71, v71, v75
	v_add_f32_e32 v74, v76, v71
	v_sub_f32_e32 v75, v74, v76
	v_ldexp_f32 v62, v62, 1
	v_sub_f32_e32 v71, v71, v75
	v_add_f32_e32 v62, v62, v71
	v_add_f32_e32 v71, v74, v62
	v_sub_f32_e32 v74, v71, v74
	v_sub_f32_e32 v62, v62, v74
	v_add_f32_e32 v74, v63, v71
	v_sub_f32_e32 v75, v74, v63
	v_sub_f32_e32 v76, v74, v75
	v_sub_f32_e32 v70, v77, v70
	v_sub_f32_e32 v63, v63, v76
	v_sub_f32_e32 v71, v71, v75
	v_add_f32_e32 v63, v71, v63
	v_add_f32_e32 v71, v70, v62
	v_sub_f32_e32 v75, v71, v70
	v_sub_f32_e32 v76, v71, v75
	v_sub_f32_e32 v70, v70, v76
	v_sub_f32_e32 v62, v62, v75
	v_add_f32_e32 v63, v71, v63
	v_add_f32_e32 v62, v62, v70
	v_add_f32_e32 v70, v74, v63
	v_sub_f32_e32 v71, v70, v74
	v_sub_f32_e32 v63, v63, v71
	v_add_f32_e32 v62, v62, v63
	v_add_f32_e32 v62, v70, v62
	v_cndmask_b32_e32 v62, v226, v62, vcc
	v_cmp_lt_f32_e64 vcc, |v69|, s63
	s_nop 1
	v_cndmask_b32_e32 v62, v62, v69, vcc
	v_sub_f32_e32 v62, v68, v62
	v_mul_f32_e32 v68, 0x3fb8aa3b, v62
	v_lshl_add_u64 v[62:63], v[72:73], 0, s[34:35]
	global_store_dword v[62:63], v68, off
	v_readlane_b32 s100, v254, 4
	s_nop 1
	v_mov_b32_e32 v68, s100
	s_or_b32 s34, s30, 4
	s_ashr_i32 s35, s34, 31
	s_lshl_b64 s[34:35], s[34:35], 14
	v_fmac_f32_e32 v68, v56, v172
	v_mul_f32_e64 v69, |v68|, s94
	v_fma_f32 v70, |v68|, s94, -v69
	v_rndne_f32_e32 v71, v69
	v_fma_f32 v70, |v68|, s64, v70
	v_sub_f32_e32 v69, v69, v71
	v_add_f32_e32 v69, v69, v70
	v_exp_f32_e32 v69, v69
	v_cvt_i32_f32_e32 v70, v71
	v_cmp_ngt_f32_e64 vcc, |v68|, s58
	v_min_f32_e32 v56, 0, v68
	v_ldexp_f32 v69, v69, v70
	v_cndmask_b32_e32 v69, 0, v69, vcc
	v_cmp_nlt_f32_e64 vcc, |v68|, s59
	s_nop 1
	v_cndmask_b32_e32 v70, v226, v69, vcc
	v_add_f32_e32 v71, 1.0, v70
	v_add_f32_e32 v68, -1.0, v71
	v_sub_f32_e32 v69, v68, v71
	v_add_f32_e32 v69, 1.0, v69
	v_sub_f32_e32 v68, v70, v68
	v_add_f32_e32 v74, v68, v69
	v_frexp_mant_f32_e32 v68, v71
	v_cmp_gt_f32_e32 vcc, s77, v68
	v_cvt_f64_f32_e32 v[68:69], v71
	v_frexp_exp_i32_f64_e32 v68, v[68:69]
	v_subbrev_co_u32_e32 v68, vcc, 0, v68, vcc
	v_sub_u32_e32 v69, 0, v68
	v_ldexp_f32 v71, v71, v69
	v_ldexp_f32 v69, v74, v69
	v_add_f32_e32 v74, -1.0, v71
	v_add_f32_e32 v75, 1.0, v74
	v_sub_f32_e32 v75, v71, v75
	v_add_f32_e32 v75, v69, v75
	v_add_f32_e32 v76, v74, v75
	v_sub_f32_e32 v74, v74, v76
	v_add_f32_e32 v74, v75, v74
	v_add_f32_e32 v75, 1.0, v71
	v_add_f32_e32 v77, -1.0, v75
	v_sub_f32_e32 v71, v71, v77
	v_add_f32_e32 v69, v69, v71
	v_add_f32_e32 v71, v75, v69
	v_sub_f32_e32 v75, v75, v71
	v_add_f32_e32 v69, v69, v75
	v_rcp_f32_e32 v75, v71
	v_cvt_f32_i32_e32 v68, v68
	v_cmp_neq_f32_e32 vcc, s62, v70
	v_mul_f32_e32 v77, v76, v75
	v_mul_f32_e32 v78, v71, v77
	v_fma_f32 v79, v77, v71, -v78
	v_fmac_f32_e32 v79, v77, v69
	v_add_f32_e32 v80, v78, v79
	v_sub_f32_e32 v81, v76, v80
	v_sub_f32_e32 v76, v76, v81
	v_sub_f32_e32 v78, v80, v78
	v_sub_f32_e32 v76, v76, v80
	v_add_f32_e32 v74, v74, v76
	v_sub_f32_e32 v76, v78, v79
	v_add_f32_e32 v74, v76, v74
	v_add_f32_e32 v76, v81, v74
	v_mul_f32_e32 v78, v75, v76
	v_mul_f32_e32 v79, v71, v78
	v_fma_f32 v71, v78, v71, -v79
	v_fmac_f32_e32 v71, v78, v69
	v_sub_f32_e32 v69, v81, v76
	v_add_f32_e32 v69, v74, v69
	v_add_f32_e32 v74, v79, v71
	v_sub_f32_e32 v80, v76, v74
	v_sub_f32_e32 v76, v76, v80
	v_sub_f32_e32 v79, v74, v79
	v_sub_f32_e32 v74, v76, v74
	v_add_f32_e32 v69, v69, v74
	v_sub_f32_e32 v71, v79, v71
	v_add_f32_e32 v69, v71, v69
	v_add_f32_e32 v71, v77, v78
	v_add_f32_e32 v69, v80, v69
	v_sub_f32_e32 v74, v71, v77
	v_mul_f32_e32 v69, v75, v69
	v_sub_f32_e32 v74, v78, v74
	v_add_f32_e32 v69, v74, v69
	v_mul_f32_e32 v77, 0x3f317218, v68
	v_add_f32_e32 v74, v71, v69
	v_fma_f32 v78, v68, s78, -v77
	v_mul_f32_e32 v75, v74, v74
	v_fmac_f32_e32 v78, 0xb102e308, v68
	v_sub_f32_e32 v68, v74, v71
	v_fmamk_f32 v76, v75, 0x3e9b6dac, v185
	v_sub_f32_e32 v68, v69, v68
	v_add_f32_e32 v69, v77, v78
	v_fmaak_f32 v76, v75, v76, 0x3f2aaada
	v_sub_f32_e32 v71, v69, v77
	v_ldexp_f32 v77, v74, 1
	v_mul_f32_e32 v74, v74, v75
	v_mul_f32_e32 v74, v74, v76
	v_add_f32_e32 v75, v77, v74
	v_sub_f32_e32 v76, v75, v77
	v_ldexp_f32 v68, v68, 1
	v_sub_f32_e32 v74, v74, v76
	v_add_f32_e32 v68, v68, v74
	v_add_f32_e32 v74, v75, v68
	v_sub_f32_e32 v75, v74, v75
	v_sub_f32_e32 v68, v68, v75
	v_add_f32_e32 v75, v69, v74
	v_sub_f32_e32 v76, v75, v69
	v_sub_f32_e32 v77, v75, v76
	v_sub_f32_e32 v71, v78, v71
	v_sub_f32_e32 v69, v69, v77
	v_sub_f32_e32 v74, v74, v76
	v_add_f32_e32 v69, v74, v69
	v_add_f32_e32 v74, v71, v68
	v_sub_f32_e32 v76, v74, v71
	v_sub_f32_e32 v77, v74, v76
	v_sub_f32_e32 v71, v71, v77
	v_sub_f32_e32 v68, v68, v76
	v_add_f32_e32 v69, v74, v69
	v_add_f32_e32 v68, v68, v71
	v_add_f32_e32 v71, v75, v69
	v_sub_f32_e32 v74, v71, v75
	v_sub_f32_e32 v69, v69, v74
	v_add_f32_e32 v68, v68, v69
	v_add_f32_e32 v68, v71, v68
	v_cndmask_b32_e32 v68, v226, v68, vcc
	v_cmp_lt_f32_e64 vcc, |v70|, s63
	s_nop 1
	v_cndmask_b32_e32 v68, v68, v70, vcc
	v_sub_f32_e32 v56, v56, v68
	v_mul_f32_e32 v56, 0x3fb8aa3b, v56
	v_lshl_add_u64 v[68:69], v[72:73], 0, s[34:35]
	global_store_dword v[68:69], v56, off
	v_readlane_b32 s100, v254, 5
	s_nop 1
	v_mov_b32_e32 v56, s100
	s_or_b32 s34, s30, 5
	s_ashr_i32 s35, s34, 31
	s_lshl_b64 s[34:35], s[34:35], 14
	s_or_b32 s30, s30, 6
	s_ashr_i32 s31, s30, 31
	s_lshl_b64 s[30:31], s[30:31], 14
	v_fmac_f32_e32 v56, v57, v172
	v_mul_f32_e64 v57, |v56|, s94
	v_fma_f32 v71, |v56|, s94, -v57
	v_rndne_f32_e32 v74, v57
	v_fma_f32 v71, |v56|, s64, v71
	v_sub_f32_e32 v57, v57, v74
	v_add_f32_e32 v57, v57, v71
	v_exp_f32_e32 v57, v57
	v_cvt_i32_f32_e32 v71, v74
	v_cmp_ngt_f32_e64 vcc, |v56|, s58
	v_min_f32_e32 v70, 0, v56
	v_ldexp_f32 v57, v57, v71
	v_cndmask_b32_e32 v57, 0, v57, vcc
	v_cmp_nlt_f32_e64 vcc, |v56|, s59
	s_nop 1
	v_cndmask_b32_e32 v71, v226, v57, vcc
	v_add_f32_e32 v74, 1.0, v71
	v_add_f32_e32 v56, -1.0, v74
	v_sub_f32_e32 v57, v56, v74
	v_add_f32_e32 v57, 1.0, v57
	v_sub_f32_e32 v56, v71, v56
	v_add_f32_e32 v75, v56, v57
	v_frexp_mant_f32_e32 v56, v74
	v_cmp_gt_f32_e32 vcc, s77, v56
	v_cvt_f64_f32_e32 v[56:57], v74
	v_frexp_exp_i32_f64_e32 v56, v[56:57]
	v_subbrev_co_u32_e32 v56, vcc, 0, v56, vcc
	v_sub_u32_e32 v57, 0, v56
	v_ldexp_f32 v74, v74, v57
	v_ldexp_f32 v57, v75, v57
	v_add_f32_e32 v75, -1.0, v74
	v_add_f32_e32 v76, 1.0, v75
	v_sub_f32_e32 v76, v74, v76
	v_add_f32_e32 v76, v57, v76
	v_add_f32_e32 v77, v75, v76
	v_sub_f32_e32 v75, v75, v77
	v_add_f32_e32 v75, v76, v75
	v_add_f32_e32 v76, 1.0, v74
	v_add_f32_e32 v78, -1.0, v76
	v_sub_f32_e32 v74, v74, v78
	v_add_f32_e32 v57, v57, v74
	v_add_f32_e32 v74, v76, v57
	v_sub_f32_e32 v76, v76, v74
	v_add_f32_e32 v57, v57, v76
	v_rcp_f32_e32 v76, v74
	v_cvt_f32_i32_e32 v56, v56
	v_cmp_neq_f32_e32 vcc, s62, v71
	v_mul_f32_e32 v78, v77, v76
	v_mul_f32_e32 v79, v74, v78
	v_fma_f32 v80, v78, v74, -v79
	v_fmac_f32_e32 v80, v78, v57
	v_add_f32_e32 v81, v79, v80
	v_sub_f32_e32 v82, v77, v81
	v_sub_f32_e32 v77, v77, v82
	v_sub_f32_e32 v79, v81, v79
	v_sub_f32_e32 v77, v77, v81
	v_add_f32_e32 v75, v75, v77
	v_sub_f32_e32 v77, v79, v80
	v_add_f32_e32 v75, v77, v75
	v_add_f32_e32 v77, v82, v75
	v_mul_f32_e32 v79, v76, v77
	v_mul_f32_e32 v80, v74, v79
	v_fma_f32 v74, v79, v74, -v80
	v_fmac_f32_e32 v74, v79, v57
	v_sub_f32_e32 v57, v82, v77
	v_add_f32_e32 v57, v75, v57
	v_add_f32_e32 v75, v80, v74
	v_sub_f32_e32 v81, v77, v75
	v_sub_f32_e32 v77, v77, v81
	v_sub_f32_e32 v80, v75, v80
	v_sub_f32_e32 v75, v77, v75
	v_add_f32_e32 v57, v57, v75
	v_sub_f32_e32 v74, v80, v74
	v_add_f32_e32 v57, v74, v57
	v_add_f32_e32 v74, v78, v79
	v_add_f32_e32 v57, v81, v57
	v_sub_f32_e32 v75, v74, v78
	v_mul_f32_e32 v57, v76, v57
	v_sub_f32_e32 v75, v79, v75
	v_add_f32_e32 v57, v75, v57
	v_mul_f32_e32 v78, 0x3f317218, v56
	v_add_f32_e32 v75, v74, v57
	v_fma_f32 v79, v56, s78, -v78
	v_mul_f32_e32 v76, v75, v75
	v_fmac_f32_e32 v79, 0xb102e308, v56
	v_sub_f32_e32 v56, v75, v74
	v_fmamk_f32 v77, v76, 0x3e9b6dac, v185
	v_sub_f32_e32 v56, v57, v56
	v_add_f32_e32 v57, v78, v79
	v_fmaak_f32 v77, v76, v77, 0x3f2aaada
	v_sub_f32_e32 v74, v57, v78
	v_ldexp_f32 v78, v75, 1
	v_mul_f32_e32 v75, v75, v76
	v_mul_f32_e32 v75, v75, v77
	v_add_f32_e32 v76, v78, v75
	v_sub_f32_e32 v77, v76, v78
	v_ldexp_f32 v56, v56, 1
	v_sub_f32_e32 v75, v75, v77
	v_add_f32_e32 v56, v56, v75
	v_add_f32_e32 v75, v76, v56
	v_sub_f32_e32 v76, v75, v76
	v_sub_f32_e32 v56, v56, v76
	v_add_f32_e32 v76, v57, v75
	v_sub_f32_e32 v77, v76, v57
	v_sub_f32_e32 v78, v76, v77
	v_sub_f32_e32 v74, v79, v74
	v_sub_f32_e32 v57, v57, v78
	v_sub_f32_e32 v75, v75, v77
	v_add_f32_e32 v57, v75, v57
	v_add_f32_e32 v75, v74, v56
	v_sub_f32_e32 v77, v75, v74
	v_sub_f32_e32 v78, v75, v77
	v_sub_f32_e32 v74, v74, v78
	v_sub_f32_e32 v56, v56, v77
	v_add_f32_e32 v57, v75, v57
	v_add_f32_e32 v56, v56, v74
	v_add_f32_e32 v74, v76, v57
	v_sub_f32_e32 v75, v74, v76
	v_sub_f32_e32 v57, v57, v75
	v_add_f32_e32 v56, v56, v57
	v_add_f32_e32 v56, v74, v56
	v_cndmask_b32_e32 v56, v226, v56, vcc
	v_cmp_lt_f32_e64 vcc, |v71|, s63
	s_nop 1
	v_cndmask_b32_e32 v56, v56, v71, vcc
	v_sub_f32_e32 v56, v70, v56
	v_mul_f32_e32 v70, 0x3fb8aa3b, v56
	v_lshl_add_u64 v[56:57], v[72:73], 0, s[34:35]
	global_store_dword v[56:57], v70, off
	v_readlane_b32 s100, v254, 6
	s_nop 1
	v_mov_b32_e32 v70, s100
	v_fmac_f32_e32 v70, v58, v172
	v_mul_f32_e64 v71, |v70|, s94
	v_fma_f32 v74, |v70|, s94, -v71
	v_rndne_f32_e32 v75, v71
	v_fma_f32 v74, |v70|, s64, v74
	v_sub_f32_e32 v71, v71, v75
	v_add_f32_e32 v71, v71, v74
	v_exp_f32_e32 v71, v71
	v_cvt_i32_f32_e32 v74, v75
	v_cmp_ngt_f32_e64 vcc, |v70|, s58
	v_min_f32_e32 v58, 0, v70
	v_ldexp_f32 v71, v71, v74
	v_cndmask_b32_e32 v71, 0, v71, vcc
	v_cmp_nlt_f32_e64 vcc, |v70|, s59
	s_nop 1
	v_cndmask_b32_e32 v74, v226, v71, vcc
	v_add_f32_e32 v75, 1.0, v74
	v_add_f32_e32 v70, -1.0, v75
	v_sub_f32_e32 v71, v70, v75
	v_add_f32_e32 v71, 1.0, v71
	v_sub_f32_e32 v70, v74, v70
	v_add_f32_e32 v76, v70, v71
	v_frexp_mant_f32_e32 v70, v75
	v_cmp_gt_f32_e32 vcc, s77, v70
	v_cvt_f64_f32_e32 v[70:71], v75
	v_frexp_exp_i32_f64_e32 v70, v[70:71]
	v_subbrev_co_u32_e32 v70, vcc, 0, v70, vcc
	v_sub_u32_e32 v71, 0, v70
	v_ldexp_f32 v75, v75, v71
	v_ldexp_f32 v71, v76, v71
	v_add_f32_e32 v76, -1.0, v75
	v_add_f32_e32 v77, 1.0, v76
	v_sub_f32_e32 v77, v75, v77
	v_add_f32_e32 v77, v71, v77
	v_add_f32_e32 v78, v76, v77
	v_sub_f32_e32 v76, v76, v78
	v_add_f32_e32 v76, v77, v76
	v_add_f32_e32 v77, 1.0, v75
	v_add_f32_e32 v79, -1.0, v77
	v_sub_f32_e32 v75, v75, v79
	v_add_f32_e32 v71, v71, v75
	v_add_f32_e32 v75, v77, v71
	v_sub_f32_e32 v77, v77, v75
	v_add_f32_e32 v71, v71, v77
	v_rcp_f32_e32 v77, v75
	v_cvt_f32_i32_e32 v70, v70
	v_cmp_neq_f32_e32 vcc, s62, v74
	v_mul_f32_e32 v79, v78, v77
	v_mul_f32_e32 v80, v75, v79
	v_fma_f32 v81, v79, v75, -v80
	v_fmac_f32_e32 v81, v79, v71
	v_add_f32_e32 v82, v80, v81
	v_sub_f32_e32 v83, v78, v82
	v_sub_f32_e32 v78, v78, v83
	v_sub_f32_e32 v80, v82, v80
	v_sub_f32_e32 v78, v78, v82
	v_add_f32_e32 v76, v76, v78
	v_sub_f32_e32 v78, v80, v81
	v_add_f32_e32 v76, v78, v76
	v_add_f32_e32 v78, v83, v76
	v_mul_f32_e32 v80, v77, v78
	v_mul_f32_e32 v81, v75, v80
	v_fma_f32 v75, v80, v75, -v81
	v_fmac_f32_e32 v75, v80, v71
	v_sub_f32_e32 v71, v83, v78
	v_add_f32_e32 v71, v76, v71
	v_add_f32_e32 v76, v81, v75
	v_sub_f32_e32 v82, v78, v76
	v_sub_f32_e32 v78, v78, v82
	v_sub_f32_e32 v81, v76, v81
	v_sub_f32_e32 v76, v78, v76
	v_add_f32_e32 v71, v71, v76
	v_sub_f32_e32 v75, v81, v75
	v_add_f32_e32 v71, v75, v71
	v_add_f32_e32 v75, v79, v80
	v_add_f32_e32 v71, v82, v71
	v_sub_f32_e32 v76, v75, v79
	v_mul_f32_e32 v71, v77, v71
	v_sub_f32_e32 v76, v80, v76
	v_add_f32_e32 v71, v76, v71
	v_mul_f32_e32 v79, 0x3f317218, v70
	v_add_f32_e32 v76, v75, v71
	v_fma_f32 v80, v70, s78, -v79
	v_mul_f32_e32 v77, v76, v76
	v_fmac_f32_e32 v80, 0xb102e308, v70
	v_sub_f32_e32 v70, v76, v75
	v_fmamk_f32 v78, v77, 0x3e9b6dac, v185
	v_sub_f32_e32 v70, v71, v70
	v_add_f32_e32 v71, v79, v80
	v_fmaak_f32 v78, v77, v78, 0x3f2aaada
	v_sub_f32_e32 v75, v71, v79
	v_ldexp_f32 v79, v76, 1
	v_mul_f32_e32 v76, v76, v77
	v_mul_f32_e32 v76, v76, v78
	v_add_f32_e32 v77, v79, v76
	v_sub_f32_e32 v78, v77, v79
	v_ldexp_f32 v70, v70, 1
	v_sub_f32_e32 v76, v76, v78
	v_add_f32_e32 v70, v70, v76
	v_add_f32_e32 v76, v77, v70
	v_sub_f32_e32 v77, v76, v77
	v_sub_f32_e32 v70, v70, v77
	v_add_f32_e32 v77, v71, v76
	v_sub_f32_e32 v78, v77, v71
	v_sub_f32_e32 v79, v77, v78
	v_sub_f32_e32 v75, v80, v75
	v_sub_f32_e32 v71, v71, v79
	v_sub_f32_e32 v76, v76, v78
	v_add_f32_e32 v71, v76, v71
	v_add_f32_e32 v76, v75, v70
	v_sub_f32_e32 v78, v76, v75
	v_sub_f32_e32 v79, v76, v78
	v_sub_f32_e32 v75, v75, v79
	v_sub_f32_e32 v70, v70, v78
	v_add_f32_e32 v71, v76, v71
	v_add_f32_e32 v70, v70, v75
	v_add_f32_e32 v75, v77, v71
	v_sub_f32_e32 v76, v75, v77
	v_sub_f32_e32 v71, v71, v76
	v_add_f32_e32 v70, v70, v71
	v_add_f32_e32 v70, v75, v70
	v_cndmask_b32_e32 v70, v226, v70, vcc
	v_cmp_lt_f32_e64 vcc, |v74|, s63
	s_nop 1
	v_cndmask_b32_e32 v70, v70, v74, vcc
	v_sub_f32_e32 v58, v58, v70
	v_mul_f32_e32 v58, 0x3fb8aa3b, v58
	v_lshl_add_u64 v[70:71], v[72:73], 0, s[30:31]
	global_store_dword v[70:71], v58, off
	v_readlane_b32 s100, v254, 7
	s_nop 1
	v_mov_b32_e32 v58, s100
	s_or_b32 s30, s23, 7
	s_ashr_i32 s31, s30, 31
	s_lshl_b64 s[30:31], s[30:31], 14
	v_fmac_f32_e32 v58, v59, v172
	v_mul_f32_e64 v59, |v58|, s94
	v_fma_f32 v75, |v58|, s94, -v59
	v_rndne_f32_e32 v76, v59
	v_fma_f32 v75, |v58|, s64, v75
	v_sub_f32_e32 v59, v59, v76
	v_add_f32_e32 v59, v59, v75
	v_exp_f32_e32 v59, v59
	v_cvt_i32_f32_e32 v75, v76
	v_cmp_ngt_f32_e64 vcc, |v58|, s58
	v_min_f32_e32 v74, 0, v58
	v_ldexp_f32 v59, v59, v75
	v_cndmask_b32_e32 v59, 0, v59, vcc
	v_cmp_nlt_f32_e64 vcc, |v58|, s59
	s_nop 1
	v_cndmask_b32_e32 v75, v226, v59, vcc
	v_add_f32_e32 v76, 1.0, v75
	v_add_f32_e32 v58, -1.0, v76
	v_sub_f32_e32 v59, v58, v76
	v_add_f32_e32 v59, 1.0, v59
	v_sub_f32_e32 v58, v75, v58
	v_add_f32_e32 v77, v58, v59
	v_frexp_mant_f32_e32 v58, v76
	v_cmp_gt_f32_e32 vcc, s77, v58
	v_cvt_f64_f32_e32 v[58:59], v76
	v_frexp_exp_i32_f64_e32 v58, v[58:59]
	v_subbrev_co_u32_e32 v58, vcc, 0, v58, vcc
	v_sub_u32_e32 v59, 0, v58
	v_ldexp_f32 v76, v76, v59
	v_ldexp_f32 v59, v77, v59
	v_add_f32_e32 v77, -1.0, v76
	v_add_f32_e32 v78, 1.0, v77
	v_sub_f32_e32 v78, v76, v78
	v_add_f32_e32 v78, v59, v78
	v_add_f32_e32 v79, v77, v78
	v_sub_f32_e32 v77, v77, v79
	v_add_f32_e32 v77, v78, v77
	v_add_f32_e32 v78, 1.0, v76
	v_add_f32_e32 v80, -1.0, v78
	v_sub_f32_e32 v76, v76, v80
	v_add_f32_e32 v59, v59, v76
	v_add_f32_e32 v76, v78, v59
	v_sub_f32_e32 v78, v78, v76
	v_add_f32_e32 v59, v59, v78
	v_rcp_f32_e32 v78, v76
	v_cvt_f32_i32_e32 v58, v58
	v_cmp_neq_f32_e32 vcc, s62, v75
	v_mul_f32_e32 v80, v79, v78
	v_mul_f32_e32 v81, v76, v80
	v_fma_f32 v82, v80, v76, -v81
	v_fmac_f32_e32 v82, v80, v59
	v_add_f32_e32 v83, v81, v82
	v_sub_f32_e32 v84, v79, v83
	v_sub_f32_e32 v79, v79, v84
	v_sub_f32_e32 v81, v83, v81
	v_sub_f32_e32 v79, v79, v83
	v_add_f32_e32 v77, v77, v79
	v_sub_f32_e32 v79, v81, v82
	v_add_f32_e32 v77, v79, v77
	v_add_f32_e32 v79, v84, v77
	v_mul_f32_e32 v81, v78, v79
	v_mul_f32_e32 v82, v76, v81
	v_fma_f32 v76, v81, v76, -v82
	v_fmac_f32_e32 v76, v81, v59
	v_sub_f32_e32 v59, v84, v79
	v_add_f32_e32 v59, v77, v59
	v_add_f32_e32 v77, v82, v76
	v_sub_f32_e32 v83, v79, v77
	v_sub_f32_e32 v79, v79, v83
	v_sub_f32_e32 v82, v77, v82
	v_sub_f32_e32 v77, v79, v77
	v_add_f32_e32 v59, v59, v77
	v_sub_f32_e32 v76, v82, v76
	v_add_f32_e32 v59, v76, v59
	v_add_f32_e32 v76, v80, v81
	v_add_f32_e32 v59, v83, v59
	v_sub_f32_e32 v77, v76, v80
	v_mul_f32_e32 v59, v78, v59
	v_sub_f32_e32 v77, v81, v77
	v_add_f32_e32 v59, v77, v59
	v_mul_f32_e32 v80, 0x3f317218, v58
	v_add_f32_e32 v77, v76, v59
	v_fma_f32 v81, v58, s78, -v80
	v_mul_f32_e32 v78, v77, v77
	v_fmac_f32_e32 v81, 0xb102e308, v58
	v_sub_f32_e32 v58, v77, v76
	v_fmamk_f32 v79, v78, 0x3e9b6dac, v185
	v_sub_f32_e32 v58, v59, v58
	v_add_f32_e32 v59, v80, v81
	v_fmaak_f32 v79, v78, v79, 0x3f2aaada
	v_sub_f32_e32 v76, v59, v80
	v_ldexp_f32 v80, v77, 1
	v_mul_f32_e32 v77, v77, v78
	v_mul_f32_e32 v77, v77, v79
	v_add_f32_e32 v78, v80, v77
	v_sub_f32_e32 v79, v78, v80
	v_ldexp_f32 v58, v58, 1
	v_sub_f32_e32 v77, v77, v79
	v_add_f32_e32 v58, v58, v77
	v_add_f32_e32 v77, v78, v58
	v_sub_f32_e32 v78, v77, v78
	v_sub_f32_e32 v58, v58, v78
	v_add_f32_e32 v78, v59, v77
	v_sub_f32_e32 v79, v78, v59
	v_sub_f32_e32 v80, v78, v79
	v_sub_f32_e32 v76, v81, v76
	v_sub_f32_e32 v59, v59, v80
	v_sub_f32_e32 v77, v77, v79
	v_add_f32_e32 v59, v77, v59
	v_add_f32_e32 v77, v76, v58
	v_sub_f32_e32 v79, v77, v76
	v_sub_f32_e32 v80, v77, v79
	v_sub_f32_e32 v76, v76, v80
	v_sub_f32_e32 v58, v58, v79
	v_add_f32_e32 v59, v77, v59
	v_add_f32_e32 v58, v58, v76
	v_add_f32_e32 v76, v78, v59
	v_sub_f32_e32 v77, v76, v78
	v_sub_f32_e32 v59, v59, v77
	v_add_f32_e32 v58, v58, v59
	v_add_f32_e32 v58, v76, v58
	v_cndmask_b32_e32 v58, v226, v58, vcc
	v_cmp_lt_f32_e64 vcc, |v75|, s63
	s_nop 1
	v_cndmask_b32_e32 v58, v58, v75, vcc
	v_sub_f32_e32 v58, v74, v58
	v_mul_f32_e32 v74, 0x3fb8aa3b, v58
	v_lshl_add_u64 v[58:59], v[72:73], 0, s[30:31]
	global_store_dword v[58:59], v74, off
	v_readlane_b32 s100, v254, 0
	s_nop 1
	v_mov_b32_e32 v72, s100
	v_fmac_f32_e32 v72, v52, v170
	v_mul_f32_e64 v73, |v72|, s94
	v_fma_f32 v74, |v72|, s94, -v73
	v_rndne_f32_e32 v75, v73
	v_fma_f32 v74, |v72|, s64, v74
	v_sub_f32_e32 v73, v73, v75
	v_add_f32_e32 v73, v73, v74
	v_exp_f32_e32 v73, v73
	v_cvt_i32_f32_e32 v74, v75
	v_cmp_ngt_f32_e64 vcc, |v72|, s58
	v_min_f32_e32 v52, 0, v72
	v_ldexp_f32 v73, v73, v74
	v_cndmask_b32_e32 v73, 0, v73, vcc
	v_cmp_nlt_f32_e64 vcc, |v72|, s59
	s_nop 1
	v_cndmask_b32_e32 v72, v226, v73, vcc
	v_add_f32_e32 v73, 1.0, v72
	v_add_f32_e32 v74, -1.0, v73
	v_sub_f32_e32 v75, v74, v73
	v_add_f32_e32 v75, 1.0, v75
	v_sub_f32_e32 v74, v72, v74
	v_add_f32_e32 v76, v74, v75
	v_frexp_mant_f32_e32 v74, v73
	v_cmp_gt_f32_e32 vcc, s77, v74
	v_cvt_f64_f32_e32 v[74:75], v73
	v_frexp_exp_i32_f64_e32 v74, v[74:75]
	v_subbrev_co_u32_e32 v74, vcc, 0, v74, vcc
	v_sub_u32_e32 v75, 0, v74
	v_ldexp_f32 v73, v73, v75
	v_ldexp_f32 v75, v76, v75
	v_add_f32_e32 v76, -1.0, v73
	v_add_f32_e32 v77, 1.0, v76
	v_sub_f32_e32 v77, v73, v77
	v_add_f32_e32 v77, v75, v77
	v_add_f32_e32 v78, v76, v77
	v_sub_f32_e32 v76, v76, v78
	v_add_f32_e32 v76, v77, v76
	v_add_f32_e32 v77, 1.0, v73
	v_add_f32_e32 v79, -1.0, v77
	v_sub_f32_e32 v73, v73, v79
	v_add_f32_e32 v73, v75, v73
	v_add_f32_e32 v75, v77, v73
	v_sub_f32_e32 v77, v77, v75
	v_add_f32_e32 v73, v73, v77
	v_rcp_f32_e32 v77, v75
	v_cvt_f32_i32_e32 v74, v74
	v_cmp_neq_f32_e32 vcc, s62, v72
	v_mul_f32_e32 v79, v78, v77
	v_mul_f32_e32 v80, v75, v79
	v_fma_f32 v81, v79, v75, -v80
	v_fmac_f32_e32 v81, v79, v73
	v_add_f32_e32 v82, v80, v81
	v_sub_f32_e32 v83, v78, v82
	v_sub_f32_e32 v78, v78, v83
	v_sub_f32_e32 v80, v82, v80
	v_sub_f32_e32 v78, v78, v82
	v_add_f32_e32 v76, v76, v78
	v_sub_f32_e32 v78, v80, v81
	v_add_f32_e32 v76, v78, v76
	v_add_f32_e32 v78, v83, v76
	v_mul_f32_e32 v80, v77, v78
	v_mul_f32_e32 v81, v75, v80
	v_fma_f32 v75, v80, v75, -v81
	v_fmac_f32_e32 v75, v80, v73
	v_sub_f32_e32 v73, v83, v78
	v_add_f32_e32 v73, v76, v73
	v_add_f32_e32 v76, v81, v75
	v_sub_f32_e32 v82, v78, v76
	v_sub_f32_e32 v78, v78, v82
	v_sub_f32_e32 v81, v76, v81
	v_sub_f32_e32 v76, v78, v76
	v_add_f32_e32 v73, v73, v76
	v_sub_f32_e32 v75, v81, v75
	v_add_f32_e32 v73, v75, v73
	v_add_f32_e32 v75, v79, v80
	v_add_f32_e32 v73, v82, v73
	v_sub_f32_e32 v76, v75, v79
	v_mul_f32_e32 v73, v77, v73
	v_sub_f32_e32 v76, v80, v76
	v_add_f32_e32 v73, v76, v73
	v_mul_f32_e32 v79, 0x3f317218, v74
	v_add_f32_e32 v76, v75, v73
	v_fma_f32 v80, v74, s78, -v79
	v_mul_f32_e32 v77, v76, v76
	v_fmac_f32_e32 v80, 0xb102e308, v74
	v_sub_f32_e32 v74, v76, v75
	v_fmamk_f32 v78, v77, 0x3e9b6dac, v185
	v_sub_f32_e32 v73, v73, v74
	v_add_f32_e32 v74, v79, v80
	v_fmaak_f32 v78, v77, v78, 0x3f2aaada
	v_sub_f32_e32 v75, v74, v79
	v_ldexp_f32 v79, v76, 1
	v_mul_f32_e32 v76, v76, v77
	v_mul_f32_e32 v76, v76, v78
	v_add_f32_e32 v77, v79, v76
	v_sub_f32_e32 v78, v77, v79
	v_ldexp_f32 v73, v73, 1
	v_sub_f32_e32 v76, v76, v78
	v_add_f32_e32 v73, v73, v76
	v_add_f32_e32 v76, v77, v73
	v_sub_f32_e32 v77, v76, v77
	v_sub_f32_e32 v73, v73, v77
	v_add_f32_e32 v77, v74, v76
	v_sub_f32_e32 v78, v77, v74
	v_sub_f32_e32 v79, v77, v78
	v_sub_f32_e32 v75, v80, v75
	v_sub_f32_e32 v74, v74, v79
	v_sub_f32_e32 v76, v76, v78
	v_add_f32_e32 v74, v76, v74
	v_add_f32_e32 v76, v75, v73
	v_sub_f32_e32 v78, v76, v75
	v_sub_f32_e32 v79, v76, v78
	v_sub_f32_e32 v75, v75, v79
	v_sub_f32_e32 v73, v73, v78
	v_add_f32_e32 v74, v76, v74
	v_add_f32_e32 v73, v73, v75
	v_add_f32_e32 v75, v77, v74
	v_sub_f32_e32 v76, v75, v77
	v_sub_f32_e32 v74, v74, v76
	v_add_f32_e32 v73, v73, v74
	v_add_f32_e32 v73, v75, v73
	v_cndmask_b32_e32 v73, v226, v73, vcc
	v_cmp_lt_f32_e64 vcc, |v72|, s63
	s_nop 1
	v_cndmask_b32_e32 v72, v73, v72, vcc
	v_sub_f32_e32 v52, v52, v72
	v_mul_f32_e32 v52, 0x3fb8aa3b, v52
	global_store_dword v[64:65], v52, off offset:64
	v_readlane_b32 s100, v254, 1
	s_nop 1
	v_mov_b32_e32 v72, s100
	v_fmac_f32_e32 v72, v53, v170
	v_mul_f32_e64 v53, |v72|, s94
	v_fma_f32 v73, |v72|, s94, -v53
	v_rndne_f32_e32 v74, v53
	v_fma_f32 v73, |v72|, s64, v73
	v_sub_f32_e32 v53, v53, v74
	v_add_f32_e32 v53, v53, v73
	v_exp_f32_e32 v53, v53
	v_cvt_i32_f32_e32 v73, v74
	v_cmp_ngt_f32_e64 vcc, |v72|, s58
	v_min_f32_e32 v52, 0, v72
	v_ldexp_f32 v53, v53, v73
	v_cndmask_b32_e32 v53, 0, v53, vcc
	v_cmp_nlt_f32_e64 vcc, |v72|, s59
	s_nop 1
	v_cndmask_b32_e32 v53, v226, v53, vcc
	v_add_f32_e32 v74, 1.0, v53
	v_add_f32_e32 v72, -1.0, v74
	v_sub_f32_e32 v73, v72, v74
	v_add_f32_e32 v73, 1.0, v73
	v_sub_f32_e32 v72, v53, v72
	v_add_f32_e32 v75, v72, v73
	v_frexp_mant_f32_e32 v72, v74
	v_cmp_gt_f32_e32 vcc, s77, v72
	v_cvt_f64_f32_e32 v[72:73], v74
	v_frexp_exp_i32_f64_e32 v72, v[72:73]
	v_subbrev_co_u32_e32 v72, vcc, 0, v72, vcc
	v_sub_u32_e32 v73, 0, v72
	v_ldexp_f32 v74, v74, v73
	v_ldexp_f32 v73, v75, v73
	v_add_f32_e32 v75, -1.0, v74
	v_add_f32_e32 v76, 1.0, v75
	v_sub_f32_e32 v76, v74, v76
	v_add_f32_e32 v76, v73, v76
	v_add_f32_e32 v77, v75, v76
	v_sub_f32_e32 v75, v75, v77
	v_add_f32_e32 v75, v76, v75
	v_add_f32_e32 v76, 1.0, v74
	v_add_f32_e32 v78, -1.0, v76
	v_sub_f32_e32 v74, v74, v78
	v_add_f32_e32 v73, v73, v74
	v_add_f32_e32 v74, v76, v73
	v_sub_f32_e32 v76, v76, v74
	v_add_f32_e32 v73, v73, v76
	v_rcp_f32_e32 v76, v74
	v_cvt_f32_i32_e32 v72, v72
	v_cmp_neq_f32_e32 vcc, s62, v53
	v_mul_f32_e32 v78, v77, v76
	v_mul_f32_e32 v79, v74, v78
	v_fma_f32 v80, v78, v74, -v79
	v_fmac_f32_e32 v80, v78, v73
	v_add_f32_e32 v81, v79, v80
	v_sub_f32_e32 v82, v77, v81
	v_sub_f32_e32 v77, v77, v82
	v_sub_f32_e32 v79, v81, v79
	v_sub_f32_e32 v77, v77, v81
	v_add_f32_e32 v75, v75, v77
	v_sub_f32_e32 v77, v79, v80
	v_add_f32_e32 v75, v77, v75
	v_add_f32_e32 v77, v82, v75
	v_mul_f32_e32 v79, v76, v77
	v_mul_f32_e32 v80, v74, v79
	v_fma_f32 v74, v79, v74, -v80
	v_fmac_f32_e32 v74, v79, v73
	v_sub_f32_e32 v73, v82, v77
	v_add_f32_e32 v73, v75, v73
	v_add_f32_e32 v75, v80, v74
	v_sub_f32_e32 v81, v77, v75
	v_sub_f32_e32 v77, v77, v81
	v_sub_f32_e32 v80, v75, v80
	v_sub_f32_e32 v75, v77, v75
	v_add_f32_e32 v73, v73, v75
	v_sub_f32_e32 v74, v80, v74
	v_add_f32_e32 v73, v74, v73
	v_add_f32_e32 v74, v78, v79
	v_add_f32_e32 v73, v81, v73
	v_sub_f32_e32 v75, v74, v78
	v_mul_f32_e32 v73, v76, v73
	v_sub_f32_e32 v75, v79, v75
	v_add_f32_e32 v73, v75, v73
	v_mul_f32_e32 v78, 0x3f317218, v72
	v_add_f32_e32 v75, v74, v73
	v_fma_f32 v79, v72, s78, -v78
	v_mul_f32_e32 v76, v75, v75
	v_fmac_f32_e32 v79, 0xb102e308, v72
	v_sub_f32_e32 v72, v75, v74
	v_fmamk_f32 v77, v76, 0x3e9b6dac, v185
	v_sub_f32_e32 v72, v73, v72
	v_add_f32_e32 v73, v78, v79
	v_fmaak_f32 v77, v76, v77, 0x3f2aaada
	v_sub_f32_e32 v74, v73, v78
	v_ldexp_f32 v78, v75, 1
	v_mul_f32_e32 v75, v75, v76
	v_mul_f32_e32 v75, v75, v77
	v_add_f32_e32 v76, v78, v75
	v_sub_f32_e32 v77, v76, v78
	v_ldexp_f32 v72, v72, 1
	v_sub_f32_e32 v75, v75, v77
	v_add_f32_e32 v72, v72, v75
	v_add_f32_e32 v75, v76, v72
	v_sub_f32_e32 v76, v75, v76
	v_sub_f32_e32 v72, v72, v76
	v_add_f32_e32 v76, v73, v75
	v_sub_f32_e32 v77, v76, v73
	v_sub_f32_e32 v78, v76, v77
	v_sub_f32_e32 v74, v79, v74
	v_sub_f32_e32 v73, v73, v78
	v_sub_f32_e32 v75, v75, v77
	v_add_f32_e32 v73, v75, v73
	v_add_f32_e32 v75, v74, v72
	v_sub_f32_e32 v77, v75, v74
	v_sub_f32_e32 v78, v75, v77
	v_sub_f32_e32 v74, v74, v78
	v_sub_f32_e32 v72, v72, v77
	v_add_f32_e32 v73, v75, v73
	v_add_f32_e32 v72, v72, v74
	v_add_f32_e32 v74, v76, v73
	v_sub_f32_e32 v75, v74, v76
	v_sub_f32_e32 v73, v73, v75
	v_add_f32_e32 v72, v72, v73
	v_add_f32_e32 v72, v74, v72
	v_cndmask_b32_e32 v72, v226, v72, vcc
	v_cmp_lt_f32_e64 vcc, |v53|, s63
	s_nop 1
	v_cndmask_b32_e32 v53, v72, v53, vcc
	v_sub_f32_e32 v52, v52, v53
	v_mul_f32_e32 v52, 0x3fb8aa3b, v52
	global_store_dword v[60:61], v52, off offset:64
	v_readlane_b32 s100, v254, 2
	s_nop 1
	v_mov_b32_e32 v53, s100
	v_fmac_f32_e32 v53, v54, v170
	v_mul_f32_e64 v54, |v53|, s94
	v_fma_f32 v72, |v53|, s94, -v54
	v_rndne_f32_e32 v73, v54
	v_fma_f32 v72, |v53|, s64, v72
	v_sub_f32_e32 v54, v54, v73
	v_add_f32_e32 v54, v54, v72
	v_exp_f32_e32 v54, v54
	v_cvt_i32_f32_e32 v72, v73
	v_cmp_ngt_f32_e64 vcc, |v53|, s58
	v_min_f32_e32 v52, 0, v53
	v_ldexp_f32 v54, v54, v72
	v_cndmask_b32_e32 v54, 0, v54, vcc
	v_cmp_nlt_f32_e64 vcc, |v53|, s59
	s_nop 1
	v_cndmask_b32_e32 v53, v226, v54, vcc
	v_add_f32_e32 v54, 1.0, v53
	v_add_f32_e32 v72, -1.0, v54
	v_sub_f32_e32 v73, v72, v54
	v_add_f32_e32 v73, 1.0, v73
	v_sub_f32_e32 v72, v53, v72
	v_add_f32_e32 v74, v72, v73
	v_frexp_mant_f32_e32 v72, v54
	v_cmp_gt_f32_e32 vcc, s77, v72
	v_cvt_f64_f32_e32 v[72:73], v54
	v_frexp_exp_i32_f64_e32 v72, v[72:73]
	v_subbrev_co_u32_e32 v72, vcc, 0, v72, vcc
	v_sub_u32_e32 v73, 0, v72
	v_ldexp_f32 v54, v54, v73
	v_ldexp_f32 v73, v74, v73
	v_add_f32_e32 v74, -1.0, v54
	v_add_f32_e32 v75, 1.0, v74
	v_sub_f32_e32 v75, v54, v75
	v_add_f32_e32 v75, v73, v75
	v_add_f32_e32 v76, v74, v75
	v_sub_f32_e32 v74, v74, v76
	v_add_f32_e32 v74, v75, v74
	v_add_f32_e32 v75, 1.0, v54
	v_add_f32_e32 v77, -1.0, v75
	v_sub_f32_e32 v54, v54, v77
	v_add_f32_e32 v54, v73, v54
	v_add_f32_e32 v73, v75, v54
	v_sub_f32_e32 v75, v75, v73
	v_add_f32_e32 v54, v54, v75
	v_rcp_f32_e32 v75, v73
	v_cvt_f32_i32_e32 v72, v72
	v_cmp_neq_f32_e32 vcc, s62, v53
	v_mul_f32_e32 v77, v76, v75
	v_mul_f32_e32 v78, v73, v77
	v_fma_f32 v79, v77, v73, -v78
	v_fmac_f32_e32 v79, v77, v54
	v_add_f32_e32 v80, v78, v79
	v_sub_f32_e32 v81, v76, v80
	v_sub_f32_e32 v76, v76, v81
	v_sub_f32_e32 v78, v80, v78
	v_sub_f32_e32 v76, v76, v80
	v_add_f32_e32 v74, v74, v76
	v_sub_f32_e32 v76, v78, v79
	v_add_f32_e32 v74, v76, v74
	v_add_f32_e32 v76, v81, v74
	v_mul_f32_e32 v78, v75, v76
	v_mul_f32_e32 v79, v73, v78
	v_fma_f32 v73, v78, v73, -v79
	v_fmac_f32_e32 v73, v78, v54
	v_sub_f32_e32 v54, v81, v76
	v_add_f32_e32 v54, v74, v54
	v_add_f32_e32 v74, v79, v73
	v_sub_f32_e32 v80, v76, v74
	v_sub_f32_e32 v76, v76, v80
	v_sub_f32_e32 v79, v74, v79
	v_sub_f32_e32 v74, v76, v74
	v_add_f32_e32 v54, v54, v74
	v_sub_f32_e32 v73, v79, v73
	v_add_f32_e32 v54, v73, v54
	v_add_f32_e32 v73, v77, v78
	v_add_f32_e32 v54, v80, v54
	v_sub_f32_e32 v74, v73, v77
	v_mul_f32_e32 v54, v75, v54
	v_sub_f32_e32 v74, v78, v74
	v_add_f32_e32 v54, v74, v54
	v_mul_f32_e32 v77, 0x3f317218, v72
	v_add_f32_e32 v74, v73, v54
	v_fma_f32 v78, v72, s78, -v77
	v_mul_f32_e32 v75, v74, v74
	v_fmac_f32_e32 v78, 0xb102e308, v72
	v_sub_f32_e32 v72, v74, v73
	v_fmamk_f32 v76, v75, 0x3e9b6dac, v185
	v_sub_f32_e32 v54, v54, v72
	v_add_f32_e32 v72, v77, v78
	v_fmaak_f32 v76, v75, v76, 0x3f2aaada
	v_sub_f32_e32 v73, v72, v77
	v_ldexp_f32 v77, v74, 1
	v_mul_f32_e32 v74, v74, v75
	v_mul_f32_e32 v74, v74, v76
	v_add_f32_e32 v75, v77, v74
	v_sub_f32_e32 v76, v75, v77
	v_ldexp_f32 v54, v54, 1
	v_sub_f32_e32 v74, v74, v76
	v_add_f32_e32 v54, v54, v74
	v_add_f32_e32 v74, v75, v54
	v_sub_f32_e32 v75, v74, v75
	v_sub_f32_e32 v54, v54, v75
	v_add_f32_e32 v75, v72, v74
	v_sub_f32_e32 v76, v75, v72
	v_sub_f32_e32 v77, v75, v76
	v_sub_f32_e32 v73, v78, v73
	v_sub_f32_e32 v72, v72, v77
	v_sub_f32_e32 v74, v74, v76
	v_add_f32_e32 v72, v74, v72
	v_add_f32_e32 v74, v73, v54
	v_sub_f32_e32 v76, v74, v73
	v_sub_f32_e32 v77, v74, v76
	v_sub_f32_e32 v73, v73, v77
	v_sub_f32_e32 v54, v54, v76
	v_add_f32_e32 v72, v74, v72
	v_add_f32_e32 v54, v54, v73
	v_add_f32_e32 v73, v75, v72
	v_sub_f32_e32 v74, v73, v75
	v_sub_f32_e32 v72, v72, v74
	v_add_f32_e32 v54, v54, v72
	v_add_f32_e32 v54, v73, v54
	v_cndmask_b32_e32 v54, v226, v54, vcc
	v_cmp_lt_f32_e64 vcc, |v53|, s63
	s_nop 1
	v_cndmask_b32_e32 v53, v54, v53, vcc
	v_sub_f32_e32 v52, v52, v53
	v_mul_f32_e32 v52, 0x3fb8aa3b, v52
	global_store_dword v[66:67], v52, off offset:64
	v_readlane_b32 s100, v254, 3
	s_nop 1
	v_mov_b32_e32 v53, s100
	v_fmac_f32_e32 v53, v55, v170
	v_mul_f32_e64 v54, |v53|, s94
	v_fma_f32 v55, |v53|, s94, -v54
	v_rndne_f32_e32 v72, v54
	v_fma_f32 v55, |v53|, s64, v55
	v_sub_f32_e32 v54, v54, v72
	v_add_f32_e32 v54, v54, v55
	v_exp_f32_e32 v54, v54
	v_cvt_i32_f32_e32 v55, v72
	v_cmp_ngt_f32_e64 vcc, |v53|, s58
	v_min_f32_e32 v52, 0, v53
	v_ldexp_f32 v54, v54, v55
	v_cndmask_b32_e32 v54, 0, v54, vcc
	v_cmp_nlt_f32_e64 vcc, |v53|, s59
	s_nop 1
	v_cndmask_b32_e32 v53, v226, v54, vcc
	v_add_f32_e32 v72, 1.0, v53
	v_add_f32_e32 v54, -1.0, v72
	v_sub_f32_e32 v55, v54, v72
	v_add_f32_e32 v55, 1.0, v55
	v_sub_f32_e32 v54, v53, v54
	v_add_f32_e32 v73, v54, v55
	v_frexp_mant_f32_e32 v54, v72
	v_cmp_gt_f32_e32 vcc, s77, v54
	v_cvt_f64_f32_e32 v[54:55], v72
	v_frexp_exp_i32_f64_e32 v54, v[54:55]
	v_subbrev_co_u32_e32 v54, vcc, 0, v54, vcc
	v_sub_u32_e32 v55, 0, v54
	v_ldexp_f32 v72, v72, v55
	v_ldexp_f32 v55, v73, v55
	v_add_f32_e32 v73, -1.0, v72
	v_add_f32_e32 v74, 1.0, v73
	v_sub_f32_e32 v74, v72, v74
	v_add_f32_e32 v74, v55, v74
	v_add_f32_e32 v75, v73, v74
	v_sub_f32_e32 v73, v73, v75
	v_add_f32_e32 v73, v74, v73
	v_add_f32_e32 v74, 1.0, v72
	v_add_f32_e32 v76, -1.0, v74
	v_sub_f32_e32 v72, v72, v76
	v_add_f32_e32 v55, v55, v72
	v_add_f32_e32 v72, v74, v55
	v_sub_f32_e32 v74, v74, v72
	v_add_f32_e32 v55, v55, v74
	v_rcp_f32_e32 v74, v72
	v_cvt_f32_i32_e32 v54, v54
	v_cmp_neq_f32_e32 vcc, s62, v53
	v_mul_f32_e32 v76, v75, v74
	v_mul_f32_e32 v77, v72, v76
	v_fma_f32 v78, v76, v72, -v77
	v_fmac_f32_e32 v78, v76, v55
	v_add_f32_e32 v79, v77, v78
	v_sub_f32_e32 v80, v75, v79
	v_sub_f32_e32 v75, v75, v80
	v_sub_f32_e32 v77, v79, v77
	v_sub_f32_e32 v75, v75, v79
	v_add_f32_e32 v73, v73, v75
	v_sub_f32_e32 v75, v77, v78
	v_add_f32_e32 v73, v75, v73
	v_add_f32_e32 v75, v80, v73
	v_mul_f32_e32 v77, v74, v75
	v_mul_f32_e32 v78, v72, v77
	v_fma_f32 v72, v77, v72, -v78
	v_fmac_f32_e32 v72, v77, v55
	v_sub_f32_e32 v55, v80, v75
	v_add_f32_e32 v55, v73, v55
	v_add_f32_e32 v73, v78, v72
	v_sub_f32_e32 v79, v75, v73
	v_sub_f32_e32 v75, v75, v79
	v_sub_f32_e32 v78, v73, v78
	v_sub_f32_e32 v73, v75, v73
	v_add_f32_e32 v55, v55, v73
	v_sub_f32_e32 v72, v78, v72
	v_add_f32_e32 v55, v72, v55
	v_add_f32_e32 v72, v76, v77
	v_add_f32_e32 v55, v79, v55
	v_sub_f32_e32 v73, v72, v76
	v_mul_f32_e32 v55, v74, v55
	v_sub_f32_e32 v73, v77, v73
	v_add_f32_e32 v55, v73, v55
	v_mul_f32_e32 v76, 0x3f317218, v54
	v_add_f32_e32 v73, v72, v55
	v_fma_f32 v77, v54, s78, -v76
	v_mul_f32_e32 v74, v73, v73
	v_fmac_f32_e32 v77, 0xb102e308, v54
	v_sub_f32_e32 v54, v73, v72
	v_fmamk_f32 v75, v74, 0x3e9b6dac, v185
	v_sub_f32_e32 v54, v55, v54
	v_add_f32_e32 v55, v76, v77
	v_fmaak_f32 v75, v74, v75, 0x3f2aaada
	v_sub_f32_e32 v72, v55, v76
	v_ldexp_f32 v76, v73, 1
	v_mul_f32_e32 v73, v73, v74
	v_mul_f32_e32 v73, v73, v75
	v_add_f32_e32 v74, v76, v73
	v_sub_f32_e32 v75, v74, v76
	v_ldexp_f32 v54, v54, 1
	v_sub_f32_e32 v73, v73, v75
	v_add_f32_e32 v54, v54, v73
	v_add_f32_e32 v73, v74, v54
	v_sub_f32_e32 v74, v73, v74
	v_sub_f32_e32 v54, v54, v74
	v_add_f32_e32 v74, v55, v73
	v_sub_f32_e32 v75, v74, v55
	v_sub_f32_e32 v76, v74, v75
	v_sub_f32_e32 v72, v77, v72
	v_sub_f32_e32 v55, v55, v76
	v_sub_f32_e32 v73, v73, v75
	v_add_f32_e32 v55, v73, v55
	v_add_f32_e32 v73, v72, v54
	v_sub_f32_e32 v75, v73, v72
	v_sub_f32_e32 v76, v73, v75
	v_sub_f32_e32 v72, v72, v76
	v_sub_f32_e32 v54, v54, v75
	v_add_f32_e32 v55, v73, v55
	v_add_f32_e32 v54, v54, v72
	v_add_f32_e32 v72, v74, v55
	v_sub_f32_e32 v73, v72, v74
	v_sub_f32_e32 v55, v55, v73
	v_add_f32_e32 v54, v54, v55
	v_add_f32_e32 v54, v72, v54
	v_cndmask_b32_e32 v54, v226, v54, vcc
	v_cmp_lt_f32_e64 vcc, |v53|, s63
	s_nop 1
	v_cndmask_b32_e32 v53, v54, v53, vcc
	v_sub_f32_e32 v52, v52, v53
	v_mul_f32_e32 v52, 0x3fb8aa3b, v52
	global_store_dword v[62:63], v52, off offset:64
	v_readlane_b32 s100, v254, 4
	s_nop 1
	v_mov_b32_e32 v52, s100
	v_fmac_f32_e32 v52, v48, v170
	v_mul_f32_e64 v53, |v52|, s94
	v_fma_f32 v54, |v52|, s94, -v53
	v_rndne_f32_e32 v55, v53
	v_fma_f32 v54, |v52|, s64, v54
	v_sub_f32_e32 v53, v53, v55
	v_add_f32_e32 v53, v53, v54
	v_exp_f32_e32 v53, v53
	v_cvt_i32_f32_e32 v54, v55
	v_cmp_ngt_f32_e64 vcc, |v52|, s58
	v_min_f32_e32 v48, 0, v52
	v_ldexp_f32 v53, v53, v54
	v_cndmask_b32_e32 v53, 0, v53, vcc
	v_cmp_nlt_f32_e64 vcc, |v52|, s59
	s_nop 1
	v_cndmask_b32_e32 v52, v226, v53, vcc
	v_add_f32_e32 v53, 1.0, v52
	v_add_f32_e32 v54, -1.0, v53
	v_sub_f32_e32 v55, v54, v53
	v_add_f32_e32 v55, 1.0, v55
	v_sub_f32_e32 v54, v52, v54
	v_add_f32_e32 v72, v54, v55
	v_frexp_mant_f32_e32 v54, v53
	v_cmp_gt_f32_e32 vcc, s77, v54
	v_cvt_f64_f32_e32 v[54:55], v53
	v_frexp_exp_i32_f64_e32 v54, v[54:55]
	v_subbrev_co_u32_e32 v54, vcc, 0, v54, vcc
	v_sub_u32_e32 v55, 0, v54
	v_ldexp_f32 v53, v53, v55
	v_ldexp_f32 v55, v72, v55
	v_add_f32_e32 v72, -1.0, v53
	v_add_f32_e32 v73, 1.0, v72
	v_sub_f32_e32 v73, v53, v73
	v_add_f32_e32 v73, v55, v73
	v_add_f32_e32 v74, v72, v73
	v_sub_f32_e32 v72, v72, v74
	v_add_f32_e32 v72, v73, v72
	v_add_f32_e32 v73, 1.0, v53
	v_add_f32_e32 v75, -1.0, v73
	v_sub_f32_e32 v53, v53, v75
	v_add_f32_e32 v53, v55, v53
	v_add_f32_e32 v55, v73, v53
	v_sub_f32_e32 v73, v73, v55
	v_add_f32_e32 v53, v53, v73
	v_rcp_f32_e32 v73, v55
	v_cvt_f32_i32_e32 v54, v54
	v_cmp_neq_f32_e32 vcc, s62, v52
	v_mul_f32_e32 v75, v74, v73
	v_mul_f32_e32 v76, v55, v75
	v_fma_f32 v77, v75, v55, -v76
	v_fmac_f32_e32 v77, v75, v53
	v_add_f32_e32 v78, v76, v77
	v_sub_f32_e32 v79, v74, v78
	v_sub_f32_e32 v74, v74, v79
	v_sub_f32_e32 v76, v78, v76
	v_sub_f32_e32 v74, v74, v78
	v_add_f32_e32 v72, v72, v74
	v_sub_f32_e32 v74, v76, v77
	v_add_f32_e32 v72, v74, v72
	v_add_f32_e32 v74, v79, v72
	v_mul_f32_e32 v76, v73, v74
	v_mul_f32_e32 v77, v55, v76
	v_fma_f32 v55, v76, v55, -v77
	v_fmac_f32_e32 v55, v76, v53
	v_sub_f32_e32 v53, v79, v74
	v_add_f32_e32 v53, v72, v53
	v_add_f32_e32 v72, v77, v55
	v_sub_f32_e32 v78, v74, v72
	v_sub_f32_e32 v74, v74, v78
	v_sub_f32_e32 v77, v72, v77
	v_sub_f32_e32 v72, v74, v72
	v_add_f32_e32 v53, v53, v72
	v_sub_f32_e32 v55, v77, v55
	v_add_f32_e32 v53, v55, v53
	v_add_f32_e32 v55, v75, v76
	v_add_f32_e32 v53, v78, v53
	v_sub_f32_e32 v72, v55, v75
	v_mul_f32_e32 v53, v73, v53
	v_sub_f32_e32 v72, v76, v72
	v_add_f32_e32 v53, v72, v53
	v_mul_f32_e32 v75, 0x3f317218, v54
	v_add_f32_e32 v72, v55, v53
	v_fma_f32 v76, v54, s78, -v75
	v_mul_f32_e32 v73, v72, v72
	v_fmac_f32_e32 v76, 0xb102e308, v54
	v_sub_f32_e32 v54, v72, v55
	v_fmamk_f32 v74, v73, 0x3e9b6dac, v185
	v_sub_f32_e32 v53, v53, v54
	v_add_f32_e32 v54, v75, v76
	v_fmaak_f32 v74, v73, v74, 0x3f2aaada
	v_sub_f32_e32 v55, v54, v75
	v_ldexp_f32 v75, v72, 1
	v_mul_f32_e32 v72, v72, v73
	v_mul_f32_e32 v72, v72, v74
	v_add_f32_e32 v73, v75, v72
	v_sub_f32_e32 v74, v73, v75
	v_ldexp_f32 v53, v53, 1
	v_sub_f32_e32 v72, v72, v74
	v_add_f32_e32 v53, v53, v72
	v_add_f32_e32 v72, v73, v53
	v_sub_f32_e32 v73, v72, v73
	v_sub_f32_e32 v53, v53, v73
	v_add_f32_e32 v73, v54, v72
	v_sub_f32_e32 v74, v73, v54
	v_sub_f32_e32 v75, v73, v74
	v_sub_f32_e32 v55, v76, v55
	v_sub_f32_e32 v54, v54, v75
	v_sub_f32_e32 v72, v72, v74
	v_add_f32_e32 v54, v72, v54
	v_add_f32_e32 v72, v55, v53
	v_sub_f32_e32 v74, v72, v55
	v_sub_f32_e32 v75, v72, v74
	v_sub_f32_e32 v55, v55, v75
	v_sub_f32_e32 v53, v53, v74
	v_add_f32_e32 v54, v72, v54
	v_add_f32_e32 v53, v53, v55
	v_add_f32_e32 v55, v73, v54
	v_sub_f32_e32 v72, v55, v73
	v_sub_f32_e32 v54, v54, v72
	v_add_f32_e32 v53, v53, v54
	v_add_f32_e32 v53, v55, v53
	v_cndmask_b32_e32 v53, v226, v53, vcc
	v_cmp_lt_f32_e64 vcc, |v52|, s63
	s_nop 1
	v_cndmask_b32_e32 v52, v53, v52, vcc
	v_sub_f32_e32 v48, v48, v52
	v_mul_f32_e32 v48, 0x3fb8aa3b, v48
	global_store_dword v[68:69], v48, off offset:64
	v_readlane_b32 s100, v254, 5
	s_nop 1
	v_mov_b32_e32 v52, s100
	v_fmac_f32_e32 v52, v49, v170
	v_mul_f32_e64 v49, |v52|, s94
	v_fma_f32 v53, |v52|, s94, -v49
	v_rndne_f32_e32 v54, v49
	v_fma_f32 v53, |v52|, s64, v53
	v_sub_f32_e32 v49, v49, v54
	v_add_f32_e32 v49, v49, v53
	v_exp_f32_e32 v49, v49
	v_cvt_i32_f32_e32 v53, v54
	v_cmp_ngt_f32_e64 vcc, |v52|, s58
	v_min_f32_e32 v48, 0, v52
	v_ldexp_f32 v49, v49, v53
	v_cndmask_b32_e32 v49, 0, v49, vcc
	v_cmp_nlt_f32_e64 vcc, |v52|, s59
	s_nop 1
	v_cndmask_b32_e32 v49, v226, v49, vcc
	v_add_f32_e32 v54, 1.0, v49
	v_add_f32_e32 v52, -1.0, v54
	v_sub_f32_e32 v53, v52, v54
	v_add_f32_e32 v53, 1.0, v53
	v_sub_f32_e32 v52, v49, v52
	v_add_f32_e32 v55, v52, v53
	v_frexp_mant_f32_e32 v52, v54
	v_cmp_gt_f32_e32 vcc, s77, v52
	v_cvt_f64_f32_e32 v[52:53], v54
	v_frexp_exp_i32_f64_e32 v52, v[52:53]
	v_subbrev_co_u32_e32 v52, vcc, 0, v52, vcc
	v_sub_u32_e32 v53, 0, v52
	v_ldexp_f32 v54, v54, v53
	v_ldexp_f32 v53, v55, v53
	v_add_f32_e32 v55, -1.0, v54
	v_add_f32_e32 v72, 1.0, v55
	v_sub_f32_e32 v72, v54, v72
	v_add_f32_e32 v72, v53, v72
	v_add_f32_e32 v73, v55, v72
	v_sub_f32_e32 v55, v55, v73
	v_add_f32_e32 v55, v72, v55
	v_add_f32_e32 v72, 1.0, v54
	v_add_f32_e32 v74, -1.0, v72
	v_sub_f32_e32 v54, v54, v74
	v_add_f32_e32 v53, v53, v54
	v_add_f32_e32 v54, v72, v53
	v_sub_f32_e32 v72, v72, v54
	v_add_f32_e32 v53, v53, v72
	v_rcp_f32_e32 v72, v54
	v_cvt_f32_i32_e32 v52, v52
	v_cmp_neq_f32_e32 vcc, s62, v49
	v_mul_f32_e32 v74, v73, v72
	v_mul_f32_e32 v75, v54, v74
	v_fma_f32 v76, v74, v54, -v75
	v_fmac_f32_e32 v76, v74, v53
	v_add_f32_e32 v77, v75, v76
	v_sub_f32_e32 v78, v73, v77
	v_sub_f32_e32 v73, v73, v78
	v_sub_f32_e32 v75, v77, v75
	v_sub_f32_e32 v73, v73, v77
	v_add_f32_e32 v55, v55, v73
	v_sub_f32_e32 v73, v75, v76
	v_add_f32_e32 v55, v73, v55
	v_add_f32_e32 v73, v78, v55
	v_mul_f32_e32 v75, v72, v73
	v_mul_f32_e32 v76, v54, v75
	v_fma_f32 v54, v75, v54, -v76
	v_fmac_f32_e32 v54, v75, v53
	v_sub_f32_e32 v53, v78, v73
	v_add_f32_e32 v53, v55, v53
	v_add_f32_e32 v55, v76, v54
	v_sub_f32_e32 v77, v73, v55
	v_sub_f32_e32 v73, v73, v77
	v_sub_f32_e32 v76, v55, v76
	v_sub_f32_e32 v55, v73, v55
	v_add_f32_e32 v53, v53, v55
	v_sub_f32_e32 v54, v76, v54
	v_add_f32_e32 v53, v54, v53
	v_add_f32_e32 v54, v74, v75
	v_add_f32_e32 v53, v77, v53
	v_sub_f32_e32 v55, v54, v74
	v_mul_f32_e32 v53, v72, v53
	v_sub_f32_e32 v55, v75, v55
	v_add_f32_e32 v53, v55, v53
	v_mul_f32_e32 v74, 0x3f317218, v52
	v_add_f32_e32 v55, v54, v53
	v_fma_f32 v75, v52, s78, -v74
	v_mul_f32_e32 v72, v55, v55
	v_fmac_f32_e32 v75, 0xb102e308, v52
	v_sub_f32_e32 v52, v55, v54
	v_fmamk_f32 v73, v72, 0x3e9b6dac, v185
	v_sub_f32_e32 v52, v53, v52
	v_add_f32_e32 v53, v74, v75
	v_fmaak_f32 v73, v72, v73, 0x3f2aaada
	v_sub_f32_e32 v54, v53, v74
	v_ldexp_f32 v74, v55, 1
	v_mul_f32_e32 v55, v55, v72
	v_mul_f32_e32 v55, v55, v73
	v_add_f32_e32 v72, v74, v55
	v_sub_f32_e32 v73, v72, v74
	v_ldexp_f32 v52, v52, 1
	v_sub_f32_e32 v55, v55, v73
	v_add_f32_e32 v52, v52, v55
	v_add_f32_e32 v55, v72, v52
	v_sub_f32_e32 v72, v55, v72
	v_sub_f32_e32 v52, v52, v72
	v_add_f32_e32 v72, v53, v55
	v_sub_f32_e32 v73, v72, v53
	v_sub_f32_e32 v74, v72, v73
	v_sub_f32_e32 v54, v75, v54
	v_sub_f32_e32 v53, v53, v74
	v_sub_f32_e32 v55, v55, v73
	v_add_f32_e32 v53, v55, v53
	v_add_f32_e32 v55, v54, v52
	v_sub_f32_e32 v73, v55, v54
	v_sub_f32_e32 v74, v55, v73
	v_sub_f32_e32 v54, v54, v74
	v_sub_f32_e32 v52, v52, v73
	v_add_f32_e32 v53, v55, v53
	v_add_f32_e32 v52, v52, v54
	v_add_f32_e32 v54, v72, v53
	v_sub_f32_e32 v55, v54, v72
	v_sub_f32_e32 v53, v53, v55
	v_add_f32_e32 v52, v52, v53
	v_add_f32_e32 v52, v54, v52
	v_cndmask_b32_e32 v52, v226, v52, vcc
	v_cmp_lt_f32_e64 vcc, |v49|, s63
	s_nop 1
	v_cndmask_b32_e32 v49, v52, v49, vcc
	v_sub_f32_e32 v48, v48, v49
	v_mul_f32_e32 v48, 0x3fb8aa3b, v48
	global_store_dword v[56:57], v48, off offset:64
	v_readlane_b32 s100, v254, 6
	s_nop 1
	v_mov_b32_e32 v49, s100
	v_fmac_f32_e32 v49, v50, v170
	v_mul_f32_e64 v50, |v49|, s94
	v_fma_f32 v52, |v49|, s94, -v50
	v_rndne_f32_e32 v53, v50
	v_fma_f32 v52, |v49|, s64, v52
	v_sub_f32_e32 v50, v50, v53
	v_add_f32_e32 v50, v50, v52
	v_exp_f32_e32 v50, v50
	v_cvt_i32_f32_e32 v52, v53
	v_cmp_ngt_f32_e64 vcc, |v49|, s58
	v_min_f32_e32 v48, 0, v49
	v_ldexp_f32 v50, v50, v52
	v_cndmask_b32_e32 v50, 0, v50, vcc
	v_cmp_nlt_f32_e64 vcc, |v49|, s59
	s_nop 1
	v_cndmask_b32_e32 v49, v226, v50, vcc
	v_add_f32_e32 v50, 1.0, v49
	v_add_f32_e32 v52, -1.0, v50
	v_sub_f32_e32 v53, v52, v50
	v_add_f32_e32 v53, 1.0, v53
	v_sub_f32_e32 v52, v49, v52
	v_add_f32_e32 v54, v52, v53
	v_frexp_mant_f32_e32 v52, v50
	v_cmp_gt_f32_e32 vcc, s77, v52
	v_cvt_f64_f32_e32 v[52:53], v50
	v_frexp_exp_i32_f64_e32 v52, v[52:53]
	v_subbrev_co_u32_e32 v52, vcc, 0, v52, vcc
	v_sub_u32_e32 v53, 0, v52
	v_ldexp_f32 v50, v50, v53
	v_ldexp_f32 v53, v54, v53
	v_add_f32_e32 v54, -1.0, v50
	v_add_f32_e32 v55, 1.0, v54
	v_sub_f32_e32 v55, v50, v55
	v_add_f32_e32 v55, v53, v55
	v_add_f32_e32 v72, v54, v55
	v_sub_f32_e32 v54, v54, v72
	v_add_f32_e32 v54, v55, v54
	v_add_f32_e32 v55, 1.0, v50
	v_add_f32_e32 v73, -1.0, v55
	v_sub_f32_e32 v50, v50, v73
	v_add_f32_e32 v50, v53, v50
	v_add_f32_e32 v53, v55, v50
	v_sub_f32_e32 v55, v55, v53
	v_add_f32_e32 v50, v50, v55
	v_rcp_f32_e32 v55, v53
	v_cvt_f32_i32_e32 v52, v52
	v_cmp_neq_f32_e32 vcc, s62, v49
	v_mul_f32_e32 v73, v72, v55
	v_mul_f32_e32 v74, v53, v73
	v_fma_f32 v75, v73, v53, -v74
	v_fmac_f32_e32 v75, v73, v50
	v_add_f32_e32 v76, v74, v75
	v_sub_f32_e32 v77, v72, v76
	v_sub_f32_e32 v72, v72, v77
	v_sub_f32_e32 v74, v76, v74
	v_sub_f32_e32 v72, v72, v76
	v_add_f32_e32 v54, v54, v72
	v_sub_f32_e32 v72, v74, v75
	v_add_f32_e32 v54, v72, v54
	v_add_f32_e32 v72, v77, v54
	v_mul_f32_e32 v74, v55, v72
	v_mul_f32_e32 v75, v53, v74
	v_fma_f32 v53, v74, v53, -v75
	v_fmac_f32_e32 v53, v74, v50
	v_sub_f32_e32 v50, v77, v72
	v_add_f32_e32 v50, v54, v50
	v_add_f32_e32 v54, v75, v53
	v_sub_f32_e32 v76, v72, v54
	v_sub_f32_e32 v72, v72, v76
	v_sub_f32_e32 v75, v54, v75
	v_sub_f32_e32 v54, v72, v54
	v_add_f32_e32 v50, v50, v54
	v_sub_f32_e32 v53, v75, v53
	v_add_f32_e32 v50, v53, v50
	v_add_f32_e32 v53, v73, v74
	v_add_f32_e32 v50, v76, v50
	v_sub_f32_e32 v54, v53, v73
	v_mul_f32_e32 v50, v55, v50
	v_sub_f32_e32 v54, v74, v54
	v_add_f32_e32 v50, v54, v50
	v_mul_f32_e32 v73, 0x3f317218, v52
	v_add_f32_e32 v54, v53, v50
	v_fma_f32 v74, v52, s78, -v73
	v_mul_f32_e32 v55, v54, v54
	v_fmac_f32_e32 v74, 0xb102e308, v52
	v_sub_f32_e32 v52, v54, v53
	v_fmamk_f32 v72, v55, 0x3e9b6dac, v185
	v_sub_f32_e32 v50, v50, v52
	v_add_f32_e32 v52, v73, v74
	v_fmaak_f32 v72, v55, v72, 0x3f2aaada
	v_sub_f32_e32 v53, v52, v73
	v_ldexp_f32 v73, v54, 1
	v_mul_f32_e32 v54, v54, v55
	v_mul_f32_e32 v54, v54, v72
	v_add_f32_e32 v55, v73, v54
	v_sub_f32_e32 v72, v55, v73
	v_ldexp_f32 v50, v50, 1
	v_sub_f32_e32 v54, v54, v72
	v_add_f32_e32 v50, v50, v54
	v_add_f32_e32 v54, v55, v50
	v_sub_f32_e32 v55, v54, v55
	v_sub_f32_e32 v50, v50, v55
	v_add_f32_e32 v55, v52, v54
	v_sub_f32_e32 v72, v55, v52
	v_sub_f32_e32 v73, v55, v72
	v_sub_f32_e32 v53, v74, v53
	v_sub_f32_e32 v52, v52, v73
	v_sub_f32_e32 v54, v54, v72
	v_add_f32_e32 v52, v54, v52
	v_add_f32_e32 v54, v53, v50
	v_sub_f32_e32 v72, v54, v53
	v_sub_f32_e32 v73, v54, v72
	v_sub_f32_e32 v53, v53, v73
	v_sub_f32_e32 v50, v50, v72
	v_add_f32_e32 v52, v54, v52
	v_add_f32_e32 v50, v50, v53
	v_add_f32_e32 v53, v55, v52
	v_sub_f32_e32 v54, v53, v55
	v_sub_f32_e32 v52, v52, v54
	v_add_f32_e32 v50, v50, v52
	v_add_f32_e32 v50, v53, v50
	v_cndmask_b32_e32 v50, v226, v50, vcc
	v_cmp_lt_f32_e64 vcc, |v49|, s63
	s_nop 1
	v_cndmask_b32_e32 v49, v50, v49, vcc
	v_sub_f32_e32 v48, v48, v49
	v_mul_f32_e32 v48, 0x3fb8aa3b, v48
	global_store_dword v[70:71], v48, off offset:64
	v_readlane_b32 s100, v254, 7
	s_nop 1
	v_mov_b32_e32 v49, s100
	v_fmac_f32_e32 v49, v51, v170
	v_mul_f32_e64 v50, |v49|, s94
	v_fma_f32 v51, |v49|, s94, -v50
	v_rndne_f32_e32 v52, v50
	v_fma_f32 v51, |v49|, s64, v51
	v_sub_f32_e32 v50, v50, v52
	v_add_f32_e32 v50, v50, v51
	v_exp_f32_e32 v50, v50
	v_cvt_i32_f32_e32 v51, v52
	v_cmp_ngt_f32_e64 vcc, |v49|, s58
	v_min_f32_e32 v48, 0, v49
	v_ldexp_f32 v50, v50, v51
	v_cndmask_b32_e32 v50, 0, v50, vcc
	v_cmp_nlt_f32_e64 vcc, |v49|, s59
	s_nop 1
	v_cndmask_b32_e32 v49, v226, v50, vcc
	v_add_f32_e32 v52, 1.0, v49
	v_add_f32_e32 v50, -1.0, v52
	v_sub_f32_e32 v51, v50, v52
	v_add_f32_e32 v51, 1.0, v51
	v_sub_f32_e32 v50, v49, v50
	v_add_f32_e32 v53, v50, v51
	v_frexp_mant_f32_e32 v50, v52
	v_cmp_gt_f32_e32 vcc, s77, v50
	v_cvt_f64_f32_e32 v[50:51], v52
	v_frexp_exp_i32_f64_e32 v50, v[50:51]
	v_subbrev_co_u32_e32 v50, vcc, 0, v50, vcc
	v_sub_u32_e32 v51, 0, v50
	v_ldexp_f32 v52, v52, v51
	v_ldexp_f32 v51, v53, v51
	v_add_f32_e32 v53, -1.0, v52
	v_add_f32_e32 v54, 1.0, v53
	v_sub_f32_e32 v54, v52, v54
	v_add_f32_e32 v54, v51, v54
	v_add_f32_e32 v55, v53, v54
	v_sub_f32_e32 v53, v53, v55
	v_add_f32_e32 v53, v54, v53
	v_add_f32_e32 v54, 1.0, v52
	v_add_f32_e32 v72, -1.0, v54
	v_sub_f32_e32 v52, v52, v72
	v_add_f32_e32 v51, v51, v52
	v_add_f32_e32 v52, v54, v51
	v_sub_f32_e32 v54, v54, v52
	v_add_f32_e32 v51, v51, v54
	v_rcp_f32_e32 v54, v52
	v_cvt_f32_i32_e32 v50, v50
	v_cmp_neq_f32_e32 vcc, s62, v49
	v_mul_f32_e32 v72, v55, v54
	v_mul_f32_e32 v73, v52, v72
	v_fma_f32 v74, v72, v52, -v73
	v_fmac_f32_e32 v74, v72, v51
	v_add_f32_e32 v75, v73, v74
	v_sub_f32_e32 v76, v55, v75
	v_sub_f32_e32 v55, v55, v76
	v_sub_f32_e32 v73, v75, v73
	v_sub_f32_e32 v55, v55, v75
	v_add_f32_e32 v53, v53, v55
	v_sub_f32_e32 v55, v73, v74
	v_add_f32_e32 v53, v55, v53
	v_add_f32_e32 v55, v76, v53
	v_mul_f32_e32 v73, v54, v55
	v_mul_f32_e32 v74, v52, v73
	v_fma_f32 v52, v73, v52, -v74
	v_fmac_f32_e32 v52, v73, v51
	v_sub_f32_e32 v51, v76, v55
	v_add_f32_e32 v51, v53, v51
	v_add_f32_e32 v53, v74, v52
	v_sub_f32_e32 v75, v55, v53
	v_sub_f32_e32 v55, v55, v75
	v_sub_f32_e32 v74, v53, v74
	v_sub_f32_e32 v53, v55, v53
	v_add_f32_e32 v51, v51, v53
	v_sub_f32_e32 v52, v74, v52
	v_add_f32_e32 v51, v52, v51
	v_add_f32_e32 v52, v72, v73
	v_add_f32_e32 v51, v75, v51
	v_sub_f32_e32 v53, v52, v72
	v_mul_f32_e32 v51, v54, v51
	v_sub_f32_e32 v53, v73, v53
	v_add_f32_e32 v51, v53, v51
	v_mul_f32_e32 v72, 0x3f317218, v50
	v_add_f32_e32 v53, v52, v51
	v_fma_f32 v73, v50, s78, -v72
	v_mul_f32_e32 v54, v53, v53
	v_fmac_f32_e32 v73, 0xb102e308, v50
	v_sub_f32_e32 v50, v53, v52
	v_fmamk_f32 v55, v54, 0x3e9b6dac, v185
	v_sub_f32_e32 v50, v51, v50
	v_add_f32_e32 v51, v72, v73
	v_fmaak_f32 v55, v54, v55, 0x3f2aaada
	v_sub_f32_e32 v52, v51, v72
	v_ldexp_f32 v72, v53, 1
	v_mul_f32_e32 v53, v53, v54
	v_mul_f32_e32 v53, v53, v55
	v_add_f32_e32 v54, v72, v53
	v_sub_f32_e32 v55, v54, v72
	v_ldexp_f32 v50, v50, 1
	v_sub_f32_e32 v53, v53, v55
	v_add_f32_e32 v50, v50, v53
	v_add_f32_e32 v53, v54, v50
	v_sub_f32_e32 v54, v53, v54
	v_sub_f32_e32 v50, v50, v54
	v_add_f32_e32 v54, v51, v53
	v_sub_f32_e32 v55, v54, v51
	v_sub_f32_e32 v72, v54, v55
	v_sub_f32_e32 v52, v73, v52
	v_sub_f32_e32 v51, v51, v72
	v_sub_f32_e32 v53, v53, v55
	v_add_f32_e32 v51, v53, v51
	v_add_f32_e32 v53, v52, v50
	v_sub_f32_e32 v55, v53, v52
	v_sub_f32_e32 v72, v53, v55
	v_sub_f32_e32 v52, v52, v72
	v_sub_f32_e32 v50, v50, v55
	v_add_f32_e32 v51, v53, v51
	v_add_f32_e32 v50, v50, v52
	v_add_f32_e32 v52, v54, v51
	v_sub_f32_e32 v53, v52, v54
	v_sub_f32_e32 v51, v51, v53
	v_add_f32_e32 v50, v50, v51
	v_add_f32_e32 v50, v52, v50
	v_cndmask_b32_e32 v50, v226, v50, vcc
	v_cmp_lt_f32_e64 vcc, |v49|, s63
	s_nop 1
	v_cndmask_b32_e32 v49, v50, v49, vcc
	v_sub_f32_e32 v48, v48, v49
	v_mul_f32_e32 v48, 0x3fb8aa3b, v48
	global_store_dword v[58:59], v48, off offset:64
	v_readlane_b32 s100, v254, 0
	s_nop 1
	v_mov_b32_e32 v48, s100
	v_fmac_f32_e32 v48, v44, v168
	v_mul_f32_e64 v49, |v48|, s94
	v_fma_f32 v50, |v48|, s94, -v49
	v_rndne_f32_e32 v51, v49
	v_fma_f32 v50, |v48|, s64, v50
	v_sub_f32_e32 v49, v49, v51
	v_add_f32_e32 v49, v49, v50
	v_exp_f32_e32 v49, v49
	v_cvt_i32_f32_e32 v50, v51
	v_cmp_ngt_f32_e64 vcc, |v48|, s58
	v_min_f32_e32 v44, 0, v48
	v_ldexp_f32 v49, v49, v50
	v_cndmask_b32_e32 v49, 0, v49, vcc
	v_cmp_nlt_f32_e64 vcc, |v48|, s59
	s_nop 1
	v_cndmask_b32_e32 v48, v226, v49, vcc
	v_add_f32_e32 v49, 1.0, v48
	v_add_f32_e32 v50, -1.0, v49
	v_sub_f32_e32 v51, v50, v49
	v_add_f32_e32 v51, 1.0, v51
	v_sub_f32_e32 v50, v48, v50
	v_add_f32_e32 v52, v50, v51
	v_frexp_mant_f32_e32 v50, v49
	v_cmp_gt_f32_e32 vcc, s77, v50
	v_cvt_f64_f32_e32 v[50:51], v49
	v_frexp_exp_i32_f64_e32 v50, v[50:51]
	v_subbrev_co_u32_e32 v50, vcc, 0, v50, vcc
	v_sub_u32_e32 v51, 0, v50
	v_ldexp_f32 v49, v49, v51
	v_ldexp_f32 v51, v52, v51
	v_add_f32_e32 v52, -1.0, v49
	v_add_f32_e32 v53, 1.0, v52
	v_sub_f32_e32 v53, v49, v53
	v_add_f32_e32 v53, v51, v53
	v_add_f32_e32 v54, v52, v53
	v_sub_f32_e32 v52, v52, v54
	v_add_f32_e32 v52, v53, v52
	v_add_f32_e32 v53, 1.0, v49
	v_add_f32_e32 v55, -1.0, v53
	v_sub_f32_e32 v49, v49, v55
	v_add_f32_e32 v49, v51, v49
	v_add_f32_e32 v51, v53, v49
	v_sub_f32_e32 v53, v53, v51
	v_add_f32_e32 v49, v49, v53
	v_rcp_f32_e32 v53, v51
	v_cvt_f32_i32_e32 v50, v50
	v_cmp_neq_f32_e32 vcc, s62, v48
	v_mul_f32_e32 v55, v54, v53
	v_mul_f32_e32 v72, v51, v55
	v_fma_f32 v73, v55, v51, -v72
	v_fmac_f32_e32 v73, v55, v49
	v_add_f32_e32 v74, v72, v73
	v_sub_f32_e32 v75, v54, v74
	v_sub_f32_e32 v54, v54, v75
	v_sub_f32_e32 v72, v74, v72
	v_sub_f32_e32 v54, v54, v74
	v_add_f32_e32 v52, v52, v54
	v_sub_f32_e32 v54, v72, v73
	v_add_f32_e32 v52, v54, v52
	v_add_f32_e32 v54, v75, v52
	v_mul_f32_e32 v72, v53, v54
	v_mul_f32_e32 v73, v51, v72
	v_fma_f32 v51, v72, v51, -v73
	v_fmac_f32_e32 v51, v72, v49
	v_sub_f32_e32 v49, v75, v54
	v_add_f32_e32 v49, v52, v49
	v_add_f32_e32 v52, v73, v51
	v_sub_f32_e32 v74, v54, v52
	v_sub_f32_e32 v54, v54, v74
	v_sub_f32_e32 v73, v52, v73
	v_sub_f32_e32 v52, v54, v52
	v_add_f32_e32 v49, v49, v52
	v_sub_f32_e32 v51, v73, v51
	v_add_f32_e32 v49, v51, v49
	v_add_f32_e32 v51, v55, v72
	v_add_f32_e32 v49, v74, v49
	v_sub_f32_e32 v52, v51, v55
	v_mul_f32_e32 v49, v53, v49
	v_sub_f32_e32 v52, v72, v52
	v_add_f32_e32 v49, v52, v49
	v_mul_f32_e32 v55, 0x3f317218, v50
	v_add_f32_e32 v52, v51, v49
	v_fma_f32 v72, v50, s78, -v55
	v_mul_f32_e32 v53, v52, v52
	v_fmac_f32_e32 v72, 0xb102e308, v50
	v_sub_f32_e32 v50, v52, v51
	v_fmamk_f32 v54, v53, 0x3e9b6dac, v185
	v_sub_f32_e32 v49, v49, v50
	v_add_f32_e32 v50, v55, v72
	v_fmaak_f32 v54, v53, v54, 0x3f2aaada
	v_sub_f32_e32 v51, v50, v55
	v_ldexp_f32 v55, v52, 1
	v_mul_f32_e32 v52, v52, v53
	v_mul_f32_e32 v52, v52, v54
	v_add_f32_e32 v53, v55, v52
	v_sub_f32_e32 v54, v53, v55
	v_ldexp_f32 v49, v49, 1
	v_sub_f32_e32 v52, v52, v54
	v_add_f32_e32 v49, v49, v52
	v_add_f32_e32 v52, v53, v49
	v_sub_f32_e32 v53, v52, v53
	v_sub_f32_e32 v49, v49, v53
	v_add_f32_e32 v53, v50, v52
	v_sub_f32_e32 v54, v53, v50
	v_sub_f32_e32 v55, v53, v54
	v_sub_f32_e32 v51, v72, v51
	v_sub_f32_e32 v50, v50, v55
	v_sub_f32_e32 v52, v52, v54
	v_add_f32_e32 v50, v52, v50
	v_add_f32_e32 v52, v51, v49
	v_sub_f32_e32 v54, v52, v51
	v_sub_f32_e32 v55, v52, v54
	v_sub_f32_e32 v51, v51, v55
	v_sub_f32_e32 v49, v49, v54
	v_add_f32_e32 v50, v52, v50
	v_add_f32_e32 v49, v49, v51
	v_add_f32_e32 v51, v53, v50
	v_sub_f32_e32 v52, v51, v53
	v_sub_f32_e32 v50, v50, v52
	v_add_f32_e32 v49, v49, v50
	v_add_f32_e32 v49, v51, v49
	v_cndmask_b32_e32 v49, v226, v49, vcc
	v_cmp_lt_f32_e64 vcc, |v48|, s63
	s_nop 1
	v_cndmask_b32_e32 v48, v49, v48, vcc
	v_sub_f32_e32 v44, v44, v48
	v_mul_f32_e32 v44, 0x3fb8aa3b, v44
	global_store_dword v[64:65], v44, off offset:128
	v_readlane_b32 s100, v254, 1
	s_nop 1
	v_mov_b32_e32 v48, s100
	v_fmac_f32_e32 v48, v45, v168
	v_mul_f32_e64 v45, |v48|, s94
	v_fma_f32 v49, |v48|, s94, -v45
	v_rndne_f32_e32 v50, v45
	v_fma_f32 v49, |v48|, s64, v49
	v_sub_f32_e32 v45, v45, v50
	v_add_f32_e32 v45, v45, v49
	v_exp_f32_e32 v45, v45
	v_cvt_i32_f32_e32 v49, v50
	v_cmp_ngt_f32_e64 vcc, |v48|, s58
	v_min_f32_e32 v44, 0, v48
	v_ldexp_f32 v45, v45, v49
	v_cndmask_b32_e32 v45, 0, v45, vcc
	v_cmp_nlt_f32_e64 vcc, |v48|, s59
	s_nop 1
	v_cndmask_b32_e32 v45, v226, v45, vcc
	v_add_f32_e32 v50, 1.0, v45
	v_add_f32_e32 v48, -1.0, v50
	v_sub_f32_e32 v49, v48, v50
	v_add_f32_e32 v49, 1.0, v49
	v_sub_f32_e32 v48, v45, v48
	v_add_f32_e32 v51, v48, v49
	v_frexp_mant_f32_e32 v48, v50
	v_cmp_gt_f32_e32 vcc, s77, v48
	v_cvt_f64_f32_e32 v[48:49], v50
	v_frexp_exp_i32_f64_e32 v48, v[48:49]
	v_subbrev_co_u32_e32 v48, vcc, 0, v48, vcc
	v_sub_u32_e32 v49, 0, v48
	v_ldexp_f32 v50, v50, v49
	v_ldexp_f32 v49, v51, v49
	v_add_f32_e32 v51, -1.0, v50
	v_add_f32_e32 v52, 1.0, v51
	v_sub_f32_e32 v52, v50, v52
	v_add_f32_e32 v52, v49, v52
	v_add_f32_e32 v53, v51, v52
	v_sub_f32_e32 v51, v51, v53
	v_add_f32_e32 v51, v52, v51
	v_add_f32_e32 v52, 1.0, v50
	v_add_f32_e32 v54, -1.0, v52
	v_sub_f32_e32 v50, v50, v54
	v_add_f32_e32 v49, v49, v50
	v_add_f32_e32 v50, v52, v49
	v_sub_f32_e32 v52, v52, v50
	v_add_f32_e32 v49, v49, v52
	v_rcp_f32_e32 v52, v50
	v_cvt_f32_i32_e32 v48, v48
	v_cmp_neq_f32_e32 vcc, s62, v45
	v_mul_f32_e32 v54, v53, v52
	v_mul_f32_e32 v55, v50, v54
	v_fma_f32 v72, v54, v50, -v55
	v_fmac_f32_e32 v72, v54, v49
	v_add_f32_e32 v73, v55, v72
	v_sub_f32_e32 v74, v53, v73
	v_sub_f32_e32 v53, v53, v74
	v_sub_f32_e32 v55, v73, v55
	v_sub_f32_e32 v53, v53, v73
	v_add_f32_e32 v51, v51, v53
	v_sub_f32_e32 v53, v55, v72
	v_add_f32_e32 v51, v53, v51
	v_add_f32_e32 v53, v74, v51
	v_mul_f32_e32 v55, v52, v53
	v_mul_f32_e32 v72, v50, v55
	v_fma_f32 v50, v55, v50, -v72
	v_fmac_f32_e32 v50, v55, v49
	v_sub_f32_e32 v49, v74, v53
	v_add_f32_e32 v49, v51, v49
	v_add_f32_e32 v51, v72, v50
	v_sub_f32_e32 v73, v53, v51
	v_sub_f32_e32 v53, v53, v73
	v_sub_f32_e32 v72, v51, v72
	v_sub_f32_e32 v51, v53, v51
	v_add_f32_e32 v49, v49, v51
	v_sub_f32_e32 v50, v72, v50
	v_add_f32_e32 v49, v50, v49
	v_add_f32_e32 v50, v54, v55
	v_add_f32_e32 v49, v73, v49
	v_sub_f32_e32 v51, v50, v54
	v_mul_f32_e32 v49, v52, v49
	v_sub_f32_e32 v51, v55, v51
	v_add_f32_e32 v49, v51, v49
	v_mul_f32_e32 v54, 0x3f317218, v48
	v_add_f32_e32 v51, v50, v49
	v_fma_f32 v55, v48, s78, -v54
	v_mul_f32_e32 v52, v51, v51
	v_fmac_f32_e32 v55, 0xb102e308, v48
	v_sub_f32_e32 v48, v51, v50
	v_fmamk_f32 v53, v52, 0x3e9b6dac, v185
	v_sub_f32_e32 v48, v49, v48
	v_add_f32_e32 v49, v54, v55
	v_fmaak_f32 v53, v52, v53, 0x3f2aaada
	v_sub_f32_e32 v50, v49, v54
	v_ldexp_f32 v54, v51, 1
	v_mul_f32_e32 v51, v51, v52
	v_mul_f32_e32 v51, v51, v53
	v_add_f32_e32 v52, v54, v51
	v_sub_f32_e32 v53, v52, v54
	v_ldexp_f32 v48, v48, 1
	v_sub_f32_e32 v51, v51, v53
	v_add_f32_e32 v48, v48, v51
	v_add_f32_e32 v51, v52, v48
	v_sub_f32_e32 v52, v51, v52
	v_sub_f32_e32 v48, v48, v52
	v_add_f32_e32 v52, v49, v51
	v_sub_f32_e32 v53, v52, v49
	v_sub_f32_e32 v54, v52, v53
	v_sub_f32_e32 v50, v55, v50
	v_sub_f32_e32 v49, v49, v54
	v_sub_f32_e32 v51, v51, v53
	v_add_f32_e32 v49, v51, v49
	v_add_f32_e32 v51, v50, v48
	v_sub_f32_e32 v53, v51, v50
	v_sub_f32_e32 v54, v51, v53
	v_sub_f32_e32 v50, v50, v54
	v_sub_f32_e32 v48, v48, v53
	v_add_f32_e32 v49, v51, v49
	v_add_f32_e32 v48, v48, v50
	v_add_f32_e32 v50, v52, v49
	v_sub_f32_e32 v51, v50, v52
	v_sub_f32_e32 v49, v49, v51
	v_add_f32_e32 v48, v48, v49
	v_add_f32_e32 v48, v50, v48
	v_cndmask_b32_e32 v48, v226, v48, vcc
	v_cmp_lt_f32_e64 vcc, |v45|, s63
	s_nop 1
	v_cndmask_b32_e32 v45, v48, v45, vcc
	v_sub_f32_e32 v44, v44, v45
	v_mul_f32_e32 v44, 0x3fb8aa3b, v44
	global_store_dword v[60:61], v44, off offset:128
	v_readlane_b32 s100, v254, 2
	s_nop 1
	v_mov_b32_e32 v45, s100
	v_fmac_f32_e32 v45, v46, v168
	v_mul_f32_e64 v46, |v45|, s94
	v_fma_f32 v48, |v45|, s94, -v46
	v_rndne_f32_e32 v49, v46
	v_fma_f32 v48, |v45|, s64, v48
	v_sub_f32_e32 v46, v46, v49
	v_add_f32_e32 v46, v46, v48
	v_exp_f32_e32 v46, v46
	v_cvt_i32_f32_e32 v48, v49
	v_cmp_ngt_f32_e64 vcc, |v45|, s58
	v_min_f32_e32 v44, 0, v45
	v_ldexp_f32 v46, v46, v48
	v_cndmask_b32_e32 v46, 0, v46, vcc
	v_cmp_nlt_f32_e64 vcc, |v45|, s59
	s_nop 1
	v_cndmask_b32_e32 v45, v226, v46, vcc
	v_add_f32_e32 v46, 1.0, v45
	v_add_f32_e32 v48, -1.0, v46
	v_sub_f32_e32 v49, v48, v46
	v_add_f32_e32 v49, 1.0, v49
	v_sub_f32_e32 v48, v45, v48
	v_add_f32_e32 v50, v48, v49
	v_frexp_mant_f32_e32 v48, v46
	v_cmp_gt_f32_e32 vcc, s77, v48
	v_cvt_f64_f32_e32 v[48:49], v46
	v_frexp_exp_i32_f64_e32 v48, v[48:49]
	v_subbrev_co_u32_e32 v48, vcc, 0, v48, vcc
	v_sub_u32_e32 v49, 0, v48
	v_ldexp_f32 v46, v46, v49
	v_ldexp_f32 v49, v50, v49
	v_add_f32_e32 v50, -1.0, v46
	v_add_f32_e32 v51, 1.0, v50
	v_sub_f32_e32 v51, v46, v51
	v_add_f32_e32 v51, v49, v51
	v_add_f32_e32 v52, v50, v51
	v_sub_f32_e32 v50, v50, v52
	v_add_f32_e32 v50, v51, v50
	v_add_f32_e32 v51, 1.0, v46
	v_add_f32_e32 v53, -1.0, v51
	v_sub_f32_e32 v46, v46, v53
	v_add_f32_e32 v46, v49, v46
	v_add_f32_e32 v49, v51, v46
	v_sub_f32_e32 v51, v51, v49
	v_add_f32_e32 v46, v46, v51
	v_rcp_f32_e32 v51, v49
	v_cvt_f32_i32_e32 v48, v48
	v_cmp_neq_f32_e32 vcc, s62, v45
	v_mul_f32_e32 v53, v52, v51
	v_mul_f32_e32 v54, v49, v53
	v_fma_f32 v55, v53, v49, -v54
	v_fmac_f32_e32 v55, v53, v46
	v_add_f32_e32 v72, v54, v55
	v_sub_f32_e32 v73, v52, v72
	v_sub_f32_e32 v52, v52, v73
	v_sub_f32_e32 v54, v72, v54
	v_sub_f32_e32 v52, v52, v72
	v_add_f32_e32 v50, v50, v52
	v_sub_f32_e32 v52, v54, v55
	v_add_f32_e32 v50, v52, v50
	v_add_f32_e32 v52, v73, v50
	v_mul_f32_e32 v54, v51, v52
	v_mul_f32_e32 v55, v49, v54
	v_fma_f32 v49, v54, v49, -v55
	v_fmac_f32_e32 v49, v54, v46
	v_sub_f32_e32 v46, v73, v52
	v_add_f32_e32 v46, v50, v46
	v_add_f32_e32 v50, v55, v49
	v_sub_f32_e32 v72, v52, v50
	v_sub_f32_e32 v52, v52, v72
	v_sub_f32_e32 v55, v50, v55
	v_sub_f32_e32 v50, v52, v50
	v_add_f32_e32 v46, v46, v50
	v_sub_f32_e32 v49, v55, v49
	v_add_f32_e32 v46, v49, v46
	v_add_f32_e32 v49, v53, v54
	v_add_f32_e32 v46, v72, v46
	v_sub_f32_e32 v50, v49, v53
	v_mul_f32_e32 v46, v51, v46
	v_sub_f32_e32 v50, v54, v50
	v_add_f32_e32 v46, v50, v46
	v_mul_f32_e32 v53, 0x3f317218, v48
	v_add_f32_e32 v50, v49, v46
	v_fma_f32 v54, v48, s78, -v53
	v_mul_f32_e32 v51, v50, v50
	v_fmac_f32_e32 v54, 0xb102e308, v48
	v_sub_f32_e32 v48, v50, v49
	v_fmamk_f32 v52, v51, 0x3e9b6dac, v185
	v_sub_f32_e32 v46, v46, v48
	v_add_f32_e32 v48, v53, v54
	v_fmaak_f32 v52, v51, v52, 0x3f2aaada
	v_sub_f32_e32 v49, v48, v53
	v_ldexp_f32 v53, v50, 1
	v_mul_f32_e32 v50, v50, v51
	v_mul_f32_e32 v50, v50, v52
	v_add_f32_e32 v51, v53, v50
	v_sub_f32_e32 v52, v51, v53
	v_ldexp_f32 v46, v46, 1
	v_sub_f32_e32 v50, v50, v52
	v_add_f32_e32 v46, v46, v50
	v_add_f32_e32 v50, v51, v46
	v_sub_f32_e32 v51, v50, v51
	v_sub_f32_e32 v46, v46, v51
	v_add_f32_e32 v51, v48, v50
	v_sub_f32_e32 v52, v51, v48
	v_sub_f32_e32 v53, v51, v52
	v_sub_f32_e32 v49, v54, v49
	v_sub_f32_e32 v48, v48, v53
	v_sub_f32_e32 v50, v50, v52
	v_add_f32_e32 v48, v50, v48
	v_add_f32_e32 v50, v49, v46
	v_sub_f32_e32 v52, v50, v49
	v_sub_f32_e32 v53, v50, v52
	v_sub_f32_e32 v49, v49, v53
	v_sub_f32_e32 v46, v46, v52
	v_add_f32_e32 v48, v50, v48
	v_add_f32_e32 v46, v46, v49
	v_add_f32_e32 v49, v51, v48
	v_sub_f32_e32 v50, v49, v51
	v_sub_f32_e32 v48, v48, v50
	v_add_f32_e32 v46, v46, v48
	v_add_f32_e32 v46, v49, v46
	v_cndmask_b32_e32 v46, v226, v46, vcc
	v_cmp_lt_f32_e64 vcc, |v45|, s63
	s_nop 1
	v_cndmask_b32_e32 v45, v46, v45, vcc
	v_sub_f32_e32 v44, v44, v45
	v_mul_f32_e32 v44, 0x3fb8aa3b, v44
	global_store_dword v[66:67], v44, off offset:128
	v_readlane_b32 s100, v254, 3
	s_nop 1
	v_mov_b32_e32 v45, s100
	v_fmac_f32_e32 v45, v47, v168
	v_mul_f32_e64 v46, |v45|, s94
	v_fma_f32 v47, |v45|, s94, -v46
	v_rndne_f32_e32 v48, v46
	v_fma_f32 v47, |v45|, s64, v47
	v_sub_f32_e32 v46, v46, v48
	v_add_f32_e32 v46, v46, v47
	v_exp_f32_e32 v46, v46
	v_cvt_i32_f32_e32 v47, v48
	v_cmp_ngt_f32_e64 vcc, |v45|, s58
	v_min_f32_e32 v44, 0, v45
	v_ldexp_f32 v46, v46, v47
	v_cndmask_b32_e32 v46, 0, v46, vcc
	v_cmp_nlt_f32_e64 vcc, |v45|, s59
	s_nop 1
	v_cndmask_b32_e32 v45, v226, v46, vcc
	v_add_f32_e32 v48, 1.0, v45
	v_add_f32_e32 v46, -1.0, v48
	v_sub_f32_e32 v47, v46, v48
	v_add_f32_e32 v47, 1.0, v47
	v_sub_f32_e32 v46, v45, v46
	v_add_f32_e32 v49, v46, v47
	v_frexp_mant_f32_e32 v46, v48
	v_cmp_gt_f32_e32 vcc, s77, v46
	v_cvt_f64_f32_e32 v[46:47], v48
	v_frexp_exp_i32_f64_e32 v46, v[46:47]
	v_subbrev_co_u32_e32 v46, vcc, 0, v46, vcc
	v_sub_u32_e32 v47, 0, v46
	v_ldexp_f32 v48, v48, v47
	v_ldexp_f32 v47, v49, v47
	v_add_f32_e32 v49, -1.0, v48
	v_add_f32_e32 v50, 1.0, v49
	v_sub_f32_e32 v50, v48, v50
	v_add_f32_e32 v50, v47, v50
	v_add_f32_e32 v51, v49, v50
	v_sub_f32_e32 v49, v49, v51
	v_add_f32_e32 v49, v50, v49
	v_add_f32_e32 v50, 1.0, v48
	v_add_f32_e32 v52, -1.0, v50
	v_sub_f32_e32 v48, v48, v52
	v_add_f32_e32 v47, v47, v48
	v_add_f32_e32 v48, v50, v47
	v_sub_f32_e32 v50, v50, v48
	v_add_f32_e32 v47, v47, v50
	v_rcp_f32_e32 v50, v48
	v_cvt_f32_i32_e32 v46, v46
	v_cmp_neq_f32_e32 vcc, s62, v45
	v_mul_f32_e32 v52, v51, v50
	v_mul_f32_e32 v53, v48, v52
	v_fma_f32 v54, v52, v48, -v53
	v_fmac_f32_e32 v54, v52, v47
	v_add_f32_e32 v55, v53, v54
	v_sub_f32_e32 v72, v51, v55
	v_sub_f32_e32 v51, v51, v72
	v_sub_f32_e32 v53, v55, v53
	v_sub_f32_e32 v51, v51, v55
	v_add_f32_e32 v49, v49, v51
	v_sub_f32_e32 v51, v53, v54
	v_add_f32_e32 v49, v51, v49
	v_add_f32_e32 v51, v72, v49
	v_mul_f32_e32 v53, v50, v51
	v_mul_f32_e32 v54, v48, v53
	v_fma_f32 v48, v53, v48, -v54
	v_fmac_f32_e32 v48, v53, v47
	v_sub_f32_e32 v47, v72, v51
	v_add_f32_e32 v47, v49, v47
	v_add_f32_e32 v49, v54, v48
	v_sub_f32_e32 v55, v51, v49
	v_sub_f32_e32 v51, v51, v55
	v_sub_f32_e32 v54, v49, v54
	v_sub_f32_e32 v49, v51, v49
	v_add_f32_e32 v47, v47, v49
	v_sub_f32_e32 v48, v54, v48
	v_add_f32_e32 v47, v48, v47
	v_add_f32_e32 v48, v52, v53
	v_add_f32_e32 v47, v55, v47
	v_sub_f32_e32 v49, v48, v52
	v_mul_f32_e32 v47, v50, v47
	v_sub_f32_e32 v49, v53, v49
	v_add_f32_e32 v47, v49, v47
	v_mul_f32_e32 v52, 0x3f317218, v46
	v_add_f32_e32 v49, v48, v47
	v_fma_f32 v53, v46, s78, -v52
	v_mul_f32_e32 v50, v49, v49
	v_fmac_f32_e32 v53, 0xb102e308, v46
	v_sub_f32_e32 v46, v49, v48
	v_fmamk_f32 v51, v50, 0x3e9b6dac, v185
	v_sub_f32_e32 v46, v47, v46
	v_add_f32_e32 v47, v52, v53
	v_fmaak_f32 v51, v50, v51, 0x3f2aaada
	v_sub_f32_e32 v48, v47, v52
	v_ldexp_f32 v52, v49, 1
	v_mul_f32_e32 v49, v49, v50
	v_mul_f32_e32 v49, v49, v51
	v_add_f32_e32 v50, v52, v49
	v_sub_f32_e32 v51, v50, v52
	v_ldexp_f32 v46, v46, 1
	v_sub_f32_e32 v49, v49, v51
	v_add_f32_e32 v46, v46, v49
	v_add_f32_e32 v49, v50, v46
	v_sub_f32_e32 v50, v49, v50
	v_sub_f32_e32 v46, v46, v50
	v_add_f32_e32 v50, v47, v49
	v_sub_f32_e32 v51, v50, v47
	v_sub_f32_e32 v52, v50, v51
	v_sub_f32_e32 v48, v53, v48
	v_sub_f32_e32 v47, v47, v52
	v_sub_f32_e32 v49, v49, v51
	v_add_f32_e32 v47, v49, v47
	v_add_f32_e32 v49, v48, v46
	v_sub_f32_e32 v51, v49, v48
	v_sub_f32_e32 v52, v49, v51
	v_sub_f32_e32 v48, v48, v52
	v_sub_f32_e32 v46, v46, v51
	v_add_f32_e32 v47, v49, v47
	v_add_f32_e32 v46, v46, v48
	v_add_f32_e32 v48, v50, v47
	v_sub_f32_e32 v49, v48, v50
	v_sub_f32_e32 v47, v47, v49
	v_add_f32_e32 v46, v46, v47
	v_add_f32_e32 v46, v48, v46
	v_cndmask_b32_e32 v46, v226, v46, vcc
	v_cmp_lt_f32_e64 vcc, |v45|, s63
	s_nop 1
	v_cndmask_b32_e32 v45, v46, v45, vcc
	v_sub_f32_e32 v44, v44, v45
	v_mul_f32_e32 v44, 0x3fb8aa3b, v44
	global_store_dword v[62:63], v44, off offset:128
	v_readlane_b32 s100, v254, 4
	s_nop 1
	v_mov_b32_e32 v44, s100
	v_fmac_f32_e32 v44, v40, v168
	v_mul_f32_e64 v45, |v44|, s94
	v_fma_f32 v46, |v44|, s94, -v45
	v_rndne_f32_e32 v47, v45
	v_fma_f32 v46, |v44|, s64, v46
	v_sub_f32_e32 v45, v45, v47
	v_add_f32_e32 v45, v45, v46
	v_exp_f32_e32 v45, v45
	v_cvt_i32_f32_e32 v46, v47
	v_cmp_ngt_f32_e64 vcc, |v44|, s58
	v_min_f32_e32 v40, 0, v44
	v_ldexp_f32 v45, v45, v46
	v_cndmask_b32_e32 v45, 0, v45, vcc
	v_cmp_nlt_f32_e64 vcc, |v44|, s59
	s_nop 1
	v_cndmask_b32_e32 v44, v226, v45, vcc
	v_add_f32_e32 v45, 1.0, v44
	v_add_f32_e32 v46, -1.0, v45
	v_sub_f32_e32 v47, v46, v45
	v_add_f32_e32 v47, 1.0, v47
	v_sub_f32_e32 v46, v44, v46
	v_add_f32_e32 v48, v46, v47
	v_frexp_mant_f32_e32 v46, v45
	v_cmp_gt_f32_e32 vcc, s77, v46
	v_cvt_f64_f32_e32 v[46:47], v45
	v_frexp_exp_i32_f64_e32 v46, v[46:47]
	v_subbrev_co_u32_e32 v46, vcc, 0, v46, vcc
	v_sub_u32_e32 v47, 0, v46
	v_ldexp_f32 v45, v45, v47
	v_ldexp_f32 v47, v48, v47
	v_add_f32_e32 v48, -1.0, v45
	v_add_f32_e32 v49, 1.0, v48
	v_sub_f32_e32 v49, v45, v49
	v_add_f32_e32 v49, v47, v49
	v_add_f32_e32 v50, v48, v49
	v_sub_f32_e32 v48, v48, v50
	v_add_f32_e32 v48, v49, v48
	v_add_f32_e32 v49, 1.0, v45
	v_add_f32_e32 v51, -1.0, v49
	v_sub_f32_e32 v45, v45, v51
	v_add_f32_e32 v45, v47, v45
	v_add_f32_e32 v47, v49, v45
	v_sub_f32_e32 v49, v49, v47
	v_add_f32_e32 v45, v45, v49
	v_rcp_f32_e32 v49, v47
	v_cvt_f32_i32_e32 v46, v46
	v_cmp_neq_f32_e32 vcc, s62, v44
	v_mul_f32_e32 v51, v50, v49
	v_mul_f32_e32 v52, v47, v51
	v_fma_f32 v53, v51, v47, -v52
	v_fmac_f32_e32 v53, v51, v45
	v_add_f32_e32 v54, v52, v53
	v_sub_f32_e32 v55, v50, v54
	v_sub_f32_e32 v50, v50, v55
	v_sub_f32_e32 v52, v54, v52
	v_sub_f32_e32 v50, v50, v54
	v_add_f32_e32 v48, v48, v50
	v_sub_f32_e32 v50, v52, v53
	v_add_f32_e32 v48, v50, v48
	v_add_f32_e32 v50, v55, v48
	v_mul_f32_e32 v52, v49, v50
	v_mul_f32_e32 v53, v47, v52
	v_fma_f32 v47, v52, v47, -v53
	v_fmac_f32_e32 v47, v52, v45
	v_sub_f32_e32 v45, v55, v50
	v_add_f32_e32 v45, v48, v45
	v_add_f32_e32 v48, v53, v47
	v_sub_f32_e32 v54, v50, v48
	v_sub_f32_e32 v50, v50, v54
	v_sub_f32_e32 v53, v48, v53
	v_sub_f32_e32 v48, v50, v48
	v_add_f32_e32 v45, v45, v48
	v_sub_f32_e32 v47, v53, v47
	v_add_f32_e32 v45, v47, v45
	v_add_f32_e32 v47, v51, v52
	v_add_f32_e32 v45, v54, v45
	v_sub_f32_e32 v48, v47, v51
	v_mul_f32_e32 v45, v49, v45
	v_sub_f32_e32 v48, v52, v48
	v_add_f32_e32 v45, v48, v45
	v_mul_f32_e32 v51, 0x3f317218, v46
	v_add_f32_e32 v48, v47, v45
	v_fma_f32 v52, v46, s78, -v51
	v_mul_f32_e32 v49, v48, v48
	v_fmac_f32_e32 v52, 0xb102e308, v46
	v_sub_f32_e32 v46, v48, v47
	v_fmamk_f32 v50, v49, 0x3e9b6dac, v185
	v_sub_f32_e32 v45, v45, v46
	v_add_f32_e32 v46, v51, v52
	v_fmaak_f32 v50, v49, v50, 0x3f2aaada
	v_sub_f32_e32 v47, v46, v51
	v_ldexp_f32 v51, v48, 1
	v_mul_f32_e32 v48, v48, v49
	v_mul_f32_e32 v48, v48, v50
	v_add_f32_e32 v49, v51, v48
	v_sub_f32_e32 v50, v49, v51
	v_ldexp_f32 v45, v45, 1
	v_sub_f32_e32 v48, v48, v50
	v_add_f32_e32 v45, v45, v48
	v_add_f32_e32 v48, v49, v45
	v_sub_f32_e32 v49, v48, v49
	v_sub_f32_e32 v45, v45, v49
	v_add_f32_e32 v49, v46, v48
	v_sub_f32_e32 v50, v49, v46
	v_sub_f32_e32 v51, v49, v50
	v_sub_f32_e32 v47, v52, v47
	v_sub_f32_e32 v46, v46, v51
	v_sub_f32_e32 v48, v48, v50
	v_add_f32_e32 v46, v48, v46
	v_add_f32_e32 v48, v47, v45
	v_sub_f32_e32 v50, v48, v47
	v_sub_f32_e32 v51, v48, v50
	v_sub_f32_e32 v47, v47, v51
	v_sub_f32_e32 v45, v45, v50
	v_add_f32_e32 v46, v48, v46
	v_add_f32_e32 v45, v45, v47
	v_add_f32_e32 v47, v49, v46
	v_sub_f32_e32 v48, v47, v49
	v_sub_f32_e32 v46, v46, v48
	v_add_f32_e32 v45, v45, v46
	v_add_f32_e32 v45, v47, v45
	v_cndmask_b32_e32 v45, v226, v45, vcc
	v_cmp_lt_f32_e64 vcc, |v44|, s63
	s_nop 1
	v_cndmask_b32_e32 v44, v45, v44, vcc
	v_sub_f32_e32 v40, v40, v44
	v_mul_f32_e32 v40, 0x3fb8aa3b, v40
	global_store_dword v[68:69], v40, off offset:128
	v_readlane_b32 s100, v254, 5
	s_nop 1
	v_mov_b32_e32 v44, s100
	v_fmac_f32_e32 v44, v41, v168
	v_mul_f32_e64 v41, |v44|, s94
	v_fma_f32 v45, |v44|, s94, -v41
	v_rndne_f32_e32 v46, v41
	v_fma_f32 v45, |v44|, s64, v45
	v_sub_f32_e32 v41, v41, v46
	v_add_f32_e32 v41, v41, v45
	v_exp_f32_e32 v41, v41
	v_cvt_i32_f32_e32 v45, v46
	v_cmp_ngt_f32_e64 vcc, |v44|, s58
	v_min_f32_e32 v40, 0, v44
	v_ldexp_f32 v41, v41, v45
	v_cndmask_b32_e32 v41, 0, v41, vcc
	v_cmp_nlt_f32_e64 vcc, |v44|, s59
	s_nop 1
	v_cndmask_b32_e32 v41, v226, v41, vcc
	v_add_f32_e32 v46, 1.0, v41
	v_add_f32_e32 v44, -1.0, v46
	v_sub_f32_e32 v45, v44, v46
	v_add_f32_e32 v45, 1.0, v45
	v_sub_f32_e32 v44, v41, v44
	v_add_f32_e32 v47, v44, v45
	v_frexp_mant_f32_e32 v44, v46
	v_cmp_gt_f32_e32 vcc, s77, v44
	v_cvt_f64_f32_e32 v[44:45], v46
	v_frexp_exp_i32_f64_e32 v44, v[44:45]
	v_subbrev_co_u32_e32 v44, vcc, 0, v44, vcc
	v_sub_u32_e32 v45, 0, v44
	v_ldexp_f32 v46, v46, v45
	v_ldexp_f32 v45, v47, v45
	v_add_f32_e32 v47, -1.0, v46
	v_add_f32_e32 v48, 1.0, v47
	v_sub_f32_e32 v48, v46, v48
	v_add_f32_e32 v48, v45, v48
	v_add_f32_e32 v49, v47, v48
	v_sub_f32_e32 v47, v47, v49
	v_add_f32_e32 v47, v48, v47
	v_add_f32_e32 v48, 1.0, v46
	v_add_f32_e32 v50, -1.0, v48
	v_sub_f32_e32 v46, v46, v50
	v_add_f32_e32 v45, v45, v46
	v_add_f32_e32 v46, v48, v45
	v_sub_f32_e32 v48, v48, v46
	v_add_f32_e32 v45, v45, v48
	v_rcp_f32_e32 v48, v46
	v_cvt_f32_i32_e32 v44, v44
	v_cmp_neq_f32_e32 vcc, s62, v41
	v_mul_f32_e32 v50, v49, v48
	v_mul_f32_e32 v51, v46, v50
	v_fma_f32 v52, v50, v46, -v51
	v_fmac_f32_e32 v52, v50, v45
	v_add_f32_e32 v53, v51, v52
	v_sub_f32_e32 v54, v49, v53
	v_sub_f32_e32 v49, v49, v54
	v_sub_f32_e32 v51, v53, v51
	v_sub_f32_e32 v49, v49, v53
	v_add_f32_e32 v47, v47, v49
	v_sub_f32_e32 v49, v51, v52
	v_add_f32_e32 v47, v49, v47
	v_add_f32_e32 v49, v54, v47
	v_mul_f32_e32 v51, v48, v49
	v_mul_f32_e32 v52, v46, v51
	v_fma_f32 v46, v51, v46, -v52
	v_fmac_f32_e32 v46, v51, v45
	v_sub_f32_e32 v45, v54, v49
	v_add_f32_e32 v45, v47, v45
	v_add_f32_e32 v47, v52, v46
	v_sub_f32_e32 v53, v49, v47
	v_sub_f32_e32 v49, v49, v53
	v_sub_f32_e32 v52, v47, v52
	v_sub_f32_e32 v47, v49, v47
	v_add_f32_e32 v45, v45, v47
	v_sub_f32_e32 v46, v52, v46
	v_add_f32_e32 v45, v46, v45
	v_add_f32_e32 v46, v50, v51
	v_add_f32_e32 v45, v53, v45
	v_sub_f32_e32 v47, v46, v50
	v_mul_f32_e32 v45, v48, v45
	v_sub_f32_e32 v47, v51, v47
	v_add_f32_e32 v45, v47, v45
	v_mul_f32_e32 v50, 0x3f317218, v44
	v_add_f32_e32 v47, v46, v45
	v_fma_f32 v51, v44, s78, -v50
	v_mul_f32_e32 v48, v47, v47
	v_fmac_f32_e32 v51, 0xb102e308, v44
	v_sub_f32_e32 v44, v47, v46
	v_fmamk_f32 v49, v48, 0x3e9b6dac, v185
	v_sub_f32_e32 v44, v45, v44
	v_add_f32_e32 v45, v50, v51
	v_fmaak_f32 v49, v48, v49, 0x3f2aaada
	v_sub_f32_e32 v46, v45, v50
	v_ldexp_f32 v50, v47, 1
	v_mul_f32_e32 v47, v47, v48
	v_mul_f32_e32 v47, v47, v49
	v_add_f32_e32 v48, v50, v47
	v_sub_f32_e32 v49, v48, v50
	v_ldexp_f32 v44, v44, 1
	v_sub_f32_e32 v47, v47, v49
	v_add_f32_e32 v44, v44, v47
	v_add_f32_e32 v47, v48, v44
	v_sub_f32_e32 v48, v47, v48
	v_sub_f32_e32 v44, v44, v48
	v_add_f32_e32 v48, v45, v47
	v_sub_f32_e32 v49, v48, v45
	v_sub_f32_e32 v50, v48, v49
	v_sub_f32_e32 v46, v51, v46
	v_sub_f32_e32 v45, v45, v50
	v_sub_f32_e32 v47, v47, v49
	v_add_f32_e32 v45, v47, v45
	v_add_f32_e32 v47, v46, v44
	v_sub_f32_e32 v49, v47, v46
	v_sub_f32_e32 v50, v47, v49
	v_sub_f32_e32 v46, v46, v50
	v_sub_f32_e32 v44, v44, v49
	v_add_f32_e32 v45, v47, v45
	v_add_f32_e32 v44, v44, v46
	v_add_f32_e32 v46, v48, v45
	v_sub_f32_e32 v47, v46, v48
	v_sub_f32_e32 v45, v45, v47
	v_add_f32_e32 v44, v44, v45
	v_add_f32_e32 v44, v46, v44
	v_cndmask_b32_e32 v44, v226, v44, vcc
	v_cmp_lt_f32_e64 vcc, |v41|, s63
	s_nop 1
	v_cndmask_b32_e32 v41, v44, v41, vcc
	v_sub_f32_e32 v40, v40, v41
	v_mul_f32_e32 v40, 0x3fb8aa3b, v40
	global_store_dword v[56:57], v40, off offset:128
	v_readlane_b32 s100, v254, 6
	s_nop 1
	v_mov_b32_e32 v41, s100
	v_fmac_f32_e32 v41, v42, v168
	v_mul_f32_e64 v42, |v41|, s94
	v_fma_f32 v44, |v41|, s94, -v42
	v_rndne_f32_e32 v45, v42
	v_fma_f32 v44, |v41|, s64, v44
	v_sub_f32_e32 v42, v42, v45
	v_add_f32_e32 v42, v42, v44
	v_exp_f32_e32 v42, v42
	v_cvt_i32_f32_e32 v44, v45
	v_cmp_ngt_f32_e64 vcc, |v41|, s58
	v_min_f32_e32 v40, 0, v41
	v_ldexp_f32 v42, v42, v44
	v_cndmask_b32_e32 v42, 0, v42, vcc
	v_cmp_nlt_f32_e64 vcc, |v41|, s59
	s_nop 1
	v_cndmask_b32_e32 v41, v226, v42, vcc
	v_add_f32_e32 v42, 1.0, v41
	v_add_f32_e32 v44, -1.0, v42
	v_sub_f32_e32 v45, v44, v42
	v_add_f32_e32 v45, 1.0, v45
	v_sub_f32_e32 v44, v41, v44
	v_add_f32_e32 v46, v44, v45
	v_frexp_mant_f32_e32 v44, v42
	v_cmp_gt_f32_e32 vcc, s77, v44
	v_cvt_f64_f32_e32 v[44:45], v42
	v_frexp_exp_i32_f64_e32 v44, v[44:45]
	v_subbrev_co_u32_e32 v44, vcc, 0, v44, vcc
	v_sub_u32_e32 v45, 0, v44
	v_ldexp_f32 v42, v42, v45
	v_ldexp_f32 v45, v46, v45
	v_add_f32_e32 v46, -1.0, v42
	v_add_f32_e32 v47, 1.0, v46
	v_sub_f32_e32 v47, v42, v47
	v_add_f32_e32 v47, v45, v47
	v_add_f32_e32 v48, v46, v47
	v_sub_f32_e32 v46, v46, v48
	v_add_f32_e32 v46, v47, v46
	v_add_f32_e32 v47, 1.0, v42
	v_add_f32_e32 v49, -1.0, v47
	v_sub_f32_e32 v42, v42, v49
	v_add_f32_e32 v42, v45, v42
	v_add_f32_e32 v45, v47, v42
	v_sub_f32_e32 v47, v47, v45
	v_add_f32_e32 v42, v42, v47
	v_rcp_f32_e32 v47, v45
	v_cvt_f32_i32_e32 v44, v44
	v_cmp_neq_f32_e32 vcc, s62, v41
	v_mul_f32_e32 v49, v48, v47
	v_mul_f32_e32 v50, v45, v49
	v_fma_f32 v51, v49, v45, -v50
	v_fmac_f32_e32 v51, v49, v42
	v_add_f32_e32 v52, v50, v51
	v_sub_f32_e32 v53, v48, v52
	v_sub_f32_e32 v48, v48, v53
	v_sub_f32_e32 v50, v52, v50
	v_sub_f32_e32 v48, v48, v52
	v_add_f32_e32 v46, v46, v48
	v_sub_f32_e32 v48, v50, v51
	v_add_f32_e32 v46, v48, v46
	v_add_f32_e32 v48, v53, v46
	v_mul_f32_e32 v50, v47, v48
	v_mul_f32_e32 v51, v45, v50
	v_fma_f32 v45, v50, v45, -v51
	v_fmac_f32_e32 v45, v50, v42
	v_sub_f32_e32 v42, v53, v48
	v_add_f32_e32 v42, v46, v42
	v_add_f32_e32 v46, v51, v45
	v_sub_f32_e32 v52, v48, v46
	v_sub_f32_e32 v48, v48, v52
	v_sub_f32_e32 v51, v46, v51
	v_sub_f32_e32 v46, v48, v46
	v_add_f32_e32 v42, v42, v46
	v_sub_f32_e32 v45, v51, v45
	v_add_f32_e32 v42, v45, v42
	v_add_f32_e32 v45, v49, v50
	v_add_f32_e32 v42, v52, v42
	v_sub_f32_e32 v46, v45, v49
	v_mul_f32_e32 v42, v47, v42
	v_sub_f32_e32 v46, v50, v46
	v_add_f32_e32 v42, v46, v42
	v_mul_f32_e32 v49, 0x3f317218, v44
	v_add_f32_e32 v46, v45, v42
	v_fma_f32 v50, v44, s78, -v49
	v_mul_f32_e32 v47, v46, v46
	v_fmac_f32_e32 v50, 0xb102e308, v44
	v_sub_f32_e32 v44, v46, v45
	v_fmamk_f32 v48, v47, 0x3e9b6dac, v185
	v_sub_f32_e32 v42, v42, v44
	v_add_f32_e32 v44, v49, v50
	v_fmaak_f32 v48, v47, v48, 0x3f2aaada
	v_sub_f32_e32 v45, v44, v49
	v_ldexp_f32 v49, v46, 1
	v_mul_f32_e32 v46, v46, v47
	v_mul_f32_e32 v46, v46, v48
	v_add_f32_e32 v47, v49, v46
	v_sub_f32_e32 v48, v47, v49
	v_ldexp_f32 v42, v42, 1
	v_sub_f32_e32 v46, v46, v48
	v_add_f32_e32 v42, v42, v46
	v_add_f32_e32 v46, v47, v42
	v_sub_f32_e32 v47, v46, v47
	v_sub_f32_e32 v42, v42, v47
	v_add_f32_e32 v47, v44, v46
	v_sub_f32_e32 v48, v47, v44
	v_sub_f32_e32 v49, v47, v48
	v_sub_f32_e32 v45, v50, v45
	v_sub_f32_e32 v44, v44, v49
	v_sub_f32_e32 v46, v46, v48
	v_add_f32_e32 v44, v46, v44
	v_add_f32_e32 v46, v45, v42
	v_sub_f32_e32 v48, v46, v45
	v_sub_f32_e32 v49, v46, v48
	v_sub_f32_e32 v45, v45, v49
	v_sub_f32_e32 v42, v42, v48
	v_add_f32_e32 v44, v46, v44
	v_add_f32_e32 v42, v42, v45
	v_add_f32_e32 v45, v47, v44
	v_sub_f32_e32 v46, v45, v47
	v_sub_f32_e32 v44, v44, v46
	v_add_f32_e32 v42, v42, v44
	v_add_f32_e32 v42, v45, v42
	v_cndmask_b32_e32 v42, v226, v42, vcc
	v_cmp_lt_f32_e64 vcc, |v41|, s63
	s_nop 1
	v_cndmask_b32_e32 v41, v42, v41, vcc
	v_sub_f32_e32 v40, v40, v41
	v_mul_f32_e32 v40, 0x3fb8aa3b, v40
	global_store_dword v[70:71], v40, off offset:128
	v_readlane_b32 s100, v254, 7
	s_nop 1
	v_mov_b32_e32 v41, s100
	v_fmac_f32_e32 v41, v43, v168
	v_mul_f32_e64 v42, |v41|, s94
	v_fma_f32 v43, |v41|, s94, -v42
	v_rndne_f32_e32 v44, v42
	v_fma_f32 v43, |v41|, s64, v43
	v_sub_f32_e32 v42, v42, v44
	v_add_f32_e32 v42, v42, v43
	v_exp_f32_e32 v42, v42
	v_cvt_i32_f32_e32 v43, v44
	v_cmp_ngt_f32_e64 vcc, |v41|, s58
	v_min_f32_e32 v40, 0, v41
	v_ldexp_f32 v42, v42, v43
	v_cndmask_b32_e32 v42, 0, v42, vcc
	v_cmp_nlt_f32_e64 vcc, |v41|, s59
	s_nop 1
	v_cndmask_b32_e32 v41, v226, v42, vcc
	v_add_f32_e32 v44, 1.0, v41
	v_add_f32_e32 v42, -1.0, v44
	v_sub_f32_e32 v43, v42, v44
	v_add_f32_e32 v43, 1.0, v43
	v_sub_f32_e32 v42, v41, v42
	v_add_f32_e32 v45, v42, v43
	v_frexp_mant_f32_e32 v42, v44
	v_cmp_gt_f32_e32 vcc, s77, v42
	v_cvt_f64_f32_e32 v[42:43], v44
	v_frexp_exp_i32_f64_e32 v42, v[42:43]
	v_subbrev_co_u32_e32 v42, vcc, 0, v42, vcc
	v_sub_u32_e32 v43, 0, v42
	v_ldexp_f32 v44, v44, v43
	v_ldexp_f32 v43, v45, v43
	v_add_f32_e32 v45, -1.0, v44
	v_add_f32_e32 v46, 1.0, v45
	v_sub_f32_e32 v46, v44, v46
	v_add_f32_e32 v46, v43, v46
	v_add_f32_e32 v47, v45, v46
	v_sub_f32_e32 v45, v45, v47
	v_add_f32_e32 v45, v46, v45
	v_add_f32_e32 v46, 1.0, v44
	v_add_f32_e32 v48, -1.0, v46
	v_sub_f32_e32 v44, v44, v48
	v_add_f32_e32 v43, v43, v44
	v_add_f32_e32 v44, v46, v43
	v_sub_f32_e32 v46, v46, v44
	v_add_f32_e32 v43, v43, v46
	v_rcp_f32_e32 v46, v44
	v_cvt_f32_i32_e32 v42, v42
	v_cmp_neq_f32_e32 vcc, s62, v41
	v_mul_f32_e32 v48, v47, v46
	v_mul_f32_e32 v49, v44, v48
	v_fma_f32 v50, v48, v44, -v49
	v_fmac_f32_e32 v50, v48, v43
	v_add_f32_e32 v51, v49, v50
	v_sub_f32_e32 v52, v47, v51
	v_sub_f32_e32 v47, v47, v52
	v_sub_f32_e32 v49, v51, v49
	v_sub_f32_e32 v47, v47, v51
	v_add_f32_e32 v45, v45, v47
	v_sub_f32_e32 v47, v49, v50
	v_add_f32_e32 v45, v47, v45
	v_add_f32_e32 v47, v52, v45
	v_mul_f32_e32 v49, v46, v47
	v_mul_f32_e32 v50, v44, v49
	v_fma_f32 v44, v49, v44, -v50
	v_fmac_f32_e32 v44, v49, v43
	v_sub_f32_e32 v43, v52, v47
	v_add_f32_e32 v43, v45, v43
	v_add_f32_e32 v45, v50, v44
	v_sub_f32_e32 v51, v47, v45
	v_sub_f32_e32 v47, v47, v51
	v_sub_f32_e32 v50, v45, v50
	v_sub_f32_e32 v45, v47, v45
	v_add_f32_e32 v43, v43, v45
	v_sub_f32_e32 v44, v50, v44
	v_add_f32_e32 v43, v44, v43
	v_add_f32_e32 v44, v48, v49
	v_add_f32_e32 v43, v51, v43
	v_sub_f32_e32 v45, v44, v48
	v_mul_f32_e32 v43, v46, v43
	v_sub_f32_e32 v45, v49, v45
	v_add_f32_e32 v43, v45, v43
	v_mul_f32_e32 v48, 0x3f317218, v42
	v_add_f32_e32 v45, v44, v43
	v_fma_f32 v49, v42, s78, -v48
	v_mul_f32_e32 v46, v45, v45
	v_fmac_f32_e32 v49, 0xb102e308, v42
	v_sub_f32_e32 v42, v45, v44
	v_fmamk_f32 v47, v46, 0x3e9b6dac, v185
	v_sub_f32_e32 v42, v43, v42
	v_add_f32_e32 v43, v48, v49
	v_fmaak_f32 v47, v46, v47, 0x3f2aaada
	v_sub_f32_e32 v44, v43, v48
	v_ldexp_f32 v48, v45, 1
	v_mul_f32_e32 v45, v45, v46
	v_mul_f32_e32 v45, v45, v47
	v_add_f32_e32 v46, v48, v45
	v_sub_f32_e32 v47, v46, v48
	v_ldexp_f32 v42, v42, 1
	v_sub_f32_e32 v45, v45, v47
	v_add_f32_e32 v42, v42, v45
	v_add_f32_e32 v45, v46, v42
	v_sub_f32_e32 v46, v45, v46
	v_sub_f32_e32 v42, v42, v46
	v_add_f32_e32 v46, v43, v45
	v_sub_f32_e32 v47, v46, v43
	v_sub_f32_e32 v48, v46, v47
	v_sub_f32_e32 v44, v49, v44
	v_sub_f32_e32 v43, v43, v48
	v_sub_f32_e32 v45, v45, v47
	v_add_f32_e32 v43, v45, v43
	v_add_f32_e32 v45, v44, v42
	v_sub_f32_e32 v47, v45, v44
	v_sub_f32_e32 v48, v45, v47
	v_sub_f32_e32 v44, v44, v48
	v_sub_f32_e32 v42, v42, v47
	v_add_f32_e32 v43, v45, v43
	v_add_f32_e32 v42, v42, v44
	v_add_f32_e32 v44, v46, v43
	v_sub_f32_e32 v45, v44, v46
	v_sub_f32_e32 v43, v43, v45
	v_add_f32_e32 v42, v42, v43
	v_add_f32_e32 v42, v44, v42
	v_cndmask_b32_e32 v42, v226, v42, vcc
	v_cmp_lt_f32_e64 vcc, |v41|, s63
	s_nop 1
	v_cndmask_b32_e32 v41, v42, v41, vcc
	v_sub_f32_e32 v40, v40, v41
	v_mul_f32_e32 v40, 0x3fb8aa3b, v40
	global_store_dword v[58:59], v40, off offset:128
	v_readlane_b32 s100, v254, 0
	s_nop 1
	v_mov_b32_e32 v40, s100
	v_fmac_f32_e32 v40, v36, v166
	v_mul_f32_e64 v41, |v40|, s94
	v_fma_f32 v42, |v40|, s94, -v41
	v_rndne_f32_e32 v43, v41
	v_fma_f32 v42, |v40|, s64, v42
	v_sub_f32_e32 v41, v41, v43
	v_add_f32_e32 v41, v41, v42
	v_exp_f32_e32 v41, v41
	v_cvt_i32_f32_e32 v42, v43
	v_cmp_ngt_f32_e64 vcc, |v40|, s58
	v_min_f32_e32 v36, 0, v40
	v_ldexp_f32 v41, v41, v42
	v_cndmask_b32_e32 v41, 0, v41, vcc
	v_cmp_nlt_f32_e64 vcc, |v40|, s59
	s_nop 1
	v_cndmask_b32_e32 v40, v226, v41, vcc
	v_add_f32_e32 v41, 1.0, v40
	v_add_f32_e32 v42, -1.0, v41
	v_sub_f32_e32 v43, v42, v41
	v_add_f32_e32 v43, 1.0, v43
	v_sub_f32_e32 v42, v40, v42
	v_add_f32_e32 v44, v42, v43
	v_frexp_mant_f32_e32 v42, v41
	v_cmp_gt_f32_e32 vcc, s77, v42
	v_cvt_f64_f32_e32 v[42:43], v41
	v_frexp_exp_i32_f64_e32 v42, v[42:43]
	v_subbrev_co_u32_e32 v42, vcc, 0, v42, vcc
	v_sub_u32_e32 v43, 0, v42
	v_ldexp_f32 v41, v41, v43
	v_ldexp_f32 v43, v44, v43
	v_add_f32_e32 v44, -1.0, v41
	v_add_f32_e32 v45, 1.0, v44
	v_sub_f32_e32 v45, v41, v45
	v_add_f32_e32 v45, v43, v45
	v_add_f32_e32 v46, v44, v45
	v_sub_f32_e32 v44, v44, v46
	v_add_f32_e32 v44, v45, v44
	v_add_f32_e32 v45, 1.0, v41
	v_add_f32_e32 v47, -1.0, v45
	v_sub_f32_e32 v41, v41, v47
	v_add_f32_e32 v41, v43, v41
	v_add_f32_e32 v43, v45, v41
	v_sub_f32_e32 v45, v45, v43
	v_add_f32_e32 v41, v41, v45
	v_rcp_f32_e32 v45, v43
	v_cvt_f32_i32_e32 v42, v42
	v_cmp_neq_f32_e32 vcc, s62, v40
	v_mul_f32_e32 v47, v46, v45
	v_mul_f32_e32 v48, v43, v47
	v_fma_f32 v49, v47, v43, -v48
	v_fmac_f32_e32 v49, v47, v41
	v_add_f32_e32 v50, v48, v49
	v_sub_f32_e32 v51, v46, v50
	v_sub_f32_e32 v46, v46, v51
	v_sub_f32_e32 v48, v50, v48
	v_sub_f32_e32 v46, v46, v50
	v_add_f32_e32 v44, v44, v46
	v_sub_f32_e32 v46, v48, v49
	v_add_f32_e32 v44, v46, v44
	v_add_f32_e32 v46, v51, v44
	v_mul_f32_e32 v48, v45, v46
	v_mul_f32_e32 v49, v43, v48
	v_fma_f32 v43, v48, v43, -v49
	v_fmac_f32_e32 v43, v48, v41
	v_sub_f32_e32 v41, v51, v46
	v_add_f32_e32 v41, v44, v41
	v_add_f32_e32 v44, v49, v43
	v_sub_f32_e32 v50, v46, v44
	v_sub_f32_e32 v46, v46, v50
	v_sub_f32_e32 v49, v44, v49
	v_sub_f32_e32 v44, v46, v44
	v_add_f32_e32 v41, v41, v44
	v_sub_f32_e32 v43, v49, v43
	v_add_f32_e32 v41, v43, v41
	v_add_f32_e32 v43, v47, v48
	v_add_f32_e32 v41, v50, v41
	v_sub_f32_e32 v44, v43, v47
	v_mul_f32_e32 v41, v45, v41
	v_sub_f32_e32 v44, v48, v44
	v_add_f32_e32 v41, v44, v41
	v_mul_f32_e32 v47, 0x3f317218, v42
	v_add_f32_e32 v44, v43, v41
	v_fma_f32 v48, v42, s78, -v47
	v_mul_f32_e32 v45, v44, v44
	v_fmac_f32_e32 v48, 0xb102e308, v42
	v_sub_f32_e32 v42, v44, v43
	v_fmamk_f32 v46, v45, 0x3e9b6dac, v185
	v_sub_f32_e32 v41, v41, v42
	v_add_f32_e32 v42, v47, v48
	v_fmaak_f32 v46, v45, v46, 0x3f2aaada
	v_sub_f32_e32 v43, v42, v47
	v_ldexp_f32 v47, v44, 1
	v_mul_f32_e32 v44, v44, v45
	v_mul_f32_e32 v44, v44, v46
	v_add_f32_e32 v45, v47, v44
	v_sub_f32_e32 v46, v45, v47
	v_ldexp_f32 v41, v41, 1
	v_sub_f32_e32 v44, v44, v46
	v_add_f32_e32 v41, v41, v44
	v_add_f32_e32 v44, v45, v41
	v_sub_f32_e32 v45, v44, v45
	v_sub_f32_e32 v41, v41, v45
	v_add_f32_e32 v45, v42, v44
	v_sub_f32_e32 v46, v45, v42
	v_sub_f32_e32 v47, v45, v46
	v_sub_f32_e32 v43, v48, v43
	v_sub_f32_e32 v42, v42, v47
	v_sub_f32_e32 v44, v44, v46
	v_add_f32_e32 v42, v44, v42
	v_add_f32_e32 v44, v43, v41
	v_sub_f32_e32 v46, v44, v43
	v_sub_f32_e32 v47, v44, v46
	v_sub_f32_e32 v43, v43, v47
	v_sub_f32_e32 v41, v41, v46
	v_add_f32_e32 v42, v44, v42
	v_add_f32_e32 v41, v41, v43
	v_add_f32_e32 v43, v45, v42
	v_sub_f32_e32 v44, v43, v45
	v_sub_f32_e32 v42, v42, v44
	v_add_f32_e32 v41, v41, v42
	v_add_f32_e32 v41, v43, v41
	v_cndmask_b32_e32 v41, v226, v41, vcc
	v_cmp_lt_f32_e64 vcc, |v40|, s63
	s_nop 1
	v_cndmask_b32_e32 v40, v41, v40, vcc
	v_sub_f32_e32 v36, v36, v40
	v_mul_f32_e32 v36, 0x3fb8aa3b, v36
	global_store_dword v[64:65], v36, off offset:192
	v_readlane_b32 s100, v254, 1
	s_nop 1
	v_mov_b32_e32 v40, s100
	v_fmac_f32_e32 v40, v37, v166
	v_mul_f32_e64 v37, |v40|, s94
	v_fma_f32 v41, |v40|, s94, -v37
	v_rndne_f32_e32 v42, v37
	v_fma_f32 v41, |v40|, s64, v41
	v_sub_f32_e32 v37, v37, v42
	v_add_f32_e32 v37, v37, v41
	v_exp_f32_e32 v37, v37
	v_cvt_i32_f32_e32 v41, v42
	v_cmp_ngt_f32_e64 vcc, |v40|, s58
	v_min_f32_e32 v36, 0, v40
	v_ldexp_f32 v37, v37, v41
	v_cndmask_b32_e32 v37, 0, v37, vcc
	v_cmp_nlt_f32_e64 vcc, |v40|, s59
	s_nop 1
	v_cndmask_b32_e32 v37, v226, v37, vcc
	v_add_f32_e32 v42, 1.0, v37
	v_add_f32_e32 v40, -1.0, v42
	v_sub_f32_e32 v41, v40, v42
	v_add_f32_e32 v41, 1.0, v41
	v_sub_f32_e32 v40, v37, v40
	v_add_f32_e32 v43, v40, v41
	v_frexp_mant_f32_e32 v40, v42
	v_cmp_gt_f32_e32 vcc, s77, v40
	v_cvt_f64_f32_e32 v[40:41], v42
	v_frexp_exp_i32_f64_e32 v40, v[40:41]
	v_subbrev_co_u32_e32 v40, vcc, 0, v40, vcc
	v_sub_u32_e32 v41, 0, v40
	v_ldexp_f32 v42, v42, v41
	v_ldexp_f32 v41, v43, v41
	v_add_f32_e32 v43, -1.0, v42
	v_add_f32_e32 v44, 1.0, v43
	v_sub_f32_e32 v44, v42, v44
	v_add_f32_e32 v44, v41, v44
	v_add_f32_e32 v45, v43, v44
	v_sub_f32_e32 v43, v43, v45
	v_add_f32_e32 v43, v44, v43
	v_add_f32_e32 v44, 1.0, v42
	v_add_f32_e32 v46, -1.0, v44
	v_sub_f32_e32 v42, v42, v46
	v_add_f32_e32 v41, v41, v42
	v_add_f32_e32 v42, v44, v41
	v_sub_f32_e32 v44, v44, v42
	v_add_f32_e32 v41, v41, v44
	v_rcp_f32_e32 v44, v42
	v_cvt_f32_i32_e32 v40, v40
	v_cmp_neq_f32_e32 vcc, s62, v37
	v_mul_f32_e32 v46, v45, v44
	v_mul_f32_e32 v47, v42, v46
	v_fma_f32 v48, v46, v42, -v47
	v_fmac_f32_e32 v48, v46, v41
	v_add_f32_e32 v49, v47, v48
	v_sub_f32_e32 v50, v45, v49
	v_sub_f32_e32 v45, v45, v50
	v_sub_f32_e32 v47, v49, v47
	v_sub_f32_e32 v45, v45, v49
	v_add_f32_e32 v43, v43, v45
	v_sub_f32_e32 v45, v47, v48
	v_add_f32_e32 v43, v45, v43
	v_add_f32_e32 v45, v50, v43
	v_mul_f32_e32 v47, v44, v45
	v_mul_f32_e32 v48, v42, v47
	v_fma_f32 v42, v47, v42, -v48
	v_fmac_f32_e32 v42, v47, v41
	v_sub_f32_e32 v41, v50, v45
	v_add_f32_e32 v41, v43, v41
	v_add_f32_e32 v43, v48, v42
	v_sub_f32_e32 v49, v45, v43
	v_sub_f32_e32 v45, v45, v49
	v_sub_f32_e32 v48, v43, v48
	v_sub_f32_e32 v43, v45, v43
	v_add_f32_e32 v41, v41, v43
	v_sub_f32_e32 v42, v48, v42
	v_add_f32_e32 v41, v42, v41
	v_add_f32_e32 v42, v46, v47
	v_add_f32_e32 v41, v49, v41
	v_sub_f32_e32 v43, v42, v46
	v_mul_f32_e32 v41, v44, v41
	v_sub_f32_e32 v43, v47, v43
	v_add_f32_e32 v41, v43, v41
	v_mul_f32_e32 v46, 0x3f317218, v40
	v_add_f32_e32 v43, v42, v41
	v_fma_f32 v47, v40, s78, -v46
	v_mul_f32_e32 v44, v43, v43
	v_fmac_f32_e32 v47, 0xb102e308, v40
	v_sub_f32_e32 v40, v43, v42
	v_fmamk_f32 v45, v44, 0x3e9b6dac, v185
	v_sub_f32_e32 v40, v41, v40
	v_add_f32_e32 v41, v46, v47
	v_fmaak_f32 v45, v44, v45, 0x3f2aaada
	v_sub_f32_e32 v42, v41, v46
	v_ldexp_f32 v46, v43, 1
	v_mul_f32_e32 v43, v43, v44
	v_mul_f32_e32 v43, v43, v45
	v_add_f32_e32 v44, v46, v43
	v_sub_f32_e32 v45, v44, v46
	v_ldexp_f32 v40, v40, 1
	v_sub_f32_e32 v43, v43, v45
	v_add_f32_e32 v40, v40, v43
	v_add_f32_e32 v43, v44, v40
	v_sub_f32_e32 v44, v43, v44
	v_sub_f32_e32 v40, v40, v44
	v_add_f32_e32 v44, v41, v43
	v_sub_f32_e32 v45, v44, v41
	v_sub_f32_e32 v46, v44, v45
	v_sub_f32_e32 v42, v47, v42
	v_sub_f32_e32 v41, v41, v46
	v_sub_f32_e32 v43, v43, v45
	v_add_f32_e32 v41, v43, v41
	v_add_f32_e32 v43, v42, v40
	v_sub_f32_e32 v45, v43, v42
	v_sub_f32_e32 v46, v43, v45
	v_sub_f32_e32 v42, v42, v46
	v_sub_f32_e32 v40, v40, v45
	v_add_f32_e32 v41, v43, v41
	v_add_f32_e32 v40, v40, v42
	v_add_f32_e32 v42, v44, v41
	v_sub_f32_e32 v43, v42, v44
	v_sub_f32_e32 v41, v41, v43
	v_add_f32_e32 v40, v40, v41
	v_add_f32_e32 v40, v42, v40
	v_cndmask_b32_e32 v40, v226, v40, vcc
	v_cmp_lt_f32_e64 vcc, |v37|, s63
	s_nop 1
	v_cndmask_b32_e32 v37, v40, v37, vcc
	v_sub_f32_e32 v36, v36, v37
	v_mul_f32_e32 v36, 0x3fb8aa3b, v36
	global_store_dword v[60:61], v36, off offset:192
	v_readlane_b32 s100, v254, 2
	s_nop 1
	v_mov_b32_e32 v37, s100
	v_fmac_f32_e32 v37, v38, v166
	v_mul_f32_e64 v38, |v37|, s94
	v_fma_f32 v40, |v37|, s94, -v38
	v_rndne_f32_e32 v41, v38
	v_fma_f32 v40, |v37|, s64, v40
	v_sub_f32_e32 v38, v38, v41
	v_add_f32_e32 v38, v38, v40
	v_exp_f32_e32 v38, v38
	v_cvt_i32_f32_e32 v40, v41
	v_cmp_ngt_f32_e64 vcc, |v37|, s58
	v_min_f32_e32 v36, 0, v37
	v_ldexp_f32 v38, v38, v40
	v_cndmask_b32_e32 v38, 0, v38, vcc
	v_cmp_nlt_f32_e64 vcc, |v37|, s59
	s_nop 1
	v_cndmask_b32_e32 v37, v226, v38, vcc
	v_add_f32_e32 v38, 1.0, v37
	v_add_f32_e32 v40, -1.0, v38
	v_sub_f32_e32 v41, v40, v38
	v_add_f32_e32 v41, 1.0, v41
	v_sub_f32_e32 v40, v37, v40
	v_add_f32_e32 v42, v40, v41
	v_frexp_mant_f32_e32 v40, v38
	v_cmp_gt_f32_e32 vcc, s77, v40
	v_cvt_f64_f32_e32 v[40:41], v38
	v_frexp_exp_i32_f64_e32 v40, v[40:41]
	v_subbrev_co_u32_e32 v40, vcc, 0, v40, vcc
	v_sub_u32_e32 v41, 0, v40
	v_ldexp_f32 v38, v38, v41
	v_ldexp_f32 v41, v42, v41
	v_add_f32_e32 v42, -1.0, v38
	v_add_f32_e32 v43, 1.0, v42
	v_sub_f32_e32 v43, v38, v43
	v_add_f32_e32 v43, v41, v43
	v_add_f32_e32 v44, v42, v43
	v_sub_f32_e32 v42, v42, v44
	v_add_f32_e32 v42, v43, v42
	v_add_f32_e32 v43, 1.0, v38
	v_add_f32_e32 v45, -1.0, v43
	v_sub_f32_e32 v38, v38, v45
	v_add_f32_e32 v38, v41, v38
	v_add_f32_e32 v41, v43, v38
	v_sub_f32_e32 v43, v43, v41
	v_add_f32_e32 v38, v38, v43
	v_rcp_f32_e32 v43, v41
	v_cvt_f32_i32_e32 v40, v40
	v_cmp_neq_f32_e32 vcc, s62, v37
	v_mul_f32_e32 v45, v44, v43
	v_mul_f32_e32 v46, v41, v45
	v_fma_f32 v47, v45, v41, -v46
	v_fmac_f32_e32 v47, v45, v38
	v_add_f32_e32 v48, v46, v47
	v_sub_f32_e32 v49, v44, v48
	v_sub_f32_e32 v44, v44, v49
	v_sub_f32_e32 v46, v48, v46
	v_sub_f32_e32 v44, v44, v48
	v_add_f32_e32 v42, v42, v44
	v_sub_f32_e32 v44, v46, v47
	v_add_f32_e32 v42, v44, v42
	v_add_f32_e32 v44, v49, v42
	v_mul_f32_e32 v46, v43, v44
	v_mul_f32_e32 v47, v41, v46
	v_fma_f32 v41, v46, v41, -v47
	v_fmac_f32_e32 v41, v46, v38
	v_sub_f32_e32 v38, v49, v44
	v_add_f32_e32 v38, v42, v38
	v_add_f32_e32 v42, v47, v41
	v_sub_f32_e32 v48, v44, v42
	v_sub_f32_e32 v44, v44, v48
	v_sub_f32_e32 v47, v42, v47
	v_sub_f32_e32 v42, v44, v42
	v_add_f32_e32 v38, v38, v42
	v_sub_f32_e32 v41, v47, v41
	v_add_f32_e32 v38, v41, v38
	v_add_f32_e32 v41, v45, v46
	v_add_f32_e32 v38, v48, v38
	v_sub_f32_e32 v42, v41, v45
	v_mul_f32_e32 v38, v43, v38
	v_sub_f32_e32 v42, v46, v42
	v_add_f32_e32 v38, v42, v38
	v_mul_f32_e32 v45, 0x3f317218, v40
	v_add_f32_e32 v42, v41, v38
	v_fma_f32 v46, v40, s78, -v45
	v_mul_f32_e32 v43, v42, v42
	v_fmac_f32_e32 v46, 0xb102e308, v40
	v_sub_f32_e32 v40, v42, v41
	v_fmamk_f32 v44, v43, 0x3e9b6dac, v185
	v_sub_f32_e32 v38, v38, v40
	v_add_f32_e32 v40, v45, v46
	v_fmaak_f32 v44, v43, v44, 0x3f2aaada
	v_sub_f32_e32 v41, v40, v45
	v_ldexp_f32 v45, v42, 1
	v_mul_f32_e32 v42, v42, v43
	v_mul_f32_e32 v42, v42, v44
	v_add_f32_e32 v43, v45, v42
	v_sub_f32_e32 v44, v43, v45
	v_ldexp_f32 v38, v38, 1
	v_sub_f32_e32 v42, v42, v44
	v_add_f32_e32 v38, v38, v42
	v_add_f32_e32 v42, v43, v38
	v_sub_f32_e32 v43, v42, v43
	v_sub_f32_e32 v38, v38, v43
	v_add_f32_e32 v43, v40, v42
	v_sub_f32_e32 v44, v43, v40
	v_sub_f32_e32 v45, v43, v44
	v_sub_f32_e32 v41, v46, v41
	v_sub_f32_e32 v40, v40, v45
	v_sub_f32_e32 v42, v42, v44
	v_add_f32_e32 v40, v42, v40
	v_add_f32_e32 v42, v41, v38
	v_sub_f32_e32 v44, v42, v41
	v_sub_f32_e32 v45, v42, v44
	v_sub_f32_e32 v41, v41, v45
	v_sub_f32_e32 v38, v38, v44
	v_add_f32_e32 v40, v42, v40
	v_add_f32_e32 v38, v38, v41
	v_add_f32_e32 v41, v43, v40
	v_sub_f32_e32 v42, v41, v43
	v_sub_f32_e32 v40, v40, v42
	v_add_f32_e32 v38, v38, v40
	v_add_f32_e32 v38, v41, v38
	v_cndmask_b32_e32 v38, v226, v38, vcc
	v_cmp_lt_f32_e64 vcc, |v37|, s63
	s_nop 1
	v_cndmask_b32_e32 v37, v38, v37, vcc
	v_sub_f32_e32 v36, v36, v37
	v_mul_f32_e32 v36, 0x3fb8aa3b, v36
	global_store_dword v[66:67], v36, off offset:192
	v_readlane_b32 s100, v254, 3
	s_nop 1
	v_mov_b32_e32 v37, s100
	v_fmac_f32_e32 v37, v39, v166
	v_mul_f32_e64 v38, |v37|, s94
	v_fma_f32 v39, |v37|, s94, -v38
	v_rndne_f32_e32 v40, v38
	v_fma_f32 v39, |v37|, s64, v39
	v_sub_f32_e32 v38, v38, v40
	v_add_f32_e32 v38, v38, v39
	v_exp_f32_e32 v38, v38
	v_cvt_i32_f32_e32 v39, v40
	v_cmp_ngt_f32_e64 vcc, |v37|, s58
	v_min_f32_e32 v36, 0, v37
	v_ldexp_f32 v38, v38, v39
	v_cndmask_b32_e32 v38, 0, v38, vcc
	v_cmp_nlt_f32_e64 vcc, |v37|, s59
	s_nop 1
	v_cndmask_b32_e32 v37, v226, v38, vcc
	v_add_f32_e32 v40, 1.0, v37
	v_add_f32_e32 v38, -1.0, v40
	v_sub_f32_e32 v39, v38, v40
	v_add_f32_e32 v39, 1.0, v39
	v_sub_f32_e32 v38, v37, v38
	v_add_f32_e32 v41, v38, v39
	v_frexp_mant_f32_e32 v38, v40
	v_cmp_gt_f32_e32 vcc, s77, v38
	v_cvt_f64_f32_e32 v[38:39], v40
	v_frexp_exp_i32_f64_e32 v38, v[38:39]
	v_subbrev_co_u32_e32 v38, vcc, 0, v38, vcc
	v_sub_u32_e32 v39, 0, v38
	v_ldexp_f32 v40, v40, v39
	v_ldexp_f32 v39, v41, v39
	v_add_f32_e32 v41, -1.0, v40
	v_add_f32_e32 v42, 1.0, v41
	v_sub_f32_e32 v42, v40, v42
	v_add_f32_e32 v42, v39, v42
	v_add_f32_e32 v43, v41, v42
	v_sub_f32_e32 v41, v41, v43
	v_add_f32_e32 v41, v42, v41
	v_add_f32_e32 v42, 1.0, v40
	v_add_f32_e32 v44, -1.0, v42
	v_sub_f32_e32 v40, v40, v44
	v_add_f32_e32 v39, v39, v40
	v_add_f32_e32 v40, v42, v39
	v_sub_f32_e32 v42, v42, v40
	v_add_f32_e32 v39, v39, v42
	v_rcp_f32_e32 v42, v40
	v_cvt_f32_i32_e32 v38, v38
	v_cmp_neq_f32_e32 vcc, s62, v37
	v_mul_f32_e32 v44, v43, v42
	v_mul_f32_e32 v45, v40, v44
	v_fma_f32 v46, v44, v40, -v45
	v_fmac_f32_e32 v46, v44, v39
	v_add_f32_e32 v47, v45, v46
	v_sub_f32_e32 v48, v43, v47
	v_sub_f32_e32 v43, v43, v48
	v_sub_f32_e32 v45, v47, v45
	v_sub_f32_e32 v43, v43, v47
	v_add_f32_e32 v41, v41, v43
	v_sub_f32_e32 v43, v45, v46
	v_add_f32_e32 v41, v43, v41
	v_add_f32_e32 v43, v48, v41
	v_mul_f32_e32 v45, v42, v43
	v_mul_f32_e32 v46, v40, v45
	v_fma_f32 v40, v45, v40, -v46
	v_fmac_f32_e32 v40, v45, v39
	v_sub_f32_e32 v39, v48, v43
	v_add_f32_e32 v39, v41, v39
	v_add_f32_e32 v41, v46, v40
	v_sub_f32_e32 v47, v43, v41
	v_sub_f32_e32 v43, v43, v47
	v_sub_f32_e32 v46, v41, v46
	v_sub_f32_e32 v41, v43, v41
	v_add_f32_e32 v39, v39, v41
	v_sub_f32_e32 v40, v46, v40
	v_add_f32_e32 v39, v40, v39
	v_add_f32_e32 v40, v44, v45
	v_add_f32_e32 v39, v47, v39
	v_sub_f32_e32 v41, v40, v44
	v_mul_f32_e32 v39, v42, v39
	v_sub_f32_e32 v41, v45, v41
	v_add_f32_e32 v39, v41, v39
	v_mul_f32_e32 v44, 0x3f317218, v38
	v_add_f32_e32 v41, v40, v39
	v_fma_f32 v45, v38, s78, -v44
	v_mul_f32_e32 v42, v41, v41
	v_fmac_f32_e32 v45, 0xb102e308, v38
	v_sub_f32_e32 v38, v41, v40
	v_fmamk_f32 v43, v42, 0x3e9b6dac, v185
	v_sub_f32_e32 v38, v39, v38
	v_add_f32_e32 v39, v44, v45
	v_fmaak_f32 v43, v42, v43, 0x3f2aaada
	v_sub_f32_e32 v40, v39, v44
	v_ldexp_f32 v44, v41, 1
	v_mul_f32_e32 v41, v41, v42
	v_mul_f32_e32 v41, v41, v43
	v_add_f32_e32 v42, v44, v41
	v_sub_f32_e32 v43, v42, v44
	v_ldexp_f32 v38, v38, 1
	v_sub_f32_e32 v41, v41, v43
	v_add_f32_e32 v38, v38, v41
	v_add_f32_e32 v41, v42, v38
	v_sub_f32_e32 v42, v41, v42
	v_sub_f32_e32 v38, v38, v42
	v_add_f32_e32 v42, v39, v41
	v_sub_f32_e32 v43, v42, v39
	v_sub_f32_e32 v44, v42, v43
	v_sub_f32_e32 v40, v45, v40
	v_sub_f32_e32 v39, v39, v44
	v_sub_f32_e32 v41, v41, v43
	v_add_f32_e32 v39, v41, v39
	v_add_f32_e32 v41, v40, v38
	v_sub_f32_e32 v43, v41, v40
	v_sub_f32_e32 v44, v41, v43
	v_sub_f32_e32 v40, v40, v44
	v_sub_f32_e32 v38, v38, v43
	v_add_f32_e32 v39, v41, v39
	v_add_f32_e32 v38, v38, v40
	v_add_f32_e32 v40, v42, v39
	v_sub_f32_e32 v41, v40, v42
	v_sub_f32_e32 v39, v39, v41
	v_add_f32_e32 v38, v38, v39
	v_add_f32_e32 v38, v40, v38
	v_cndmask_b32_e32 v38, v226, v38, vcc
	v_cmp_lt_f32_e64 vcc, |v37|, s63
	s_nop 1
	v_cndmask_b32_e32 v37, v38, v37, vcc
	v_sub_f32_e32 v36, v36, v37
	v_mul_f32_e32 v36, 0x3fb8aa3b, v36
	global_store_dword v[62:63], v36, off offset:192
	v_readlane_b32 s100, v254, 4
	s_nop 1
	v_mov_b32_e32 v36, s100
	v_fmac_f32_e32 v36, v32, v166
	v_mul_f32_e64 v37, |v36|, s94
	v_fma_f32 v38, |v36|, s94, -v37
	v_rndne_f32_e32 v39, v37
	v_fma_f32 v38, |v36|, s64, v38
	v_sub_f32_e32 v37, v37, v39
	v_add_f32_e32 v37, v37, v38
	v_exp_f32_e32 v37, v37
	v_cvt_i32_f32_e32 v38, v39
	v_cmp_ngt_f32_e64 vcc, |v36|, s58
	v_min_f32_e32 v32, 0, v36
	v_ldexp_f32 v37, v37, v38
	v_cndmask_b32_e32 v37, 0, v37, vcc
	v_cmp_nlt_f32_e64 vcc, |v36|, s59
	s_nop 1
	v_cndmask_b32_e32 v36, v226, v37, vcc
	v_add_f32_e32 v37, 1.0, v36
	v_add_f32_e32 v38, -1.0, v37
	v_sub_f32_e32 v39, v38, v37
	v_add_f32_e32 v39, 1.0, v39
	v_sub_f32_e32 v38, v36, v38
	v_add_f32_e32 v40, v38, v39
	v_frexp_mant_f32_e32 v38, v37
	v_cmp_gt_f32_e32 vcc, s77, v38
	v_cvt_f64_f32_e32 v[38:39], v37
	v_frexp_exp_i32_f64_e32 v38, v[38:39]
	v_subbrev_co_u32_e32 v38, vcc, 0, v38, vcc
	v_sub_u32_e32 v39, 0, v38
	v_ldexp_f32 v37, v37, v39
	v_ldexp_f32 v39, v40, v39
	v_add_f32_e32 v40, -1.0, v37
	v_add_f32_e32 v41, 1.0, v40
	v_sub_f32_e32 v41, v37, v41
	v_add_f32_e32 v41, v39, v41
	v_add_f32_e32 v42, v40, v41
	v_sub_f32_e32 v40, v40, v42
	v_add_f32_e32 v40, v41, v40
	v_add_f32_e32 v41, 1.0, v37
	v_add_f32_e32 v43, -1.0, v41
	v_sub_f32_e32 v37, v37, v43
	v_add_f32_e32 v37, v39, v37
	v_add_f32_e32 v39, v41, v37
	v_sub_f32_e32 v41, v41, v39
	v_add_f32_e32 v37, v37, v41
	v_rcp_f32_e32 v41, v39
	v_cvt_f32_i32_e32 v38, v38
	v_cmp_neq_f32_e32 vcc, s62, v36
	v_mul_f32_e32 v43, v42, v41
	v_mul_f32_e32 v44, v39, v43
	v_fma_f32 v45, v43, v39, -v44
	v_fmac_f32_e32 v45, v43, v37
	v_add_f32_e32 v46, v44, v45
	v_sub_f32_e32 v47, v42, v46
	v_sub_f32_e32 v42, v42, v47
	v_sub_f32_e32 v44, v46, v44
	v_sub_f32_e32 v42, v42, v46
	v_add_f32_e32 v40, v40, v42
	v_sub_f32_e32 v42, v44, v45
	v_add_f32_e32 v40, v42, v40
	v_add_f32_e32 v42, v47, v40
	v_mul_f32_e32 v44, v41, v42
	v_mul_f32_e32 v45, v39, v44
	v_fma_f32 v39, v44, v39, -v45
	v_fmac_f32_e32 v39, v44, v37
	v_sub_f32_e32 v37, v47, v42
	v_add_f32_e32 v37, v40, v37
	v_add_f32_e32 v40, v45, v39
	v_sub_f32_e32 v46, v42, v40
	v_sub_f32_e32 v42, v42, v46
	v_sub_f32_e32 v45, v40, v45
	v_sub_f32_e32 v40, v42, v40
	v_add_f32_e32 v37, v37, v40
	v_sub_f32_e32 v39, v45, v39
	v_add_f32_e32 v37, v39, v37
	v_add_f32_e32 v39, v43, v44
	v_add_f32_e32 v37, v46, v37
	v_sub_f32_e32 v40, v39, v43
	v_mul_f32_e32 v37, v41, v37
	v_sub_f32_e32 v40, v44, v40
	v_add_f32_e32 v37, v40, v37
	v_mul_f32_e32 v43, 0x3f317218, v38
	v_add_f32_e32 v40, v39, v37
	v_fma_f32 v44, v38, s78, -v43
	v_mul_f32_e32 v41, v40, v40
	v_fmac_f32_e32 v44, 0xb102e308, v38
	v_sub_f32_e32 v38, v40, v39
	v_fmamk_f32 v42, v41, 0x3e9b6dac, v185
	v_sub_f32_e32 v37, v37, v38
	v_add_f32_e32 v38, v43, v44
	v_fmaak_f32 v42, v41, v42, 0x3f2aaada
	v_sub_f32_e32 v39, v38, v43
	v_ldexp_f32 v43, v40, 1
	v_mul_f32_e32 v40, v40, v41
	v_mul_f32_e32 v40, v40, v42
	v_add_f32_e32 v41, v43, v40
	v_sub_f32_e32 v42, v41, v43
	v_ldexp_f32 v37, v37, 1
	v_sub_f32_e32 v40, v40, v42
	v_add_f32_e32 v37, v37, v40
	v_add_f32_e32 v40, v41, v37
	v_sub_f32_e32 v41, v40, v41
	v_sub_f32_e32 v37, v37, v41
	v_add_f32_e32 v41, v38, v40
	v_sub_f32_e32 v42, v41, v38
	v_sub_f32_e32 v43, v41, v42
	v_sub_f32_e32 v39, v44, v39
	v_sub_f32_e32 v38, v38, v43
	v_sub_f32_e32 v40, v40, v42
	v_add_f32_e32 v38, v40, v38
	v_add_f32_e32 v40, v39, v37
	v_sub_f32_e32 v42, v40, v39
	v_sub_f32_e32 v43, v40, v42
	v_sub_f32_e32 v39, v39, v43
	v_sub_f32_e32 v37, v37, v42
	v_add_f32_e32 v38, v40, v38
	v_add_f32_e32 v37, v37, v39
	v_add_f32_e32 v39, v41, v38
	v_sub_f32_e32 v40, v39, v41
	v_sub_f32_e32 v38, v38, v40
	v_add_f32_e32 v37, v37, v38
	v_add_f32_e32 v37, v39, v37
	v_cndmask_b32_e32 v37, v226, v37, vcc
	v_cmp_lt_f32_e64 vcc, |v36|, s63
	s_nop 1
	v_cndmask_b32_e32 v36, v37, v36, vcc
	v_sub_f32_e32 v32, v32, v36
	v_mul_f32_e32 v32, 0x3fb8aa3b, v32
	global_store_dword v[68:69], v32, off offset:192
	v_readlane_b32 s100, v254, 5
	s_nop 1
	v_mov_b32_e32 v36, s100
	v_fmac_f32_e32 v36, v33, v166
	v_mul_f32_e64 v33, |v36|, s94
	v_fma_f32 v37, |v36|, s94, -v33
	v_rndne_f32_e32 v38, v33
	v_fma_f32 v37, |v36|, s64, v37
	v_sub_f32_e32 v33, v33, v38
	v_add_f32_e32 v33, v33, v37
	v_exp_f32_e32 v33, v33
	v_cvt_i32_f32_e32 v37, v38
	v_cmp_ngt_f32_e64 vcc, |v36|, s58
	v_min_f32_e32 v32, 0, v36
	v_ldexp_f32 v33, v33, v37
	v_cndmask_b32_e32 v33, 0, v33, vcc
	v_cmp_nlt_f32_e64 vcc, |v36|, s59
	s_nop 1
	v_cndmask_b32_e32 v33, v226, v33, vcc
	v_add_f32_e32 v38, 1.0, v33
	v_add_f32_e32 v36, -1.0, v38
	v_sub_f32_e32 v37, v36, v38
	v_add_f32_e32 v37, 1.0, v37
	v_sub_f32_e32 v36, v33, v36
	v_add_f32_e32 v39, v36, v37
	v_frexp_mant_f32_e32 v36, v38
	v_cmp_gt_f32_e32 vcc, s77, v36
	v_cvt_f64_f32_e32 v[36:37], v38
	v_frexp_exp_i32_f64_e32 v36, v[36:37]
	v_subbrev_co_u32_e32 v36, vcc, 0, v36, vcc
	v_sub_u32_e32 v37, 0, v36
	v_ldexp_f32 v38, v38, v37
	v_ldexp_f32 v37, v39, v37
	v_add_f32_e32 v39, -1.0, v38
	v_add_f32_e32 v40, 1.0, v39
	v_sub_f32_e32 v40, v38, v40
	v_add_f32_e32 v40, v37, v40
	v_add_f32_e32 v41, v39, v40
	v_sub_f32_e32 v39, v39, v41
	v_add_f32_e32 v39, v40, v39
	v_add_f32_e32 v40, 1.0, v38
	v_add_f32_e32 v42, -1.0, v40
	v_sub_f32_e32 v38, v38, v42
	v_add_f32_e32 v37, v37, v38
	v_add_f32_e32 v38, v40, v37
	v_sub_f32_e32 v40, v40, v38
	v_add_f32_e32 v37, v37, v40
	v_rcp_f32_e32 v40, v38
	v_cvt_f32_i32_e32 v36, v36
	v_cmp_neq_f32_e32 vcc, s62, v33
	v_mul_f32_e32 v42, v41, v40
	v_mul_f32_e32 v43, v38, v42
	v_fma_f32 v44, v42, v38, -v43
	v_fmac_f32_e32 v44, v42, v37
	v_add_f32_e32 v45, v43, v44
	v_sub_f32_e32 v46, v41, v45
	v_sub_f32_e32 v41, v41, v46
	v_sub_f32_e32 v43, v45, v43
	v_sub_f32_e32 v41, v41, v45
	v_add_f32_e32 v39, v39, v41
	v_sub_f32_e32 v41, v43, v44
	v_add_f32_e32 v39, v41, v39
	v_add_f32_e32 v41, v46, v39
	v_mul_f32_e32 v43, v40, v41
	v_mul_f32_e32 v44, v38, v43
	v_fma_f32 v38, v43, v38, -v44
	v_fmac_f32_e32 v38, v43, v37
	v_sub_f32_e32 v37, v46, v41
	v_add_f32_e32 v37, v39, v37
	v_add_f32_e32 v39, v44, v38
	v_sub_f32_e32 v45, v41, v39
	v_sub_f32_e32 v41, v41, v45
	v_sub_f32_e32 v44, v39, v44
	v_sub_f32_e32 v39, v41, v39
	v_add_f32_e32 v37, v37, v39
	v_sub_f32_e32 v38, v44, v38
	v_add_f32_e32 v37, v38, v37
	v_add_f32_e32 v38, v42, v43
	v_add_f32_e32 v37, v45, v37
	v_sub_f32_e32 v39, v38, v42
	v_mul_f32_e32 v37, v40, v37
	v_sub_f32_e32 v39, v43, v39
	v_add_f32_e32 v37, v39, v37
	v_mul_f32_e32 v42, 0x3f317218, v36
	v_add_f32_e32 v39, v38, v37
	v_fma_f32 v43, v36, s78, -v42
	v_mul_f32_e32 v40, v39, v39
	v_fmac_f32_e32 v43, 0xb102e308, v36
	v_sub_f32_e32 v36, v39, v38
	v_fmamk_f32 v41, v40, 0x3e9b6dac, v185
	v_sub_f32_e32 v36, v37, v36
	v_add_f32_e32 v37, v42, v43
	v_fmaak_f32 v41, v40, v41, 0x3f2aaada
	v_sub_f32_e32 v38, v37, v42
	v_ldexp_f32 v42, v39, 1
	v_mul_f32_e32 v39, v39, v40
	v_mul_f32_e32 v39, v39, v41
	v_add_f32_e32 v40, v42, v39
	v_sub_f32_e32 v41, v40, v42
	v_ldexp_f32 v36, v36, 1
	v_sub_f32_e32 v39, v39, v41
	v_add_f32_e32 v36, v36, v39
	v_add_f32_e32 v39, v40, v36
	v_sub_f32_e32 v40, v39, v40
	v_sub_f32_e32 v36, v36, v40
	v_add_f32_e32 v40, v37, v39
	v_sub_f32_e32 v41, v40, v37
	v_sub_f32_e32 v42, v40, v41
	v_sub_f32_e32 v38, v43, v38
	v_sub_f32_e32 v37, v37, v42
	v_sub_f32_e32 v39, v39, v41
	v_add_f32_e32 v37, v39, v37
	v_add_f32_e32 v39, v38, v36
	v_sub_f32_e32 v41, v39, v38
	v_sub_f32_e32 v42, v39, v41
	v_sub_f32_e32 v38, v38, v42
	v_sub_f32_e32 v36, v36, v41
	v_add_f32_e32 v37, v39, v37
	v_add_f32_e32 v36, v36, v38
	v_add_f32_e32 v38, v40, v37
	v_sub_f32_e32 v39, v38, v40
	v_sub_f32_e32 v37, v37, v39
	v_add_f32_e32 v36, v36, v37
	v_add_f32_e32 v36, v38, v36
	v_cndmask_b32_e32 v36, v226, v36, vcc
	v_cmp_lt_f32_e64 vcc, |v33|, s63
	s_nop 1
	v_cndmask_b32_e32 v33, v36, v33, vcc
	v_sub_f32_e32 v32, v32, v33
	v_mul_f32_e32 v32, 0x3fb8aa3b, v32
	global_store_dword v[56:57], v32, off offset:192
	v_readlane_b32 s100, v254, 6
	s_nop 1
	v_mov_b32_e32 v33, s100
	v_fmac_f32_e32 v33, v34, v166
	v_mul_f32_e64 v34, |v33|, s94
	v_fma_f32 v36, |v33|, s94, -v34
	v_rndne_f32_e32 v37, v34
	v_fma_f32 v36, |v33|, s64, v36
	v_sub_f32_e32 v34, v34, v37
	v_add_f32_e32 v34, v34, v36
	v_exp_f32_e32 v34, v34
	v_cvt_i32_f32_e32 v36, v37
	v_cmp_ngt_f32_e64 vcc, |v33|, s58
	v_min_f32_e32 v32, 0, v33
	v_ldexp_f32 v34, v34, v36
	v_cndmask_b32_e32 v34, 0, v34, vcc
	v_cmp_nlt_f32_e64 vcc, |v33|, s59
	s_nop 1
	v_cndmask_b32_e32 v33, v226, v34, vcc
	v_add_f32_e32 v34, 1.0, v33
	v_add_f32_e32 v36, -1.0, v34
	v_sub_f32_e32 v37, v36, v34
	v_add_f32_e32 v37, 1.0, v37
	v_sub_f32_e32 v36, v33, v36
	v_add_f32_e32 v38, v36, v37
	v_frexp_mant_f32_e32 v36, v34
	v_cmp_gt_f32_e32 vcc, s77, v36
	v_cvt_f64_f32_e32 v[36:37], v34
	v_frexp_exp_i32_f64_e32 v36, v[36:37]
	v_subbrev_co_u32_e32 v36, vcc, 0, v36, vcc
	v_sub_u32_e32 v37, 0, v36
	v_ldexp_f32 v34, v34, v37
	v_ldexp_f32 v37, v38, v37
	v_add_f32_e32 v38, -1.0, v34
	v_add_f32_e32 v39, 1.0, v38
	v_sub_f32_e32 v39, v34, v39
	v_add_f32_e32 v39, v37, v39
	v_add_f32_e32 v40, v38, v39
	v_sub_f32_e32 v38, v38, v40
	v_add_f32_e32 v38, v39, v38
	v_add_f32_e32 v39, 1.0, v34
	v_add_f32_e32 v41, -1.0, v39
	v_sub_f32_e32 v34, v34, v41
	v_add_f32_e32 v34, v37, v34
	v_add_f32_e32 v37, v39, v34
	v_sub_f32_e32 v39, v39, v37
	v_add_f32_e32 v34, v34, v39
	v_rcp_f32_e32 v39, v37
	v_cvt_f32_i32_e32 v36, v36
	v_cmp_neq_f32_e32 vcc, s62, v33
	v_mul_f32_e32 v41, v40, v39
	v_mul_f32_e32 v42, v37, v41
	v_fma_f32 v43, v41, v37, -v42
	v_fmac_f32_e32 v43, v41, v34
	v_add_f32_e32 v44, v42, v43
	v_sub_f32_e32 v45, v40, v44
	v_sub_f32_e32 v40, v40, v45
	v_sub_f32_e32 v42, v44, v42
	v_sub_f32_e32 v40, v40, v44
	v_add_f32_e32 v38, v38, v40
	v_sub_f32_e32 v40, v42, v43
	v_add_f32_e32 v38, v40, v38
	v_add_f32_e32 v40, v45, v38
	v_mul_f32_e32 v42, v39, v40
	v_mul_f32_e32 v43, v37, v42
	v_fma_f32 v37, v42, v37, -v43
	v_fmac_f32_e32 v37, v42, v34
	v_sub_f32_e32 v34, v45, v40
	v_add_f32_e32 v34, v38, v34
	v_add_f32_e32 v38, v43, v37
	v_sub_f32_e32 v44, v40, v38
	v_sub_f32_e32 v40, v40, v44
	v_sub_f32_e32 v43, v38, v43
	v_sub_f32_e32 v38, v40, v38
	v_add_f32_e32 v34, v34, v38
	v_sub_f32_e32 v37, v43, v37
	v_add_f32_e32 v34, v37, v34
	v_add_f32_e32 v37, v41, v42
	v_add_f32_e32 v34, v44, v34
	v_sub_f32_e32 v38, v37, v41
	v_mul_f32_e32 v34, v39, v34
	v_sub_f32_e32 v38, v42, v38
	v_add_f32_e32 v34, v38, v34
	v_mul_f32_e32 v41, 0x3f317218, v36
	v_add_f32_e32 v38, v37, v34
	v_fma_f32 v42, v36, s78, -v41
	v_mul_f32_e32 v39, v38, v38
	v_fmac_f32_e32 v42, 0xb102e308, v36
	v_sub_f32_e32 v36, v38, v37
	v_fmamk_f32 v40, v39, 0x3e9b6dac, v185
	v_sub_f32_e32 v34, v34, v36
	v_add_f32_e32 v36, v41, v42
	v_fmaak_f32 v40, v39, v40, 0x3f2aaada
	v_sub_f32_e32 v37, v36, v41
	v_ldexp_f32 v41, v38, 1
	v_mul_f32_e32 v38, v38, v39
	v_mul_f32_e32 v38, v38, v40
	v_add_f32_e32 v39, v41, v38
	v_sub_f32_e32 v40, v39, v41
	v_ldexp_f32 v34, v34, 1
	v_sub_f32_e32 v38, v38, v40
	v_add_f32_e32 v34, v34, v38
	v_add_f32_e32 v38, v39, v34
	v_sub_f32_e32 v39, v38, v39
	v_sub_f32_e32 v34, v34, v39
	v_add_f32_e32 v39, v36, v38
	v_sub_f32_e32 v40, v39, v36
	v_sub_f32_e32 v41, v39, v40
	v_sub_f32_e32 v37, v42, v37
	v_sub_f32_e32 v36, v36, v41
	v_sub_f32_e32 v38, v38, v40
	v_add_f32_e32 v36, v38, v36
	v_add_f32_e32 v38, v37, v34
	v_sub_f32_e32 v40, v38, v37
	v_sub_f32_e32 v41, v38, v40
	v_sub_f32_e32 v37, v37, v41
	v_sub_f32_e32 v34, v34, v40
	v_add_f32_e32 v36, v38, v36
	v_add_f32_e32 v34, v34, v37
	v_add_f32_e32 v37, v39, v36
	v_sub_f32_e32 v38, v37, v39
	v_sub_f32_e32 v36, v36, v38
	v_add_f32_e32 v34, v34, v36
	v_add_f32_e32 v34, v37, v34
	v_cndmask_b32_e32 v34, v226, v34, vcc
	v_cmp_lt_f32_e64 vcc, |v33|, s63
	s_nop 1
	v_cndmask_b32_e32 v33, v34, v33, vcc
	v_sub_f32_e32 v32, v32, v33
	v_mul_f32_e32 v32, 0x3fb8aa3b, v32
	global_store_dword v[70:71], v32, off offset:192
	v_readlane_b32 s100, v254, 7
	s_nop 1
	v_mov_b32_e32 v33, s100
	v_fmac_f32_e32 v33, v35, v166
	v_mul_f32_e64 v34, |v33|, s94
	v_fma_f32 v35, |v33|, s94, -v34
	v_rndne_f32_e32 v36, v34
	v_fma_f32 v35, |v33|, s64, v35
	v_sub_f32_e32 v34, v34, v36
	v_add_f32_e32 v34, v34, v35
	v_exp_f32_e32 v34, v34
	v_cvt_i32_f32_e32 v35, v36
	v_cmp_ngt_f32_e64 vcc, |v33|, s58
	v_min_f32_e32 v32, 0, v33
	v_ldexp_f32 v34, v34, v35
	v_cndmask_b32_e32 v34, 0, v34, vcc
	v_cmp_nlt_f32_e64 vcc, |v33|, s59
	s_nop 1
	v_cndmask_b32_e32 v33, v226, v34, vcc
	v_add_f32_e32 v36, 1.0, v33
	v_add_f32_e32 v34, -1.0, v36
	v_sub_f32_e32 v35, v34, v36
	v_add_f32_e32 v35, 1.0, v35
	v_sub_f32_e32 v34, v33, v34
	v_add_f32_e32 v37, v34, v35
	v_frexp_mant_f32_e32 v34, v36
	v_cmp_gt_f32_e32 vcc, s77, v34
	v_cvt_f64_f32_e32 v[34:35], v36
	v_frexp_exp_i32_f64_e32 v34, v[34:35]
	v_subbrev_co_u32_e32 v34, vcc, 0, v34, vcc
	v_sub_u32_e32 v35, 0, v34
	v_ldexp_f32 v36, v36, v35
	v_ldexp_f32 v35, v37, v35
	v_add_f32_e32 v37, -1.0, v36
	v_add_f32_e32 v38, 1.0, v37
	v_sub_f32_e32 v38, v36, v38
	v_add_f32_e32 v38, v35, v38
	v_add_f32_e32 v39, v37, v38
	v_sub_f32_e32 v37, v37, v39
	v_add_f32_e32 v37, v38, v37
	v_add_f32_e32 v38, 1.0, v36
	v_add_f32_e32 v40, -1.0, v38
	v_sub_f32_e32 v36, v36, v40
	v_add_f32_e32 v35, v35, v36
	v_add_f32_e32 v36, v38, v35
	v_sub_f32_e32 v38, v38, v36
	v_add_f32_e32 v35, v35, v38
	v_rcp_f32_e32 v38, v36
	v_cvt_f32_i32_e32 v34, v34
	v_cmp_neq_f32_e32 vcc, s62, v33
	v_mul_f32_e32 v40, v39, v38
	v_mul_f32_e32 v41, v36, v40
	v_fma_f32 v42, v40, v36, -v41
	v_fmac_f32_e32 v42, v40, v35
	v_add_f32_e32 v43, v41, v42
	v_sub_f32_e32 v44, v39, v43
	v_sub_f32_e32 v39, v39, v44
	v_sub_f32_e32 v41, v43, v41
	v_sub_f32_e32 v39, v39, v43
	v_add_f32_e32 v37, v37, v39
	v_sub_f32_e32 v39, v41, v42
	v_add_f32_e32 v37, v39, v37
	v_add_f32_e32 v39, v44, v37
	v_mul_f32_e32 v41, v38, v39
	v_mul_f32_e32 v42, v36, v41
	v_fma_f32 v36, v41, v36, -v42
	v_fmac_f32_e32 v36, v41, v35
	v_sub_f32_e32 v35, v44, v39
	v_add_f32_e32 v35, v37, v35
	v_add_f32_e32 v37, v42, v36
	v_sub_f32_e32 v43, v39, v37
	v_sub_f32_e32 v39, v39, v43
	v_sub_f32_e32 v42, v37, v42
	v_sub_f32_e32 v37, v39, v37
	v_add_f32_e32 v35, v35, v37
	v_sub_f32_e32 v36, v42, v36
	v_add_f32_e32 v35, v36, v35
	v_add_f32_e32 v36, v40, v41
	v_add_f32_e32 v35, v43, v35
	v_sub_f32_e32 v37, v36, v40
	v_mul_f32_e32 v35, v38, v35
	v_sub_f32_e32 v37, v41, v37
	v_add_f32_e32 v35, v37, v35
	v_mul_f32_e32 v40, 0x3f317218, v34
	v_add_f32_e32 v37, v36, v35
	v_fma_f32 v41, v34, s78, -v40
	v_mul_f32_e32 v38, v37, v37
	v_fmac_f32_e32 v41, 0xb102e308, v34
	v_sub_f32_e32 v34, v37, v36
	v_fmamk_f32 v39, v38, 0x3e9b6dac, v185
	v_sub_f32_e32 v34, v35, v34
	v_add_f32_e32 v35, v40, v41
	v_fmaak_f32 v39, v38, v39, 0x3f2aaada
	v_sub_f32_e32 v36, v35, v40
	v_ldexp_f32 v40, v37, 1
	v_mul_f32_e32 v37, v37, v38
	v_mul_f32_e32 v37, v37, v39
	v_add_f32_e32 v38, v40, v37
	v_sub_f32_e32 v39, v38, v40
	v_ldexp_f32 v34, v34, 1
	v_sub_f32_e32 v37, v37, v39
	v_add_f32_e32 v34, v34, v37
	v_add_f32_e32 v37, v38, v34
	v_sub_f32_e32 v38, v37, v38
	v_sub_f32_e32 v34, v34, v38
	v_add_f32_e32 v38, v35, v37
	v_sub_f32_e32 v39, v38, v35
	v_sub_f32_e32 v40, v38, v39
	v_sub_f32_e32 v36, v41, v36
	v_sub_f32_e32 v35, v35, v40
	v_sub_f32_e32 v37, v37, v39
	v_add_f32_e32 v35, v37, v35
	v_add_f32_e32 v37, v36, v34
	v_sub_f32_e32 v39, v37, v36
	v_sub_f32_e32 v40, v37, v39
	v_sub_f32_e32 v36, v36, v40
	v_sub_f32_e32 v34, v34, v39
	v_add_f32_e32 v35, v37, v35
	v_add_f32_e32 v34, v34, v36
	v_add_f32_e32 v36, v38, v35
	v_sub_f32_e32 v37, v36, v38
	v_sub_f32_e32 v35, v35, v37
	v_add_f32_e32 v34, v34, v35
	v_add_f32_e32 v34, v36, v34
	v_cndmask_b32_e32 v34, v226, v34, vcc
	v_cmp_lt_f32_e64 vcc, |v33|, s63
	v_ashrrev_i32_e32 v42, 9, v164
	v_and_b32_e32 v38, -8, v42
	v_cndmask_b32_e32 v33, v34, v33, vcc
	v_sub_f32_e32 v32, v32, v33
	v_mul_f32_e32 v32, 0x3fb8aa3b, v32
	global_store_dword v[58:59], v32, off offset:192
	v_and_b32_e32 v32, 0xfcf, v164
	v_lshlrev_b32_e32 v190, 2, v32
	v_readlane_b32 s100, v254, 0
	s_nop 1
	v_mov_b32_e32 v32, s100
	v_lshl_add_u64 v[40:41], s[52:53], 0, v[190:191]
	v_fmac_f32_e32 v32, v28, v162
	v_mul_f32_e64 v33, |v32|, s94
	v_fma_f32 v34, |v32|, s94, -v33
	v_rndne_f32_e32 v35, v33
	v_fma_f32 v34, |v32|, s64, v34
	v_sub_f32_e32 v33, v33, v35
	v_add_f32_e32 v33, v33, v34
	v_exp_f32_e32 v33, v33
	v_cvt_i32_f32_e32 v34, v35
	v_cmp_ngt_f32_e64 vcc, |v32|, s58
	v_min_f32_e32 v28, 0, v32
	v_ldexp_f32 v33, v33, v34
	v_cndmask_b32_e32 v33, 0, v33, vcc
	v_cmp_nlt_f32_e64 vcc, |v32|, s59
	s_nop 1
	v_cndmask_b32_e32 v34, v226, v33, vcc
	v_add_f32_e32 v35, 1.0, v34
	v_add_f32_e32 v32, -1.0, v35
	v_sub_f32_e32 v33, v32, v35
	v_add_f32_e32 v33, 1.0, v33
	v_sub_f32_e32 v32, v34, v32
	v_add_f32_e32 v36, v32, v33
	v_frexp_mant_f32_e32 v32, v35
	v_cmp_gt_f32_e32 vcc, s77, v32
	v_cvt_f64_f32_e32 v[32:33], v35
	v_frexp_exp_i32_f64_e32 v32, v[32:33]
	v_subbrev_co_u32_e32 v32, vcc, 0, v32, vcc
	v_sub_u32_e32 v33, 0, v32
	v_ldexp_f32 v35, v35, v33
	v_ldexp_f32 v33, v36, v33
	v_add_f32_e32 v36, -1.0, v35
	v_add_f32_e32 v37, 1.0, v36
	v_sub_f32_e32 v37, v35, v37
	v_add_f32_e32 v37, v33, v37
	v_add_f32_e32 v39, v36, v37
	v_sub_f32_e32 v36, v36, v39
	v_add_f32_e32 v36, v37, v36
	v_add_f32_e32 v37, 1.0, v35
	v_add_f32_e32 v43, -1.0, v37
	v_sub_f32_e32 v35, v35, v43
	v_add_f32_e32 v33, v33, v35
	v_add_f32_e32 v35, v37, v33
	v_sub_f32_e32 v37, v37, v35
	v_add_f32_e32 v33, v33, v37
	v_rcp_f32_e32 v37, v35
	v_cvt_f32_i32_e32 v32, v32
	v_cmp_neq_f32_e32 vcc, s62, v34
	v_mul_f32_e32 v43, v39, v37
	v_mul_f32_e32 v44, v35, v43
	v_fma_f32 v45, v43, v35, -v44
	v_fmac_f32_e32 v45, v43, v33
	v_add_f32_e32 v46, v44, v45
	v_sub_f32_e32 v47, v39, v46
	v_sub_f32_e32 v39, v39, v47
	v_sub_f32_e32 v44, v46, v44
	v_sub_f32_e32 v39, v39, v46
	v_add_f32_e32 v36, v36, v39
	v_sub_f32_e32 v39, v44, v45
	v_add_f32_e32 v36, v39, v36
	v_add_f32_e32 v39, v47, v36
	v_mul_f32_e32 v44, v37, v39
	v_mul_f32_e32 v45, v35, v44
	v_fma_f32 v35, v44, v35, -v45
	v_fmac_f32_e32 v35, v44, v33
	v_sub_f32_e32 v33, v47, v39
	v_add_f32_e32 v33, v36, v33
	v_add_f32_e32 v36, v45, v35
	v_sub_f32_e32 v46, v39, v36
	v_sub_f32_e32 v39, v39, v46
	v_sub_f32_e32 v45, v36, v45
	v_sub_f32_e32 v36, v39, v36
	v_add_f32_e32 v33, v33, v36
	v_sub_f32_e32 v35, v45, v35
	v_add_f32_e32 v33, v35, v33
	v_add_f32_e32 v35, v43, v44
	v_add_f32_e32 v33, v46, v33
	v_sub_f32_e32 v36, v35, v43
	v_mul_f32_e32 v33, v37, v33
	v_sub_f32_e32 v36, v44, v36
	v_add_f32_e32 v33, v36, v33
	v_mul_f32_e32 v43, 0x3f317218, v32
	v_add_f32_e32 v36, v35, v33
	v_fma_f32 v44, v32, s78, -v43
	v_mul_f32_e32 v37, v36, v36
	v_fmac_f32_e32 v44, 0xb102e308, v32
	v_sub_f32_e32 v32, v36, v35
	v_fmamk_f32 v39, v37, 0x3e9b6dac, v185
	v_sub_f32_e32 v32, v33, v32
	v_add_f32_e32 v33, v43, v44
	v_fmaak_f32 v39, v37, v39, 0x3f2aaada
	v_sub_f32_e32 v35, v33, v43
	v_ldexp_f32 v43, v36, 1
	v_mul_f32_e32 v36, v36, v37
	v_mul_f32_e32 v36, v36, v39
	v_add_f32_e32 v37, v43, v36
	v_sub_f32_e32 v39, v37, v43
	v_ldexp_f32 v32, v32, 1
	v_sub_f32_e32 v36, v36, v39
	v_add_f32_e32 v32, v32, v36
	v_add_f32_e32 v36, v37, v32
	v_sub_f32_e32 v37, v36, v37
	v_sub_f32_e32 v32, v32, v37
	v_add_f32_e32 v37, v33, v36
	v_sub_f32_e32 v39, v37, v33
	v_sub_f32_e32 v43, v37, v39
	v_sub_f32_e32 v35, v44, v35
	v_sub_f32_e32 v33, v33, v43
	v_sub_f32_e32 v36, v36, v39
	v_add_f32_e32 v33, v36, v33
	v_add_f32_e32 v36, v35, v32
	v_sub_f32_e32 v39, v36, v35
	v_sub_f32_e32 v43, v36, v39
	v_sub_f32_e32 v35, v35, v43
	v_sub_f32_e32 v32, v32, v39
	v_add_f32_e32 v33, v36, v33
	v_add_f32_e32 v32, v32, v35
	v_add_f32_e32 v35, v37, v33
	v_sub_f32_e32 v36, v35, v37
	v_sub_f32_e32 v33, v33, v36
	v_add_f32_e32 v32, v32, v33
	v_add_f32_e32 v32, v35, v32
	v_cndmask_b32_e32 v32, v226, v32, vcc
	v_cmp_lt_f32_e64 vcc, |v34|, s63
	v_ashrrev_i32_e32 v39, 31, v38
	s_nop 0
	v_cndmask_b32_e32 v32, v32, v34, vcc
	v_sub_f32_e32 v28, v28, v32
	v_lshlrev_b64 v[32:33], 14, v[38:39]
	v_mul_f32_e32 v28, 0x3fb8aa3b, v28
	v_lshl_add_u64 v[32:33], v[40:41], 0, v[32:33]
	global_store_dword v[32:33], v28, off
	v_readlane_b32 s100, v254, 1
	s_nop 1
	v_mov_b32_e32 v28, s100
	v_fmac_f32_e32 v28, v29, v162
	v_mul_f32_e64 v29, |v28|, s94
	v_fma_f32 v35, |v28|, s94, -v29
	v_rndne_f32_e32 v36, v29
	v_fma_f32 v35, |v28|, s64, v35
	v_sub_f32_e32 v29, v29, v36
	v_add_f32_e32 v29, v29, v35
	v_exp_f32_e32 v29, v29
	v_cvt_i32_f32_e32 v35, v36
	v_cmp_ngt_f32_e64 vcc, |v28|, s58
	v_min_f32_e32 v34, 0, v28
	v_ldexp_f32 v29, v29, v35
	v_cndmask_b32_e32 v29, 0, v29, vcc
	v_cmp_nlt_f32_e64 vcc, |v28|, s59
	s_nop 1
	v_cndmask_b32_e32 v35, v226, v29, vcc
	v_add_f32_e32 v36, 1.0, v35
	v_add_f32_e32 v28, -1.0, v36
	v_sub_f32_e32 v29, v28, v36
	v_add_f32_e32 v29, 1.0, v29
	v_sub_f32_e32 v28, v35, v28
	v_add_f32_e32 v37, v28, v29
	v_frexp_mant_f32_e32 v28, v36
	v_cmp_gt_f32_e32 vcc, s77, v28
	v_cvt_f64_f32_e32 v[28:29], v36
	v_frexp_exp_i32_f64_e32 v28, v[28:29]
	v_subbrev_co_u32_e32 v28, vcc, 0, v28, vcc
	v_sub_u32_e32 v29, 0, v28
	v_ldexp_f32 v36, v36, v29
	v_ldexp_f32 v29, v37, v29
	v_add_f32_e32 v37, -1.0, v36
	v_add_f32_e32 v39, 1.0, v37
	v_sub_f32_e32 v39, v36, v39
	v_add_f32_e32 v39, v29, v39
	v_add_f32_e32 v43, v37, v39
	v_sub_f32_e32 v37, v37, v43
	v_add_f32_e32 v37, v39, v37
	v_add_f32_e32 v39, 1.0, v36
	v_add_f32_e32 v44, -1.0, v39
	v_sub_f32_e32 v36, v36, v44
	v_add_f32_e32 v29, v29, v36
	v_add_f32_e32 v36, v39, v29
	v_sub_f32_e32 v39, v39, v36
	v_add_f32_e32 v29, v29, v39
	v_rcp_f32_e32 v39, v36
	v_cvt_f32_i32_e32 v28, v28
	v_cmp_neq_f32_e32 vcc, s62, v35
	v_mul_f32_e32 v44, v43, v39
	v_mul_f32_e32 v45, v36, v44
	v_fma_f32 v46, v44, v36, -v45
	v_fmac_f32_e32 v46, v44, v29
	v_add_f32_e32 v47, v45, v46
	v_sub_f32_e32 v48, v43, v47
	v_sub_f32_e32 v43, v43, v48
	v_sub_f32_e32 v45, v47, v45
	v_sub_f32_e32 v43, v43, v47
	v_add_f32_e32 v37, v37, v43
	v_sub_f32_e32 v43, v45, v46
	v_add_f32_e32 v37, v43, v37
	v_add_f32_e32 v43, v48, v37
	v_mul_f32_e32 v45, v39, v43
	v_mul_f32_e32 v46, v36, v45
	v_fma_f32 v36, v45, v36, -v46
	v_fmac_f32_e32 v36, v45, v29
	v_sub_f32_e32 v29, v48, v43
	v_add_f32_e32 v29, v37, v29
	v_add_f32_e32 v37, v46, v36
	v_sub_f32_e32 v47, v43, v37
	v_sub_f32_e32 v43, v43, v47
	v_sub_f32_e32 v46, v37, v46
	v_sub_f32_e32 v37, v43, v37
	v_add_f32_e32 v29, v29, v37
	v_sub_f32_e32 v36, v46, v36
	v_add_f32_e32 v29, v36, v29
	v_add_f32_e32 v36, v44, v45
	v_add_f32_e32 v29, v47, v29
	v_sub_f32_e32 v37, v36, v44
	v_mul_f32_e32 v29, v39, v29
	v_sub_f32_e32 v37, v45, v37
	v_add_f32_e32 v29, v37, v29
	v_mul_f32_e32 v44, 0x3f317218, v28
	v_add_f32_e32 v37, v36, v29
	v_fma_f32 v45, v28, s78, -v44
	v_mul_f32_e32 v39, v37, v37
	v_fmac_f32_e32 v45, 0xb102e308, v28
	v_sub_f32_e32 v28, v37, v36
	v_fmamk_f32 v43, v39, 0x3e9b6dac, v185
	v_sub_f32_e32 v28, v29, v28
	v_add_f32_e32 v29, v44, v45
	v_fmaak_f32 v43, v39, v43, 0x3f2aaada
	v_sub_f32_e32 v36, v29, v44
	v_ldexp_f32 v44, v37, 1
	v_mul_f32_e32 v37, v37, v39
	v_mul_f32_e32 v37, v37, v43
	v_add_f32_e32 v39, v44, v37
	v_sub_f32_e32 v43, v39, v44
	v_ldexp_f32 v28, v28, 1
	v_sub_f32_e32 v37, v37, v43
	v_add_f32_e32 v28, v28, v37
	v_add_f32_e32 v37, v39, v28
	v_sub_f32_e32 v39, v37, v39
	v_sub_f32_e32 v28, v28, v39
	v_add_f32_e32 v39, v29, v37
	v_sub_f32_e32 v43, v39, v29
	v_sub_f32_e32 v44, v39, v43
	v_sub_f32_e32 v36, v45, v36
	v_sub_f32_e32 v29, v29, v44
	v_sub_f32_e32 v37, v37, v43
	v_add_f32_e32 v29, v37, v29
	v_add_f32_e32 v37, v36, v28
	v_sub_f32_e32 v43, v37, v36
	v_sub_f32_e32 v44, v37, v43
	v_sub_f32_e32 v36, v36, v44
	v_sub_f32_e32 v28, v28, v43
	v_add_f32_e32 v29, v37, v29
	v_add_f32_e32 v28, v28, v36
	v_add_f32_e32 v36, v39, v29
	v_sub_f32_e32 v37, v36, v39
	v_sub_f32_e32 v29, v29, v37
	v_add_f32_e32 v28, v28, v29
	v_add_f32_e32 v28, v36, v28
	v_cndmask_b32_e32 v28, v226, v28, vcc
	v_cmp_lt_f32_e64 vcc, |v35|, s63
	s_nop 1
	v_cndmask_b32_e32 v28, v28, v35, vcc
	v_sub_f32_e32 v28, v34, v28
	v_mul_f32_e32 v34, 0x3fb8aa3b, v28
	v_or_b32_e32 v28, 1, v38
	v_ashrrev_i32_e32 v29, 31, v28
	v_lshlrev_b64 v[28:29], 14, v[28:29]
	v_lshl_add_u64 v[28:29], v[40:41], 0, v[28:29]
	global_store_dword v[28:29], v34, off
	v_readlane_b32 s100, v254, 2
	s_nop 1
	v_mov_b32_e32 v34, s100
	v_fmac_f32_e32 v34, v30, v162
	v_mul_f32_e64 v35, |v34|, s94
	v_fma_f32 v36, |v34|, s94, -v35
	v_rndne_f32_e32 v37, v35
	v_fma_f32 v36, |v34|, s64, v36
	v_sub_f32_e32 v35, v35, v37
	v_add_f32_e32 v35, v35, v36
	v_exp_f32_e32 v35, v35
	v_cvt_i32_f32_e32 v36, v37
	v_cmp_ngt_f32_e64 vcc, |v34|, s58
	v_min_f32_e32 v30, 0, v34
	v_ldexp_f32 v35, v35, v36
	v_cndmask_b32_e32 v35, 0, v35, vcc
	v_cmp_nlt_f32_e64 vcc, |v34|, s59
	s_nop 1
	v_cndmask_b32_e32 v36, v226, v35, vcc
	v_add_f32_e32 v37, 1.0, v36
	v_add_f32_e32 v34, -1.0, v37
	v_sub_f32_e32 v35, v34, v37
	v_add_f32_e32 v35, 1.0, v35
	v_sub_f32_e32 v34, v36, v34
	v_add_f32_e32 v39, v34, v35
	v_frexp_mant_f32_e32 v34, v37
	v_cmp_gt_f32_e32 vcc, s77, v34
	v_cvt_f64_f32_e32 v[34:35], v37
	v_frexp_exp_i32_f64_e32 v34, v[34:35]
	v_subbrev_co_u32_e32 v34, vcc, 0, v34, vcc
	v_sub_u32_e32 v35, 0, v34
	v_ldexp_f32 v37, v37, v35
	v_ldexp_f32 v35, v39, v35
	v_add_f32_e32 v39, -1.0, v37
	v_add_f32_e32 v43, 1.0, v39
	v_sub_f32_e32 v43, v37, v43
	v_add_f32_e32 v43, v35, v43
	v_add_f32_e32 v44, v39, v43
	v_sub_f32_e32 v39, v39, v44
	v_add_f32_e32 v39, v43, v39
	v_add_f32_e32 v43, 1.0, v37
	v_add_f32_e32 v45, -1.0, v43
	v_sub_f32_e32 v37, v37, v45
	v_add_f32_e32 v35, v35, v37
	v_add_f32_e32 v37, v43, v35
	v_sub_f32_e32 v43, v43, v37
	v_add_f32_e32 v35, v35, v43
	v_rcp_f32_e32 v43, v37
	v_cvt_f32_i32_e32 v34, v34
	v_cmp_neq_f32_e32 vcc, s62, v36
	v_mul_f32_e32 v45, v44, v43
	v_mul_f32_e32 v46, v37, v45
	v_fma_f32 v47, v45, v37, -v46
	v_fmac_f32_e32 v47, v45, v35
	v_add_f32_e32 v48, v46, v47
	v_sub_f32_e32 v49, v44, v48
	v_sub_f32_e32 v44, v44, v49
	v_sub_f32_e32 v46, v48, v46
	v_sub_f32_e32 v44, v44, v48
	v_add_f32_e32 v39, v39, v44
	v_sub_f32_e32 v44, v46, v47
	v_add_f32_e32 v39, v44, v39
	v_add_f32_e32 v44, v49, v39
	v_mul_f32_e32 v46, v43, v44
	v_mul_f32_e32 v47, v37, v46
	v_fma_f32 v37, v46, v37, -v47
	v_fmac_f32_e32 v37, v46, v35
	v_sub_f32_e32 v35, v49, v44
	v_add_f32_e32 v35, v39, v35
	v_add_f32_e32 v39, v47, v37
	v_sub_f32_e32 v48, v44, v39
	v_sub_f32_e32 v44, v44, v48
	v_sub_f32_e32 v47, v39, v47
	v_sub_f32_e32 v39, v44, v39
	v_add_f32_e32 v35, v35, v39
	v_sub_f32_e32 v37, v47, v37
	v_add_f32_e32 v35, v37, v35
	v_add_f32_e32 v37, v45, v46
	v_add_f32_e32 v35, v48, v35
	v_sub_f32_e32 v39, v37, v45
	v_mul_f32_e32 v35, v43, v35
	v_sub_f32_e32 v39, v46, v39
	v_add_f32_e32 v35, v39, v35
	v_mul_f32_e32 v45, 0x3f317218, v34
	v_add_f32_e32 v39, v37, v35
	v_fma_f32 v46, v34, s78, -v45
	v_mul_f32_e32 v43, v39, v39
	v_fmac_f32_e32 v46, 0xb102e308, v34
	v_sub_f32_e32 v34, v39, v37
	v_fmamk_f32 v44, v43, 0x3e9b6dac, v185
	v_sub_f32_e32 v34, v35, v34
	v_add_f32_e32 v35, v45, v46
	v_fmaak_f32 v44, v43, v44, 0x3f2aaada
	v_sub_f32_e32 v37, v35, v45
	v_ldexp_f32 v45, v39, 1
	v_mul_f32_e32 v39, v39, v43
	v_mul_f32_e32 v39, v39, v44
	v_add_f32_e32 v43, v45, v39
	v_sub_f32_e32 v44, v43, v45
	v_ldexp_f32 v34, v34, 1
	v_sub_f32_e32 v39, v39, v44
	v_add_f32_e32 v34, v34, v39
	v_add_f32_e32 v39, v43, v34
	v_sub_f32_e32 v43, v39, v43
	v_sub_f32_e32 v34, v34, v43
	v_add_f32_e32 v43, v35, v39
	v_sub_f32_e32 v44, v43, v35
	v_sub_f32_e32 v45, v43, v44
	v_sub_f32_e32 v37, v46, v37
	v_sub_f32_e32 v35, v35, v45
	v_sub_f32_e32 v39, v39, v44
	v_add_f32_e32 v35, v39, v35
	v_add_f32_e32 v39, v37, v34
	v_sub_f32_e32 v44, v39, v37
	v_sub_f32_e32 v45, v39, v44
	v_sub_f32_e32 v37, v37, v45
	v_sub_f32_e32 v34, v34, v44
	v_add_f32_e32 v35, v39, v35
	v_add_f32_e32 v34, v34, v37
	v_add_f32_e32 v37, v43, v35
	v_sub_f32_e32 v39, v37, v43
	v_sub_f32_e32 v35, v35, v39
	v_add_f32_e32 v34, v34, v35
	v_add_f32_e32 v34, v37, v34
	v_cndmask_b32_e32 v34, v226, v34, vcc
	v_cmp_lt_f32_e64 vcc, |v36|, s63
	s_nop 1
	v_cndmask_b32_e32 v34, v34, v36, vcc
	v_sub_f32_e32 v30, v30, v34
	v_or_b32_e32 v34, 2, v38
	v_ashrrev_i32_e32 v35, 31, v34
	v_lshlrev_b64 v[34:35], 14, v[34:35]
	v_mul_f32_e32 v30, 0x3fb8aa3b, v30
	v_lshl_add_u64 v[34:35], v[40:41], 0, v[34:35]
	global_store_dword v[34:35], v30, off
	v_readlane_b32 s100, v254, 3
	s_nop 1
	v_mov_b32_e32 v30, s100
	v_fmac_f32_e32 v30, v31, v162
	v_mul_f32_e64 v31, |v30|, s94
	v_fma_f32 v37, |v30|, s94, -v31
	v_rndne_f32_e32 v39, v31
	v_fma_f32 v37, |v30|, s64, v37
	v_sub_f32_e32 v31, v31, v39
	v_add_f32_e32 v31, v31, v37
	v_exp_f32_e32 v31, v31
	v_cvt_i32_f32_e32 v37, v39
	v_cmp_ngt_f32_e64 vcc, |v30|, s58
	v_min_f32_e32 v36, 0, v30
	v_ldexp_f32 v31, v31, v37
	v_cndmask_b32_e32 v31, 0, v31, vcc
	v_cmp_nlt_f32_e64 vcc, |v30|, s59
	s_nop 1
	v_cndmask_b32_e32 v37, v226, v31, vcc
	v_add_f32_e32 v39, 1.0, v37
	v_add_f32_e32 v30, -1.0, v39
	v_sub_f32_e32 v31, v30, v39
	v_add_f32_e32 v31, 1.0, v31
	v_sub_f32_e32 v30, v37, v30
	v_add_f32_e32 v43, v30, v31
	v_frexp_mant_f32_e32 v30, v39
	v_cmp_gt_f32_e32 vcc, s77, v30
	v_cvt_f64_f32_e32 v[30:31], v39
	v_frexp_exp_i32_f64_e32 v30, v[30:31]
	v_subbrev_co_u32_e32 v30, vcc, 0, v30, vcc
	v_sub_u32_e32 v31, 0, v30
	v_ldexp_f32 v39, v39, v31
	v_ldexp_f32 v31, v43, v31
	v_add_f32_e32 v43, -1.0, v39
	v_add_f32_e32 v44, 1.0, v43
	v_sub_f32_e32 v44, v39, v44
	v_add_f32_e32 v44, v31, v44
	v_add_f32_e32 v45, v43, v44
	v_sub_f32_e32 v43, v43, v45
	v_add_f32_e32 v43, v44, v43
	v_add_f32_e32 v44, 1.0, v39
	v_add_f32_e32 v46, -1.0, v44
	v_sub_f32_e32 v39, v39, v46
	v_add_f32_e32 v31, v31, v39
	v_add_f32_e32 v39, v44, v31
	v_sub_f32_e32 v44, v44, v39
	v_add_f32_e32 v31, v31, v44
	v_rcp_f32_e32 v44, v39
	v_cvt_f32_i32_e32 v30, v30
	v_cmp_neq_f32_e32 vcc, s62, v37
	v_mul_f32_e32 v46, v45, v44
	v_mul_f32_e32 v47, v39, v46
	v_fma_f32 v48, v46, v39, -v47
	v_fmac_f32_e32 v48, v46, v31
	v_add_f32_e32 v49, v47, v48
	v_sub_f32_e32 v50, v45, v49
	v_sub_f32_e32 v45, v45, v50
	v_sub_f32_e32 v47, v49, v47
	v_sub_f32_e32 v45, v45, v49
	v_add_f32_e32 v43, v43, v45
	v_sub_f32_e32 v45, v47, v48
	v_add_f32_e32 v43, v45, v43
	v_add_f32_e32 v45, v50, v43
	v_mul_f32_e32 v47, v44, v45
	v_mul_f32_e32 v48, v39, v47
	v_fma_f32 v39, v47, v39, -v48
	v_fmac_f32_e32 v39, v47, v31
	v_sub_f32_e32 v31, v50, v45
	v_add_f32_e32 v31, v43, v31
	v_add_f32_e32 v43, v48, v39
	v_sub_f32_e32 v49, v45, v43
	v_sub_f32_e32 v45, v45, v49
	v_sub_f32_e32 v48, v43, v48
	v_sub_f32_e32 v43, v45, v43
	v_add_f32_e32 v31, v31, v43
	v_sub_f32_e32 v39, v48, v39
	v_add_f32_e32 v31, v39, v31
	v_add_f32_e32 v39, v46, v47
	v_add_f32_e32 v31, v49, v31
	v_sub_f32_e32 v43, v39, v46
	v_mul_f32_e32 v31, v44, v31
	v_sub_f32_e32 v43, v47, v43
	v_add_f32_e32 v31, v43, v31
	v_mul_f32_e32 v46, 0x3f317218, v30
	v_add_f32_e32 v43, v39, v31
	v_fma_f32 v47, v30, s78, -v46
	v_mul_f32_e32 v44, v43, v43
	v_fmac_f32_e32 v47, 0xb102e308, v30
	v_sub_f32_e32 v30, v43, v39
	v_fmamk_f32 v45, v44, 0x3e9b6dac, v185
	v_sub_f32_e32 v30, v31, v30
	v_add_f32_e32 v31, v46, v47
	v_fmaak_f32 v45, v44, v45, 0x3f2aaada
	v_sub_f32_e32 v39, v31, v46
	v_ldexp_f32 v46, v43, 1
	v_mul_f32_e32 v43, v43, v44
	v_mul_f32_e32 v43, v43, v45
	v_add_f32_e32 v44, v46, v43
	v_sub_f32_e32 v45, v44, v46
	v_ldexp_f32 v30, v30, 1
	v_sub_f32_e32 v43, v43, v45
	v_add_f32_e32 v30, v30, v43
	v_add_f32_e32 v43, v44, v30
	v_sub_f32_e32 v44, v43, v44
	v_sub_f32_e32 v30, v30, v44
	v_add_f32_e32 v44, v31, v43
	v_sub_f32_e32 v45, v44, v31
	v_sub_f32_e32 v46, v44, v45
	v_sub_f32_e32 v39, v47, v39
	v_sub_f32_e32 v31, v31, v46
	v_sub_f32_e32 v43, v43, v45
	v_add_f32_e32 v31, v43, v31
	v_add_f32_e32 v43, v39, v30
	v_sub_f32_e32 v45, v43, v39
	v_sub_f32_e32 v46, v43, v45
	v_sub_f32_e32 v39, v39, v46
	v_sub_f32_e32 v30, v30, v45
	v_add_f32_e32 v31, v43, v31
	v_add_f32_e32 v30, v30, v39
	v_add_f32_e32 v39, v44, v31
	v_sub_f32_e32 v43, v39, v44
	v_sub_f32_e32 v31, v31, v43
	v_add_f32_e32 v30, v30, v31
	v_add_f32_e32 v30, v39, v30
	v_cndmask_b32_e32 v30, v226, v30, vcc
	v_cmp_lt_f32_e64 vcc, |v37|, s63
	s_nop 1
	v_cndmask_b32_e32 v30, v30, v37, vcc
	v_sub_f32_e32 v30, v36, v30
	v_mul_f32_e32 v36, 0x3fb8aa3b, v30
	v_or_b32_e32 v30, 3, v38
	v_ashrrev_i32_e32 v31, 31, v30
	v_lshlrev_b64 v[30:31], 14, v[30:31]
	v_lshl_add_u64 v[30:31], v[40:41], 0, v[30:31]
	global_store_dword v[30:31], v36, off
	v_readlane_b32 s100, v254, 4
	s_nop 1
	v_mov_b32_e32 v36, s100
	v_fmac_f32_e32 v36, v24, v162
	v_mul_f32_e64 v37, |v36|, s94
	v_fma_f32 v39, |v36|, s94, -v37
	v_rndne_f32_e32 v43, v37
	v_fma_f32 v39, |v36|, s64, v39
	v_sub_f32_e32 v37, v37, v43
	v_add_f32_e32 v37, v37, v39
	v_exp_f32_e32 v37, v37
	v_cvt_i32_f32_e32 v39, v43
	v_cmp_ngt_f32_e64 vcc, |v36|, s58
	v_min_f32_e32 v24, 0, v36
	v_ldexp_f32 v37, v37, v39
	v_cndmask_b32_e32 v37, 0, v37, vcc
	v_cmp_nlt_f32_e64 vcc, |v36|, s59
	s_nop 1
	v_cndmask_b32_e32 v39, v226, v37, vcc
	v_add_f32_e32 v43, 1.0, v39
	v_add_f32_e32 v36, -1.0, v43
	v_sub_f32_e32 v37, v36, v43
	v_add_f32_e32 v37, 1.0, v37
	v_sub_f32_e32 v36, v39, v36
	v_add_f32_e32 v44, v36, v37
	v_frexp_mant_f32_e32 v36, v43
	v_cmp_gt_f32_e32 vcc, s77, v36
	v_cvt_f64_f32_e32 v[36:37], v43
	v_frexp_exp_i32_f64_e32 v36, v[36:37]
	v_subbrev_co_u32_e32 v36, vcc, 0, v36, vcc
	v_sub_u32_e32 v37, 0, v36
	v_ldexp_f32 v43, v43, v37
	v_ldexp_f32 v37, v44, v37
	v_add_f32_e32 v44, -1.0, v43
	v_add_f32_e32 v45, 1.0, v44
	v_sub_f32_e32 v45, v43, v45
	v_add_f32_e32 v45, v37, v45
	v_add_f32_e32 v46, v44, v45
	v_sub_f32_e32 v44, v44, v46
	v_add_f32_e32 v44, v45, v44
	v_add_f32_e32 v45, 1.0, v43
	v_add_f32_e32 v47, -1.0, v45
	v_sub_f32_e32 v43, v43, v47
	v_add_f32_e32 v37, v37, v43
	v_add_f32_e32 v43, v45, v37
	v_sub_f32_e32 v45, v45, v43
	v_add_f32_e32 v37, v37, v45
	v_rcp_f32_e32 v45, v43
	v_cvt_f32_i32_e32 v36, v36
	v_cmp_neq_f32_e32 vcc, s62, v39
	v_mul_f32_e32 v47, v46, v45
	v_mul_f32_e32 v48, v43, v47
	v_fma_f32 v49, v47, v43, -v48
	v_fmac_f32_e32 v49, v47, v37
	v_add_f32_e32 v50, v48, v49
	v_sub_f32_e32 v51, v46, v50
	v_sub_f32_e32 v46, v46, v51
	v_sub_f32_e32 v48, v50, v48
	v_sub_f32_e32 v46, v46, v50
	v_add_f32_e32 v44, v44, v46
	v_sub_f32_e32 v46, v48, v49
	v_add_f32_e32 v44, v46, v44
	v_add_f32_e32 v46, v51, v44
	v_mul_f32_e32 v48, v45, v46
	v_mul_f32_e32 v49, v43, v48
	v_fma_f32 v43, v48, v43, -v49
	v_fmac_f32_e32 v43, v48, v37
	v_sub_f32_e32 v37, v51, v46
	v_add_f32_e32 v37, v44, v37
	v_add_f32_e32 v44, v49, v43
	v_sub_f32_e32 v50, v46, v44
	v_sub_f32_e32 v46, v46, v50
	v_sub_f32_e32 v49, v44, v49
	v_sub_f32_e32 v44, v46, v44
	v_add_f32_e32 v37, v37, v44
	v_sub_f32_e32 v43, v49, v43
	v_add_f32_e32 v37, v43, v37
	v_add_f32_e32 v43, v47, v48
	v_add_f32_e32 v37, v50, v37
	v_sub_f32_e32 v44, v43, v47
	v_mul_f32_e32 v37, v45, v37
	v_sub_f32_e32 v44, v48, v44
	v_add_f32_e32 v37, v44, v37
	v_mul_f32_e32 v47, 0x3f317218, v36
	v_add_f32_e32 v44, v43, v37
	v_fma_f32 v48, v36, s78, -v47
	v_mul_f32_e32 v45, v44, v44
	v_fmac_f32_e32 v48, 0xb102e308, v36
	v_sub_f32_e32 v36, v44, v43
	v_fmamk_f32 v46, v45, 0x3e9b6dac, v185
	v_sub_f32_e32 v36, v37, v36
	v_add_f32_e32 v37, v47, v48
	v_fmaak_f32 v46, v45, v46, 0x3f2aaada
	v_sub_f32_e32 v43, v37, v47
	v_ldexp_f32 v47, v44, 1
	v_mul_f32_e32 v44, v44, v45
	v_mul_f32_e32 v44, v44, v46
	v_add_f32_e32 v45, v47, v44
	v_sub_f32_e32 v46, v45, v47
	v_ldexp_f32 v36, v36, 1
	v_sub_f32_e32 v44, v44, v46
	v_add_f32_e32 v36, v36, v44
	v_add_f32_e32 v44, v45, v36
	v_sub_f32_e32 v45, v44, v45
	v_sub_f32_e32 v36, v36, v45
	v_add_f32_e32 v45, v37, v44
	v_sub_f32_e32 v46, v45, v37
	v_sub_f32_e32 v47, v45, v46
	v_sub_f32_e32 v43, v48, v43
	v_sub_f32_e32 v37, v37, v47
	v_sub_f32_e32 v44, v44, v46
	v_add_f32_e32 v37, v44, v37
	v_add_f32_e32 v44, v43, v36
	v_sub_f32_e32 v46, v44, v43
	v_sub_f32_e32 v47, v44, v46
	v_sub_f32_e32 v43, v43, v47
	v_sub_f32_e32 v36, v36, v46
	v_add_f32_e32 v37, v44, v37
	v_add_f32_e32 v36, v36, v43
	v_add_f32_e32 v43, v45, v37
	v_sub_f32_e32 v44, v43, v45
	v_sub_f32_e32 v37, v37, v44
	v_add_f32_e32 v36, v36, v37
	v_add_f32_e32 v36, v43, v36
	v_cndmask_b32_e32 v36, v226, v36, vcc
	v_cmp_lt_f32_e64 vcc, |v39|, s63
	s_nop 1
	v_cndmask_b32_e32 v36, v36, v39, vcc
	v_sub_f32_e32 v24, v24, v36
	v_or_b32_e32 v36, 4, v38
	v_ashrrev_i32_e32 v37, 31, v36
	v_lshlrev_b64 v[36:37], 14, v[36:37]
	v_mul_f32_e32 v24, 0x3fb8aa3b, v24
	v_lshl_add_u64 v[36:37], v[40:41], 0, v[36:37]
	global_store_dword v[36:37], v24, off
	v_readlane_b32 s100, v254, 5
	s_nop 1
	v_mov_b32_e32 v24, s100
	v_fmac_f32_e32 v24, v25, v162
	v_mul_f32_e64 v25, |v24|, s94
	v_fma_f32 v43, |v24|, s94, -v25
	v_rndne_f32_e32 v44, v25
	v_fma_f32 v43, |v24|, s64, v43
	v_sub_f32_e32 v25, v25, v44
	v_add_f32_e32 v25, v25, v43
	v_exp_f32_e32 v25, v25
	v_cvt_i32_f32_e32 v43, v44
	v_cmp_ngt_f32_e64 vcc, |v24|, s58
	v_min_f32_e32 v39, 0, v24
	v_ldexp_f32 v25, v25, v43
	v_cndmask_b32_e32 v25, 0, v25, vcc
	v_cmp_nlt_f32_e64 vcc, |v24|, s59
	s_nop 1
	v_cndmask_b32_e32 v43, v226, v25, vcc
	v_add_f32_e32 v44, 1.0, v43
	v_add_f32_e32 v24, -1.0, v44
	v_sub_f32_e32 v25, v24, v44
	v_add_f32_e32 v25, 1.0, v25
	v_sub_f32_e32 v24, v43, v24
	v_add_f32_e32 v45, v24, v25
	v_frexp_mant_f32_e32 v24, v44
	v_cmp_gt_f32_e32 vcc, s77, v24
	v_cvt_f64_f32_e32 v[24:25], v44
	v_frexp_exp_i32_f64_e32 v24, v[24:25]
	v_subbrev_co_u32_e32 v24, vcc, 0, v24, vcc
	v_sub_u32_e32 v25, 0, v24
	v_ldexp_f32 v44, v44, v25
	v_ldexp_f32 v25, v45, v25
	v_add_f32_e32 v45, -1.0, v44
	v_add_f32_e32 v46, 1.0, v45
	v_sub_f32_e32 v46, v44, v46
	v_add_f32_e32 v46, v25, v46
	v_add_f32_e32 v47, v45, v46
	v_sub_f32_e32 v45, v45, v47
	v_add_f32_e32 v45, v46, v45
	v_add_f32_e32 v46, 1.0, v44
	v_add_f32_e32 v48, -1.0, v46
	v_sub_f32_e32 v44, v44, v48
	v_add_f32_e32 v25, v25, v44
	v_add_f32_e32 v44, v46, v25
	v_sub_f32_e32 v46, v46, v44
	v_add_f32_e32 v25, v25, v46
	v_rcp_f32_e32 v46, v44
	v_cvt_f32_i32_e32 v24, v24
	v_cmp_neq_f32_e32 vcc, s62, v43
	v_mul_f32_e32 v48, v47, v46
	v_mul_f32_e32 v49, v44, v48
	v_fma_f32 v50, v48, v44, -v49
	v_fmac_f32_e32 v50, v48, v25
	v_add_f32_e32 v51, v49, v50
	v_sub_f32_e32 v52, v47, v51
	v_sub_f32_e32 v47, v47, v52
	v_sub_f32_e32 v49, v51, v49
	v_sub_f32_e32 v47, v47, v51
	v_add_f32_e32 v45, v45, v47
	v_sub_f32_e32 v47, v49, v50
	v_add_f32_e32 v45, v47, v45
	v_add_f32_e32 v47, v52, v45
	v_mul_f32_e32 v49, v46, v47
	v_mul_f32_e32 v50, v44, v49
	v_fma_f32 v44, v49, v44, -v50
	v_fmac_f32_e32 v44, v49, v25
	v_sub_f32_e32 v25, v52, v47
	v_add_f32_e32 v25, v45, v25
	v_add_f32_e32 v45, v50, v44
	v_sub_f32_e32 v51, v47, v45
	v_sub_f32_e32 v47, v47, v51
	v_sub_f32_e32 v50, v45, v50
	v_sub_f32_e32 v45, v47, v45
	v_add_f32_e32 v25, v25, v45
	v_sub_f32_e32 v44, v50, v44
	v_add_f32_e32 v25, v44, v25
	v_add_f32_e32 v44, v48, v49
	v_add_f32_e32 v25, v51, v25
	v_sub_f32_e32 v45, v44, v48
	v_mul_f32_e32 v25, v46, v25
	v_sub_f32_e32 v45, v49, v45
	v_add_f32_e32 v25, v45, v25
	v_mul_f32_e32 v48, 0x3f317218, v24
	v_add_f32_e32 v45, v44, v25
	v_fma_f32 v49, v24, s78, -v48
	v_mul_f32_e32 v46, v45, v45
	v_fmac_f32_e32 v49, 0xb102e308, v24
	v_sub_f32_e32 v24, v45, v44
	v_fmamk_f32 v47, v46, 0x3e9b6dac, v185
	v_sub_f32_e32 v24, v25, v24
	v_add_f32_e32 v25, v48, v49
	v_fmaak_f32 v47, v46, v47, 0x3f2aaada
	v_sub_f32_e32 v44, v25, v48
	v_ldexp_f32 v48, v45, 1
	v_mul_f32_e32 v45, v45, v46
	v_mul_f32_e32 v45, v45, v47
	v_add_f32_e32 v46, v48, v45
	v_sub_f32_e32 v47, v46, v48
	v_ldexp_f32 v24, v24, 1
	v_sub_f32_e32 v45, v45, v47
	v_add_f32_e32 v24, v24, v45
	v_add_f32_e32 v45, v46, v24
	v_sub_f32_e32 v46, v45, v46
	v_sub_f32_e32 v24, v24, v46
	v_add_f32_e32 v46, v25, v45
	v_sub_f32_e32 v47, v46, v25
	v_sub_f32_e32 v48, v46, v47
	v_sub_f32_e32 v44, v49, v44
	v_sub_f32_e32 v25, v25, v48
	v_sub_f32_e32 v45, v45, v47
	v_add_f32_e32 v25, v45, v25
	v_add_f32_e32 v45, v44, v24
	v_sub_f32_e32 v47, v45, v44
	v_sub_f32_e32 v48, v45, v47
	v_sub_f32_e32 v44, v44, v48
	v_sub_f32_e32 v24, v24, v47
	v_add_f32_e32 v25, v45, v25
	v_add_f32_e32 v24, v24, v44
	v_add_f32_e32 v44, v46, v25
	v_sub_f32_e32 v45, v44, v46
	v_sub_f32_e32 v25, v25, v45
	v_add_f32_e32 v24, v24, v25
	v_add_f32_e32 v24, v44, v24
	v_cndmask_b32_e32 v24, v226, v24, vcc
	v_cmp_lt_f32_e64 vcc, |v43|, s63
	s_nop 1
	v_cndmask_b32_e32 v24, v24, v43, vcc
	v_sub_f32_e32 v24, v39, v24
	v_mul_f32_e32 v39, 0x3fb8aa3b, v24
	v_or_b32_e32 v24, 5, v38
	v_ashrrev_i32_e32 v25, 31, v24
	v_lshlrev_b64 v[24:25], 14, v[24:25]
	v_lshl_add_u64 v[24:25], v[40:41], 0, v[24:25]
	global_store_dword v[24:25], v39, off
	v_readlane_b32 s100, v254, 6
	s_nop 1
	v_mov_b32_e32 v39, s100
	v_or_b32_e32 v38, 6, v38
	v_fmac_f32_e32 v39, v26, v162
	v_mul_f32_e64 v43, |v39|, s94
	v_fma_f32 v44, |v39|, s94, -v43
	v_rndne_f32_e32 v45, v43
	v_fma_f32 v44, |v39|, s64, v44
	v_sub_f32_e32 v43, v43, v45
	v_add_f32_e32 v43, v43, v44
	v_exp_f32_e32 v43, v43
	v_cvt_i32_f32_e32 v44, v45
	v_cmp_ngt_f32_e64 vcc, |v39|, s58
	v_min_f32_e32 v26, 0, v39
	v_ldexp_f32 v43, v43, v44
	v_cndmask_b32_e32 v43, 0, v43, vcc
	v_cmp_nlt_f32_e64 vcc, |v39|, s59
	s_nop 1
	v_cndmask_b32_e32 v39, v226, v43, vcc
	v_add_f32_e32 v43, 1.0, v39
	v_add_f32_e32 v44, -1.0, v43
	v_sub_f32_e32 v45, v44, v43
	v_add_f32_e32 v45, 1.0, v45
	v_sub_f32_e32 v44, v39, v44
	v_add_f32_e32 v46, v44, v45
	v_frexp_mant_f32_e32 v44, v43
	v_cmp_gt_f32_e32 vcc, s77, v44
	v_cvt_f64_f32_e32 v[44:45], v43
	v_frexp_exp_i32_f64_e32 v44, v[44:45]
	v_subbrev_co_u32_e32 v44, vcc, 0, v44, vcc
	v_sub_u32_e32 v45, 0, v44
	v_ldexp_f32 v43, v43, v45
	v_ldexp_f32 v45, v46, v45
	v_add_f32_e32 v46, -1.0, v43
	v_add_f32_e32 v47, 1.0, v46
	v_sub_f32_e32 v47, v43, v47
	v_add_f32_e32 v47, v45, v47
	v_add_f32_e32 v48, v46, v47
	v_sub_f32_e32 v46, v46, v48
	v_add_f32_e32 v46, v47, v46
	v_add_f32_e32 v47, 1.0, v43
	v_add_f32_e32 v49, -1.0, v47
	v_sub_f32_e32 v43, v43, v49
	v_add_f32_e32 v43, v45, v43
	v_add_f32_e32 v45, v47, v43
	v_sub_f32_e32 v47, v47, v45
	v_add_f32_e32 v43, v43, v47
	v_rcp_f32_e32 v47, v45
	v_cvt_f32_i32_e32 v44, v44
	v_cmp_neq_f32_e32 vcc, s62, v39
	v_mul_f32_e32 v49, v48, v47
	v_mul_f32_e32 v50, v45, v49
	v_fma_f32 v51, v49, v45, -v50
	v_fmac_f32_e32 v51, v49, v43
	v_add_f32_e32 v52, v50, v51
	v_sub_f32_e32 v53, v48, v52
	v_sub_f32_e32 v48, v48, v53
	v_sub_f32_e32 v50, v52, v50
	v_sub_f32_e32 v48, v48, v52
	v_add_f32_e32 v46, v46, v48
	v_sub_f32_e32 v48, v50, v51
	v_add_f32_e32 v46, v48, v46
	v_add_f32_e32 v48, v53, v46
	v_mul_f32_e32 v50, v47, v48
	v_mul_f32_e32 v51, v45, v50
	v_fma_f32 v45, v50, v45, -v51
	v_fmac_f32_e32 v45, v50, v43
	v_sub_f32_e32 v43, v53, v48
	v_add_f32_e32 v43, v46, v43
	v_add_f32_e32 v46, v51, v45
	v_sub_f32_e32 v52, v48, v46
	v_sub_f32_e32 v48, v48, v52
	v_sub_f32_e32 v51, v46, v51
	v_sub_f32_e32 v46, v48, v46
	v_add_f32_e32 v43, v43, v46
	v_sub_f32_e32 v45, v51, v45
	v_add_f32_e32 v43, v45, v43
	v_add_f32_e32 v45, v49, v50
	v_add_f32_e32 v43, v52, v43
	v_sub_f32_e32 v46, v45, v49
	v_mul_f32_e32 v43, v47, v43
	v_sub_f32_e32 v46, v50, v46
	v_add_f32_e32 v43, v46, v43
	v_mul_f32_e32 v49, 0x3f317218, v44
	v_add_f32_e32 v46, v45, v43
	v_fma_f32 v50, v44, s78, -v49
	v_mul_f32_e32 v47, v46, v46
	v_fmac_f32_e32 v50, 0xb102e308, v44
	v_sub_f32_e32 v44, v46, v45
	v_fmamk_f32 v48, v47, 0x3e9b6dac, v185
	v_sub_f32_e32 v43, v43, v44
	v_add_f32_e32 v44, v49, v50
	v_fmaak_f32 v48, v47, v48, 0x3f2aaada
	v_sub_f32_e32 v45, v44, v49
	v_ldexp_f32 v49, v46, 1
	v_mul_f32_e32 v46, v46, v47
	v_mul_f32_e32 v46, v46, v48
	v_add_f32_e32 v47, v49, v46
	v_sub_f32_e32 v48, v47, v49
	v_ldexp_f32 v43, v43, 1
	v_sub_f32_e32 v46, v46, v48
	v_add_f32_e32 v43, v43, v46
	v_add_f32_e32 v46, v47, v43
	v_sub_f32_e32 v47, v46, v47
	v_sub_f32_e32 v43, v43, v47
	v_add_f32_e32 v47, v44, v46
	v_sub_f32_e32 v48, v47, v44
	v_sub_f32_e32 v49, v47, v48
	v_sub_f32_e32 v45, v50, v45
	v_sub_f32_e32 v44, v44, v49
	v_sub_f32_e32 v46, v46, v48
	v_add_f32_e32 v44, v46, v44
	v_add_f32_e32 v46, v45, v43
	v_sub_f32_e32 v48, v46, v45
	v_sub_f32_e32 v49, v46, v48
	v_sub_f32_e32 v45, v45, v49
	v_sub_f32_e32 v43, v43, v48
	v_add_f32_e32 v44, v46, v44
	v_add_f32_e32 v43, v43, v45
	v_add_f32_e32 v45, v47, v44
	v_sub_f32_e32 v46, v45, v47
	v_sub_f32_e32 v44, v44, v46
	v_add_f32_e32 v43, v43, v44
	v_add_f32_e32 v43, v45, v43
	v_cndmask_b32_e32 v43, v226, v43, vcc
	v_cmp_lt_f32_e64 vcc, |v39|, s63
	s_nop 1
	v_cndmask_b32_e32 v39, v43, v39, vcc
	v_sub_f32_e32 v26, v26, v39
	v_ashrrev_i32_e32 v39, 31, v38
	v_lshlrev_b64 v[38:39], 14, v[38:39]
	v_mul_f32_e32 v26, 0x3fb8aa3b, v26
	v_lshl_add_u64 v[38:39], v[40:41], 0, v[38:39]
	global_store_dword v[38:39], v26, off
	v_readlane_b32 s100, v254, 7
	s_nop 1
	v_mov_b32_e32 v26, s100
	v_fmac_f32_e32 v26, v27, v162
	v_mul_f32_e64 v27, |v26|, s94
	v_fma_f32 v44, |v26|, s94, -v27
	v_rndne_f32_e32 v45, v27
	v_fma_f32 v44, |v26|, s64, v44
	v_sub_f32_e32 v27, v27, v45
	v_add_f32_e32 v27, v27, v44
	v_exp_f32_e32 v27, v27
	v_cvt_i32_f32_e32 v44, v45
	v_cmp_ngt_f32_e64 vcc, |v26|, s58
	v_min_f32_e32 v43, 0, v26
	v_ldexp_f32 v27, v27, v44
	v_cndmask_b32_e32 v27, 0, v27, vcc
	v_cmp_nlt_f32_e64 vcc, |v26|, s59
	s_nop 1
	v_cndmask_b32_e32 v44, v226, v27, vcc
	v_add_f32_e32 v45, 1.0, v44
	v_add_f32_e32 v26, -1.0, v45
	v_sub_f32_e32 v27, v26, v45
	v_add_f32_e32 v27, 1.0, v27
	v_sub_f32_e32 v26, v44, v26
	v_add_f32_e32 v46, v26, v27
	v_frexp_mant_f32_e32 v26, v45
	v_cmp_gt_f32_e32 vcc, s77, v26
	v_cvt_f64_f32_e32 v[26:27], v45
	v_frexp_exp_i32_f64_e32 v26, v[26:27]
	v_subbrev_co_u32_e32 v26, vcc, 0, v26, vcc
	v_sub_u32_e32 v27, 0, v26
	v_ldexp_f32 v45, v45, v27
	v_ldexp_f32 v27, v46, v27
	v_add_f32_e32 v46, -1.0, v45
	v_add_f32_e32 v47, 1.0, v46
	v_sub_f32_e32 v47, v45, v47
	v_add_f32_e32 v47, v27, v47
	v_add_f32_e32 v48, v46, v47
	v_sub_f32_e32 v46, v46, v48
	v_add_f32_e32 v46, v47, v46
	v_add_f32_e32 v47, 1.0, v45
	v_add_f32_e32 v49, -1.0, v47
	v_sub_f32_e32 v45, v45, v49
	v_add_f32_e32 v27, v27, v45
	v_add_f32_e32 v45, v47, v27
	v_sub_f32_e32 v47, v47, v45
	v_add_f32_e32 v27, v27, v47
	v_rcp_f32_e32 v47, v45
	v_cvt_f32_i32_e32 v26, v26
	v_cmp_neq_f32_e32 vcc, s62, v44
	v_mul_f32_e32 v49, v48, v47
	v_mul_f32_e32 v50, v45, v49
	v_fma_f32 v51, v49, v45, -v50
	v_fmac_f32_e32 v51, v49, v27
	v_add_f32_e32 v52, v50, v51
	v_sub_f32_e32 v53, v48, v52
	v_sub_f32_e32 v48, v48, v53
	v_sub_f32_e32 v50, v52, v50
	v_sub_f32_e32 v48, v48, v52
	v_add_f32_e32 v46, v46, v48
	v_sub_f32_e32 v48, v50, v51
	v_add_f32_e32 v46, v48, v46
	v_add_f32_e32 v48, v53, v46
	v_mul_f32_e32 v50, v47, v48
	v_mul_f32_e32 v51, v45, v50
	v_fma_f32 v45, v50, v45, -v51
	v_fmac_f32_e32 v45, v50, v27
	v_sub_f32_e32 v27, v53, v48
	v_add_f32_e32 v27, v46, v27
	v_add_f32_e32 v46, v51, v45
	v_sub_f32_e32 v52, v48, v46
	v_sub_f32_e32 v48, v48, v52
	v_sub_f32_e32 v51, v46, v51
	v_sub_f32_e32 v46, v48, v46
	v_add_f32_e32 v27, v27, v46
	v_sub_f32_e32 v45, v51, v45
	v_add_f32_e32 v27, v45, v27
	v_add_f32_e32 v45, v49, v50
	v_add_f32_e32 v27, v52, v27
	v_sub_f32_e32 v46, v45, v49
	v_mul_f32_e32 v27, v47, v27
	v_sub_f32_e32 v46, v50, v46
	v_add_f32_e32 v27, v46, v27
	v_mul_f32_e32 v49, 0x3f317218, v26
	v_add_f32_e32 v46, v45, v27
	v_fma_f32 v50, v26, s78, -v49
	v_mul_f32_e32 v47, v46, v46
	v_fmac_f32_e32 v50, 0xb102e308, v26
	v_sub_f32_e32 v26, v46, v45
	v_fmamk_f32 v48, v47, 0x3e9b6dac, v185
	v_sub_f32_e32 v26, v27, v26
	v_add_f32_e32 v27, v49, v50
	v_fmaak_f32 v48, v47, v48, 0x3f2aaada
	v_sub_f32_e32 v45, v27, v49
	v_ldexp_f32 v49, v46, 1
	v_mul_f32_e32 v46, v46, v47
	v_mul_f32_e32 v46, v46, v48
	v_add_f32_e32 v47, v49, v46
	v_sub_f32_e32 v48, v47, v49
	v_ldexp_f32 v26, v26, 1
	v_sub_f32_e32 v46, v46, v48
	v_add_f32_e32 v26, v26, v46
	v_add_f32_e32 v46, v47, v26
	v_sub_f32_e32 v47, v46, v47
	v_sub_f32_e32 v26, v26, v47
	v_add_f32_e32 v47, v27, v46
	v_sub_f32_e32 v48, v47, v27
	v_sub_f32_e32 v49, v47, v48
	v_sub_f32_e32 v45, v50, v45
	v_sub_f32_e32 v27, v27, v49
	v_sub_f32_e32 v46, v46, v48
	v_add_f32_e32 v27, v46, v27
	v_add_f32_e32 v46, v45, v26
	v_sub_f32_e32 v48, v46, v45
	v_sub_f32_e32 v49, v46, v48
	v_sub_f32_e32 v45, v45, v49
	v_sub_f32_e32 v26, v26, v48
	v_add_f32_e32 v27, v46, v27
	v_add_f32_e32 v26, v26, v45
	v_add_f32_e32 v45, v47, v27
	v_sub_f32_e32 v46, v45, v47
	v_sub_f32_e32 v27, v27, v46
	v_add_f32_e32 v26, v26, v27
	v_add_f32_e32 v26, v45, v26
	v_cndmask_b32_e32 v26, v226, v26, vcc
	v_cmp_lt_f32_e64 vcc, |v44|, s63
	s_nop 1
	v_cndmask_b32_e32 v26, v26, v44, vcc
	v_sub_f32_e32 v26, v43, v26
	v_mul_f32_e32 v43, 0x3fb8aa3b, v26
	v_or_b32_e32 v26, 7, v42
	v_ashrrev_i32_e32 v27, 31, v26
	v_lshlrev_b64 v[26:27], 14, v[26:27]
	v_lshl_add_u64 v[26:27], v[40:41], 0, v[26:27]
	global_store_dword v[26:27], v43, off
	v_readlane_b32 s100, v254, 0
	s_nop 1
	v_mov_b32_e32 v40, s100
	v_fmac_f32_e32 v40, v20, v160
	v_mul_f32_e64 v41, |v40|, s94
	v_fma_f32 v42, |v40|, s94, -v41
	v_rndne_f32_e32 v43, v41
	v_fma_f32 v42, |v40|, s64, v42
	v_sub_f32_e32 v41, v41, v43
	v_add_f32_e32 v41, v41, v42
	v_exp_f32_e32 v41, v41
	v_cvt_i32_f32_e32 v42, v43
	v_cmp_ngt_f32_e64 vcc, |v40|, s58
	v_min_f32_e32 v20, 0, v40
	v_ldexp_f32 v41, v41, v42
	v_cndmask_b32_e32 v41, 0, v41, vcc
	v_cmp_nlt_f32_e64 vcc, |v40|, s59
	s_nop 1
	v_cndmask_b32_e32 v40, v226, v41, vcc
	v_add_f32_e32 v41, 1.0, v40
	v_add_f32_e32 v42, -1.0, v41
	v_sub_f32_e32 v43, v42, v41
	v_add_f32_e32 v43, 1.0, v43
	v_sub_f32_e32 v42, v40, v42
	v_add_f32_e32 v44, v42, v43
	v_frexp_mant_f32_e32 v42, v41
	v_cmp_gt_f32_e32 vcc, s77, v42
	v_cvt_f64_f32_e32 v[42:43], v41
	v_frexp_exp_i32_f64_e32 v42, v[42:43]
	v_subbrev_co_u32_e32 v42, vcc, 0, v42, vcc
	v_sub_u32_e32 v43, 0, v42
	v_ldexp_f32 v41, v41, v43
	v_ldexp_f32 v43, v44, v43
	v_add_f32_e32 v44, -1.0, v41
	v_add_f32_e32 v45, 1.0, v44
	v_sub_f32_e32 v45, v41, v45
	v_add_f32_e32 v45, v43, v45
	v_add_f32_e32 v46, v44, v45
	v_sub_f32_e32 v44, v44, v46
	v_add_f32_e32 v44, v45, v44
	v_add_f32_e32 v45, 1.0, v41
	v_add_f32_e32 v47, -1.0, v45
	v_sub_f32_e32 v41, v41, v47
	v_add_f32_e32 v41, v43, v41
	v_add_f32_e32 v43, v45, v41
	v_sub_f32_e32 v45, v45, v43
	v_add_f32_e32 v41, v41, v45
	v_rcp_f32_e32 v45, v43
	v_cvt_f32_i32_e32 v42, v42
	v_cmp_neq_f32_e32 vcc, s62, v40
	v_mul_f32_e32 v47, v46, v45
	v_mul_f32_e32 v48, v43, v47
	v_fma_f32 v49, v47, v43, -v48
	v_fmac_f32_e32 v49, v47, v41
	v_add_f32_e32 v50, v48, v49
	v_sub_f32_e32 v51, v46, v50
	v_sub_f32_e32 v46, v46, v51
	v_sub_f32_e32 v48, v50, v48
	v_sub_f32_e32 v46, v46, v50
	v_add_f32_e32 v44, v44, v46
	v_sub_f32_e32 v46, v48, v49
	v_add_f32_e32 v44, v46, v44
	v_add_f32_e32 v46, v51, v44
	v_mul_f32_e32 v48, v45, v46
	v_mul_f32_e32 v49, v43, v48
	v_fma_f32 v43, v48, v43, -v49
	v_fmac_f32_e32 v43, v48, v41
	v_sub_f32_e32 v41, v51, v46
	v_add_f32_e32 v41, v44, v41
	v_add_f32_e32 v44, v49, v43
	v_sub_f32_e32 v50, v46, v44
	v_sub_f32_e32 v46, v46, v50
	v_sub_f32_e32 v49, v44, v49
	v_sub_f32_e32 v44, v46, v44
	v_add_f32_e32 v41, v41, v44
	v_sub_f32_e32 v43, v49, v43
	v_add_f32_e32 v41, v43, v41
	v_add_f32_e32 v43, v47, v48
	v_add_f32_e32 v41, v50, v41
	v_sub_f32_e32 v44, v43, v47
	v_mul_f32_e32 v41, v45, v41
	v_sub_f32_e32 v44, v48, v44
	v_add_f32_e32 v41, v44, v41
	v_mul_f32_e32 v47, 0x3f317218, v42
	v_add_f32_e32 v44, v43, v41
	v_fma_f32 v48, v42, s78, -v47
	v_mul_f32_e32 v45, v44, v44
	v_fmac_f32_e32 v48, 0xb102e308, v42
	v_sub_f32_e32 v42, v44, v43
	v_fmamk_f32 v46, v45, 0x3e9b6dac, v185
	v_sub_f32_e32 v41, v41, v42
	v_add_f32_e32 v42, v47, v48
	v_fmaak_f32 v46, v45, v46, 0x3f2aaada
	v_sub_f32_e32 v43, v42, v47
	v_ldexp_f32 v47, v44, 1
	v_mul_f32_e32 v44, v44, v45
	v_mul_f32_e32 v44, v44, v46
	v_add_f32_e32 v45, v47, v44
	v_sub_f32_e32 v46, v45, v47
	v_ldexp_f32 v41, v41, 1
	v_sub_f32_e32 v44, v44, v46
	v_add_f32_e32 v41, v41, v44
	v_add_f32_e32 v44, v45, v41
	v_sub_f32_e32 v45, v44, v45
	v_sub_f32_e32 v41, v41, v45
	v_add_f32_e32 v45, v42, v44
	v_sub_f32_e32 v46, v45, v42
	v_sub_f32_e32 v47, v45, v46
	v_sub_f32_e32 v43, v48, v43
	v_sub_f32_e32 v42, v42, v47
	v_sub_f32_e32 v44, v44, v46
	v_add_f32_e32 v42, v44, v42
	v_add_f32_e32 v44, v43, v41
	v_sub_f32_e32 v46, v44, v43
	v_sub_f32_e32 v47, v44, v46
	v_sub_f32_e32 v43, v43, v47
	v_sub_f32_e32 v41, v41, v46
	v_add_f32_e32 v42, v44, v42
	v_add_f32_e32 v41, v41, v43
	v_add_f32_e32 v43, v45, v42
	v_sub_f32_e32 v44, v43, v45
	v_sub_f32_e32 v42, v42, v44
	v_add_f32_e32 v41, v41, v42
	v_add_f32_e32 v41, v43, v41
	v_cndmask_b32_e32 v41, v226, v41, vcc
	v_cmp_lt_f32_e64 vcc, |v40|, s63
	s_nop 1
	v_cndmask_b32_e32 v40, v41, v40, vcc
	v_sub_f32_e32 v20, v20, v40
	v_mul_f32_e32 v20, 0x3fb8aa3b, v20
	global_store_dword v[32:33], v20, off offset:64
	v_readlane_b32 s100, v254, 1
	s_nop 1
	v_mov_b32_e32 v40, s100
	v_fmac_f32_e32 v40, v21, v160
	v_mul_f32_e64 v21, |v40|, s94
	v_fma_f32 v41, |v40|, s94, -v21
	v_rndne_f32_e32 v42, v21
	v_fma_f32 v41, |v40|, s64, v41
	v_sub_f32_e32 v21, v21, v42
	v_add_f32_e32 v21, v21, v41
	v_exp_f32_e32 v21, v21
	v_cvt_i32_f32_e32 v41, v42
	v_cmp_ngt_f32_e64 vcc, |v40|, s58
	v_min_f32_e32 v20, 0, v40
	v_ldexp_f32 v21, v21, v41
	v_cndmask_b32_e32 v21, 0, v21, vcc
	v_cmp_nlt_f32_e64 vcc, |v40|, s59
	s_nop 1
	v_cndmask_b32_e32 v21, v226, v21, vcc
	v_add_f32_e32 v42, 1.0, v21
	v_add_f32_e32 v40, -1.0, v42
	v_sub_f32_e32 v41, v40, v42
	v_add_f32_e32 v41, 1.0, v41
	v_sub_f32_e32 v40, v21, v40
	v_add_f32_e32 v43, v40, v41
	v_frexp_mant_f32_e32 v40, v42
	v_cmp_gt_f32_e32 vcc, s77, v40
	v_cvt_f64_f32_e32 v[40:41], v42
	v_frexp_exp_i32_f64_e32 v40, v[40:41]
	v_subbrev_co_u32_e32 v40, vcc, 0, v40, vcc
	v_sub_u32_e32 v41, 0, v40
	v_ldexp_f32 v42, v42, v41
	v_ldexp_f32 v41, v43, v41
	v_add_f32_e32 v43, -1.0, v42
	v_add_f32_e32 v44, 1.0, v43
	v_sub_f32_e32 v44, v42, v44
	v_add_f32_e32 v44, v41, v44
	v_add_f32_e32 v45, v43, v44
	v_sub_f32_e32 v43, v43, v45
	v_add_f32_e32 v43, v44, v43
	v_add_f32_e32 v44, 1.0, v42
	v_add_f32_e32 v46, -1.0, v44
	v_sub_f32_e32 v42, v42, v46
	v_add_f32_e32 v41, v41, v42
	v_add_f32_e32 v42, v44, v41
	v_sub_f32_e32 v44, v44, v42
	v_add_f32_e32 v41, v41, v44
	v_rcp_f32_e32 v44, v42
	v_cvt_f32_i32_e32 v40, v40
	v_cmp_neq_f32_e32 vcc, s62, v21
	v_mul_f32_e32 v46, v45, v44
	v_mul_f32_e32 v47, v42, v46
	v_fma_f32 v48, v46, v42, -v47
	v_fmac_f32_e32 v48, v46, v41
	v_add_f32_e32 v49, v47, v48
	v_sub_f32_e32 v50, v45, v49
	v_sub_f32_e32 v45, v45, v50
	v_sub_f32_e32 v47, v49, v47
	v_sub_f32_e32 v45, v45, v49
	v_add_f32_e32 v43, v43, v45
	v_sub_f32_e32 v45, v47, v48
	v_add_f32_e32 v43, v45, v43
	v_add_f32_e32 v45, v50, v43
	v_mul_f32_e32 v47, v44, v45
	v_mul_f32_e32 v48, v42, v47
	v_fma_f32 v42, v47, v42, -v48
	v_fmac_f32_e32 v42, v47, v41
	v_sub_f32_e32 v41, v50, v45
	v_add_f32_e32 v41, v43, v41
	v_add_f32_e32 v43, v48, v42
	v_sub_f32_e32 v49, v45, v43
	v_sub_f32_e32 v45, v45, v49
	v_sub_f32_e32 v48, v43, v48
	v_sub_f32_e32 v43, v45, v43
	v_add_f32_e32 v41, v41, v43
	v_sub_f32_e32 v42, v48, v42
	v_add_f32_e32 v41, v42, v41
	v_add_f32_e32 v42, v46, v47
	v_add_f32_e32 v41, v49, v41
	v_sub_f32_e32 v43, v42, v46
	v_mul_f32_e32 v41, v44, v41
	v_sub_f32_e32 v43, v47, v43
	v_add_f32_e32 v41, v43, v41
	v_mul_f32_e32 v46, 0x3f317218, v40
	v_add_f32_e32 v43, v42, v41
	v_fma_f32 v47, v40, s78, -v46
	v_mul_f32_e32 v44, v43, v43
	v_fmac_f32_e32 v47, 0xb102e308, v40
	v_sub_f32_e32 v40, v43, v42
	v_fmamk_f32 v45, v44, 0x3e9b6dac, v185
	v_sub_f32_e32 v40, v41, v40
	v_add_f32_e32 v41, v46, v47
	v_fmaak_f32 v45, v44, v45, 0x3f2aaada
	v_sub_f32_e32 v42, v41, v46
	v_ldexp_f32 v46, v43, 1
	v_mul_f32_e32 v43, v43, v44
	v_mul_f32_e32 v43, v43, v45
	v_add_f32_e32 v44, v46, v43
	v_sub_f32_e32 v45, v44, v46
	v_ldexp_f32 v40, v40, 1
	v_sub_f32_e32 v43, v43, v45
	v_add_f32_e32 v40, v40, v43
	v_add_f32_e32 v43, v44, v40
	v_sub_f32_e32 v44, v43, v44
	v_sub_f32_e32 v40, v40, v44
	v_add_f32_e32 v44, v41, v43
	v_sub_f32_e32 v45, v44, v41
	v_sub_f32_e32 v46, v44, v45
	v_sub_f32_e32 v42, v47, v42
	v_sub_f32_e32 v41, v41, v46
	v_sub_f32_e32 v43, v43, v45
	v_add_f32_e32 v41, v43, v41
	v_add_f32_e32 v43, v42, v40
	v_sub_f32_e32 v45, v43, v42
	v_sub_f32_e32 v46, v43, v45
	v_sub_f32_e32 v42, v42, v46
	v_sub_f32_e32 v40, v40, v45
	v_add_f32_e32 v41, v43, v41
	v_add_f32_e32 v40, v40, v42
	v_add_f32_e32 v42, v44, v41
	v_sub_f32_e32 v43, v42, v44
	v_sub_f32_e32 v41, v41, v43
	v_add_f32_e32 v40, v40, v41
	v_add_f32_e32 v40, v42, v40
	v_cndmask_b32_e32 v40, v226, v40, vcc
	v_cmp_lt_f32_e64 vcc, |v21|, s63
	s_nop 1
	v_cndmask_b32_e32 v21, v40, v21, vcc
	v_sub_f32_e32 v20, v20, v21
	v_mul_f32_e32 v20, 0x3fb8aa3b, v20
	global_store_dword v[28:29], v20, off offset:64
	v_readlane_b32 s100, v254, 2
	s_nop 1
	v_mov_b32_e32 v21, s100
	v_fmac_f32_e32 v21, v22, v160
	v_mul_f32_e64 v22, |v21|, s94
	v_fma_f32 v40, |v21|, s94, -v22
	v_rndne_f32_e32 v41, v22
	v_fma_f32 v40, |v21|, s64, v40
	v_sub_f32_e32 v22, v22, v41
	v_add_f32_e32 v22, v22, v40
	v_exp_f32_e32 v22, v22
	v_cvt_i32_f32_e32 v40, v41
	v_cmp_ngt_f32_e64 vcc, |v21|, s58
	v_min_f32_e32 v20, 0, v21
	v_ldexp_f32 v22, v22, v40
	v_cndmask_b32_e32 v22, 0, v22, vcc
	v_cmp_nlt_f32_e64 vcc, |v21|, s59
	s_nop 1
	v_cndmask_b32_e32 v21, v226, v22, vcc
	v_add_f32_e32 v22, 1.0, v21
	v_add_f32_e32 v40, -1.0, v22
	v_sub_f32_e32 v41, v40, v22
	v_add_f32_e32 v41, 1.0, v41
	v_sub_f32_e32 v40, v21, v40
	v_add_f32_e32 v42, v40, v41
	v_frexp_mant_f32_e32 v40, v22
	v_cmp_gt_f32_e32 vcc, s77, v40
	v_cvt_f64_f32_e32 v[40:41], v22
	v_frexp_exp_i32_f64_e32 v40, v[40:41]
	v_subbrev_co_u32_e32 v40, vcc, 0, v40, vcc
	v_sub_u32_e32 v41, 0, v40
	v_ldexp_f32 v22, v22, v41
	v_ldexp_f32 v41, v42, v41
	v_add_f32_e32 v42, -1.0, v22
	v_add_f32_e32 v43, 1.0, v42
	v_sub_f32_e32 v43, v22, v43
	v_add_f32_e32 v43, v41, v43
	v_add_f32_e32 v44, v42, v43
	v_sub_f32_e32 v42, v42, v44
	v_add_f32_e32 v42, v43, v42
	v_add_f32_e32 v43, 1.0, v22
	v_add_f32_e32 v45, -1.0, v43
	v_sub_f32_e32 v22, v22, v45
	v_add_f32_e32 v22, v41, v22
	v_add_f32_e32 v41, v43, v22
	v_sub_f32_e32 v43, v43, v41
	v_add_f32_e32 v22, v22, v43
	v_rcp_f32_e32 v43, v41
	v_cvt_f32_i32_e32 v40, v40
	v_cmp_neq_f32_e32 vcc, s62, v21
	v_mul_f32_e32 v45, v44, v43
	v_mul_f32_e32 v46, v41, v45
	v_fma_f32 v47, v45, v41, -v46
	v_fmac_f32_e32 v47, v45, v22
	v_add_f32_e32 v48, v46, v47
	v_sub_f32_e32 v49, v44, v48
	v_sub_f32_e32 v44, v44, v49
	v_sub_f32_e32 v46, v48, v46
	v_sub_f32_e32 v44, v44, v48
	v_add_f32_e32 v42, v42, v44
	v_sub_f32_e32 v44, v46, v47
	v_add_f32_e32 v42, v44, v42
	v_add_f32_e32 v44, v49, v42
	v_mul_f32_e32 v46, v43, v44
	v_mul_f32_e32 v47, v41, v46
	v_fma_f32 v41, v46, v41, -v47
	v_fmac_f32_e32 v41, v46, v22
	v_sub_f32_e32 v22, v49, v44
	v_add_f32_e32 v22, v42, v22
	v_add_f32_e32 v42, v47, v41
	v_sub_f32_e32 v48, v44, v42
	v_sub_f32_e32 v44, v44, v48
	v_sub_f32_e32 v47, v42, v47
	v_sub_f32_e32 v42, v44, v42
	v_add_f32_e32 v22, v22, v42
	v_sub_f32_e32 v41, v47, v41
	v_add_f32_e32 v22, v41, v22
	v_add_f32_e32 v41, v45, v46
	v_add_f32_e32 v22, v48, v22
	v_sub_f32_e32 v42, v41, v45
	v_mul_f32_e32 v22, v43, v22
	v_sub_f32_e32 v42, v46, v42
	v_add_f32_e32 v22, v42, v22
	v_mul_f32_e32 v45, 0x3f317218, v40
	v_add_f32_e32 v42, v41, v22
	v_fma_f32 v46, v40, s78, -v45
	v_mul_f32_e32 v43, v42, v42
	v_fmac_f32_e32 v46, 0xb102e308, v40
	v_sub_f32_e32 v40, v42, v41
	v_fmamk_f32 v44, v43, 0x3e9b6dac, v185
	v_sub_f32_e32 v22, v22, v40
	v_add_f32_e32 v40, v45, v46
	v_fmaak_f32 v44, v43, v44, 0x3f2aaada
	v_sub_f32_e32 v41, v40, v45
	v_ldexp_f32 v45, v42, 1
	v_mul_f32_e32 v42, v42, v43
	v_mul_f32_e32 v42, v42, v44
	v_add_f32_e32 v43, v45, v42
	v_sub_f32_e32 v44, v43, v45
	v_ldexp_f32 v22, v22, 1
	v_sub_f32_e32 v42, v42, v44
	v_add_f32_e32 v22, v22, v42
	v_add_f32_e32 v42, v43, v22
	v_sub_f32_e32 v43, v42, v43
	v_sub_f32_e32 v22, v22, v43
	v_add_f32_e32 v43, v40, v42
	v_sub_f32_e32 v44, v43, v40
	v_sub_f32_e32 v45, v43, v44
	v_sub_f32_e32 v41, v46, v41
	v_sub_f32_e32 v40, v40, v45
	v_sub_f32_e32 v42, v42, v44
	v_add_f32_e32 v40, v42, v40
	v_add_f32_e32 v42, v41, v22
	v_sub_f32_e32 v44, v42, v41
	v_sub_f32_e32 v45, v42, v44
	v_sub_f32_e32 v41, v41, v45
	v_sub_f32_e32 v22, v22, v44
	v_add_f32_e32 v40, v42, v40
	v_add_f32_e32 v22, v22, v41
	v_add_f32_e32 v41, v43, v40
	v_sub_f32_e32 v42, v41, v43
	v_sub_f32_e32 v40, v40, v42
	v_add_f32_e32 v22, v22, v40
	v_add_f32_e32 v22, v41, v22
	v_cndmask_b32_e32 v22, v226, v22, vcc
	v_cmp_lt_f32_e64 vcc, |v21|, s63
	s_nop 1
	v_cndmask_b32_e32 v21, v22, v21, vcc
	v_sub_f32_e32 v20, v20, v21
	v_mul_f32_e32 v20, 0x3fb8aa3b, v20
	global_store_dword v[34:35], v20, off offset:64
	v_readlane_b32 s100, v254, 3
	s_nop 1
	v_mov_b32_e32 v21, s100
	v_fmac_f32_e32 v21, v23, v160
	v_mul_f32_e64 v22, |v21|, s94
	v_fma_f32 v23, |v21|, s94, -v22
	v_rndne_f32_e32 v40, v22
	v_fma_f32 v23, |v21|, s64, v23
	v_sub_f32_e32 v22, v22, v40
	v_add_f32_e32 v22, v22, v23
	v_exp_f32_e32 v22, v22
	v_cvt_i32_f32_e32 v23, v40
	v_cmp_ngt_f32_e64 vcc, |v21|, s58
	v_min_f32_e32 v20, 0, v21
	v_ldexp_f32 v22, v22, v23
	v_cndmask_b32_e32 v22, 0, v22, vcc
	v_cmp_nlt_f32_e64 vcc, |v21|, s59
	s_nop 1
	v_cndmask_b32_e32 v21, v226, v22, vcc
	v_add_f32_e32 v40, 1.0, v21
	v_add_f32_e32 v22, -1.0, v40
	v_sub_f32_e32 v23, v22, v40
	v_add_f32_e32 v23, 1.0, v23
	v_sub_f32_e32 v22, v21, v22
	v_add_f32_e32 v41, v22, v23
	v_frexp_mant_f32_e32 v22, v40
	v_cmp_gt_f32_e32 vcc, s77, v22
	v_cvt_f64_f32_e32 v[22:23], v40
	v_frexp_exp_i32_f64_e32 v22, v[22:23]
	v_subbrev_co_u32_e32 v22, vcc, 0, v22, vcc
	v_sub_u32_e32 v23, 0, v22
	v_ldexp_f32 v40, v40, v23
	v_ldexp_f32 v23, v41, v23
	v_add_f32_e32 v41, -1.0, v40
	v_add_f32_e32 v42, 1.0, v41
	v_sub_f32_e32 v42, v40, v42
	v_add_f32_e32 v42, v23, v42
	v_add_f32_e32 v43, v41, v42
	v_sub_f32_e32 v41, v41, v43
	v_add_f32_e32 v41, v42, v41
	v_add_f32_e32 v42, 1.0, v40
	v_add_f32_e32 v44, -1.0, v42
	v_sub_f32_e32 v40, v40, v44
	v_add_f32_e32 v23, v23, v40
	v_add_f32_e32 v40, v42, v23
	v_sub_f32_e32 v42, v42, v40
	v_add_f32_e32 v23, v23, v42
	v_rcp_f32_e32 v42, v40
	v_cvt_f32_i32_e32 v22, v22
	v_cmp_neq_f32_e32 vcc, s62, v21
	v_mul_f32_e32 v44, v43, v42
	v_mul_f32_e32 v45, v40, v44
	v_fma_f32 v46, v44, v40, -v45
	v_fmac_f32_e32 v46, v44, v23
	v_add_f32_e32 v47, v45, v46
	v_sub_f32_e32 v48, v43, v47
	v_sub_f32_e32 v43, v43, v48
	v_sub_f32_e32 v45, v47, v45
	v_sub_f32_e32 v43, v43, v47
	v_add_f32_e32 v41, v41, v43
	v_sub_f32_e32 v43, v45, v46
	v_add_f32_e32 v41, v43, v41
	v_add_f32_e32 v43, v48, v41
	v_mul_f32_e32 v45, v42, v43
	v_mul_f32_e32 v46, v40, v45
	v_fma_f32 v40, v45, v40, -v46
	v_fmac_f32_e32 v40, v45, v23
	v_sub_f32_e32 v23, v48, v43
	v_add_f32_e32 v23, v41, v23
	v_add_f32_e32 v41, v46, v40
	v_sub_f32_e32 v47, v43, v41
	v_sub_f32_e32 v43, v43, v47
	v_sub_f32_e32 v46, v41, v46
	v_sub_f32_e32 v41, v43, v41
	v_add_f32_e32 v23, v23, v41
	v_sub_f32_e32 v40, v46, v40
	v_add_f32_e32 v23, v40, v23
	v_add_f32_e32 v40, v44, v45
	v_add_f32_e32 v23, v47, v23
	v_sub_f32_e32 v41, v40, v44
	v_mul_f32_e32 v23, v42, v23
	v_sub_f32_e32 v41, v45, v41
	v_add_f32_e32 v23, v41, v23
	v_mul_f32_e32 v44, 0x3f317218, v22
	v_add_f32_e32 v41, v40, v23
	v_fma_f32 v45, v22, s78, -v44
	v_mul_f32_e32 v42, v41, v41
	v_fmac_f32_e32 v45, 0xb102e308, v22
	v_sub_f32_e32 v22, v41, v40
	v_fmamk_f32 v43, v42, 0x3e9b6dac, v185
	v_sub_f32_e32 v22, v23, v22
	v_add_f32_e32 v23, v44, v45
	v_fmaak_f32 v43, v42, v43, 0x3f2aaada
	v_sub_f32_e32 v40, v23, v44
	v_ldexp_f32 v44, v41, 1
	v_mul_f32_e32 v41, v41, v42
	v_mul_f32_e32 v41, v41, v43
	v_add_f32_e32 v42, v44, v41
	v_sub_f32_e32 v43, v42, v44
	v_ldexp_f32 v22, v22, 1
	v_sub_f32_e32 v41, v41, v43
	v_add_f32_e32 v22, v22, v41
	v_add_f32_e32 v41, v42, v22
	v_sub_f32_e32 v42, v41, v42
	v_sub_f32_e32 v22, v22, v42
	v_add_f32_e32 v42, v23, v41
	v_sub_f32_e32 v43, v42, v23
	v_sub_f32_e32 v44, v42, v43
	v_sub_f32_e32 v40, v45, v40
	v_sub_f32_e32 v23, v23, v44
	v_sub_f32_e32 v41, v41, v43
	v_add_f32_e32 v23, v41, v23
	v_add_f32_e32 v41, v40, v22
	v_sub_f32_e32 v43, v41, v40
	v_sub_f32_e32 v44, v41, v43
	v_sub_f32_e32 v40, v40, v44
	v_sub_f32_e32 v22, v22, v43
	v_add_f32_e32 v23, v41, v23
	v_add_f32_e32 v22, v22, v40
	v_add_f32_e32 v40, v42, v23
	v_sub_f32_e32 v41, v40, v42
	v_sub_f32_e32 v23, v23, v41
	v_add_f32_e32 v22, v22, v23
	v_add_f32_e32 v22, v40, v22
	v_cndmask_b32_e32 v22, v226, v22, vcc
	v_cmp_lt_f32_e64 vcc, |v21|, s63
	s_nop 1
	v_cndmask_b32_e32 v21, v22, v21, vcc
	v_sub_f32_e32 v20, v20, v21
	v_mul_f32_e32 v20, 0x3fb8aa3b, v20
	global_store_dword v[30:31], v20, off offset:64
	v_readlane_b32 s100, v254, 4
	s_nop 1
	v_mov_b32_e32 v20, s100
	v_fmac_f32_e32 v20, v16, v160
	v_mul_f32_e64 v21, |v20|, s94
	v_fma_f32 v22, |v20|, s94, -v21
	v_rndne_f32_e32 v23, v21
	v_fma_f32 v22, |v20|, s64, v22
	v_sub_f32_e32 v21, v21, v23
	v_add_f32_e32 v21, v21, v22
	v_exp_f32_e32 v21, v21
	v_cvt_i32_f32_e32 v22, v23
	v_cmp_ngt_f32_e64 vcc, |v20|, s58
	v_min_f32_e32 v16, 0, v20
	v_ldexp_f32 v21, v21, v22
	v_cndmask_b32_e32 v21, 0, v21, vcc
	v_cmp_nlt_f32_e64 vcc, |v20|, s59
	s_nop 1
	v_cndmask_b32_e32 v20, v226, v21, vcc
	v_add_f32_e32 v21, 1.0, v20
	v_add_f32_e32 v22, -1.0, v21
	v_sub_f32_e32 v23, v22, v21
	v_add_f32_e32 v23, 1.0, v23
	v_sub_f32_e32 v22, v20, v22
	v_add_f32_e32 v40, v22, v23
	v_frexp_mant_f32_e32 v22, v21
	v_cmp_gt_f32_e32 vcc, s77, v22
	v_cvt_f64_f32_e32 v[22:23], v21
	v_frexp_exp_i32_f64_e32 v22, v[22:23]
	v_subbrev_co_u32_e32 v22, vcc, 0, v22, vcc
	v_sub_u32_e32 v23, 0, v22
	v_ldexp_f32 v21, v21, v23
	v_ldexp_f32 v23, v40, v23
	v_add_f32_e32 v40, -1.0, v21
	v_add_f32_e32 v41, 1.0, v40
	v_sub_f32_e32 v41, v21, v41
	v_add_f32_e32 v41, v23, v41
	v_add_f32_e32 v42, v40, v41
	v_sub_f32_e32 v40, v40, v42
	v_add_f32_e32 v40, v41, v40
	v_add_f32_e32 v41, 1.0, v21
	v_add_f32_e32 v43, -1.0, v41
	v_sub_f32_e32 v21, v21, v43
	v_add_f32_e32 v21, v23, v21
	v_add_f32_e32 v23, v41, v21
	v_sub_f32_e32 v41, v41, v23
	v_add_f32_e32 v21, v21, v41
	v_rcp_f32_e32 v41, v23
	v_cvt_f32_i32_e32 v22, v22
	v_cmp_neq_f32_e32 vcc, s62, v20
	v_mul_f32_e32 v43, v42, v41
	v_mul_f32_e32 v44, v23, v43
	v_fma_f32 v45, v43, v23, -v44
	v_fmac_f32_e32 v45, v43, v21
	v_add_f32_e32 v46, v44, v45
	v_sub_f32_e32 v47, v42, v46
	v_sub_f32_e32 v42, v42, v47
	v_sub_f32_e32 v44, v46, v44
	v_sub_f32_e32 v42, v42, v46
	v_add_f32_e32 v40, v40, v42
	v_sub_f32_e32 v42, v44, v45
	v_add_f32_e32 v40, v42, v40
	v_add_f32_e32 v42, v47, v40
	v_mul_f32_e32 v44, v41, v42
	v_mul_f32_e32 v45, v23, v44
	v_fma_f32 v23, v44, v23, -v45
	v_fmac_f32_e32 v23, v44, v21
	v_sub_f32_e32 v21, v47, v42
	v_add_f32_e32 v21, v40, v21
	v_add_f32_e32 v40, v45, v23
	v_sub_f32_e32 v46, v42, v40
	v_sub_f32_e32 v42, v42, v46
	v_sub_f32_e32 v45, v40, v45
	v_sub_f32_e32 v40, v42, v40
	v_add_f32_e32 v21, v21, v40
	v_sub_f32_e32 v23, v45, v23
	v_add_f32_e32 v21, v23, v21
	v_add_f32_e32 v23, v43, v44
	v_add_f32_e32 v21, v46, v21
	v_sub_f32_e32 v40, v23, v43
	v_mul_f32_e32 v21, v41, v21
	v_sub_f32_e32 v40, v44, v40
	v_add_f32_e32 v21, v40, v21
	v_mul_f32_e32 v43, 0x3f317218, v22
	v_add_f32_e32 v40, v23, v21
	v_fma_f32 v44, v22, s78, -v43
	v_mul_f32_e32 v41, v40, v40
	v_fmac_f32_e32 v44, 0xb102e308, v22
	v_sub_f32_e32 v22, v40, v23
	v_fmamk_f32 v42, v41, 0x3e9b6dac, v185
	v_sub_f32_e32 v21, v21, v22
	v_add_f32_e32 v22, v43, v44
	v_fmaak_f32 v42, v41, v42, 0x3f2aaada
	v_sub_f32_e32 v23, v22, v43
	v_ldexp_f32 v43, v40, 1
	v_mul_f32_e32 v40, v40, v41
	v_mul_f32_e32 v40, v40, v42
	v_add_f32_e32 v41, v43, v40
	v_sub_f32_e32 v42, v41, v43
	v_ldexp_f32 v21, v21, 1
	v_sub_f32_e32 v40, v40, v42
	v_add_f32_e32 v21, v21, v40
	v_add_f32_e32 v40, v41, v21
	v_sub_f32_e32 v41, v40, v41
	v_sub_f32_e32 v21, v21, v41
	v_add_f32_e32 v41, v22, v40
	v_sub_f32_e32 v42, v41, v22
	v_sub_f32_e32 v43, v41, v42
	v_sub_f32_e32 v23, v44, v23
	v_sub_f32_e32 v22, v22, v43
	v_sub_f32_e32 v40, v40, v42
	v_add_f32_e32 v22, v40, v22
	v_add_f32_e32 v40, v23, v21
	v_sub_f32_e32 v42, v40, v23
	v_sub_f32_e32 v43, v40, v42
	v_sub_f32_e32 v23, v23, v43
	v_sub_f32_e32 v21, v21, v42
	v_add_f32_e32 v22, v40, v22
	v_add_f32_e32 v21, v21, v23
	v_add_f32_e32 v23, v41, v22
	v_sub_f32_e32 v40, v23, v41
	v_sub_f32_e32 v22, v22, v40
	v_add_f32_e32 v21, v21, v22
	v_add_f32_e32 v21, v23, v21
	v_cndmask_b32_e32 v21, v226, v21, vcc
	v_cmp_lt_f32_e64 vcc, |v20|, s63
	s_nop 1
	v_cndmask_b32_e32 v20, v21, v20, vcc
	v_sub_f32_e32 v16, v16, v20
	v_mul_f32_e32 v16, 0x3fb8aa3b, v16
	global_store_dword v[36:37], v16, off offset:64
	v_readlane_b32 s100, v254, 5
	s_nop 1
	v_mov_b32_e32 v20, s100
	v_fmac_f32_e32 v20, v17, v160
	v_mul_f32_e64 v17, |v20|, s94
	v_fma_f32 v21, |v20|, s94, -v17
	v_rndne_f32_e32 v22, v17
	v_fma_f32 v21, |v20|, s64, v21
	v_sub_f32_e32 v17, v17, v22
	v_add_f32_e32 v17, v17, v21
	v_exp_f32_e32 v17, v17
	v_cvt_i32_f32_e32 v21, v22
	v_cmp_ngt_f32_e64 vcc, |v20|, s58
	v_min_f32_e32 v16, 0, v20
	v_ldexp_f32 v17, v17, v21
	v_cndmask_b32_e32 v17, 0, v17, vcc
	v_cmp_nlt_f32_e64 vcc, |v20|, s59
	s_nop 1
	v_cndmask_b32_e32 v17, v226, v17, vcc
	v_add_f32_e32 v22, 1.0, v17
	v_add_f32_e32 v20, -1.0, v22
	v_sub_f32_e32 v21, v20, v22
	v_add_f32_e32 v21, 1.0, v21
	v_sub_f32_e32 v20, v17, v20
	v_add_f32_e32 v23, v20, v21
	v_frexp_mant_f32_e32 v20, v22
	v_cmp_gt_f32_e32 vcc, s77, v20
	v_cvt_f64_f32_e32 v[20:21], v22
	v_frexp_exp_i32_f64_e32 v20, v[20:21]
	v_subbrev_co_u32_e32 v20, vcc, 0, v20, vcc
	v_sub_u32_e32 v21, 0, v20
	v_ldexp_f32 v22, v22, v21
	v_ldexp_f32 v21, v23, v21
	v_add_f32_e32 v23, -1.0, v22
	v_add_f32_e32 v40, 1.0, v23
	v_sub_f32_e32 v40, v22, v40
	v_add_f32_e32 v40, v21, v40
	v_add_f32_e32 v41, v23, v40
	v_sub_f32_e32 v23, v23, v41
	v_add_f32_e32 v23, v40, v23
	v_add_f32_e32 v40, 1.0, v22
	v_add_f32_e32 v42, -1.0, v40
	v_sub_f32_e32 v22, v22, v42
	v_add_f32_e32 v21, v21, v22
	v_add_f32_e32 v22, v40, v21
	v_sub_f32_e32 v40, v40, v22
	v_add_f32_e32 v21, v21, v40
	v_rcp_f32_e32 v40, v22
	v_cvt_f32_i32_e32 v20, v20
	v_cmp_neq_f32_e32 vcc, s62, v17
	v_mul_f32_e32 v42, v41, v40
	v_mul_f32_e32 v43, v22, v42
	v_fma_f32 v44, v42, v22, -v43
	v_fmac_f32_e32 v44, v42, v21
	v_add_f32_e32 v45, v43, v44
	v_sub_f32_e32 v46, v41, v45
	v_sub_f32_e32 v41, v41, v46
	v_sub_f32_e32 v43, v45, v43
	v_sub_f32_e32 v41, v41, v45
	v_add_f32_e32 v23, v23, v41
	v_sub_f32_e32 v41, v43, v44
	v_add_f32_e32 v23, v41, v23
	v_add_f32_e32 v41, v46, v23
	v_mul_f32_e32 v43, v40, v41
	v_mul_f32_e32 v44, v22, v43
	v_fma_f32 v22, v43, v22, -v44
	v_fmac_f32_e32 v22, v43, v21
	v_sub_f32_e32 v21, v46, v41
	v_add_f32_e32 v21, v23, v21
	v_add_f32_e32 v23, v44, v22
	v_sub_f32_e32 v45, v41, v23
	v_sub_f32_e32 v41, v41, v45
	v_sub_f32_e32 v44, v23, v44
	v_sub_f32_e32 v23, v41, v23
	v_add_f32_e32 v21, v21, v23
	v_sub_f32_e32 v22, v44, v22
	v_add_f32_e32 v21, v22, v21
	v_add_f32_e32 v22, v42, v43
	v_add_f32_e32 v21, v45, v21
	v_sub_f32_e32 v23, v22, v42
	v_mul_f32_e32 v21, v40, v21
	v_sub_f32_e32 v23, v43, v23
	v_add_f32_e32 v21, v23, v21
	v_mul_f32_e32 v42, 0x3f317218, v20
	v_add_f32_e32 v23, v22, v21
	v_fma_f32 v43, v20, s78, -v42
	v_mul_f32_e32 v40, v23, v23
	v_fmac_f32_e32 v43, 0xb102e308, v20
	v_sub_f32_e32 v20, v23, v22
	v_fmamk_f32 v41, v40, 0x3e9b6dac, v185
	v_sub_f32_e32 v20, v21, v20
	v_add_f32_e32 v21, v42, v43
	v_fmaak_f32 v41, v40, v41, 0x3f2aaada
	v_sub_f32_e32 v22, v21, v42
	v_ldexp_f32 v42, v23, 1
	v_mul_f32_e32 v23, v23, v40
	v_mul_f32_e32 v23, v23, v41
	v_add_f32_e32 v40, v42, v23
	v_sub_f32_e32 v41, v40, v42
	v_ldexp_f32 v20, v20, 1
	v_sub_f32_e32 v23, v23, v41
	v_add_f32_e32 v20, v20, v23
	v_add_f32_e32 v23, v40, v20
	v_sub_f32_e32 v40, v23, v40
	v_sub_f32_e32 v20, v20, v40
	v_add_f32_e32 v40, v21, v23
	v_sub_f32_e32 v41, v40, v21
	v_sub_f32_e32 v42, v40, v41
	v_sub_f32_e32 v22, v43, v22
	v_sub_f32_e32 v21, v21, v42
	v_sub_f32_e32 v23, v23, v41
	v_add_f32_e32 v21, v23, v21
	v_add_f32_e32 v23, v22, v20
	v_sub_f32_e32 v41, v23, v22
	v_sub_f32_e32 v42, v23, v41
	v_sub_f32_e32 v22, v22, v42
	v_sub_f32_e32 v20, v20, v41
	v_add_f32_e32 v21, v23, v21
	v_add_f32_e32 v20, v20, v22
	v_add_f32_e32 v22, v40, v21
	v_sub_f32_e32 v23, v22, v40
	v_sub_f32_e32 v21, v21, v23
	v_add_f32_e32 v20, v20, v21
	v_add_f32_e32 v20, v22, v20
	v_cndmask_b32_e32 v20, v226, v20, vcc
	v_cmp_lt_f32_e64 vcc, |v17|, s63
	s_nop 1
	v_cndmask_b32_e32 v17, v20, v17, vcc
	v_sub_f32_e32 v16, v16, v17
	v_mul_f32_e32 v16, 0x3fb8aa3b, v16
	global_store_dword v[24:25], v16, off offset:64
	v_readlane_b32 s100, v254, 6
	s_nop 1
	v_mov_b32_e32 v17, s100
	v_fmac_f32_e32 v17, v18, v160
	v_mul_f32_e64 v18, |v17|, s94
	v_fma_f32 v20, |v17|, s94, -v18
	v_rndne_f32_e32 v21, v18
	v_fma_f32 v20, |v17|, s64, v20
	v_sub_f32_e32 v18, v18, v21
	v_add_f32_e32 v18, v18, v20
	v_exp_f32_e32 v18, v18
	v_cvt_i32_f32_e32 v20, v21
	v_cmp_ngt_f32_e64 vcc, |v17|, s58
	v_min_f32_e32 v16, 0, v17
	v_ldexp_f32 v18, v18, v20
	v_cndmask_b32_e32 v18, 0, v18, vcc
	v_cmp_nlt_f32_e64 vcc, |v17|, s59
	s_nop 1
	v_cndmask_b32_e32 v17, v226, v18, vcc
	v_add_f32_e32 v18, 1.0, v17
	v_add_f32_e32 v20, -1.0, v18
	v_sub_f32_e32 v21, v20, v18
	v_add_f32_e32 v21, 1.0, v21
	v_sub_f32_e32 v20, v17, v20
	v_add_f32_e32 v22, v20, v21
	v_frexp_mant_f32_e32 v20, v18
	v_cmp_gt_f32_e32 vcc, s77, v20
	v_cvt_f64_f32_e32 v[20:21], v18
	v_frexp_exp_i32_f64_e32 v20, v[20:21]
	v_subbrev_co_u32_e32 v20, vcc, 0, v20, vcc
	v_sub_u32_e32 v21, 0, v20
	v_ldexp_f32 v18, v18, v21
	v_ldexp_f32 v21, v22, v21
	v_add_f32_e32 v22, -1.0, v18
	v_add_f32_e32 v23, 1.0, v22
	v_sub_f32_e32 v23, v18, v23
	v_add_f32_e32 v23, v21, v23
	v_add_f32_e32 v40, v22, v23
	v_sub_f32_e32 v22, v22, v40
	v_add_f32_e32 v22, v23, v22
	v_add_f32_e32 v23, 1.0, v18
	v_add_f32_e32 v41, -1.0, v23
	v_sub_f32_e32 v18, v18, v41
	v_add_f32_e32 v18, v21, v18
	v_add_f32_e32 v21, v23, v18
	v_sub_f32_e32 v23, v23, v21
	v_add_f32_e32 v18, v18, v23
	v_rcp_f32_e32 v23, v21
	v_cvt_f32_i32_e32 v20, v20
	v_cmp_neq_f32_e32 vcc, s62, v17
	v_mul_f32_e32 v41, v40, v23
	v_mul_f32_e32 v42, v21, v41
	v_fma_f32 v43, v41, v21, -v42
	v_fmac_f32_e32 v43, v41, v18
	v_add_f32_e32 v44, v42, v43
	v_sub_f32_e32 v45, v40, v44
	v_sub_f32_e32 v40, v40, v45
	v_sub_f32_e32 v42, v44, v42
	v_sub_f32_e32 v40, v40, v44
	v_add_f32_e32 v22, v22, v40
	v_sub_f32_e32 v40, v42, v43
	v_add_f32_e32 v22, v40, v22
	v_add_f32_e32 v40, v45, v22
	v_mul_f32_e32 v42, v23, v40
	v_mul_f32_e32 v43, v21, v42
	v_fma_f32 v21, v42, v21, -v43
	v_fmac_f32_e32 v21, v42, v18
	v_sub_f32_e32 v18, v45, v40
	v_add_f32_e32 v18, v22, v18
	v_add_f32_e32 v22, v43, v21
	v_sub_f32_e32 v44, v40, v22
	v_sub_f32_e32 v40, v40, v44
	v_sub_f32_e32 v43, v22, v43
	v_sub_f32_e32 v22, v40, v22
	v_add_f32_e32 v18, v18, v22
	v_sub_f32_e32 v21, v43, v21
	v_add_f32_e32 v18, v21, v18
	v_add_f32_e32 v21, v41, v42
	v_add_f32_e32 v18, v44, v18
	v_sub_f32_e32 v22, v21, v41
	v_mul_f32_e32 v18, v23, v18
	v_sub_f32_e32 v22, v42, v22
	v_add_f32_e32 v18, v22, v18
	v_mul_f32_e32 v41, 0x3f317218, v20
	v_add_f32_e32 v22, v21, v18
	v_fma_f32 v42, v20, s78, -v41
	v_mul_f32_e32 v23, v22, v22
	v_fmac_f32_e32 v42, 0xb102e308, v20
	v_sub_f32_e32 v20, v22, v21
	v_fmamk_f32 v40, v23, 0x3e9b6dac, v185
	v_sub_f32_e32 v18, v18, v20
	v_add_f32_e32 v20, v41, v42
	v_fmaak_f32 v40, v23, v40, 0x3f2aaada
	v_sub_f32_e32 v21, v20, v41
	v_ldexp_f32 v41, v22, 1
	v_mul_f32_e32 v22, v22, v23
	v_mul_f32_e32 v22, v22, v40
	v_add_f32_e32 v23, v41, v22
	v_sub_f32_e32 v40, v23, v41
	v_ldexp_f32 v18, v18, 1
	v_sub_f32_e32 v22, v22, v40
	v_add_f32_e32 v18, v18, v22
	v_add_f32_e32 v22, v23, v18
	v_sub_f32_e32 v23, v22, v23
	v_sub_f32_e32 v18, v18, v23
	v_add_f32_e32 v23, v20, v22
	v_sub_f32_e32 v40, v23, v20
	v_sub_f32_e32 v41, v23, v40
	v_sub_f32_e32 v21, v42, v21
	v_sub_f32_e32 v20, v20, v41
	v_sub_f32_e32 v22, v22, v40
	v_add_f32_e32 v20, v22, v20
	v_add_f32_e32 v22, v21, v18
	v_sub_f32_e32 v40, v22, v21
	v_sub_f32_e32 v41, v22, v40
	v_sub_f32_e32 v21, v21, v41
	v_sub_f32_e32 v18, v18, v40
	v_add_f32_e32 v20, v22, v20
	v_add_f32_e32 v18, v18, v21
	v_add_f32_e32 v21, v23, v20
	v_sub_f32_e32 v22, v21, v23
	v_sub_f32_e32 v20, v20, v22
	v_add_f32_e32 v18, v18, v20
	v_add_f32_e32 v18, v21, v18
	v_cndmask_b32_e32 v18, v226, v18, vcc
	v_cmp_lt_f32_e64 vcc, |v17|, s63
	s_nop 1
	v_cndmask_b32_e32 v17, v18, v17, vcc
	v_sub_f32_e32 v16, v16, v17
	v_mul_f32_e32 v16, 0x3fb8aa3b, v16
	global_store_dword v[38:39], v16, off offset:64
	v_readlane_b32 s100, v254, 7
	s_nop 1
	v_mov_b32_e32 v17, s100
	v_fmac_f32_e32 v17, v19, v160
	v_mul_f32_e64 v18, |v17|, s94
	v_fma_f32 v19, |v17|, s94, -v18
	v_rndne_f32_e32 v20, v18
	v_fma_f32 v19, |v17|, s64, v19
	v_sub_f32_e32 v18, v18, v20
	v_add_f32_e32 v18, v18, v19
	v_exp_f32_e32 v18, v18
	v_cvt_i32_f32_e32 v19, v20
	v_cmp_ngt_f32_e64 vcc, |v17|, s58
	v_min_f32_e32 v16, 0, v17
	v_ldexp_f32 v18, v18, v19
	v_cndmask_b32_e32 v18, 0, v18, vcc
	v_cmp_nlt_f32_e64 vcc, |v17|, s59
	s_nop 1
	v_cndmask_b32_e32 v17, v226, v18, vcc
	v_add_f32_e32 v20, 1.0, v17
	v_add_f32_e32 v18, -1.0, v20
	v_sub_f32_e32 v19, v18, v20
	v_add_f32_e32 v19, 1.0, v19
	v_sub_f32_e32 v18, v17, v18
	v_add_f32_e32 v21, v18, v19
	v_frexp_mant_f32_e32 v18, v20
	v_cmp_gt_f32_e32 vcc, s77, v18
	v_cvt_f64_f32_e32 v[18:19], v20
	v_frexp_exp_i32_f64_e32 v18, v[18:19]
	v_subbrev_co_u32_e32 v18, vcc, 0, v18, vcc
	v_sub_u32_e32 v19, 0, v18
	v_ldexp_f32 v20, v20, v19
	v_ldexp_f32 v19, v21, v19
	v_add_f32_e32 v21, -1.0, v20
	v_add_f32_e32 v22, 1.0, v21
	v_sub_f32_e32 v22, v20, v22
	v_add_f32_e32 v22, v19, v22
	v_add_f32_e32 v23, v21, v22
	v_sub_f32_e32 v21, v21, v23
	v_add_f32_e32 v21, v22, v21
	v_add_f32_e32 v22, 1.0, v20
	v_add_f32_e32 v40, -1.0, v22
	v_sub_f32_e32 v20, v20, v40
	v_add_f32_e32 v19, v19, v20
	v_add_f32_e32 v20, v22, v19
	v_sub_f32_e32 v22, v22, v20
	v_add_f32_e32 v19, v19, v22
	v_rcp_f32_e32 v22, v20
	v_cvt_f32_i32_e32 v18, v18
	v_cmp_neq_f32_e32 vcc, s62, v17
	v_mul_f32_e32 v40, v23, v22
	v_mul_f32_e32 v41, v20, v40
	v_fma_f32 v42, v40, v20, -v41
	v_fmac_f32_e32 v42, v40, v19
	v_add_f32_e32 v43, v41, v42
	v_sub_f32_e32 v44, v23, v43
	v_sub_f32_e32 v23, v23, v44
	v_sub_f32_e32 v41, v43, v41
	v_sub_f32_e32 v23, v23, v43
	v_add_f32_e32 v21, v21, v23
	v_sub_f32_e32 v23, v41, v42
	v_add_f32_e32 v21, v23, v21
	v_add_f32_e32 v23, v44, v21
	v_mul_f32_e32 v41, v22, v23
	v_mul_f32_e32 v42, v20, v41
	v_fma_f32 v20, v41, v20, -v42
	v_fmac_f32_e32 v20, v41, v19
	v_sub_f32_e32 v19, v44, v23
	v_add_f32_e32 v19, v21, v19
	v_add_f32_e32 v21, v42, v20
	v_sub_f32_e32 v43, v23, v21
	v_sub_f32_e32 v23, v23, v43
	v_sub_f32_e32 v42, v21, v42
	v_sub_f32_e32 v21, v23, v21
	v_add_f32_e32 v19, v19, v21
	v_sub_f32_e32 v20, v42, v20
	v_add_f32_e32 v19, v20, v19
	v_add_f32_e32 v20, v40, v41
	v_add_f32_e32 v19, v43, v19
	v_sub_f32_e32 v21, v20, v40
	v_mul_f32_e32 v19, v22, v19
	v_sub_f32_e32 v21, v41, v21
	v_add_f32_e32 v19, v21, v19
	v_mul_f32_e32 v40, 0x3f317218, v18
	v_add_f32_e32 v21, v20, v19
	v_fma_f32 v41, v18, s78, -v40
	v_mul_f32_e32 v22, v21, v21
	v_fmac_f32_e32 v41, 0xb102e308, v18
	v_sub_f32_e32 v18, v21, v20
	v_fmamk_f32 v23, v22, 0x3e9b6dac, v185
	v_sub_f32_e32 v18, v19, v18
	v_add_f32_e32 v19, v40, v41
	v_fmaak_f32 v23, v22, v23, 0x3f2aaada
	v_sub_f32_e32 v20, v19, v40
	v_ldexp_f32 v40, v21, 1
	v_mul_f32_e32 v21, v21, v22
	v_mul_f32_e32 v21, v21, v23
	v_add_f32_e32 v22, v40, v21
	v_sub_f32_e32 v23, v22, v40
	v_ldexp_f32 v18, v18, 1
	v_sub_f32_e32 v21, v21, v23
	v_add_f32_e32 v18, v18, v21
	v_add_f32_e32 v21, v22, v18
	v_sub_f32_e32 v22, v21, v22
	v_sub_f32_e32 v18, v18, v22
	v_add_f32_e32 v22, v19, v21
	v_sub_f32_e32 v23, v22, v19
	v_sub_f32_e32 v40, v22, v23
	v_sub_f32_e32 v20, v41, v20
	v_sub_f32_e32 v19, v19, v40
	v_sub_f32_e32 v21, v21, v23
	v_add_f32_e32 v19, v21, v19
	v_add_f32_e32 v21, v20, v18
	v_sub_f32_e32 v23, v21, v20
	v_sub_f32_e32 v40, v21, v23
	v_sub_f32_e32 v20, v20, v40
	v_sub_f32_e32 v18, v18, v23
	v_add_f32_e32 v19, v21, v19
	v_add_f32_e32 v18, v18, v20
	v_add_f32_e32 v20, v22, v19
	v_sub_f32_e32 v21, v20, v22
	v_sub_f32_e32 v19, v19, v21
	v_add_f32_e32 v18, v18, v19
	v_add_f32_e32 v18, v20, v18
	v_cndmask_b32_e32 v18, v226, v18, vcc
	v_cmp_lt_f32_e64 vcc, |v17|, s63
	s_nop 1
	v_cndmask_b32_e32 v17, v18, v17, vcc
	v_sub_f32_e32 v16, v16, v17
	v_mul_f32_e32 v16, 0x3fb8aa3b, v16
	global_store_dword v[26:27], v16, off offset:64
	v_readlane_b32 s100, v254, 0
	s_nop 1
	v_mov_b32_e32 v16, s100
	v_fmac_f32_e32 v16, v12, v158
	v_mul_f32_e64 v17, |v16|, s94
	v_fma_f32 v18, |v16|, s94, -v17
	v_rndne_f32_e32 v19, v17
	v_fma_f32 v18, |v16|, s64, v18
	v_sub_f32_e32 v17, v17, v19
	v_add_f32_e32 v17, v17, v18
	v_exp_f32_e32 v17, v17
	v_cvt_i32_f32_e32 v18, v19
	v_cmp_ngt_f32_e64 vcc, |v16|, s58
	v_min_f32_e32 v12, 0, v16
	v_ldexp_f32 v17, v17, v18
	v_cndmask_b32_e32 v17, 0, v17, vcc
	v_cmp_nlt_f32_e64 vcc, |v16|, s59
	s_nop 1
	v_cndmask_b32_e32 v16, v226, v17, vcc
	v_add_f32_e32 v17, 1.0, v16
	v_add_f32_e32 v18, -1.0, v17
	v_sub_f32_e32 v19, v18, v17
	v_add_f32_e32 v19, 1.0, v19
	v_sub_f32_e32 v18, v16, v18
	v_add_f32_e32 v20, v18, v19
	v_frexp_mant_f32_e32 v18, v17
	v_cmp_gt_f32_e32 vcc, s77, v18
	v_cvt_f64_f32_e32 v[18:19], v17
	v_frexp_exp_i32_f64_e32 v18, v[18:19]
	v_subbrev_co_u32_e32 v18, vcc, 0, v18, vcc
	v_sub_u32_e32 v19, 0, v18
	v_ldexp_f32 v17, v17, v19
	v_ldexp_f32 v19, v20, v19
	v_add_f32_e32 v20, -1.0, v17
	v_add_f32_e32 v21, 1.0, v20
	v_sub_f32_e32 v21, v17, v21
	v_add_f32_e32 v21, v19, v21
	v_add_f32_e32 v22, v20, v21
	v_sub_f32_e32 v20, v20, v22
	v_add_f32_e32 v20, v21, v20
	v_add_f32_e32 v21, 1.0, v17
	v_add_f32_e32 v23, -1.0, v21
	v_sub_f32_e32 v17, v17, v23
	v_add_f32_e32 v17, v19, v17
	v_add_f32_e32 v19, v21, v17
	v_sub_f32_e32 v21, v21, v19
	v_add_f32_e32 v17, v17, v21
	v_rcp_f32_e32 v21, v19
	v_cvt_f32_i32_e32 v18, v18
	v_cmp_neq_f32_e32 vcc, s62, v16
	v_mul_f32_e32 v23, v22, v21
	v_mul_f32_e32 v40, v19, v23
	v_fma_f32 v41, v23, v19, -v40
	v_fmac_f32_e32 v41, v23, v17
	v_add_f32_e32 v42, v40, v41
	v_sub_f32_e32 v43, v22, v42
	v_sub_f32_e32 v22, v22, v43
	v_sub_f32_e32 v40, v42, v40
	v_sub_f32_e32 v22, v22, v42
	v_add_f32_e32 v20, v20, v22
	v_sub_f32_e32 v22, v40, v41
	v_add_f32_e32 v20, v22, v20
	v_add_f32_e32 v22, v43, v20
	v_mul_f32_e32 v40, v21, v22
	v_mul_f32_e32 v41, v19, v40
	v_fma_f32 v19, v40, v19, -v41
	v_fmac_f32_e32 v19, v40, v17
	v_sub_f32_e32 v17, v43, v22
	v_add_f32_e32 v17, v20, v17
	v_add_f32_e32 v20, v41, v19
	v_sub_f32_e32 v42, v22, v20
	v_sub_f32_e32 v22, v22, v42
	v_sub_f32_e32 v41, v20, v41
	v_sub_f32_e32 v20, v22, v20
	v_add_f32_e32 v17, v17, v20
	v_sub_f32_e32 v19, v41, v19
	v_add_f32_e32 v17, v19, v17
	v_add_f32_e32 v19, v23, v40
	v_add_f32_e32 v17, v42, v17
	v_sub_f32_e32 v20, v19, v23
	v_mul_f32_e32 v17, v21, v17
	v_sub_f32_e32 v20, v40, v20
	v_add_f32_e32 v17, v20, v17
	v_mul_f32_e32 v23, 0x3f317218, v18
	v_add_f32_e32 v20, v19, v17
	v_fma_f32 v40, v18, s78, -v23
	v_mul_f32_e32 v21, v20, v20
	v_fmac_f32_e32 v40, 0xb102e308, v18
	v_sub_f32_e32 v18, v20, v19
	v_fmamk_f32 v22, v21, 0x3e9b6dac, v185
	v_sub_f32_e32 v17, v17, v18
	v_add_f32_e32 v18, v23, v40
	v_fmaak_f32 v22, v21, v22, 0x3f2aaada
	v_sub_f32_e32 v19, v18, v23
	v_ldexp_f32 v23, v20, 1
	v_mul_f32_e32 v20, v20, v21
	v_mul_f32_e32 v20, v20, v22
	v_add_f32_e32 v21, v23, v20
	v_sub_f32_e32 v22, v21, v23
	v_ldexp_f32 v17, v17, 1
	v_sub_f32_e32 v20, v20, v22
	v_add_f32_e32 v17, v17, v20
	v_add_f32_e32 v20, v21, v17
	v_sub_f32_e32 v21, v20, v21
	v_sub_f32_e32 v17, v17, v21
	v_add_f32_e32 v21, v18, v20
	v_sub_f32_e32 v22, v21, v18
	v_sub_f32_e32 v23, v21, v22
	v_sub_f32_e32 v19, v40, v19
	v_sub_f32_e32 v18, v18, v23
	v_sub_f32_e32 v20, v20, v22
	v_add_f32_e32 v18, v20, v18
	v_add_f32_e32 v20, v19, v17
	v_sub_f32_e32 v22, v20, v19
	v_sub_f32_e32 v23, v20, v22
	v_sub_f32_e32 v19, v19, v23
	v_sub_f32_e32 v17, v17, v22
	v_add_f32_e32 v18, v20, v18
	v_add_f32_e32 v17, v17, v19
	v_add_f32_e32 v19, v21, v18
	v_sub_f32_e32 v20, v19, v21
	v_sub_f32_e32 v18, v18, v20
	v_add_f32_e32 v17, v17, v18
	v_add_f32_e32 v17, v19, v17
	v_cndmask_b32_e32 v17, v226, v17, vcc
	v_cmp_lt_f32_e64 vcc, |v16|, s63
	s_nop 1
	v_cndmask_b32_e32 v16, v17, v16, vcc
	v_sub_f32_e32 v12, v12, v16
	v_mul_f32_e32 v12, 0x3fb8aa3b, v12
	global_store_dword v[32:33], v12, off offset:128
	v_readlane_b32 s100, v254, 1
	s_nop 1
	v_mov_b32_e32 v16, s100
	v_fmac_f32_e32 v16, v13, v158
	v_mul_f32_e64 v13, |v16|, s94
	v_fma_f32 v17, |v16|, s94, -v13
	v_rndne_f32_e32 v18, v13
	v_fma_f32 v17, |v16|, s64, v17
	v_sub_f32_e32 v13, v13, v18
	v_add_f32_e32 v13, v13, v17
	v_exp_f32_e32 v13, v13
	v_cvt_i32_f32_e32 v17, v18
	v_cmp_ngt_f32_e64 vcc, |v16|, s58
	v_min_f32_e32 v12, 0, v16
	v_ldexp_f32 v13, v13, v17
	v_cndmask_b32_e32 v13, 0, v13, vcc
	v_cmp_nlt_f32_e64 vcc, |v16|, s59
	s_nop 1
	v_cndmask_b32_e32 v13, v226, v13, vcc
	v_add_f32_e32 v18, 1.0, v13
	v_add_f32_e32 v16, -1.0, v18
	v_sub_f32_e32 v17, v16, v18
	v_add_f32_e32 v17, 1.0, v17
	v_sub_f32_e32 v16, v13, v16
	v_add_f32_e32 v19, v16, v17
	v_frexp_mant_f32_e32 v16, v18
	v_cmp_gt_f32_e32 vcc, s77, v16
	v_cvt_f64_f32_e32 v[16:17], v18
	v_frexp_exp_i32_f64_e32 v16, v[16:17]
	v_subbrev_co_u32_e32 v16, vcc, 0, v16, vcc
	v_sub_u32_e32 v17, 0, v16
	v_ldexp_f32 v18, v18, v17
	v_ldexp_f32 v17, v19, v17
	v_add_f32_e32 v19, -1.0, v18
	v_add_f32_e32 v20, 1.0, v19
	v_sub_f32_e32 v20, v18, v20
	v_add_f32_e32 v20, v17, v20
	v_add_f32_e32 v21, v19, v20
	v_sub_f32_e32 v19, v19, v21
	v_add_f32_e32 v19, v20, v19
	v_add_f32_e32 v20, 1.0, v18
	v_add_f32_e32 v22, -1.0, v20
	v_sub_f32_e32 v18, v18, v22
	v_add_f32_e32 v17, v17, v18
	v_add_f32_e32 v18, v20, v17
	v_sub_f32_e32 v20, v20, v18
	v_add_f32_e32 v17, v17, v20
	v_rcp_f32_e32 v20, v18
	v_cvt_f32_i32_e32 v16, v16
	v_cmp_neq_f32_e32 vcc, s62, v13
	v_mul_f32_e32 v22, v21, v20
	v_mul_f32_e32 v23, v18, v22
	v_fma_f32 v40, v22, v18, -v23
	v_fmac_f32_e32 v40, v22, v17
	v_add_f32_e32 v41, v23, v40
	v_sub_f32_e32 v42, v21, v41
	v_sub_f32_e32 v21, v21, v42
	v_sub_f32_e32 v23, v41, v23
	v_sub_f32_e32 v21, v21, v41
	v_add_f32_e32 v19, v19, v21
	v_sub_f32_e32 v21, v23, v40
	v_add_f32_e32 v19, v21, v19
	v_add_f32_e32 v21, v42, v19
	v_mul_f32_e32 v23, v20, v21
	v_mul_f32_e32 v40, v18, v23
	v_fma_f32 v18, v23, v18, -v40
	v_fmac_f32_e32 v18, v23, v17
	v_sub_f32_e32 v17, v42, v21
	v_add_f32_e32 v17, v19, v17
	v_add_f32_e32 v19, v40, v18
	v_sub_f32_e32 v41, v21, v19
	v_sub_f32_e32 v21, v21, v41
	v_sub_f32_e32 v40, v19, v40
	v_sub_f32_e32 v19, v21, v19
	v_add_f32_e32 v17, v17, v19
	v_sub_f32_e32 v18, v40, v18
	v_add_f32_e32 v17, v18, v17
	v_add_f32_e32 v18, v22, v23
	v_add_f32_e32 v17, v41, v17
	v_sub_f32_e32 v19, v18, v22
	v_mul_f32_e32 v17, v20, v17
	v_sub_f32_e32 v19, v23, v19
	v_add_f32_e32 v17, v19, v17
	v_mul_f32_e32 v22, 0x3f317218, v16
	v_add_f32_e32 v19, v18, v17
	v_fma_f32 v23, v16, s78, -v22
	v_mul_f32_e32 v20, v19, v19
	v_fmac_f32_e32 v23, 0xb102e308, v16
	v_sub_f32_e32 v16, v19, v18
	v_fmamk_f32 v21, v20, 0x3e9b6dac, v185
	v_sub_f32_e32 v16, v17, v16
	v_add_f32_e32 v17, v22, v23
	v_fmaak_f32 v21, v20, v21, 0x3f2aaada
	v_sub_f32_e32 v18, v17, v22
	v_ldexp_f32 v22, v19, 1
	v_mul_f32_e32 v19, v19, v20
	v_mul_f32_e32 v19, v19, v21
	v_add_f32_e32 v20, v22, v19
	v_sub_f32_e32 v21, v20, v22
	v_ldexp_f32 v16, v16, 1
	v_sub_f32_e32 v19, v19, v21
	v_add_f32_e32 v16, v16, v19
	v_add_f32_e32 v19, v20, v16
	v_sub_f32_e32 v20, v19, v20
	v_sub_f32_e32 v16, v16, v20
	v_add_f32_e32 v20, v17, v19
	v_sub_f32_e32 v21, v20, v17
	v_sub_f32_e32 v22, v20, v21
	v_sub_f32_e32 v18, v23, v18
	v_sub_f32_e32 v17, v17, v22
	v_sub_f32_e32 v19, v19, v21
	v_add_f32_e32 v17, v19, v17
	v_add_f32_e32 v19, v18, v16
	v_sub_f32_e32 v21, v19, v18
	v_sub_f32_e32 v22, v19, v21
	v_sub_f32_e32 v18, v18, v22
	v_sub_f32_e32 v16, v16, v21
	v_add_f32_e32 v17, v19, v17
	v_add_f32_e32 v16, v16, v18
	v_add_f32_e32 v18, v20, v17
	v_sub_f32_e32 v19, v18, v20
	v_sub_f32_e32 v17, v17, v19
	v_add_f32_e32 v16, v16, v17
	v_add_f32_e32 v16, v18, v16
	v_cndmask_b32_e32 v16, v226, v16, vcc
	v_cmp_lt_f32_e64 vcc, |v13|, s63
	s_nop 1
	v_cndmask_b32_e32 v13, v16, v13, vcc
	v_sub_f32_e32 v12, v12, v13
	v_mul_f32_e32 v12, 0x3fb8aa3b, v12
	global_store_dword v[28:29], v12, off offset:128
	v_readlane_b32 s100, v254, 2
	s_nop 1
	v_mov_b32_e32 v13, s100
	v_fmac_f32_e32 v13, v14, v158
	v_mul_f32_e64 v14, |v13|, s94
	v_fma_f32 v16, |v13|, s94, -v14
	v_rndne_f32_e32 v17, v14
	v_fma_f32 v16, |v13|, s64, v16
	v_sub_f32_e32 v14, v14, v17
	v_add_f32_e32 v14, v14, v16
	v_exp_f32_e32 v14, v14
	v_cvt_i32_f32_e32 v16, v17
	v_cmp_ngt_f32_e64 vcc, |v13|, s58
	v_min_f32_e32 v12, 0, v13
	v_ldexp_f32 v14, v14, v16
	v_cndmask_b32_e32 v14, 0, v14, vcc
	v_cmp_nlt_f32_e64 vcc, |v13|, s59
	s_nop 1
	v_cndmask_b32_e32 v13, v226, v14, vcc
	v_add_f32_e32 v14, 1.0, v13
	v_add_f32_e32 v16, -1.0, v14
	v_sub_f32_e32 v17, v16, v14
	v_add_f32_e32 v17, 1.0, v17
	v_sub_f32_e32 v16, v13, v16
	v_add_f32_e32 v18, v16, v17
	v_frexp_mant_f32_e32 v16, v14
	v_cmp_gt_f32_e32 vcc, s77, v16
	v_cvt_f64_f32_e32 v[16:17], v14
	v_frexp_exp_i32_f64_e32 v16, v[16:17]
	v_subbrev_co_u32_e32 v16, vcc, 0, v16, vcc
	v_sub_u32_e32 v17, 0, v16
	v_ldexp_f32 v14, v14, v17
	v_ldexp_f32 v17, v18, v17
	v_add_f32_e32 v18, -1.0, v14
	v_add_f32_e32 v19, 1.0, v18
	v_sub_f32_e32 v19, v14, v19
	v_add_f32_e32 v19, v17, v19
	v_add_f32_e32 v20, v18, v19
	v_sub_f32_e32 v18, v18, v20
	v_add_f32_e32 v18, v19, v18
	v_add_f32_e32 v19, 1.0, v14
	v_add_f32_e32 v21, -1.0, v19
	v_sub_f32_e32 v14, v14, v21
	v_add_f32_e32 v14, v17, v14
	v_add_f32_e32 v17, v19, v14
	v_sub_f32_e32 v19, v19, v17
	v_add_f32_e32 v14, v14, v19
	v_rcp_f32_e32 v19, v17
	v_cvt_f32_i32_e32 v16, v16
	v_cmp_neq_f32_e32 vcc, s62, v13
	v_mul_f32_e32 v21, v20, v19
	v_mul_f32_e32 v22, v17, v21
	v_fma_f32 v23, v21, v17, -v22
	v_fmac_f32_e32 v23, v21, v14
	v_add_f32_e32 v40, v22, v23
	v_sub_f32_e32 v41, v20, v40
	v_sub_f32_e32 v20, v20, v41
	v_sub_f32_e32 v22, v40, v22
	v_sub_f32_e32 v20, v20, v40
	v_add_f32_e32 v18, v18, v20
	v_sub_f32_e32 v20, v22, v23
	v_add_f32_e32 v18, v20, v18
	v_add_f32_e32 v20, v41, v18
	v_mul_f32_e32 v22, v19, v20
	v_mul_f32_e32 v23, v17, v22
	v_fma_f32 v17, v22, v17, -v23
	v_fmac_f32_e32 v17, v22, v14
	v_sub_f32_e32 v14, v41, v20
	v_add_f32_e32 v14, v18, v14
	v_add_f32_e32 v18, v23, v17
	v_sub_f32_e32 v40, v20, v18
	v_sub_f32_e32 v20, v20, v40
	v_sub_f32_e32 v23, v18, v23
	v_sub_f32_e32 v18, v20, v18
	v_add_f32_e32 v14, v14, v18
	v_sub_f32_e32 v17, v23, v17
	v_add_f32_e32 v14, v17, v14
	v_add_f32_e32 v17, v21, v22
	v_add_f32_e32 v14, v40, v14
	v_sub_f32_e32 v18, v17, v21
	v_mul_f32_e32 v14, v19, v14
	v_sub_f32_e32 v18, v22, v18
	v_add_f32_e32 v14, v18, v14
	v_mul_f32_e32 v21, 0x3f317218, v16
	v_add_f32_e32 v18, v17, v14
	v_fma_f32 v22, v16, s78, -v21
	v_mul_f32_e32 v19, v18, v18
	v_fmac_f32_e32 v22, 0xb102e308, v16
	v_sub_f32_e32 v16, v18, v17
	v_fmamk_f32 v20, v19, 0x3e9b6dac, v185
	v_sub_f32_e32 v14, v14, v16
	v_add_f32_e32 v16, v21, v22
	v_fmaak_f32 v20, v19, v20, 0x3f2aaada
	v_sub_f32_e32 v17, v16, v21
	v_ldexp_f32 v21, v18, 1
	v_mul_f32_e32 v18, v18, v19
	v_mul_f32_e32 v18, v18, v20
	v_add_f32_e32 v19, v21, v18
	v_sub_f32_e32 v20, v19, v21
	v_ldexp_f32 v14, v14, 1
	v_sub_f32_e32 v18, v18, v20
	v_add_f32_e32 v14, v14, v18
	v_add_f32_e32 v18, v19, v14
	v_sub_f32_e32 v19, v18, v19
	v_sub_f32_e32 v14, v14, v19
	v_add_f32_e32 v19, v16, v18
	v_sub_f32_e32 v20, v19, v16
	v_sub_f32_e32 v21, v19, v20
	v_sub_f32_e32 v17, v22, v17
	v_sub_f32_e32 v16, v16, v21
	v_sub_f32_e32 v18, v18, v20
	v_add_f32_e32 v16, v18, v16
	v_add_f32_e32 v18, v17, v14
	v_sub_f32_e32 v20, v18, v17
	v_sub_f32_e32 v21, v18, v20
	v_sub_f32_e32 v17, v17, v21
	v_sub_f32_e32 v14, v14, v20
	v_add_f32_e32 v16, v18, v16
	v_add_f32_e32 v14, v14, v17
	v_add_f32_e32 v17, v19, v16
	v_sub_f32_e32 v18, v17, v19
	v_sub_f32_e32 v16, v16, v18
	v_add_f32_e32 v14, v14, v16
	v_add_f32_e32 v14, v17, v14
	v_cndmask_b32_e32 v14, v226, v14, vcc
	v_cmp_lt_f32_e64 vcc, |v13|, s63
	s_nop 1
	v_cndmask_b32_e32 v13, v14, v13, vcc
	v_sub_f32_e32 v12, v12, v13
	v_mul_f32_e32 v12, 0x3fb8aa3b, v12
	global_store_dword v[34:35], v12, off offset:128
	v_readlane_b32 s100, v254, 3
	s_nop 1
	v_mov_b32_e32 v13, s100
	v_fmac_f32_e32 v13, v15, v158
	v_mul_f32_e64 v14, |v13|, s94
	v_fma_f32 v15, |v13|, s94, -v14
	v_rndne_f32_e32 v16, v14
	v_fma_f32 v15, |v13|, s64, v15
	v_sub_f32_e32 v14, v14, v16
	v_add_f32_e32 v14, v14, v15
	v_exp_f32_e32 v14, v14
	v_cvt_i32_f32_e32 v15, v16
	v_cmp_ngt_f32_e64 vcc, |v13|, s58
	v_min_f32_e32 v12, 0, v13
	v_ldexp_f32 v14, v14, v15
	v_cndmask_b32_e32 v14, 0, v14, vcc
	v_cmp_nlt_f32_e64 vcc, |v13|, s59
	s_nop 1
	v_cndmask_b32_e32 v13, v226, v14, vcc
	v_add_f32_e32 v16, 1.0, v13
	v_add_f32_e32 v14, -1.0, v16
	v_sub_f32_e32 v15, v14, v16
	v_add_f32_e32 v15, 1.0, v15
	v_sub_f32_e32 v14, v13, v14
	v_add_f32_e32 v17, v14, v15
	v_frexp_mant_f32_e32 v14, v16
	v_cmp_gt_f32_e32 vcc, s77, v14
	v_cvt_f64_f32_e32 v[14:15], v16
	v_frexp_exp_i32_f64_e32 v14, v[14:15]
	v_subbrev_co_u32_e32 v14, vcc, 0, v14, vcc
	v_sub_u32_e32 v15, 0, v14
	v_ldexp_f32 v16, v16, v15
	v_ldexp_f32 v15, v17, v15
	v_add_f32_e32 v17, -1.0, v16
	v_add_f32_e32 v18, 1.0, v17
	v_sub_f32_e32 v18, v16, v18
	v_add_f32_e32 v18, v15, v18
	v_add_f32_e32 v19, v17, v18
	v_sub_f32_e32 v17, v17, v19
	v_add_f32_e32 v17, v18, v17
	v_add_f32_e32 v18, 1.0, v16
	v_add_f32_e32 v20, -1.0, v18
	v_sub_f32_e32 v16, v16, v20
	v_add_f32_e32 v15, v15, v16
	v_add_f32_e32 v16, v18, v15
	v_sub_f32_e32 v18, v18, v16
	v_add_f32_e32 v15, v15, v18
	v_rcp_f32_e32 v18, v16
	v_cvt_f32_i32_e32 v14, v14
	v_cmp_neq_f32_e32 vcc, s62, v13
	v_mul_f32_e32 v20, v19, v18
	v_mul_f32_e32 v21, v16, v20
	v_fma_f32 v22, v20, v16, -v21
	v_fmac_f32_e32 v22, v20, v15
	v_add_f32_e32 v23, v21, v22
	v_sub_f32_e32 v40, v19, v23
	v_sub_f32_e32 v19, v19, v40
	v_sub_f32_e32 v21, v23, v21
	v_sub_f32_e32 v19, v19, v23
	v_add_f32_e32 v17, v17, v19
	v_sub_f32_e32 v19, v21, v22
	v_add_f32_e32 v17, v19, v17
	v_add_f32_e32 v19, v40, v17
	v_mul_f32_e32 v21, v18, v19
	v_mul_f32_e32 v22, v16, v21
	v_fma_f32 v16, v21, v16, -v22
	v_fmac_f32_e32 v16, v21, v15
	v_sub_f32_e32 v15, v40, v19
	v_add_f32_e32 v15, v17, v15
	v_add_f32_e32 v17, v22, v16
	v_sub_f32_e32 v23, v19, v17
	v_sub_f32_e32 v19, v19, v23
	v_sub_f32_e32 v22, v17, v22
	v_sub_f32_e32 v17, v19, v17
	v_add_f32_e32 v15, v15, v17
	v_sub_f32_e32 v16, v22, v16
	v_add_f32_e32 v15, v16, v15
	v_add_f32_e32 v16, v20, v21
	v_add_f32_e32 v15, v23, v15
	v_sub_f32_e32 v17, v16, v20
	v_mul_f32_e32 v15, v18, v15
	v_sub_f32_e32 v17, v21, v17
	v_add_f32_e32 v15, v17, v15
	v_mul_f32_e32 v20, 0x3f317218, v14
	v_add_f32_e32 v17, v16, v15
	v_fma_f32 v21, v14, s78, -v20
	v_mul_f32_e32 v18, v17, v17
	v_fmac_f32_e32 v21, 0xb102e308, v14
	v_sub_f32_e32 v14, v17, v16
	v_fmamk_f32 v19, v18, 0x3e9b6dac, v185
	v_sub_f32_e32 v14, v15, v14
	v_add_f32_e32 v15, v20, v21
	v_fmaak_f32 v19, v18, v19, 0x3f2aaada
	v_sub_f32_e32 v16, v15, v20
	v_ldexp_f32 v20, v17, 1
	v_mul_f32_e32 v17, v17, v18
	v_mul_f32_e32 v17, v17, v19
	v_add_f32_e32 v18, v20, v17
	v_sub_f32_e32 v19, v18, v20
	v_ldexp_f32 v14, v14, 1
	v_sub_f32_e32 v17, v17, v19
	v_add_f32_e32 v14, v14, v17
	v_add_f32_e32 v17, v18, v14
	v_sub_f32_e32 v18, v17, v18
	v_sub_f32_e32 v14, v14, v18
	v_add_f32_e32 v18, v15, v17
	v_sub_f32_e32 v19, v18, v15
	v_sub_f32_e32 v20, v18, v19
	v_sub_f32_e32 v16, v21, v16
	v_sub_f32_e32 v15, v15, v20
	v_sub_f32_e32 v17, v17, v19
	v_add_f32_e32 v15, v17, v15
	v_add_f32_e32 v17, v16, v14
	v_sub_f32_e32 v19, v17, v16
	v_sub_f32_e32 v20, v17, v19
	v_sub_f32_e32 v16, v16, v20
	v_sub_f32_e32 v14, v14, v19
	v_add_f32_e32 v15, v17, v15
	v_add_f32_e32 v14, v14, v16
	v_add_f32_e32 v16, v18, v15
	v_sub_f32_e32 v17, v16, v18
	v_sub_f32_e32 v15, v15, v17
	v_add_f32_e32 v14, v14, v15
	v_add_f32_e32 v14, v16, v14
	v_cndmask_b32_e32 v14, v226, v14, vcc
	v_cmp_lt_f32_e64 vcc, |v13|, s63
	s_nop 1
	v_cndmask_b32_e32 v13, v14, v13, vcc
	v_sub_f32_e32 v12, v12, v13
	v_mul_f32_e32 v12, 0x3fb8aa3b, v12
	global_store_dword v[30:31], v12, off offset:128
	v_readlane_b32 s100, v254, 4
	s_nop 1
	v_mov_b32_e32 v12, s100
	v_fmac_f32_e32 v12, v8, v158
	v_mul_f32_e64 v13, |v12|, s94
	v_fma_f32 v14, |v12|, s94, -v13
	v_rndne_f32_e32 v15, v13
	v_fma_f32 v14, |v12|, s64, v14
	v_sub_f32_e32 v13, v13, v15
	v_add_f32_e32 v13, v13, v14
	v_exp_f32_e32 v13, v13
	v_cvt_i32_f32_e32 v14, v15
	v_cmp_ngt_f32_e64 vcc, |v12|, s58
	v_min_f32_e32 v8, 0, v12
	v_ldexp_f32 v13, v13, v14
	v_cndmask_b32_e32 v13, 0, v13, vcc
	v_cmp_nlt_f32_e64 vcc, |v12|, s59
	s_nop 1
	v_cndmask_b32_e32 v12, v226, v13, vcc
	v_add_f32_e32 v13, 1.0, v12
	v_add_f32_e32 v14, -1.0, v13
	v_sub_f32_e32 v15, v14, v13
	v_add_f32_e32 v15, 1.0, v15
	v_sub_f32_e32 v14, v12, v14
	v_add_f32_e32 v16, v14, v15
	v_frexp_mant_f32_e32 v14, v13
	v_cmp_gt_f32_e32 vcc, s77, v14
	v_cvt_f64_f32_e32 v[14:15], v13
	v_frexp_exp_i32_f64_e32 v14, v[14:15]
	v_subbrev_co_u32_e32 v14, vcc, 0, v14, vcc
	v_sub_u32_e32 v15, 0, v14
	v_ldexp_f32 v13, v13, v15
	v_ldexp_f32 v15, v16, v15
	v_add_f32_e32 v16, -1.0, v13
	v_add_f32_e32 v17, 1.0, v16
	v_sub_f32_e32 v17, v13, v17
	v_add_f32_e32 v17, v15, v17
	v_add_f32_e32 v18, v16, v17
	v_sub_f32_e32 v16, v16, v18
	v_add_f32_e32 v16, v17, v16
	v_add_f32_e32 v17, 1.0, v13
	v_add_f32_e32 v19, -1.0, v17
	v_sub_f32_e32 v13, v13, v19
	v_add_f32_e32 v13, v15, v13
	v_add_f32_e32 v15, v17, v13
	v_sub_f32_e32 v17, v17, v15
	v_add_f32_e32 v13, v13, v17
	v_rcp_f32_e32 v17, v15
	v_cvt_f32_i32_e32 v14, v14
	v_cmp_neq_f32_e32 vcc, s62, v12
	v_mul_f32_e32 v19, v18, v17
	v_mul_f32_e32 v20, v15, v19
	v_fma_f32 v21, v19, v15, -v20
	v_fmac_f32_e32 v21, v19, v13
	v_add_f32_e32 v22, v20, v21
	v_sub_f32_e32 v23, v18, v22
	v_sub_f32_e32 v18, v18, v23
	v_sub_f32_e32 v20, v22, v20
	v_sub_f32_e32 v18, v18, v22
	v_add_f32_e32 v16, v16, v18
	v_sub_f32_e32 v18, v20, v21
	v_add_f32_e32 v16, v18, v16
	v_add_f32_e32 v18, v23, v16
	v_mul_f32_e32 v20, v17, v18
	v_mul_f32_e32 v21, v15, v20
	v_fma_f32 v15, v20, v15, -v21
	v_fmac_f32_e32 v15, v20, v13
	v_sub_f32_e32 v13, v23, v18
	v_add_f32_e32 v13, v16, v13
	v_add_f32_e32 v16, v21, v15
	v_sub_f32_e32 v22, v18, v16
	v_sub_f32_e32 v18, v18, v22
	v_sub_f32_e32 v21, v16, v21
	v_sub_f32_e32 v16, v18, v16
	v_add_f32_e32 v13, v13, v16
	v_sub_f32_e32 v15, v21, v15
	v_add_f32_e32 v13, v15, v13
	v_add_f32_e32 v15, v19, v20
	v_add_f32_e32 v13, v22, v13
	v_sub_f32_e32 v16, v15, v19
	v_mul_f32_e32 v13, v17, v13
	v_sub_f32_e32 v16, v20, v16
	v_add_f32_e32 v13, v16, v13
	v_mul_f32_e32 v19, 0x3f317218, v14
	v_add_f32_e32 v16, v15, v13
	v_fma_f32 v20, v14, s78, -v19
	v_mul_f32_e32 v17, v16, v16
	v_fmac_f32_e32 v20, 0xb102e308, v14
	v_sub_f32_e32 v14, v16, v15
	v_fmamk_f32 v18, v17, 0x3e9b6dac, v185
	v_sub_f32_e32 v13, v13, v14
	v_add_f32_e32 v14, v19, v20
	v_fmaak_f32 v18, v17, v18, 0x3f2aaada
	v_sub_f32_e32 v15, v14, v19
	v_ldexp_f32 v19, v16, 1
	v_mul_f32_e32 v16, v16, v17
	v_mul_f32_e32 v16, v16, v18
	v_add_f32_e32 v17, v19, v16
	v_sub_f32_e32 v18, v17, v19
	v_ldexp_f32 v13, v13, 1
	v_sub_f32_e32 v16, v16, v18
	v_add_f32_e32 v13, v13, v16
	v_add_f32_e32 v16, v17, v13
	v_sub_f32_e32 v17, v16, v17
	v_sub_f32_e32 v13, v13, v17
	v_add_f32_e32 v17, v14, v16
	v_sub_f32_e32 v18, v17, v14
	v_sub_f32_e32 v19, v17, v18
	v_sub_f32_e32 v15, v20, v15
	v_sub_f32_e32 v14, v14, v19
	v_sub_f32_e32 v16, v16, v18
	v_add_f32_e32 v14, v16, v14
	v_add_f32_e32 v16, v15, v13
	v_sub_f32_e32 v18, v16, v15
	v_sub_f32_e32 v19, v16, v18
	v_sub_f32_e32 v15, v15, v19
	v_sub_f32_e32 v13, v13, v18
	v_add_f32_e32 v14, v16, v14
	v_add_f32_e32 v13, v13, v15
	v_add_f32_e32 v15, v17, v14
	v_sub_f32_e32 v16, v15, v17
	v_sub_f32_e32 v14, v14, v16
	v_add_f32_e32 v13, v13, v14
	v_add_f32_e32 v13, v15, v13
	v_cndmask_b32_e32 v13, v226, v13, vcc
	v_cmp_lt_f32_e64 vcc, |v12|, s63
	s_nop 1
	v_cndmask_b32_e32 v12, v13, v12, vcc
	v_sub_f32_e32 v8, v8, v12
	v_mul_f32_e32 v8, 0x3fb8aa3b, v8
	global_store_dword v[36:37], v8, off offset:128
	v_readlane_b32 s100, v254, 5
	s_nop 1
	v_mov_b32_e32 v12, s100
	v_fmac_f32_e32 v12, v9, v158
	v_mul_f32_e64 v9, |v12|, s94
	v_fma_f32 v13, |v12|, s94, -v9
	v_rndne_f32_e32 v14, v9
	v_fma_f32 v13, |v12|, s64, v13
	v_sub_f32_e32 v9, v9, v14
	v_add_f32_e32 v9, v9, v13
	v_exp_f32_e32 v9, v9
	v_cvt_i32_f32_e32 v13, v14
	v_cmp_ngt_f32_e64 vcc, |v12|, s58
	v_min_f32_e32 v8, 0, v12
	v_ldexp_f32 v9, v9, v13
	v_cndmask_b32_e32 v9, 0, v9, vcc
	v_cmp_nlt_f32_e64 vcc, |v12|, s59
	s_nop 1
	v_cndmask_b32_e32 v9, v226, v9, vcc
	v_add_f32_e32 v14, 1.0, v9
	v_add_f32_e32 v12, -1.0, v14
	v_sub_f32_e32 v13, v12, v14
	v_add_f32_e32 v13, 1.0, v13
	v_sub_f32_e32 v12, v9, v12
	v_add_f32_e32 v15, v12, v13
	v_frexp_mant_f32_e32 v12, v14
	v_cmp_gt_f32_e32 vcc, s77, v12
	v_cvt_f64_f32_e32 v[12:13], v14
	v_frexp_exp_i32_f64_e32 v12, v[12:13]
	v_subbrev_co_u32_e32 v12, vcc, 0, v12, vcc
	v_sub_u32_e32 v13, 0, v12
	v_ldexp_f32 v14, v14, v13
	v_ldexp_f32 v13, v15, v13
	v_add_f32_e32 v15, -1.0, v14
	v_add_f32_e32 v16, 1.0, v15
	v_sub_f32_e32 v16, v14, v16
	v_add_f32_e32 v16, v13, v16
	v_add_f32_e32 v17, v15, v16
	v_sub_f32_e32 v15, v15, v17
	v_add_f32_e32 v15, v16, v15
	v_add_f32_e32 v16, 1.0, v14
	v_add_f32_e32 v18, -1.0, v16
	v_sub_f32_e32 v14, v14, v18
	v_add_f32_e32 v13, v13, v14
	v_add_f32_e32 v14, v16, v13
	v_sub_f32_e32 v16, v16, v14
	v_add_f32_e32 v13, v13, v16
	v_rcp_f32_e32 v16, v14
	v_cvt_f32_i32_e32 v12, v12
	v_cmp_neq_f32_e32 vcc, s62, v9
	v_mul_f32_e32 v18, v17, v16
	v_mul_f32_e32 v19, v14, v18
	v_fma_f32 v20, v18, v14, -v19
	v_fmac_f32_e32 v20, v18, v13
	v_add_f32_e32 v21, v19, v20
	v_sub_f32_e32 v22, v17, v21
	v_sub_f32_e32 v17, v17, v22
	v_sub_f32_e32 v19, v21, v19
	v_sub_f32_e32 v17, v17, v21
	v_add_f32_e32 v15, v15, v17
	v_sub_f32_e32 v17, v19, v20
	v_add_f32_e32 v15, v17, v15
	v_add_f32_e32 v17, v22, v15
	v_mul_f32_e32 v19, v16, v17
	v_mul_f32_e32 v20, v14, v19
	v_fma_f32 v14, v19, v14, -v20
	v_fmac_f32_e32 v14, v19, v13
	v_sub_f32_e32 v13, v22, v17
	v_add_f32_e32 v13, v15, v13
	v_add_f32_e32 v15, v20, v14
	v_sub_f32_e32 v21, v17, v15
	v_sub_f32_e32 v17, v17, v21
	v_sub_f32_e32 v20, v15, v20
	v_sub_f32_e32 v15, v17, v15
	v_add_f32_e32 v13, v13, v15
	v_sub_f32_e32 v14, v20, v14
	v_add_f32_e32 v13, v14, v13
	v_add_f32_e32 v14, v18, v19
	v_add_f32_e32 v13, v21, v13
	v_sub_f32_e32 v15, v14, v18
	v_mul_f32_e32 v13, v16, v13
	v_sub_f32_e32 v15, v19, v15
	v_add_f32_e32 v13, v15, v13
	v_mul_f32_e32 v18, 0x3f317218, v12
	v_add_f32_e32 v15, v14, v13
	v_fma_f32 v19, v12, s78, -v18
	v_mul_f32_e32 v16, v15, v15
	v_fmac_f32_e32 v19, 0xb102e308, v12
	v_sub_f32_e32 v12, v15, v14
	v_fmamk_f32 v17, v16, 0x3e9b6dac, v185
	v_sub_f32_e32 v12, v13, v12
	v_add_f32_e32 v13, v18, v19
	v_fmaak_f32 v17, v16, v17, 0x3f2aaada
	v_sub_f32_e32 v14, v13, v18
	v_ldexp_f32 v18, v15, 1
	v_mul_f32_e32 v15, v15, v16
	v_mul_f32_e32 v15, v15, v17
	v_add_f32_e32 v16, v18, v15
	v_sub_f32_e32 v17, v16, v18
	v_ldexp_f32 v12, v12, 1
	v_sub_f32_e32 v15, v15, v17
	v_add_f32_e32 v12, v12, v15
	v_add_f32_e32 v15, v16, v12
	v_sub_f32_e32 v16, v15, v16
	v_sub_f32_e32 v12, v12, v16
	v_add_f32_e32 v16, v13, v15
	v_sub_f32_e32 v17, v16, v13
	v_sub_f32_e32 v18, v16, v17
	v_sub_f32_e32 v14, v19, v14
	v_sub_f32_e32 v13, v13, v18
	v_sub_f32_e32 v15, v15, v17
	v_add_f32_e32 v13, v15, v13
	v_add_f32_e32 v15, v14, v12
	v_sub_f32_e32 v17, v15, v14
	v_sub_f32_e32 v18, v15, v17
	v_sub_f32_e32 v14, v14, v18
	v_sub_f32_e32 v12, v12, v17
	v_add_f32_e32 v13, v15, v13
	v_add_f32_e32 v12, v12, v14
	v_add_f32_e32 v14, v16, v13
	v_sub_f32_e32 v15, v14, v16
	v_sub_f32_e32 v13, v13, v15
	v_add_f32_e32 v12, v12, v13
	v_add_f32_e32 v12, v14, v12
	v_cndmask_b32_e32 v12, v226, v12, vcc
	v_cmp_lt_f32_e64 vcc, |v9|, s63
	s_nop 1
	v_cndmask_b32_e32 v9, v12, v9, vcc
	v_sub_f32_e32 v8, v8, v9
	v_mul_f32_e32 v8, 0x3fb8aa3b, v8
	global_store_dword v[24:25], v8, off offset:128
	v_readlane_b32 s100, v254, 6
	s_nop 1
	v_mov_b32_e32 v9, s100
	v_fmac_f32_e32 v9, v10, v158
	v_mul_f32_e64 v10, |v9|, s94
	v_fma_f32 v12, |v9|, s94, -v10
	v_rndne_f32_e32 v13, v10
	v_fma_f32 v12, |v9|, s64, v12
	v_sub_f32_e32 v10, v10, v13
	v_add_f32_e32 v10, v10, v12
	v_exp_f32_e32 v10, v10
	v_cvt_i32_f32_e32 v12, v13
	v_cmp_ngt_f32_e64 vcc, |v9|, s58
	v_min_f32_e32 v8, 0, v9
	v_ldexp_f32 v10, v10, v12
	v_cndmask_b32_e32 v10, 0, v10, vcc
	v_cmp_nlt_f32_e64 vcc, |v9|, s59
	s_nop 1
	v_cndmask_b32_e32 v9, v226, v10, vcc
	v_add_f32_e32 v10, 1.0, v9
	v_add_f32_e32 v12, -1.0, v10
	v_sub_f32_e32 v13, v12, v10
	v_add_f32_e32 v13, 1.0, v13
	v_sub_f32_e32 v12, v9, v12
	v_add_f32_e32 v14, v12, v13
	v_frexp_mant_f32_e32 v12, v10
	v_cmp_gt_f32_e32 vcc, s77, v12
	v_cvt_f64_f32_e32 v[12:13], v10
	v_frexp_exp_i32_f64_e32 v12, v[12:13]
	v_subbrev_co_u32_e32 v12, vcc, 0, v12, vcc
	v_sub_u32_e32 v13, 0, v12
	v_ldexp_f32 v10, v10, v13
	v_ldexp_f32 v13, v14, v13
	v_add_f32_e32 v14, -1.0, v10
	v_add_f32_e32 v15, 1.0, v14
	v_sub_f32_e32 v15, v10, v15
	v_add_f32_e32 v15, v13, v15
	v_add_f32_e32 v16, v14, v15
	v_sub_f32_e32 v14, v14, v16
	v_add_f32_e32 v14, v15, v14
	v_add_f32_e32 v15, 1.0, v10
	v_add_f32_e32 v17, -1.0, v15
	v_sub_f32_e32 v10, v10, v17
	v_add_f32_e32 v10, v13, v10
	v_add_f32_e32 v13, v15, v10
	v_sub_f32_e32 v15, v15, v13
	v_add_f32_e32 v10, v10, v15
	v_rcp_f32_e32 v15, v13
	v_cvt_f32_i32_e32 v12, v12
	v_cmp_neq_f32_e32 vcc, s62, v9
	v_mul_f32_e32 v17, v16, v15
	v_mul_f32_e32 v18, v13, v17
	v_fma_f32 v19, v17, v13, -v18
	v_fmac_f32_e32 v19, v17, v10
	v_add_f32_e32 v20, v18, v19
	v_sub_f32_e32 v21, v16, v20
	v_sub_f32_e32 v16, v16, v21
	v_sub_f32_e32 v18, v20, v18
	v_sub_f32_e32 v16, v16, v20
	v_add_f32_e32 v14, v14, v16
	v_sub_f32_e32 v16, v18, v19
	v_add_f32_e32 v14, v16, v14
	v_add_f32_e32 v16, v21, v14
	v_mul_f32_e32 v18, v15, v16
	v_mul_f32_e32 v19, v13, v18
	v_fma_f32 v13, v18, v13, -v19
	v_fmac_f32_e32 v13, v18, v10
	v_sub_f32_e32 v10, v21, v16
	v_add_f32_e32 v10, v14, v10
	v_add_f32_e32 v14, v19, v13
	v_sub_f32_e32 v20, v16, v14
	v_sub_f32_e32 v16, v16, v20
	v_sub_f32_e32 v19, v14, v19
	v_sub_f32_e32 v14, v16, v14
	v_add_f32_e32 v10, v10, v14
	v_sub_f32_e32 v13, v19, v13
	v_add_f32_e32 v10, v13, v10
	v_add_f32_e32 v13, v17, v18
	v_add_f32_e32 v10, v20, v10
	v_sub_f32_e32 v14, v13, v17
	v_mul_f32_e32 v10, v15, v10
	v_sub_f32_e32 v14, v18, v14
	v_add_f32_e32 v10, v14, v10
	v_mul_f32_e32 v17, 0x3f317218, v12
	v_add_f32_e32 v14, v13, v10
	v_fma_f32 v18, v12, s78, -v17
	v_mul_f32_e32 v15, v14, v14
	v_fmac_f32_e32 v18, 0xb102e308, v12
	v_sub_f32_e32 v12, v14, v13
	v_fmamk_f32 v16, v15, 0x3e9b6dac, v185
	v_sub_f32_e32 v10, v10, v12
	v_add_f32_e32 v12, v17, v18
	v_fmaak_f32 v16, v15, v16, 0x3f2aaada
	v_sub_f32_e32 v13, v12, v17
	v_ldexp_f32 v17, v14, 1
	v_mul_f32_e32 v14, v14, v15
	v_mul_f32_e32 v14, v14, v16
	v_add_f32_e32 v15, v17, v14
	v_sub_f32_e32 v16, v15, v17
	v_ldexp_f32 v10, v10, 1
	v_sub_f32_e32 v14, v14, v16
	v_add_f32_e32 v10, v10, v14
	v_add_f32_e32 v14, v15, v10
	v_sub_f32_e32 v15, v14, v15
	v_sub_f32_e32 v10, v10, v15
	v_add_f32_e32 v15, v12, v14
	v_sub_f32_e32 v16, v15, v12
	v_sub_f32_e32 v17, v15, v16
	v_sub_f32_e32 v13, v18, v13
	v_sub_f32_e32 v12, v12, v17
	v_sub_f32_e32 v14, v14, v16
	v_add_f32_e32 v12, v14, v12
	v_add_f32_e32 v14, v13, v10
	v_sub_f32_e32 v16, v14, v13
	v_sub_f32_e32 v17, v14, v16
	v_sub_f32_e32 v13, v13, v17
	v_sub_f32_e32 v10, v10, v16
	v_add_f32_e32 v12, v14, v12
	v_add_f32_e32 v10, v10, v13
	v_add_f32_e32 v13, v15, v12
	v_sub_f32_e32 v14, v13, v15
	v_sub_f32_e32 v12, v12, v14
	v_add_f32_e32 v10, v10, v12
	v_add_f32_e32 v10, v13, v10
	v_cndmask_b32_e32 v10, v226, v10, vcc
	v_cmp_lt_f32_e64 vcc, |v9|, s63
	s_nop 1
	v_cndmask_b32_e32 v9, v10, v9, vcc
	v_sub_f32_e32 v8, v8, v9
	v_mul_f32_e32 v8, 0x3fb8aa3b, v8
	global_store_dword v[38:39], v8, off offset:128
	v_readlane_b32 s100, v254, 7
	s_nop 1
	v_mov_b32_e32 v9, s100
	v_fmac_f32_e32 v9, v11, v158
	v_mul_f32_e64 v10, |v9|, s94
	v_fma_f32 v11, |v9|, s94, -v10
	v_rndne_f32_e32 v12, v10
	v_fma_f32 v11, |v9|, s64, v11
	v_sub_f32_e32 v10, v10, v12
	v_add_f32_e32 v10, v10, v11
	v_exp_f32_e32 v10, v10
	v_cvt_i32_f32_e32 v11, v12
	v_cmp_ngt_f32_e64 vcc, |v9|, s58
	v_min_f32_e32 v8, 0, v9
	v_ldexp_f32 v10, v10, v11
	v_cndmask_b32_e32 v10, 0, v10, vcc
	v_cmp_nlt_f32_e64 vcc, |v9|, s59
	s_nop 1
	v_cndmask_b32_e32 v9, v226, v10, vcc
	v_add_f32_e32 v12, 1.0, v9
	v_add_f32_e32 v10, -1.0, v12
	v_sub_f32_e32 v11, v10, v12
	v_add_f32_e32 v11, 1.0, v11
	v_sub_f32_e32 v10, v9, v10
	v_add_f32_e32 v13, v10, v11
	v_frexp_mant_f32_e32 v10, v12
	v_cmp_gt_f32_e32 vcc, s77, v10
	v_cvt_f64_f32_e32 v[10:11], v12
	v_frexp_exp_i32_f64_e32 v10, v[10:11]
	v_subbrev_co_u32_e32 v10, vcc, 0, v10, vcc
	v_sub_u32_e32 v11, 0, v10
	v_ldexp_f32 v12, v12, v11
	v_ldexp_f32 v11, v13, v11
	v_add_f32_e32 v13, -1.0, v12
	v_add_f32_e32 v14, 1.0, v13
	v_sub_f32_e32 v14, v12, v14
	v_add_f32_e32 v14, v11, v14
	v_add_f32_e32 v15, v13, v14
	v_sub_f32_e32 v13, v13, v15
	v_add_f32_e32 v13, v14, v13
	v_add_f32_e32 v14, 1.0, v12
	v_add_f32_e32 v16, -1.0, v14
	v_sub_f32_e32 v12, v12, v16
	v_add_f32_e32 v11, v11, v12
	v_add_f32_e32 v12, v14, v11
	v_sub_f32_e32 v14, v14, v12
	v_add_f32_e32 v11, v11, v14
	v_rcp_f32_e32 v14, v12
	v_cvt_f32_i32_e32 v10, v10
	v_cmp_neq_f32_e32 vcc, s62, v9
	v_mul_f32_e32 v16, v15, v14
	v_mul_f32_e32 v17, v12, v16
	v_fma_f32 v18, v16, v12, -v17
	v_fmac_f32_e32 v18, v16, v11
	v_add_f32_e32 v19, v17, v18
	v_sub_f32_e32 v20, v15, v19
	v_sub_f32_e32 v15, v15, v20
	v_sub_f32_e32 v17, v19, v17
	v_sub_f32_e32 v15, v15, v19
	v_add_f32_e32 v13, v13, v15
	v_sub_f32_e32 v15, v17, v18
	v_add_f32_e32 v13, v15, v13
	v_add_f32_e32 v15, v20, v13
	v_mul_f32_e32 v17, v14, v15
	v_mul_f32_e32 v18, v12, v17
	v_fma_f32 v12, v17, v12, -v18
	v_fmac_f32_e32 v12, v17, v11
	v_sub_f32_e32 v11, v20, v15
	v_add_f32_e32 v11, v13, v11
	v_add_f32_e32 v13, v18, v12
	v_sub_f32_e32 v19, v15, v13
	v_sub_f32_e32 v15, v15, v19
	v_sub_f32_e32 v18, v13, v18
	v_sub_f32_e32 v13, v15, v13
	v_add_f32_e32 v11, v11, v13
	v_sub_f32_e32 v12, v18, v12
	v_add_f32_e32 v11, v12, v11
	v_add_f32_e32 v12, v16, v17
	v_add_f32_e32 v11, v19, v11
	v_sub_f32_e32 v13, v12, v16
	v_mul_f32_e32 v11, v14, v11
	v_sub_f32_e32 v13, v17, v13
	v_add_f32_e32 v11, v13, v11
	v_mul_f32_e32 v16, 0x3f317218, v10
	v_add_f32_e32 v13, v12, v11
	v_fma_f32 v17, v10, s78, -v16
	v_mul_f32_e32 v14, v13, v13
	v_fmac_f32_e32 v17, 0xb102e308, v10
	v_sub_f32_e32 v10, v13, v12
	v_fmamk_f32 v15, v14, 0x3e9b6dac, v185
	v_sub_f32_e32 v10, v11, v10
	v_add_f32_e32 v11, v16, v17
	v_fmaak_f32 v15, v14, v15, 0x3f2aaada
	v_sub_f32_e32 v12, v11, v16
	v_ldexp_f32 v16, v13, 1
	v_mul_f32_e32 v13, v13, v14
	v_mul_f32_e32 v13, v13, v15
	v_add_f32_e32 v14, v16, v13
	v_sub_f32_e32 v15, v14, v16
	v_ldexp_f32 v10, v10, 1
	v_sub_f32_e32 v13, v13, v15
	v_add_f32_e32 v10, v10, v13
	v_add_f32_e32 v13, v14, v10
	v_sub_f32_e32 v14, v13, v14
	v_sub_f32_e32 v10, v10, v14
	v_add_f32_e32 v14, v11, v13
	v_sub_f32_e32 v15, v14, v11
	v_sub_f32_e32 v16, v14, v15
	v_sub_f32_e32 v12, v17, v12
	v_sub_f32_e32 v11, v11, v16
	v_sub_f32_e32 v13, v13, v15
	v_add_f32_e32 v11, v13, v11
	v_add_f32_e32 v13, v12, v10
	v_sub_f32_e32 v15, v13, v12
	v_sub_f32_e32 v16, v13, v15
	v_sub_f32_e32 v12, v12, v16
	v_sub_f32_e32 v10, v10, v15
	v_add_f32_e32 v11, v13, v11
	v_add_f32_e32 v10, v10, v12
	v_add_f32_e32 v12, v14, v11
	v_sub_f32_e32 v13, v12, v14
	v_sub_f32_e32 v11, v11, v13
	v_add_f32_e32 v10, v10, v11
	v_add_f32_e32 v10, v12, v10
	v_cndmask_b32_e32 v10, v226, v10, vcc
	v_cmp_lt_f32_e64 vcc, |v9|, s63
	s_nop 1
	v_cndmask_b32_e32 v9, v10, v9, vcc
	v_sub_f32_e32 v8, v8, v9
	v_mul_f32_e32 v8, 0x3fb8aa3b, v8
	global_store_dword v[26:27], v8, off offset:128
	v_readlane_b32 s100, v254, 0
	s_nop 1
	v_mov_b32_e32 v8, s100
	v_fmac_f32_e32 v8, v4, v156
	v_mul_f32_e64 v9, |v8|, s94
	v_fma_f32 v10, |v8|, s94, -v9
	v_rndne_f32_e32 v11, v9
	v_fma_f32 v10, |v8|, s64, v10
	v_sub_f32_e32 v9, v9, v11
	v_add_f32_e32 v9, v9, v10
	v_exp_f32_e32 v9, v9
	v_cvt_i32_f32_e32 v10, v11
	v_cmp_ngt_f32_e64 vcc, |v8|, s58
	v_min_f32_e32 v4, 0, v8
	v_ldexp_f32 v9, v9, v10
	v_cndmask_b32_e32 v9, 0, v9, vcc
	v_cmp_nlt_f32_e64 vcc, |v8|, s59
	s_nop 1
	v_cndmask_b32_e32 v8, v226, v9, vcc
	v_add_f32_e32 v9, 1.0, v8
	v_add_f32_e32 v10, -1.0, v9
	v_sub_f32_e32 v11, v10, v9
	v_add_f32_e32 v11, 1.0, v11
	v_sub_f32_e32 v10, v8, v10
	v_add_f32_e32 v12, v10, v11
	v_frexp_mant_f32_e32 v10, v9
	v_cmp_gt_f32_e32 vcc, s77, v10
	v_cvt_f64_f32_e32 v[10:11], v9
	v_frexp_exp_i32_f64_e32 v10, v[10:11]
	v_subbrev_co_u32_e32 v10, vcc, 0, v10, vcc
	v_sub_u32_e32 v11, 0, v10
	v_ldexp_f32 v9, v9, v11
	v_ldexp_f32 v11, v12, v11
	v_add_f32_e32 v12, -1.0, v9
	v_add_f32_e32 v13, 1.0, v12
	v_sub_f32_e32 v13, v9, v13
	v_add_f32_e32 v13, v11, v13
	v_add_f32_e32 v14, v12, v13
	v_sub_f32_e32 v12, v12, v14
	v_add_f32_e32 v12, v13, v12
	v_add_f32_e32 v13, 1.0, v9
	v_add_f32_e32 v15, -1.0, v13
	v_sub_f32_e32 v9, v9, v15
	v_add_f32_e32 v9, v11, v9
	v_add_f32_e32 v11, v13, v9
	v_sub_f32_e32 v13, v13, v11
	v_add_f32_e32 v9, v9, v13
	v_rcp_f32_e32 v13, v11
	v_cvt_f32_i32_e32 v10, v10
	v_cmp_neq_f32_e32 vcc, s62, v8
	v_mul_f32_e32 v15, v14, v13
	v_mul_f32_e32 v16, v11, v15
	v_fma_f32 v17, v15, v11, -v16
	v_fmac_f32_e32 v17, v15, v9
	v_add_f32_e32 v18, v16, v17
	v_sub_f32_e32 v19, v14, v18
	v_sub_f32_e32 v14, v14, v19
	v_sub_f32_e32 v16, v18, v16
	v_sub_f32_e32 v14, v14, v18
	v_add_f32_e32 v12, v12, v14
	v_sub_f32_e32 v14, v16, v17
	v_add_f32_e32 v12, v14, v12
	v_add_f32_e32 v14, v19, v12
	v_mul_f32_e32 v16, v13, v14
	v_mul_f32_e32 v17, v11, v16
	v_fma_f32 v11, v16, v11, -v17
	v_fmac_f32_e32 v11, v16, v9
	v_sub_f32_e32 v9, v19, v14
	v_add_f32_e32 v9, v12, v9
	v_add_f32_e32 v12, v17, v11
	v_sub_f32_e32 v18, v14, v12
	v_sub_f32_e32 v14, v14, v18
	v_sub_f32_e32 v17, v12, v17
	v_sub_f32_e32 v12, v14, v12
	v_add_f32_e32 v9, v9, v12
	v_sub_f32_e32 v11, v17, v11
	v_add_f32_e32 v9, v11, v9
	v_add_f32_e32 v11, v15, v16
	v_add_f32_e32 v9, v18, v9
	v_sub_f32_e32 v12, v11, v15
	v_mul_f32_e32 v9, v13, v9
	v_sub_f32_e32 v12, v16, v12
	v_add_f32_e32 v9, v12, v9
	v_mul_f32_e32 v15, 0x3f317218, v10
	v_add_f32_e32 v12, v11, v9
	v_fma_f32 v16, v10, s78, -v15
	v_mul_f32_e32 v13, v12, v12
	v_fmac_f32_e32 v16, 0xb102e308, v10
	v_sub_f32_e32 v10, v12, v11
	v_fmamk_f32 v14, v13, 0x3e9b6dac, v185
	v_sub_f32_e32 v9, v9, v10
	v_add_f32_e32 v10, v15, v16
	v_fmaak_f32 v14, v13, v14, 0x3f2aaada
	v_sub_f32_e32 v11, v10, v15
	v_ldexp_f32 v15, v12, 1
	v_mul_f32_e32 v12, v12, v13
	v_mul_f32_e32 v12, v12, v14
	v_add_f32_e32 v13, v15, v12
	v_sub_f32_e32 v14, v13, v15
	v_ldexp_f32 v9, v9, 1
	v_sub_f32_e32 v12, v12, v14
	v_add_f32_e32 v9, v9, v12
	v_add_f32_e32 v12, v13, v9
	v_sub_f32_e32 v13, v12, v13
	v_sub_f32_e32 v9, v9, v13
	v_add_f32_e32 v13, v10, v12
	v_sub_f32_e32 v14, v13, v10
	v_sub_f32_e32 v15, v13, v14
	v_sub_f32_e32 v11, v16, v11
	v_sub_f32_e32 v10, v10, v15
	v_sub_f32_e32 v12, v12, v14
	v_add_f32_e32 v10, v12, v10
	v_add_f32_e32 v12, v11, v9
	v_sub_f32_e32 v14, v12, v11
	v_sub_f32_e32 v15, v12, v14
	v_sub_f32_e32 v11, v11, v15
	v_sub_f32_e32 v9, v9, v14
	v_add_f32_e32 v10, v12, v10
	v_add_f32_e32 v9, v9, v11
	v_add_f32_e32 v11, v13, v10
	v_sub_f32_e32 v12, v11, v13
	v_sub_f32_e32 v10, v10, v12
	v_add_f32_e32 v9, v9, v10
	v_add_f32_e32 v9, v11, v9
	v_cndmask_b32_e32 v9, v226, v9, vcc
	v_cmp_lt_f32_e64 vcc, |v8|, s63
	s_nop 1
	v_cndmask_b32_e32 v8, v9, v8, vcc
	v_sub_f32_e32 v4, v4, v8
	v_mul_f32_e32 v4, 0x3fb8aa3b, v4
	global_store_dword v[32:33], v4, off offset:192
	v_readlane_b32 s100, v254, 1
	s_nop 1
	v_mov_b32_e32 v8, s100
	v_fmac_f32_e32 v8, v5, v156
	v_mul_f32_e64 v5, |v8|, s94
	v_fma_f32 v9, |v8|, s94, -v5
	v_rndne_f32_e32 v10, v5
	v_fma_f32 v9, |v8|, s64, v9
	v_sub_f32_e32 v5, v5, v10
	v_add_f32_e32 v5, v5, v9
	v_exp_f32_e32 v5, v5
	v_cvt_i32_f32_e32 v9, v10
	v_cmp_ngt_f32_e64 vcc, |v8|, s58
	v_min_f32_e32 v4, 0, v8
	v_ldexp_f32 v5, v5, v9
	v_cndmask_b32_e32 v5, 0, v5, vcc
	v_cmp_nlt_f32_e64 vcc, |v8|, s59
	s_nop 1
	v_cndmask_b32_e32 v5, v226, v5, vcc
	v_add_f32_e32 v10, 1.0, v5
	v_add_f32_e32 v8, -1.0, v10
	v_sub_f32_e32 v9, v8, v10
	v_add_f32_e32 v9, 1.0, v9
	v_sub_f32_e32 v8, v5, v8
	v_add_f32_e32 v11, v8, v9
	v_frexp_mant_f32_e32 v8, v10
	v_cmp_gt_f32_e32 vcc, s77, v8
	v_cvt_f64_f32_e32 v[8:9], v10
	v_frexp_exp_i32_f64_e32 v8, v[8:9]
	v_subbrev_co_u32_e32 v8, vcc, 0, v8, vcc
	v_sub_u32_e32 v9, 0, v8
	v_ldexp_f32 v10, v10, v9
	v_ldexp_f32 v9, v11, v9
	v_add_f32_e32 v11, -1.0, v10
	v_add_f32_e32 v12, 1.0, v11
	v_sub_f32_e32 v12, v10, v12
	v_add_f32_e32 v12, v9, v12
	v_add_f32_e32 v13, v11, v12
	v_sub_f32_e32 v11, v11, v13
	v_add_f32_e32 v11, v12, v11
	v_add_f32_e32 v12, 1.0, v10
	v_add_f32_e32 v14, -1.0, v12
	v_sub_f32_e32 v10, v10, v14
	v_add_f32_e32 v9, v9, v10
	v_add_f32_e32 v10, v12, v9
	v_sub_f32_e32 v12, v12, v10
	v_add_f32_e32 v9, v9, v12
	v_rcp_f32_e32 v12, v10
	v_cvt_f32_i32_e32 v8, v8
	v_cmp_neq_f32_e32 vcc, s62, v5
	v_mul_f32_e32 v14, v13, v12
	v_mul_f32_e32 v15, v10, v14
	v_fma_f32 v16, v14, v10, -v15
	v_fmac_f32_e32 v16, v14, v9
	v_add_f32_e32 v17, v15, v16
	v_sub_f32_e32 v18, v13, v17
	v_sub_f32_e32 v13, v13, v18
	v_sub_f32_e32 v15, v17, v15
	v_sub_f32_e32 v13, v13, v17
	v_add_f32_e32 v11, v11, v13
	v_sub_f32_e32 v13, v15, v16
	v_add_f32_e32 v11, v13, v11
	v_add_f32_e32 v13, v18, v11
	v_mul_f32_e32 v15, v12, v13
	v_mul_f32_e32 v16, v10, v15
	v_fma_f32 v10, v15, v10, -v16
	v_fmac_f32_e32 v10, v15, v9
	v_sub_f32_e32 v9, v18, v13
	v_add_f32_e32 v9, v11, v9
	v_add_f32_e32 v11, v16, v10
	v_sub_f32_e32 v17, v13, v11
	v_sub_f32_e32 v13, v13, v17
	v_sub_f32_e32 v16, v11, v16
	v_sub_f32_e32 v11, v13, v11
	v_add_f32_e32 v9, v9, v11
	v_sub_f32_e32 v10, v16, v10
	v_add_f32_e32 v9, v10, v9
	v_add_f32_e32 v10, v14, v15
	v_add_f32_e32 v9, v17, v9
	v_sub_f32_e32 v11, v10, v14
	v_mul_f32_e32 v9, v12, v9
	v_sub_f32_e32 v11, v15, v11
	v_add_f32_e32 v9, v11, v9
	v_mul_f32_e32 v14, 0x3f317218, v8
	v_add_f32_e32 v11, v10, v9
	v_fma_f32 v15, v8, s78, -v14
	v_mul_f32_e32 v12, v11, v11
	v_fmac_f32_e32 v15, 0xb102e308, v8
	v_sub_f32_e32 v8, v11, v10
	v_fmamk_f32 v13, v12, 0x3e9b6dac, v185
	v_sub_f32_e32 v8, v9, v8
	v_add_f32_e32 v9, v14, v15
	v_fmaak_f32 v13, v12, v13, 0x3f2aaada
	v_sub_f32_e32 v10, v9, v14
	v_ldexp_f32 v14, v11, 1
	v_mul_f32_e32 v11, v11, v12
	v_mul_f32_e32 v11, v11, v13
	v_add_f32_e32 v12, v14, v11
	v_sub_f32_e32 v13, v12, v14
	v_ldexp_f32 v8, v8, 1
	v_sub_f32_e32 v11, v11, v13
	v_add_f32_e32 v8, v8, v11
	v_add_f32_e32 v11, v12, v8
	v_sub_f32_e32 v12, v11, v12
	v_sub_f32_e32 v8, v8, v12
	v_add_f32_e32 v12, v9, v11
	v_sub_f32_e32 v13, v12, v9
	v_sub_f32_e32 v14, v12, v13
	v_sub_f32_e32 v10, v15, v10
	v_sub_f32_e32 v9, v9, v14
	v_sub_f32_e32 v11, v11, v13
	v_add_f32_e32 v9, v11, v9
	v_add_f32_e32 v11, v10, v8
	v_sub_f32_e32 v13, v11, v10
	v_sub_f32_e32 v14, v11, v13
	v_sub_f32_e32 v10, v10, v14
	v_sub_f32_e32 v8, v8, v13
	v_add_f32_e32 v9, v11, v9
	v_add_f32_e32 v8, v8, v10
	v_add_f32_e32 v10, v12, v9
	v_sub_f32_e32 v11, v10, v12
	v_sub_f32_e32 v9, v9, v11
	v_add_f32_e32 v8, v8, v9
	v_add_f32_e32 v8, v10, v8
	v_cndmask_b32_e32 v8, v226, v8, vcc
	v_cmp_lt_f32_e64 vcc, |v5|, s63
	s_nop 1
	v_cndmask_b32_e32 v5, v8, v5, vcc
	v_sub_f32_e32 v4, v4, v5
	v_mul_f32_e32 v4, 0x3fb8aa3b, v4
	global_store_dword v[28:29], v4, off offset:192
	v_readlane_b32 s100, v254, 2
	s_nop 1
	v_mov_b32_e32 v5, s100
	v_fmac_f32_e32 v5, v6, v156
	v_mul_f32_e64 v6, |v5|, s94
	v_fma_f32 v8, |v5|, s94, -v6
	v_rndne_f32_e32 v9, v6
	v_fma_f32 v8, |v5|, s64, v8
	v_sub_f32_e32 v6, v6, v9
	v_add_f32_e32 v6, v6, v8
	v_exp_f32_e32 v6, v6
	v_cvt_i32_f32_e32 v8, v9
	v_cmp_ngt_f32_e64 vcc, |v5|, s58
	v_min_f32_e32 v4, 0, v5
	v_ldexp_f32 v6, v6, v8
	v_cndmask_b32_e32 v6, 0, v6, vcc
	v_cmp_nlt_f32_e64 vcc, |v5|, s59
	s_nop 1
	v_cndmask_b32_e32 v5, v226, v6, vcc
	v_add_f32_e32 v6, 1.0, v5
	v_add_f32_e32 v8, -1.0, v6
	v_sub_f32_e32 v9, v8, v6
	v_add_f32_e32 v9, 1.0, v9
	v_sub_f32_e32 v8, v5, v8
	v_add_f32_e32 v10, v8, v9
	v_frexp_mant_f32_e32 v8, v6
	v_cmp_gt_f32_e32 vcc, s77, v8
	v_cvt_f64_f32_e32 v[8:9], v6
	v_frexp_exp_i32_f64_e32 v8, v[8:9]
	v_subbrev_co_u32_e32 v8, vcc, 0, v8, vcc
	v_sub_u32_e32 v9, 0, v8
	v_ldexp_f32 v6, v6, v9
	v_ldexp_f32 v9, v10, v9
	v_add_f32_e32 v10, -1.0, v6
	v_add_f32_e32 v11, 1.0, v10
	v_sub_f32_e32 v11, v6, v11
	v_add_f32_e32 v11, v9, v11
	v_add_f32_e32 v12, v10, v11
	v_sub_f32_e32 v10, v10, v12
	v_add_f32_e32 v10, v11, v10
	v_add_f32_e32 v11, 1.0, v6
	v_add_f32_e32 v13, -1.0, v11
	v_sub_f32_e32 v6, v6, v13
	v_add_f32_e32 v6, v9, v6
	v_add_f32_e32 v9, v11, v6
	v_sub_f32_e32 v11, v11, v9
	v_add_f32_e32 v6, v6, v11
	v_rcp_f32_e32 v11, v9
	v_cvt_f32_i32_e32 v8, v8
	v_cmp_neq_f32_e32 vcc, s62, v5
	v_mul_f32_e32 v13, v12, v11
	v_mul_f32_e32 v14, v9, v13
	v_fma_f32 v15, v13, v9, -v14
	v_fmac_f32_e32 v15, v13, v6
	v_add_f32_e32 v16, v14, v15
	v_sub_f32_e32 v17, v12, v16
	v_sub_f32_e32 v12, v12, v17
	v_sub_f32_e32 v14, v16, v14
	v_sub_f32_e32 v12, v12, v16
	v_add_f32_e32 v10, v10, v12
	v_sub_f32_e32 v12, v14, v15
	v_add_f32_e32 v10, v12, v10
	v_add_f32_e32 v12, v17, v10
	v_mul_f32_e32 v14, v11, v12
	v_mul_f32_e32 v15, v9, v14
	v_fma_f32 v9, v14, v9, -v15
	v_fmac_f32_e32 v9, v14, v6
	v_sub_f32_e32 v6, v17, v12
	v_add_f32_e32 v6, v10, v6
	v_add_f32_e32 v10, v15, v9
	v_sub_f32_e32 v16, v12, v10
	v_sub_f32_e32 v12, v12, v16
	v_sub_f32_e32 v15, v10, v15
	v_sub_f32_e32 v10, v12, v10
	v_add_f32_e32 v6, v6, v10
	v_sub_f32_e32 v9, v15, v9
	v_add_f32_e32 v6, v9, v6
	v_add_f32_e32 v9, v13, v14
	v_add_f32_e32 v6, v16, v6
	v_sub_f32_e32 v10, v9, v13
	v_mul_f32_e32 v6, v11, v6
	v_sub_f32_e32 v10, v14, v10
	v_add_f32_e32 v6, v10, v6
	v_mul_f32_e32 v13, 0x3f317218, v8
	v_add_f32_e32 v10, v9, v6
	v_fma_f32 v14, v8, s78, -v13
	v_mul_f32_e32 v11, v10, v10
	v_fmac_f32_e32 v14, 0xb102e308, v8
	v_sub_f32_e32 v8, v10, v9
	v_fmamk_f32 v12, v11, 0x3e9b6dac, v185
	v_sub_f32_e32 v6, v6, v8
	v_add_f32_e32 v8, v13, v14
	v_fmaak_f32 v12, v11, v12, 0x3f2aaada
	v_sub_f32_e32 v9, v8, v13
	v_ldexp_f32 v13, v10, 1
	v_mul_f32_e32 v10, v10, v11
	v_mul_f32_e32 v10, v10, v12
	v_add_f32_e32 v11, v13, v10
	v_sub_f32_e32 v12, v11, v13
	v_ldexp_f32 v6, v6, 1
	v_sub_f32_e32 v10, v10, v12
	v_add_f32_e32 v6, v6, v10
	v_add_f32_e32 v10, v11, v6
	v_sub_f32_e32 v11, v10, v11
	v_sub_f32_e32 v6, v6, v11
	v_add_f32_e32 v11, v8, v10
	v_sub_f32_e32 v12, v11, v8
	v_sub_f32_e32 v13, v11, v12
	v_sub_f32_e32 v9, v14, v9
	v_sub_f32_e32 v8, v8, v13
	v_sub_f32_e32 v10, v10, v12
	v_add_f32_e32 v8, v10, v8
	v_add_f32_e32 v10, v9, v6
	v_sub_f32_e32 v12, v10, v9
	v_sub_f32_e32 v13, v10, v12
	v_sub_f32_e32 v9, v9, v13
	v_sub_f32_e32 v6, v6, v12
	v_add_f32_e32 v8, v10, v8
	v_add_f32_e32 v6, v6, v9
	v_add_f32_e32 v9, v11, v8
	v_sub_f32_e32 v10, v9, v11
	v_sub_f32_e32 v8, v8, v10
	v_add_f32_e32 v6, v6, v8
	v_add_f32_e32 v6, v9, v6
	v_cndmask_b32_e32 v6, v226, v6, vcc
	v_cmp_lt_f32_e64 vcc, |v5|, s63
	s_nop 1
	v_cndmask_b32_e32 v5, v6, v5, vcc
	v_sub_f32_e32 v4, v4, v5
	v_mul_f32_e32 v4, 0x3fb8aa3b, v4
	global_store_dword v[34:35], v4, off offset:192
	v_readlane_b32 s100, v254, 3
	s_nop 1
	v_mov_b32_e32 v5, s100
	v_fmac_f32_e32 v5, v7, v156
	v_mul_f32_e64 v6, |v5|, s94
	v_fma_f32 v7, |v5|, s94, -v6
	v_rndne_f32_e32 v8, v6
	v_fma_f32 v7, |v5|, s64, v7
	v_sub_f32_e32 v6, v6, v8
	v_add_f32_e32 v6, v6, v7
	v_exp_f32_e32 v6, v6
	v_cvt_i32_f32_e32 v7, v8
	v_cmp_ngt_f32_e64 vcc, |v5|, s58
	v_min_f32_e32 v4, 0, v5
	v_ldexp_f32 v6, v6, v7
	v_cndmask_b32_e32 v6, 0, v6, vcc
	v_cmp_nlt_f32_e64 vcc, |v5|, s59
	s_nop 1
	v_cndmask_b32_e32 v5, v226, v6, vcc
	v_add_f32_e32 v8, 1.0, v5
	v_add_f32_e32 v6, -1.0, v8
	v_sub_f32_e32 v7, v6, v8
	v_add_f32_e32 v7, 1.0, v7
	v_sub_f32_e32 v6, v5, v6
	v_add_f32_e32 v9, v6, v7
	v_frexp_mant_f32_e32 v6, v8
	v_cmp_gt_f32_e32 vcc, s77, v6
	v_cvt_f64_f32_e32 v[6:7], v8
	v_frexp_exp_i32_f64_e32 v6, v[6:7]
	v_subbrev_co_u32_e32 v6, vcc, 0, v6, vcc
	v_sub_u32_e32 v7, 0, v6
	v_ldexp_f32 v8, v8, v7
	v_ldexp_f32 v7, v9, v7
	v_add_f32_e32 v9, -1.0, v8
	v_add_f32_e32 v10, 1.0, v9
	v_sub_f32_e32 v10, v8, v10
	v_add_f32_e32 v10, v7, v10
	v_add_f32_e32 v11, v9, v10
	v_sub_f32_e32 v9, v9, v11
	v_add_f32_e32 v9, v10, v9
	v_add_f32_e32 v10, 1.0, v8
	v_add_f32_e32 v12, -1.0, v10
	v_sub_f32_e32 v8, v8, v12
	v_add_f32_e32 v7, v7, v8
	v_add_f32_e32 v8, v10, v7
	v_sub_f32_e32 v10, v10, v8
	v_add_f32_e32 v7, v7, v10
	v_rcp_f32_e32 v10, v8
	v_cvt_f32_i32_e32 v6, v6
	v_cmp_neq_f32_e32 vcc, s62, v5
	v_mul_f32_e32 v12, v11, v10
	v_mul_f32_e32 v13, v8, v12
	v_fma_f32 v14, v12, v8, -v13
	v_fmac_f32_e32 v14, v12, v7
	v_add_f32_e32 v15, v13, v14
	v_sub_f32_e32 v16, v11, v15
	v_sub_f32_e32 v11, v11, v16
	v_sub_f32_e32 v13, v15, v13
	v_sub_f32_e32 v11, v11, v15
	v_add_f32_e32 v9, v9, v11
	v_sub_f32_e32 v11, v13, v14
	v_add_f32_e32 v9, v11, v9
	v_add_f32_e32 v11, v16, v9
	v_mul_f32_e32 v13, v10, v11
	v_mul_f32_e32 v14, v8, v13
	v_fma_f32 v8, v13, v8, -v14
	v_fmac_f32_e32 v8, v13, v7
	v_sub_f32_e32 v7, v16, v11
	v_add_f32_e32 v7, v9, v7
	v_add_f32_e32 v9, v14, v8
	v_sub_f32_e32 v15, v11, v9
	v_sub_f32_e32 v11, v11, v15
	v_sub_f32_e32 v14, v9, v14
	v_sub_f32_e32 v9, v11, v9
	v_add_f32_e32 v7, v7, v9
	v_sub_f32_e32 v8, v14, v8
	v_add_f32_e32 v7, v8, v7
	v_add_f32_e32 v8, v12, v13
	v_add_f32_e32 v7, v15, v7
	v_sub_f32_e32 v9, v8, v12
	v_mul_f32_e32 v7, v10, v7
	v_sub_f32_e32 v9, v13, v9
	v_add_f32_e32 v7, v9, v7
	v_mul_f32_e32 v12, 0x3f317218, v6
	v_add_f32_e32 v9, v8, v7
	v_fma_f32 v13, v6, s78, -v12
	v_mul_f32_e32 v10, v9, v9
	v_fmac_f32_e32 v13, 0xb102e308, v6
	v_sub_f32_e32 v6, v9, v8
	v_fmamk_f32 v11, v10, 0x3e9b6dac, v185
	v_sub_f32_e32 v6, v7, v6
	v_add_f32_e32 v7, v12, v13
	v_fmaak_f32 v11, v10, v11, 0x3f2aaada
	v_sub_f32_e32 v8, v7, v12
	v_ldexp_f32 v12, v9, 1
	v_mul_f32_e32 v9, v9, v10
	v_mul_f32_e32 v9, v9, v11
	v_add_f32_e32 v10, v12, v9
	v_sub_f32_e32 v11, v10, v12
	v_ldexp_f32 v6, v6, 1
	v_sub_f32_e32 v9, v9, v11
	v_add_f32_e32 v6, v6, v9
	v_add_f32_e32 v9, v10, v6
	v_sub_f32_e32 v10, v9, v10
	v_sub_f32_e32 v6, v6, v10
	v_add_f32_e32 v10, v7, v9
	v_sub_f32_e32 v11, v10, v7
	v_sub_f32_e32 v12, v10, v11
	v_sub_f32_e32 v8, v13, v8
	v_sub_f32_e32 v7, v7, v12
	v_sub_f32_e32 v9, v9, v11
	v_add_f32_e32 v7, v9, v7
	v_add_f32_e32 v9, v8, v6
	v_sub_f32_e32 v11, v9, v8
	v_sub_f32_e32 v12, v9, v11
	v_sub_f32_e32 v8, v8, v12
	v_sub_f32_e32 v6, v6, v11
	v_add_f32_e32 v7, v9, v7
	v_add_f32_e32 v6, v6, v8
	v_add_f32_e32 v8, v10, v7
	v_sub_f32_e32 v9, v8, v10
	v_sub_f32_e32 v7, v7, v9
	v_add_f32_e32 v6, v6, v7
	v_add_f32_e32 v6, v8, v6
	v_cndmask_b32_e32 v6, v226, v6, vcc
	v_cmp_lt_f32_e64 vcc, |v5|, s63
	s_nop 1
	v_cndmask_b32_e32 v5, v6, v5, vcc
	v_sub_f32_e32 v4, v4, v5
	v_mul_f32_e32 v4, 0x3fb8aa3b, v4
	global_store_dword v[30:31], v4, off offset:192
	v_readlane_b32 s100, v254, 4
	s_nop 1
	v_mov_b32_e32 v4, s100
	v_fmac_f32_e32 v4, v0, v156
	v_mul_f32_e64 v5, |v4|, s94
	v_fma_f32 v6, |v4|, s94, -v5
	v_rndne_f32_e32 v7, v5
	v_fma_f32 v6, |v4|, s64, v6
	v_sub_f32_e32 v5, v5, v7
	v_add_f32_e32 v5, v5, v6
	v_exp_f32_e32 v5, v5
	v_cvt_i32_f32_e32 v6, v7
	v_cmp_ngt_f32_e64 vcc, |v4|, s58
	v_min_f32_e32 v0, 0, v4
	v_ldexp_f32 v5, v5, v6
	v_cndmask_b32_e32 v5, 0, v5, vcc
	v_cmp_nlt_f32_e64 vcc, |v4|, s59
	s_nop 1
	v_cndmask_b32_e32 v4, v226, v5, vcc
	v_add_f32_e32 v5, 1.0, v4
	v_add_f32_e32 v6, -1.0, v5
	v_sub_f32_e32 v7, v6, v5
	v_add_f32_e32 v7, 1.0, v7
	v_sub_f32_e32 v6, v4, v6
	v_add_f32_e32 v8, v6, v7
	v_frexp_mant_f32_e32 v6, v5
	v_cmp_gt_f32_e32 vcc, s77, v6
	v_cvt_f64_f32_e32 v[6:7], v5
	v_frexp_exp_i32_f64_e32 v6, v[6:7]
	v_subbrev_co_u32_e32 v6, vcc, 0, v6, vcc
	v_sub_u32_e32 v7, 0, v6
	v_ldexp_f32 v5, v5, v7
	v_ldexp_f32 v7, v8, v7
	v_add_f32_e32 v8, -1.0, v5
	v_add_f32_e32 v9, 1.0, v8
	v_sub_f32_e32 v9, v5, v9
	v_add_f32_e32 v9, v7, v9
	v_add_f32_e32 v10, v8, v9
	v_sub_f32_e32 v8, v8, v10
	v_add_f32_e32 v8, v9, v8
	v_add_f32_e32 v9, 1.0, v5
	v_add_f32_e32 v11, -1.0, v9
	v_sub_f32_e32 v5, v5, v11
	v_add_f32_e32 v5, v7, v5
	v_add_f32_e32 v7, v9, v5
	v_sub_f32_e32 v9, v9, v7
	v_add_f32_e32 v5, v5, v9
	v_rcp_f32_e32 v9, v7
	v_cvt_f32_i32_e32 v6, v6
	v_cmp_neq_f32_e32 vcc, s62, v4
	v_mul_f32_e32 v11, v10, v9
	v_mul_f32_e32 v12, v7, v11
	v_fma_f32 v13, v11, v7, -v12
	v_fmac_f32_e32 v13, v11, v5
	v_add_f32_e32 v14, v12, v13
	v_sub_f32_e32 v15, v10, v14
	v_sub_f32_e32 v10, v10, v15
	v_sub_f32_e32 v12, v14, v12
	v_sub_f32_e32 v10, v10, v14
	v_add_f32_e32 v8, v8, v10
	v_sub_f32_e32 v10, v12, v13
	v_add_f32_e32 v8, v10, v8
	v_add_f32_e32 v10, v15, v8
	v_mul_f32_e32 v12, v9, v10
	v_mul_f32_e32 v13, v7, v12
	v_fma_f32 v7, v12, v7, -v13
	v_fmac_f32_e32 v7, v12, v5
	v_sub_f32_e32 v5, v15, v10
	v_add_f32_e32 v5, v8, v5
	v_add_f32_e32 v8, v13, v7
	v_sub_f32_e32 v14, v10, v8
	v_sub_f32_e32 v10, v10, v14
	v_sub_f32_e32 v13, v8, v13
	v_sub_f32_e32 v8, v10, v8
	v_add_f32_e32 v5, v5, v8
	v_sub_f32_e32 v7, v13, v7
	v_add_f32_e32 v5, v7, v5
	v_add_f32_e32 v7, v11, v12
	v_add_f32_e32 v5, v14, v5
	v_sub_f32_e32 v8, v7, v11
	v_mul_f32_e32 v5, v9, v5
	v_sub_f32_e32 v8, v12, v8
	v_add_f32_e32 v5, v8, v5
	v_mul_f32_e32 v11, 0x3f317218, v6
	v_add_f32_e32 v8, v7, v5
	v_fma_f32 v12, v6, s78, -v11
	v_mul_f32_e32 v9, v8, v8
	v_fmac_f32_e32 v12, 0xb102e308, v6
	v_sub_f32_e32 v6, v8, v7
	v_fmamk_f32 v10, v9, 0x3e9b6dac, v185
	v_sub_f32_e32 v5, v5, v6
	v_add_f32_e32 v6, v11, v12
	v_fmaak_f32 v10, v9, v10, 0x3f2aaada
	v_sub_f32_e32 v7, v6, v11
	v_ldexp_f32 v11, v8, 1
	v_mul_f32_e32 v8, v8, v9
	v_mul_f32_e32 v8, v8, v10
	v_add_f32_e32 v9, v11, v8
	v_sub_f32_e32 v10, v9, v11
	v_ldexp_f32 v5, v5, 1
	v_sub_f32_e32 v8, v8, v10
	v_add_f32_e32 v5, v5, v8
	v_add_f32_e32 v8, v9, v5
	v_sub_f32_e32 v9, v8, v9
	v_sub_f32_e32 v5, v5, v9
	v_add_f32_e32 v9, v6, v8
	v_sub_f32_e32 v10, v9, v6
	v_sub_f32_e32 v11, v9, v10
	v_sub_f32_e32 v7, v12, v7
	v_sub_f32_e32 v6, v6, v11
	v_sub_f32_e32 v8, v8, v10
	v_add_f32_e32 v6, v8, v6
	v_add_f32_e32 v8, v7, v5
	v_sub_f32_e32 v10, v8, v7
	v_sub_f32_e32 v11, v8, v10
	v_sub_f32_e32 v7, v7, v11
	v_sub_f32_e32 v5, v5, v10
	v_add_f32_e32 v6, v8, v6
	v_add_f32_e32 v5, v5, v7
	v_add_f32_e32 v7, v9, v6
	v_sub_f32_e32 v8, v7, v9
	v_sub_f32_e32 v6, v6, v8
	v_add_f32_e32 v5, v5, v6
	v_add_f32_e32 v5, v7, v5
	v_cndmask_b32_e32 v5, v226, v5, vcc
	v_cmp_lt_f32_e64 vcc, |v4|, s63
	s_nop 1
	v_cndmask_b32_e32 v4, v5, v4, vcc
	v_sub_f32_e32 v0, v0, v4
	v_mul_f32_e32 v0, 0x3fb8aa3b, v0
	global_store_dword v[36:37], v0, off offset:192
	v_readlane_b32 s100, v254, 5
	s_nop 1
	v_mov_b32_e32 v4, s100
	v_fmac_f32_e32 v4, v1, v156
	v_mul_f32_e64 v1, |v4|, s94
	v_fma_f32 v5, |v4|, s94, -v1
	v_rndne_f32_e32 v6, v1
	v_fma_f32 v5, |v4|, s64, v5
	v_sub_f32_e32 v1, v1, v6
	v_add_f32_e32 v1, v1, v5
	v_exp_f32_e32 v1, v1
	v_cvt_i32_f32_e32 v5, v6
	v_cmp_ngt_f32_e64 vcc, |v4|, s58
	v_min_f32_e32 v0, 0, v4
	v_ldexp_f32 v1, v1, v5
	v_cndmask_b32_e32 v1, 0, v1, vcc
	v_cmp_nlt_f32_e64 vcc, |v4|, s59
	s_nop 1
	v_cndmask_b32_e32 v1, v226, v1, vcc
	v_add_f32_e32 v6, 1.0, v1
	v_add_f32_e32 v4, -1.0, v6
	v_sub_f32_e32 v5, v4, v6
	v_add_f32_e32 v5, 1.0, v5
	v_sub_f32_e32 v4, v1, v4
	v_add_f32_e32 v7, v4, v5
	v_frexp_mant_f32_e32 v4, v6
	v_cmp_gt_f32_e32 vcc, s77, v4
	v_cvt_f64_f32_e32 v[4:5], v6
	v_frexp_exp_i32_f64_e32 v4, v[4:5]
	v_subbrev_co_u32_e32 v4, vcc, 0, v4, vcc
	v_sub_u32_e32 v5, 0, v4
	v_ldexp_f32 v6, v6, v5
	v_ldexp_f32 v5, v7, v5
	v_add_f32_e32 v7, -1.0, v6
	v_add_f32_e32 v8, 1.0, v7
	v_sub_f32_e32 v8, v6, v8
	v_add_f32_e32 v8, v5, v8
	v_add_f32_e32 v9, v7, v8
	v_sub_f32_e32 v7, v7, v9
	v_add_f32_e32 v7, v8, v7
	v_add_f32_e32 v8, 1.0, v6
	v_add_f32_e32 v10, -1.0, v8
	v_sub_f32_e32 v6, v6, v10
	v_add_f32_e32 v5, v5, v6
	v_add_f32_e32 v6, v8, v5
	v_sub_f32_e32 v8, v8, v6
	v_add_f32_e32 v5, v5, v8
	v_rcp_f32_e32 v8, v6
	v_cvt_f32_i32_e32 v4, v4
	v_cmp_neq_f32_e32 vcc, s62, v1
	v_mul_f32_e32 v10, v9, v8
	v_mul_f32_e32 v11, v6, v10
	v_fma_f32 v12, v10, v6, -v11
	v_fmac_f32_e32 v12, v10, v5
	v_add_f32_e32 v13, v11, v12
	v_sub_f32_e32 v14, v9, v13
	v_sub_f32_e32 v9, v9, v14
	v_sub_f32_e32 v11, v13, v11
	v_sub_f32_e32 v9, v9, v13
	v_add_f32_e32 v7, v7, v9
	v_sub_f32_e32 v9, v11, v12
	v_add_f32_e32 v7, v9, v7
	v_add_f32_e32 v9, v14, v7
	v_mul_f32_e32 v11, v8, v9
	v_mul_f32_e32 v12, v6, v11
	v_fma_f32 v6, v11, v6, -v12
	v_fmac_f32_e32 v6, v11, v5
	v_sub_f32_e32 v5, v14, v9
	v_add_f32_e32 v5, v7, v5
	v_add_f32_e32 v7, v12, v6
	v_sub_f32_e32 v13, v9, v7
	v_sub_f32_e32 v9, v9, v13
	v_sub_f32_e32 v12, v7, v12
	v_sub_f32_e32 v7, v9, v7
	v_add_f32_e32 v5, v5, v7
	v_sub_f32_e32 v6, v12, v6
	v_add_f32_e32 v5, v6, v5
	v_add_f32_e32 v6, v10, v11
	v_add_f32_e32 v5, v13, v5
	v_sub_f32_e32 v7, v6, v10
	v_mul_f32_e32 v5, v8, v5
	v_sub_f32_e32 v7, v11, v7
	v_add_f32_e32 v5, v7, v5
	v_mul_f32_e32 v10, 0x3f317218, v4
	v_add_f32_e32 v7, v6, v5
	v_fma_f32 v11, v4, s78, -v10
	v_mul_f32_e32 v8, v7, v7
	v_fmac_f32_e32 v11, 0xb102e308, v4
	v_sub_f32_e32 v4, v7, v6
	v_fmamk_f32 v9, v8, 0x3e9b6dac, v185
	v_sub_f32_e32 v4, v5, v4
	v_add_f32_e32 v5, v10, v11
	v_fmaak_f32 v9, v8, v9, 0x3f2aaada
	v_sub_f32_e32 v6, v5, v10
	v_ldexp_f32 v10, v7, 1
	v_mul_f32_e32 v7, v7, v8
	v_mul_f32_e32 v7, v7, v9
	v_add_f32_e32 v8, v10, v7
	v_sub_f32_e32 v9, v8, v10
	v_ldexp_f32 v4, v4, 1
	v_sub_f32_e32 v7, v7, v9
	v_add_f32_e32 v4, v4, v7
	v_add_f32_e32 v7, v8, v4
	v_sub_f32_e32 v8, v7, v8
	v_sub_f32_e32 v4, v4, v8
	v_add_f32_e32 v8, v5, v7
	v_sub_f32_e32 v9, v8, v5
	v_sub_f32_e32 v10, v8, v9
	v_sub_f32_e32 v6, v11, v6
	v_sub_f32_e32 v5, v5, v10
	v_sub_f32_e32 v7, v7, v9
	v_add_f32_e32 v5, v7, v5
	v_add_f32_e32 v7, v6, v4
	v_sub_f32_e32 v9, v7, v6
	v_sub_f32_e32 v10, v7, v9
	v_sub_f32_e32 v6, v6, v10
	v_sub_f32_e32 v4, v4, v9
	v_add_f32_e32 v5, v7, v5
	v_add_f32_e32 v4, v4, v6
	v_add_f32_e32 v6, v8, v5
	v_sub_f32_e32 v7, v6, v8
	v_sub_f32_e32 v5, v5, v7
	v_add_f32_e32 v4, v4, v5
	v_add_f32_e32 v4, v6, v4
	v_cndmask_b32_e32 v4, v226, v4, vcc
	v_cmp_lt_f32_e64 vcc, |v1|, s63
	s_nop 1
	v_cndmask_b32_e32 v1, v4, v1, vcc
	v_sub_f32_e32 v0, v0, v1
	v_mul_f32_e32 v0, 0x3fb8aa3b, v0
	global_store_dword v[24:25], v0, off offset:192
	v_readlane_b32 s100, v254, 6
	s_nop 1
	v_mov_b32_e32 v1, s100
	v_fmac_f32_e32 v1, v2, v156
	v_mul_f32_e64 v2, |v1|, s94
	v_fma_f32 v4, |v1|, s94, -v2
	v_rndne_f32_e32 v5, v2
	v_fma_f32 v4, |v1|, s64, v4
	v_sub_f32_e32 v2, v2, v5
	v_add_f32_e32 v2, v2, v4
	v_exp_f32_e32 v2, v2
	v_cvt_i32_f32_e32 v4, v5
	v_cmp_ngt_f32_e64 vcc, |v1|, s58
	v_min_f32_e32 v0, 0, v1
	v_ldexp_f32 v2, v2, v4
	v_cndmask_b32_e32 v2, 0, v2, vcc
	v_cmp_nlt_f32_e64 vcc, |v1|, s59
	s_nop 1
	v_cndmask_b32_e32 v1, v226, v2, vcc
	v_add_f32_e32 v2, 1.0, v1
	v_add_f32_e32 v4, -1.0, v2
	v_sub_f32_e32 v5, v4, v2
	v_add_f32_e32 v5, 1.0, v5
	v_sub_f32_e32 v4, v1, v4
	v_add_f32_e32 v6, v4, v5
	v_frexp_mant_f32_e32 v4, v2
	v_cmp_gt_f32_e32 vcc, s77, v4
	v_cvt_f64_f32_e32 v[4:5], v2
	v_frexp_exp_i32_f64_e32 v4, v[4:5]
	v_subbrev_co_u32_e32 v4, vcc, 0, v4, vcc
	v_sub_u32_e32 v5, 0, v4
	v_ldexp_f32 v2, v2, v5
	v_ldexp_f32 v5, v6, v5
	v_add_f32_e32 v6, -1.0, v2
	v_add_f32_e32 v7, 1.0, v6
	v_sub_f32_e32 v7, v2, v7
	v_add_f32_e32 v7, v5, v7
	v_add_f32_e32 v8, v6, v7
	v_sub_f32_e32 v6, v6, v8
	v_add_f32_e32 v6, v7, v6
	v_add_f32_e32 v7, 1.0, v2
	v_add_f32_e32 v9, -1.0, v7
	v_sub_f32_e32 v2, v2, v9
	v_add_f32_e32 v2, v5, v2
	v_add_f32_e32 v5, v7, v2
	v_sub_f32_e32 v7, v7, v5
	v_add_f32_e32 v2, v2, v7
	v_rcp_f32_e32 v7, v5
	v_cvt_f32_i32_e32 v4, v4
	v_cmp_neq_f32_e32 vcc, s62, v1
	v_mul_f32_e32 v9, v8, v7
	v_mul_f32_e32 v10, v5, v9
	v_fma_f32 v11, v9, v5, -v10
	v_fmac_f32_e32 v11, v9, v2
	v_add_f32_e32 v12, v10, v11
	v_sub_f32_e32 v13, v8, v12
	v_sub_f32_e32 v8, v8, v13
	v_sub_f32_e32 v10, v12, v10
	v_sub_f32_e32 v8, v8, v12
	v_add_f32_e32 v6, v6, v8
	v_sub_f32_e32 v8, v10, v11
	v_add_f32_e32 v6, v8, v6
	v_add_f32_e32 v8, v13, v6
	v_mul_f32_e32 v10, v7, v8
	v_mul_f32_e32 v11, v5, v10
	v_fma_f32 v5, v10, v5, -v11
	v_fmac_f32_e32 v5, v10, v2
	v_sub_f32_e32 v2, v13, v8
	v_add_f32_e32 v2, v6, v2
	v_add_f32_e32 v6, v11, v5
	v_sub_f32_e32 v12, v8, v6
	v_sub_f32_e32 v8, v8, v12
	v_sub_f32_e32 v11, v6, v11
	v_sub_f32_e32 v6, v8, v6
	v_add_f32_e32 v2, v2, v6
	v_sub_f32_e32 v5, v11, v5
	v_add_f32_e32 v2, v5, v2
	v_add_f32_e32 v5, v9, v10
	v_add_f32_e32 v2, v12, v2
	v_sub_f32_e32 v6, v5, v9
	v_mul_f32_e32 v2, v7, v2
	v_sub_f32_e32 v6, v10, v6
	v_add_f32_e32 v2, v6, v2
	v_mul_f32_e32 v9, 0x3f317218, v4
	v_add_f32_e32 v6, v5, v2
	v_fma_f32 v10, v4, s78, -v9
	v_mul_f32_e32 v7, v6, v6
	v_fmac_f32_e32 v10, 0xb102e308, v4
	v_sub_f32_e32 v4, v6, v5
	v_fmamk_f32 v8, v7, 0x3e9b6dac, v185
	v_sub_f32_e32 v2, v2, v4
	v_add_f32_e32 v4, v9, v10
	v_fmaak_f32 v8, v7, v8, 0x3f2aaada
	v_sub_f32_e32 v5, v4, v9
	v_ldexp_f32 v9, v6, 1
	v_mul_f32_e32 v6, v6, v7
	v_mul_f32_e32 v6, v6, v8
	v_add_f32_e32 v7, v9, v6
	v_sub_f32_e32 v8, v7, v9
	v_ldexp_f32 v2, v2, 1
	v_sub_f32_e32 v6, v6, v8
	v_add_f32_e32 v2, v2, v6
	v_add_f32_e32 v6, v7, v2
	v_sub_f32_e32 v7, v6, v7
	v_sub_f32_e32 v2, v2, v7
	v_add_f32_e32 v7, v4, v6
	v_sub_f32_e32 v8, v7, v4
	v_sub_f32_e32 v9, v7, v8
	v_sub_f32_e32 v5, v10, v5
	v_sub_f32_e32 v4, v4, v9
	v_sub_f32_e32 v6, v6, v8
	v_add_f32_e32 v4, v6, v4
	v_add_f32_e32 v6, v5, v2
	v_sub_f32_e32 v8, v6, v5
	v_sub_f32_e32 v9, v6, v8
	v_sub_f32_e32 v5, v5, v9
	v_sub_f32_e32 v2, v2, v8
	v_add_f32_e32 v4, v6, v4
	v_add_f32_e32 v2, v2, v5
	v_add_f32_e32 v5, v7, v4
	v_sub_f32_e32 v6, v5, v7
	v_sub_f32_e32 v4, v4, v6
	v_add_f32_e32 v2, v2, v4
	v_add_f32_e32 v2, v5, v2
	v_cndmask_b32_e32 v2, v226, v2, vcc
	v_cmp_lt_f32_e64 vcc, |v1|, s63
	s_nop 1
	v_cndmask_b32_e32 v1, v2, v1, vcc
	v_sub_f32_e32 v0, v0, v1
	v_mul_f32_e32 v0, 0x3fb8aa3b, v0
	global_store_dword v[38:39], v0, off offset:192
	v_readlane_b32 s100, v254, 7
	s_nop 1
	v_mov_b32_e32 v1, s100
	v_fmac_f32_e32 v1, v3, v156
	v_mul_f32_e64 v2, |v1|, s94
	v_fma_f32 v3, |v1|, s94, -v2
	v_rndne_f32_e32 v4, v2
	v_fma_f32 v3, |v1|, s64, v3
	v_sub_f32_e32 v2, v2, v4
	v_add_f32_e32 v2, v2, v3
	v_exp_f32_e32 v2, v2
	v_cvt_i32_f32_e32 v3, v4
	v_cmp_ngt_f32_e64 vcc, |v1|, s58
	v_min_f32_e32 v0, 0, v1
	v_ldexp_f32 v2, v2, v3
	v_cndmask_b32_e32 v2, 0, v2, vcc
	v_cmp_nlt_f32_e64 vcc, |v1|, s59
	s_nop 1
	v_cndmask_b32_e32 v1, v226, v2, vcc
	v_add_f32_e32 v4, 1.0, v1
	v_add_f32_e32 v2, -1.0, v4
	v_sub_f32_e32 v3, v2, v4
	v_add_f32_e32 v3, 1.0, v3
	v_sub_f32_e32 v2, v1, v2
	v_add_f32_e32 v5, v2, v3
	v_frexp_mant_f32_e32 v2, v4
	v_cmp_gt_f32_e32 vcc, s77, v2
	v_cvt_f64_f32_e32 v[2:3], v4
	v_frexp_exp_i32_f64_e32 v2, v[2:3]
	v_subbrev_co_u32_e32 v2, vcc, 0, v2, vcc
	v_sub_u32_e32 v3, 0, v2
	v_ldexp_f32 v4, v4, v3
	v_ldexp_f32 v3, v5, v3
	v_add_f32_e32 v5, -1.0, v4
	v_add_f32_e32 v6, 1.0, v5
	v_sub_f32_e32 v6, v4, v6
	v_add_f32_e32 v6, v3, v6
	v_add_f32_e32 v7, v5, v6
	v_sub_f32_e32 v5, v5, v7
	v_add_f32_e32 v5, v6, v5
	v_add_f32_e32 v6, 1.0, v4
	v_add_f32_e32 v8, -1.0, v6
	v_sub_f32_e32 v4, v4, v8
	v_add_f32_e32 v3, v3, v4
	v_add_f32_e32 v4, v6, v3
	v_sub_f32_e32 v6, v6, v4
	v_add_f32_e32 v3, v3, v6
	v_rcp_f32_e32 v6, v4
	v_cvt_f32_i32_e32 v2, v2
	v_cmp_neq_f32_e32 vcc, s62, v1
	v_mul_f32_e32 v8, v7, v6
	v_mul_f32_e32 v9, v4, v8
	v_fma_f32 v10, v8, v4, -v9
	v_fmac_f32_e32 v10, v8, v3
	v_add_f32_e32 v11, v9, v10
	v_sub_f32_e32 v12, v7, v11
	v_sub_f32_e32 v7, v7, v12
	v_sub_f32_e32 v9, v11, v9
	v_sub_f32_e32 v7, v7, v11
	v_add_f32_e32 v5, v5, v7
	v_sub_f32_e32 v7, v9, v10
	v_add_f32_e32 v5, v7, v5
	v_add_f32_e32 v7, v12, v5
	v_mul_f32_e32 v9, v6, v7
	v_mul_f32_e32 v10, v4, v9
	v_fma_f32 v4, v9, v4, -v10
	v_fmac_f32_e32 v4, v9, v3
	v_sub_f32_e32 v3, v12, v7
	v_add_f32_e32 v3, v5, v3
	v_add_f32_e32 v5, v10, v4
	v_sub_f32_e32 v11, v7, v5
	v_sub_f32_e32 v7, v7, v11
	v_sub_f32_e32 v10, v5, v10
	v_sub_f32_e32 v5, v7, v5
	v_add_f32_e32 v3, v3, v5
	v_sub_f32_e32 v4, v10, v4
	v_add_f32_e32 v3, v4, v3
	v_add_f32_e32 v4, v8, v9
	v_add_f32_e32 v3, v11, v3
	v_sub_f32_e32 v5, v4, v8
	v_mul_f32_e32 v3, v6, v3
	v_sub_f32_e32 v5, v9, v5
	v_add_f32_e32 v3, v5, v3
	v_mul_f32_e32 v8, 0x3f317218, v2
	v_add_f32_e32 v5, v4, v3
	v_fma_f32 v9, v2, s78, -v8
	v_mul_f32_e32 v6, v5, v5
	v_fmac_f32_e32 v9, 0xb102e308, v2
	v_sub_f32_e32 v2, v5, v4
	v_fmamk_f32 v7, v6, 0x3e9b6dac, v185
	v_sub_f32_e32 v2, v3, v2
	v_add_f32_e32 v3, v8, v9
	v_fmaak_f32 v7, v6, v7, 0x3f2aaada
	v_sub_f32_e32 v4, v3, v8
	v_ldexp_f32 v8, v5, 1
	v_mul_f32_e32 v5, v5, v6
	v_mul_f32_e32 v5, v5, v7
	v_add_f32_e32 v6, v8, v5
	v_sub_f32_e32 v7, v6, v8
	v_ldexp_f32 v2, v2, 1
	v_sub_f32_e32 v5, v5, v7
	v_add_f32_e32 v2, v2, v5
	v_add_f32_e32 v5, v6, v2
	v_sub_f32_e32 v6, v5, v6
	v_sub_f32_e32 v2, v2, v6
	v_add_f32_e32 v6, v3, v5
	v_sub_f32_e32 v7, v6, v3
	v_sub_f32_e32 v8, v6, v7
	v_sub_f32_e32 v4, v9, v4
	v_sub_f32_e32 v3, v3, v8
	v_sub_f32_e32 v5, v5, v7
	v_add_f32_e32 v3, v5, v3
	v_add_f32_e32 v5, v4, v2
	v_sub_f32_e32 v7, v5, v4
	v_sub_f32_e32 v8, v5, v7
	v_sub_f32_e32 v4, v4, v8
	v_sub_f32_e32 v2, v2, v7
	v_add_f32_e32 v3, v5, v3
	v_add_f32_e32 v2, v2, v4
	v_add_f32_e32 v4, v6, v3
	v_sub_f32_e32 v5, v4, v6
	v_sub_f32_e32 v3, v3, v5
	v_add_f32_e32 v2, v2, v3
	v_add_f32_e32 v2, v4, v2
	v_cndmask_b32_e32 v2, v226, v2, vcc
	v_cmp_lt_f32_e64 vcc, |v1|, s63
	s_nop 1
	v_cndmask_b32_e32 v1, v2, v1, vcc
	v_sub_f32_e32 v0, v0, v1
	v_mul_f32_e32 v0, 0x3fb8aa3b, v0
	global_store_dword v[26:27], v0, off offset:192
